# v68 + even-phase LOAD segments: the 8 ds_reads spread in pairs behind the first four LDS-DMA issues
# baseline (speedup 1.0000x reference)
.LBB0_297:
	s_add_u32 s47, s38, s46
	s_addc_u32 s66, s39, 0
	s_add_u32 s64, s47, 0x100
	s_addc_u32 s65, s66, 0
	s_and_b64 s[48:49], s[44:45], exec
	s_cselect_b32 s49, s70, s65
	s_cselect_b32 s48, s71, s64
	s_add_u32 s46, s36, s46
	s_addc_u32 s64, s37, 0
	s_add_u32 s46, s46, 0x100
	s_addc_u32 s64, s64, 0
	s_and_b64 s[44:45], s[44:45], exec
	s_cselect_b32 s65, s72, s64
	s_cselect_b32 s64, s73, s46
	s_add_u32 s68, s47, 0x10080
	ds_read_b128 v[150:153], v146
	ds_read_b128 v[154:157], v146 offset:1024
	ds_read_b128 v[158:161], v146 offset:2048
	ds_read_b128 v[162:165], v146 offset:3072
	ds_read_b128 v[166:169], v147
	ds_read_b128 v[170:173], v147 offset:1024
	ds_read_b128 v[174:177], v147 offset:2048
	ds_read_b128 v[178:181], v147 offset:3072
	s_addc_u32 s69, s66, 0
	s_add_i32 s83, s30, s2
	s_add_i32 m0, s16, 0xc000
	s_add_i32 s84, s16, 0xe000
	s_add_i32 s80, s83, 0x2000
	s_add_u32 s66, s64, 0x40000
	s_addc_u32 s67, s65, 0
	s_add_i32 s82, s31, s2
	s_add_i32 s81, s82, 0x2000
	s_add_i32 s79, 0, 0x18000
	s_add_i32 s78, 0, 0x1c000
	s_add_u32 s46, s48, 0x10000
	s_addc_u32 s47, s49, 0
	s_add_i32 s77, s79, s2
	s_add_i32 s75, s77, 0x2000
	s_add_u32 s44, s64, 0x40080
	s_addc_u32 s45, s65, 0
	s_add_i32 s76, s78, s2
	s_add_i32 s74, s76, 0x2000
	v_lshl_add_u64 v[202:203], s[68:69], 0, v[130:131]
	ds_read_b128 v[182:185], v148
	ds_read_b128 v[186:189], v148 offset:1024
	ds_read_b128 v[190:193], v148 offset:2048
	ds_read_b128 v[194:197], v148 offset:3072
	ds_read_b128 v[198:201], v148 offset:4096
	ds_read_b128 v[206:209], v148 offset:5120
	ds_read_b128 v[210:213], v148 offset:6144
	ds_read_b128 v[214:217], v148 offset:7168
	global_load_lds_dwordx4 v[202:203], off
	s_mov_b32 m0, s84
	v_lshl_add_u64 v[202:203], s[68:69], 0, v[132:133]
	global_load_lds_dwordx4 v[202:203], off
	s_waitcnt vmcnt(8) lgkmcnt(0)
	s_setprio 1
	s_barrier
	v_mfma_f32_16x16x32_bf16 v[126:129], v[150:153], v[182:185], v[126:129]
	v_mfma_f32_16x16x32_bf16 v[122:125], v[158:161], v[182:185], v[122:125]
	v_mfma_f32_16x16x32_bf16 v[118:121], v[150:153], v[190:193], v[118:121]
	v_mfma_f32_16x16x32_bf16 v[114:117], v[158:161], v[190:193], v[114:117]
	v_mfma_f32_16x16x32_bf16 v[102:105], v[150:153], v[198:201], v[102:105]
	v_mfma_f32_16x16x32_bf16 v[98:101], v[158:161], v[198:201], v[98:101]
	v_mfma_f32_16x16x32_bf16 v[86:89], v[150:153], v[210:213], v[86:89]
	v_mfma_f32_16x16x32_bf16 v[82:85], v[158:161], v[210:213], v[82:85]
	v_mfma_f32_16x16x32_bf16 v[126:129], v[154:157], v[186:189], v[126:129]
	v_mfma_f32_16x16x32_bf16 v[122:125], v[162:165], v[186:189], v[122:125]
	v_mfma_f32_16x16x32_bf16 v[118:121], v[154:157], v[194:197], v[118:121]
	v_mfma_f32_16x16x32_bf16 v[114:117], v[162:165], v[194:197], v[114:117]
	v_mfma_f32_16x16x32_bf16 v[102:105], v[154:157], v[206:209], v[102:105]
	v_mfma_f32_16x16x32_bf16 v[98:101], v[162:165], v[206:209], v[98:101]
	v_mfma_f32_16x16x32_bf16 v[86:89], v[154:157], v[214:217], v[86:89]
	v_mfma_f32_16x16x32_bf16 v[82:85], v[162:165], v[214:217], v[82:85]
	v_mfma_f32_16x16x32_bf16 v[110:113], v[166:169], v[182:185], v[110:113]
	v_mfma_f32_16x16x32_bf16 v[106:109], v[174:177], v[182:185], v[106:109]
	v_mfma_f32_16x16x32_bf16 v[94:97], v[166:169], v[190:193], v[94:97]
	v_mfma_f32_16x16x32_bf16 v[90:93], v[174:177], v[190:193], v[90:93]
	v_mfma_f32_16x16x32_bf16 v[78:81], v[166:169], v[198:201], v[78:81]
	v_mfma_f32_16x16x32_bf16 v[74:77], v[174:177], v[198:201], v[74:77]
	v_mfma_f32_16x16x32_bf16 v[70:73], v[166:169], v[210:213], v[70:73]
	v_mfma_f32_16x16x32_bf16 v[66:69], v[174:177], v[210:213], v[66:69]
	v_mfma_f32_16x16x32_bf16 v[110:113], v[170:173], v[186:189], v[110:113]
	v_mfma_f32_16x16x32_bf16 v[106:109], v[178:181], v[186:189], v[106:109]
	v_mfma_f32_16x16x32_bf16 v[94:97], v[170:173], v[194:197], v[94:97]
	v_mfma_f32_16x16x32_bf16 v[90:93], v[178:181], v[194:197], v[90:93]
	v_mfma_f32_16x16x32_bf16 v[78:81], v[170:173], v[206:209], v[78:81]
	v_mfma_f32_16x16x32_bf16 v[74:77], v[178:181], v[206:209], v[74:77]
	v_mfma_f32_16x16x32_bf16 v[70:73], v[170:173], v[214:217], v[70:73]
	v_mfma_f32_16x16x32_bf16 v[66:69], v[178:181], v[214:217], v[66:69]
	s_setprio 0
	s_barrier
	s_mov_b32 m0, s83
	v_lshl_add_u64 v[202:203], s[64:65], 0, v[136:137]
	global_load_lds_dwordx4 v[202:203], off
	ds_read_b128 v[182:185], v148 offset:16384
	ds_read_b128 v[186:189], v148 offset:17408
	v_lshl_add_u64 v[218:219], s[64:65], 0, v[134:135]
	s_mov_b32 m0, s80
	v_lshl_add_u64 v[220:221], s[66:67], 0, v[136:137]
	global_load_lds_dwordx4 v[218:219], off
	ds_read_b128 v[190:193], v148 offset:18432
	ds_read_b128 v[194:197], v148 offset:19456
	s_mov_b32 m0, s82
	v_lshl_add_u64 v[222:223], s[48:49], 0, v[132:133]
	global_load_lds_dwordx4 v[220:221], off
	ds_read_b128 v[198:201], v148 offset:20480
	ds_read_b128 v[206:209], v148 offset:21504
	s_mov_b32 m0, s81
	v_lshl_add_u64 v[220:221], s[66:67], 0, v[134:135]
	global_load_lds_dwordx4 v[220:221], off
	ds_read_b128 v[210:213], v148 offset:22528
	ds_read_b128 v[214:217], v148 offset:23552
	s_mov_b32 m0, s16
	v_lshl_add_u64 v[220:221], s[48:49], 0, v[130:131]
	global_load_lds_dwordx4 v[220:221], off
	s_mov_b32 m0, s17
	s_nop 0
	global_load_lds_dwordx4 v[222:223], off
	s_waitcnt vmcnt(8) lgkmcnt(0)
	s_setprio 1
	s_barrier
	v_mfma_f32_16x16x32_bf16 v[62:65], v[150:153], v[182:185], v[62:65]
	v_mfma_f32_16x16x32_bf16 v[58:61], v[158:161], v[182:185], v[58:61]
	v_mfma_f32_16x16x32_bf16 v[54:57], v[150:153], v[190:193], v[54:57]
	v_mfma_f32_16x16x32_bf16 v[50:53], v[158:161], v[190:193], v[50:53]
	v_mfma_f32_16x16x32_bf16 v[38:41], v[150:153], v[198:201], v[38:41]
	v_mfma_f32_16x16x32_bf16 v[34:37], v[158:161], v[198:201], v[34:37]
	v_mfma_f32_16x16x32_bf16 v[22:25], v[150:153], v[210:213], v[22:25]
	v_mfma_f32_16x16x32_bf16 v[18:21], v[158:161], v[210:213], v[18:21]
	v_mfma_f32_16x16x32_bf16 v[62:65], v[154:157], v[186:189], v[62:65]
	v_mfma_f32_16x16x32_bf16 v[58:61], v[162:165], v[186:189], v[58:61]
	v_mfma_f32_16x16x32_bf16 v[54:57], v[154:157], v[194:197], v[54:57]
	v_mfma_f32_16x16x32_bf16 v[50:53], v[162:165], v[194:197], v[50:53]
	v_mfma_f32_16x16x32_bf16 v[38:41], v[154:157], v[206:209], v[38:41]
	v_mfma_f32_16x16x32_bf16 v[34:37], v[162:165], v[206:209], v[34:37]
	v_mfma_f32_16x16x32_bf16 v[22:25], v[154:157], v[214:217], v[22:25]
	v_mfma_f32_16x16x32_bf16 v[18:21], v[162:165], v[214:217], v[18:21]
	v_mfma_f32_16x16x32_bf16 v[46:49], v[166:169], v[182:185], v[46:49]
	v_mfma_f32_16x16x32_bf16 v[42:45], v[174:177], v[182:185], v[42:45]
	v_mfma_f32_16x16x32_bf16 v[30:33], v[166:169], v[190:193], v[30:33]
	v_mfma_f32_16x16x32_bf16 v[26:29], v[174:177], v[190:193], v[26:29]
	v_mfma_f32_16x16x32_bf16 v[14:17], v[166:169], v[198:201], v[14:17]
	v_mfma_f32_16x16x32_bf16 v[10:13], v[174:177], v[198:201], v[10:13]
	v_mfma_f32_16x16x32_bf16 v[6:9], v[166:169], v[210:213], v[6:9]
	v_mfma_f32_16x16x32_bf16 v[2:5], v[174:177], v[210:213], v[2:5]
	v_mfma_f32_16x16x32_bf16 v[46:49], v[170:173], v[186:189], v[46:49]
	v_mfma_f32_16x16x32_bf16 v[42:45], v[178:181], v[186:189], v[42:45]
	v_mfma_f32_16x16x32_bf16 v[30:33], v[170:173], v[194:197], v[30:33]
	v_mfma_f32_16x16x32_bf16 v[26:29], v[178:181], v[194:197], v[26:29]
	v_mfma_f32_16x16x32_bf16 v[14:17], v[170:173], v[206:209], v[14:17]
	v_mfma_f32_16x16x32_bf16 v[10:13], v[178:181], v[206:209], v[10:13]
	v_mfma_f32_16x16x32_bf16 v[6:9], v[170:173], v[214:217], v[6:9]
	v_mfma_f32_16x16x32_bf16 v[2:5], v[178:181], v[214:217], v[2:5]
	s_setprio 0
	s_barrier
	v_add_u32_e32 v149, s79, v145
	ds_read_b128 v[150:153], v149
	ds_read_b128 v[154:157], v149 offset:1024
	ds_read_b128 v[158:161], v149 offset:2048
	ds_read_b128 v[162:165], v149 offset:3072
	v_add_u32_e32 v149, s78, v145
	ds_read_b128 v[166:169], v149
	ds_read_b128 v[170:173], v149 offset:1024
	ds_read_b128 v[174:177], v149 offset:2048
	ds_read_b128 v[178:181], v149 offset:3072
	s_mov_b32 m0, s18
	v_lshl_add_u64 v[224:225], s[46:47], 0, v[130:131]
	ds_read_b128 v[182:185], v148 offset:32768
	ds_read_b128 v[186:189], v148 offset:33792
	ds_read_b128 v[190:193], v148 offset:34816
	ds_read_b128 v[194:197], v148 offset:35840
	ds_read_b128 v[198:201], v148 offset:36864
	ds_read_b128 v[206:209], v148 offset:37888
	ds_read_b128 v[210:213], v148 offset:38912
	ds_read_b128 v[214:217], v148 offset:39936
	global_load_lds_dwordx4 v[224:225], off
	s_mov_b32 m0, s19
	v_lshl_add_u64 v[224:225], s[46:47], 0, v[132:133]
	global_load_lds_dwordx4 v[224:225], off
	s_waitcnt vmcnt(8) lgkmcnt(0)
	s_setprio 1
	s_barrier
	v_mfma_f32_16x16x32_bf16 v[126:129], v[150:153], v[182:185], v[126:129]
	v_mfma_f32_16x16x32_bf16 v[122:125], v[158:161], v[182:185], v[122:125]
	v_mfma_f32_16x16x32_bf16 v[118:121], v[150:153], v[190:193], v[118:121]
	v_mfma_f32_16x16x32_bf16 v[114:117], v[158:161], v[190:193], v[114:117]
	v_mfma_f32_16x16x32_bf16 v[102:105], v[150:153], v[198:201], v[102:105]
	v_mfma_f32_16x16x32_bf16 v[98:101], v[158:161], v[198:201], v[98:101]
	v_mfma_f32_16x16x32_bf16 v[86:89], v[150:153], v[210:213], v[86:89]
	v_mfma_f32_16x16x32_bf16 v[82:85], v[158:161], v[210:213], v[82:85]
	v_mfma_f32_16x16x32_bf16 v[126:129], v[154:157], v[186:189], v[126:129]
	v_mfma_f32_16x16x32_bf16 v[122:125], v[162:165], v[186:189], v[122:125]
	v_mfma_f32_16x16x32_bf16 v[118:121], v[154:157], v[194:197], v[118:121]
	v_mfma_f32_16x16x32_bf16 v[114:117], v[162:165], v[194:197], v[114:117]
	v_mfma_f32_16x16x32_bf16 v[102:105], v[154:157], v[206:209], v[102:105]
	v_mfma_f32_16x16x32_bf16 v[98:101], v[162:165], v[206:209], v[98:101]
	v_mfma_f32_16x16x32_bf16 v[86:89], v[154:157], v[214:217], v[86:89]
	v_mfma_f32_16x16x32_bf16 v[82:85], v[162:165], v[214:217], v[82:85]
	v_mfma_f32_16x16x32_bf16 v[110:113], v[166:169], v[182:185], v[110:113]
	v_mfma_f32_16x16x32_bf16 v[106:109], v[174:177], v[182:185], v[106:109]
	v_mfma_f32_16x16x32_bf16 v[94:97], v[166:169], v[190:193], v[94:97]
	v_mfma_f32_16x16x32_bf16 v[90:93], v[174:177], v[190:193], v[90:93]
	v_mfma_f32_16x16x32_bf16 v[78:81], v[166:169], v[198:201], v[78:81]
	v_mfma_f32_16x16x32_bf16 v[74:77], v[174:177], v[198:201], v[74:77]
	v_mfma_f32_16x16x32_bf16 v[70:73], v[166:169], v[210:213], v[70:73]
	v_mfma_f32_16x16x32_bf16 v[66:69], v[174:177], v[210:213], v[66:69]
	v_mfma_f32_16x16x32_bf16 v[110:113], v[170:173], v[186:189], v[110:113]
	v_mfma_f32_16x16x32_bf16 v[106:109], v[178:181], v[186:189], v[106:109]
	v_mfma_f32_16x16x32_bf16 v[94:97], v[170:173], v[194:197], v[94:97]
	v_mfma_f32_16x16x32_bf16 v[90:93], v[178:181], v[194:197], v[90:93]
	v_mfma_f32_16x16x32_bf16 v[78:81], v[170:173], v[206:209], v[78:81]
	v_mfma_f32_16x16x32_bf16 v[74:77], v[178:181], v[206:209], v[74:77]
	v_mfma_f32_16x16x32_bf16 v[70:73], v[170:173], v[214:217], v[70:73]
	v_mfma_f32_16x16x32_bf16 v[66:69], v[178:181], v[214:217], v[66:69]
	s_setprio 0
	s_barrier
	s_mov_b32 m0, s77
	v_lshl_add_u64 v[202:203], v[202:203], 0, s[8:9]
	global_load_lds_dwordx4 v[202:203], off
	ds_read_b128 v[182:185], v148 offset:49152
	ds_read_b128 v[186:189], v148 offset:50176
	s_mov_b32 m0, s75
	v_lshl_add_u64 v[202:203], v[218:219], 0, s[8:9]
	global_load_lds_dwordx4 v[202:203], off
	ds_read_b128 v[190:193], v148 offset:51200
	ds_read_b128 v[194:197], v148 offset:52224
	s_mov_b32 m0, s76
	v_lshl_add_u64 v[202:203], s[44:45], 0, v[136:137]
	global_load_lds_dwordx4 v[202:203], off
	ds_read_b128 v[198:201], v148 offset:53248
	ds_read_b128 v[206:209], v148 offset:54272
	s_mov_b32 m0, s74
	v_lshl_add_u64 v[202:203], s[44:45], 0, v[134:135]
	global_load_lds_dwordx4 v[202:203], off
	ds_read_b128 v[210:213], v148 offset:55296
	ds_read_b128 v[214:217], v148 offset:56320
	s_mov_b32 m0, s28
	v_lshl_add_u64 v[202:203], v[220:221], 0, s[8:9]
	global_load_lds_dwordx4 v[202:203], off
	s_mov_b32 m0, s29
	v_lshl_add_u64 v[202:203], v[222:223], 0, s[8:9]
	global_load_lds_dwordx4 v[202:203], off
	s_waitcnt vmcnt(8) lgkmcnt(0)
	s_setprio 1
	s_barrier
	v_mfma_f32_16x16x32_bf16 v[62:65], v[150:153], v[182:185], v[62:65]
	v_mfma_f32_16x16x32_bf16 v[58:61], v[158:161], v[182:185], v[58:61]
	v_mfma_f32_16x16x32_bf16 v[54:57], v[150:153], v[190:193], v[54:57]
	v_mfma_f32_16x16x32_bf16 v[50:53], v[158:161], v[190:193], v[50:53]
	v_mfma_f32_16x16x32_bf16 v[38:41], v[150:153], v[198:201], v[38:41]
	v_mfma_f32_16x16x32_bf16 v[34:37], v[158:161], v[198:201], v[34:37]
	v_mfma_f32_16x16x32_bf16 v[22:25], v[150:153], v[210:213], v[22:25]
	v_mfma_f32_16x16x32_bf16 v[18:21], v[158:161], v[210:213], v[18:21]
	v_mfma_f32_16x16x32_bf16 v[62:65], v[154:157], v[186:189], v[62:65]
	v_mfma_f32_16x16x32_bf16 v[58:61], v[162:165], v[186:189], v[58:61]
	v_mfma_f32_16x16x32_bf16 v[54:57], v[154:157], v[194:197], v[54:57]
	v_mfma_f32_16x16x32_bf16 v[50:53], v[162:165], v[194:197], v[50:53]
	v_mfma_f32_16x16x32_bf16 v[38:41], v[154:157], v[206:209], v[38:41]
	v_mfma_f32_16x16x32_bf16 v[34:37], v[162:165], v[206:209], v[34:37]
	v_mfma_f32_16x16x32_bf16 v[22:25], v[154:157], v[214:217], v[22:25]
	v_mfma_f32_16x16x32_bf16 v[18:21], v[162:165], v[214:217], v[18:21]
	v_mfma_f32_16x16x32_bf16 v[46:49], v[166:169], v[182:185], v[46:49]
	v_mfma_f32_16x16x32_bf16 v[42:45], v[174:177], v[182:185], v[42:45]
	v_mfma_f32_16x16x32_bf16 v[30:33], v[166:169], v[190:193], v[30:33]
	v_mfma_f32_16x16x32_bf16 v[26:29], v[174:177], v[190:193], v[26:29]
	v_mfma_f32_16x16x32_bf16 v[14:17], v[166:169], v[198:201], v[14:17]
	v_mfma_f32_16x16x32_bf16 v[10:13], v[174:177], v[198:201], v[10:13]
	v_mfma_f32_16x16x32_bf16 v[6:9], v[166:169], v[210:213], v[6:9]
	v_mfma_f32_16x16x32_bf16 v[2:5], v[174:177], v[210:213], v[2:5]
	v_mfma_f32_16x16x32_bf16 v[46:49], v[170:173], v[186:189], v[46:49]
	v_mfma_f32_16x16x32_bf16 v[42:45], v[178:181], v[186:189], v[42:45]
	v_mfma_f32_16x16x32_bf16 v[30:33], v[170:173], v[194:197], v[30:33]
	v_mfma_f32_16x16x32_bf16 v[26:29], v[178:181], v[194:197], v[26:29]
	v_mfma_f32_16x16x32_bf16 v[14:17], v[170:173], v[206:209], v[14:17]
	v_mfma_f32_16x16x32_bf16 v[10:13], v[178:181], v[206:209], v[10:13]
	v_mfma_f32_16x16x32_bf16 v[6:9], v[170:173], v[214:217], v[6:9]
	v_mfma_f32_16x16x32_bf16 v[2:5], v[178:181], v[214:217], v[2:5]
	s_setprio 0
	s_barrier
	s_movk_i32 s46, 0x100
	s_andn2_b64 vcc, exec, s[42:43]
	s_mov_b64 s[44:45], -1
	s_mov_b64 s[42:43], 0
	s_cbranch_vccz .LBB0_297
	s_and_b64 vcc, exec, s[10:11]
	s_cbranch_vccz .LBB0_300
	s_barrier

.LBB0_313:
	s_add_u32 s49, s38, s48
	s_addc_u32 s68, s39, 0
	s_add_u32 s66, s49, 0x100
	s_addc_u32 s67, s68, 0
	s_and_b64 s[64:65], s[46:47], exec
	s_cselect_b32 s65, s43, s67
	s_cselect_b32 s64, s75, s66
	s_add_u32 s48, s36, s48
	s_addc_u32 s66, s37, 0
	s_add_u32 s48, s48, 0x100
	s_addc_u32 s66, s66, 0
	s_and_b64 s[46:47], s[46:47], exec
	s_cselect_b32 s67, s76, s66
	s_cselect_b32 s66, s77, s48
	s_add_u32 s70, s49, 0x10080
	ds_read_b128 v[144:147], v140
	ds_read_b128 v[148:151], v140 offset:1024
	ds_read_b128 v[152:155], v140 offset:2048
	ds_read_b128 v[156:159], v140 offset:3072
	ds_read_b128 v[160:163], v141
	ds_read_b128 v[164:167], v141 offset:1024
	ds_read_b128 v[168:171], v141 offset:2048
	ds_read_b128 v[172:175], v141 offset:3072
	s_addc_u32 s71, s68, 0
	s_add_i32 s87, s33, s2
	s_add_i32 m0, s16, 0xc000
	s_add_i32 s88, s16, 0xe000
	s_add_i32 s84, s87, 0x2000
	s_add_u32 s68, s66, 0x1000
	s_addc_u32 s69, s67, 0
	s_add_i32 s86, s34, s2
	s_add_i32 s85, s86, 0x2000
	s_add_i32 s83, 0, 0x18000
	s_add_i32 s82, 0, 0x1c000
	s_add_u32 s48, s64, 0x10000
	s_addc_u32 s49, s65, 0
	s_add_i32 s81, s83, s2
	s_add_i32 s79, s81, 0x2000
	s_add_u32 s46, s66, 0x1080
	s_addc_u32 s47, s67, 0
	s_add_i32 s80, s82, s2
	s_add_i32 s78, s80, 0x2000
	v_lshl_add_u64 v[210:211], s[70:71], 0, v[130:131]
	ds_read_b128 v[176:179], v142
	ds_read_b128 v[180:183], v142 offset:1024
	ds_read_b128 v[184:187], v142 offset:2048
	ds_read_b128 v[188:191], v142 offset:3072
	ds_read_b128 v[192:195], v142 offset:4096
	ds_read_b128 v[196:199], v142 offset:5120
	ds_read_b128 v[200:203], v142 offset:6144
	ds_read_b128 v[206:209], v142 offset:7168
	global_load_lds_dwordx4 v[210:211], off
	s_mov_b32 m0, s88
	v_lshl_add_u64 v[210:211], s[70:71], 0, v[132:133]
	global_load_lds_dwordx4 v[210:211], off
	s_waitcnt vmcnt(8) lgkmcnt(0)
	s_setprio 1
	s_barrier
	v_mfma_f32_16x16x32_bf16 v[126:129], v[144:147], v[176:179], v[126:129]
	v_mfma_f32_16x16x32_bf16 v[122:125], v[152:155], v[176:179], v[122:125]
	v_mfma_f32_16x16x32_bf16 v[118:121], v[144:147], v[184:187], v[118:121]
	v_mfma_f32_16x16x32_bf16 v[114:117], v[152:155], v[184:187], v[114:117]
	v_mfma_f32_16x16x32_bf16 v[102:105], v[144:147], v[192:195], v[102:105]
	v_mfma_f32_16x16x32_bf16 v[98:101], v[152:155], v[192:195], v[98:101]
	v_mfma_f32_16x16x32_bf16 v[86:89], v[144:147], v[200:203], v[86:89]
	v_mfma_f32_16x16x32_bf16 v[82:85], v[152:155], v[200:203], v[82:85]
	v_mfma_f32_16x16x32_bf16 v[126:129], v[148:151], v[180:183], v[126:129]
	v_mfma_f32_16x16x32_bf16 v[122:125], v[156:159], v[180:183], v[122:125]
	v_mfma_f32_16x16x32_bf16 v[118:121], v[148:151], v[188:191], v[118:121]
	v_mfma_f32_16x16x32_bf16 v[114:117], v[156:159], v[188:191], v[114:117]
	v_mfma_f32_16x16x32_bf16 v[102:105], v[148:151], v[196:199], v[102:105]
	v_mfma_f32_16x16x32_bf16 v[98:101], v[156:159], v[196:199], v[98:101]
	v_mfma_f32_16x16x32_bf16 v[86:89], v[148:151], v[206:209], v[86:89]
	v_mfma_f32_16x16x32_bf16 v[82:85], v[156:159], v[206:209], v[82:85]
	v_mfma_f32_16x16x32_bf16 v[110:113], v[160:163], v[176:179], v[110:113]
	v_mfma_f32_16x16x32_bf16 v[106:109], v[168:171], v[176:179], v[106:109]
	v_mfma_f32_16x16x32_bf16 v[94:97], v[160:163], v[184:187], v[94:97]
	v_mfma_f32_16x16x32_bf16 v[90:93], v[168:171], v[184:187], v[90:93]
	v_mfma_f32_16x16x32_bf16 v[78:81], v[160:163], v[192:195], v[78:81]
	v_mfma_f32_16x16x32_bf16 v[74:77], v[168:171], v[192:195], v[74:77]
	v_mfma_f32_16x16x32_bf16 v[70:73], v[160:163], v[200:203], v[70:73]
	v_mfma_f32_16x16x32_bf16 v[66:69], v[168:171], v[200:203], v[66:69]
	v_mfma_f32_16x16x32_bf16 v[110:113], v[164:167], v[180:183], v[110:113]
	v_mfma_f32_16x16x32_bf16 v[106:109], v[172:175], v[180:183], v[106:109]
	v_mfma_f32_16x16x32_bf16 v[94:97], v[164:167], v[188:191], v[94:97]
	v_mfma_f32_16x16x32_bf16 v[90:93], v[172:175], v[188:191], v[90:93]
	v_mfma_f32_16x16x32_bf16 v[78:81], v[164:167], v[196:199], v[78:81]
	v_mfma_f32_16x16x32_bf16 v[74:77], v[172:175], v[196:199], v[74:77]
	v_mfma_f32_16x16x32_bf16 v[70:73], v[164:167], v[206:209], v[70:73]
	v_mfma_f32_16x16x32_bf16 v[66:69], v[172:175], v[206:209], v[66:69]
	s_setprio 0
	s_barrier
	s_mov_b32 m0, s87
	v_lshl_add_u64 v[210:211], s[66:67], 0, v[136:137]
	global_load_lds_dwordx4 v[210:211], off
	ds_read_b128 v[176:179], v142 offset:16384
	ds_read_b128 v[180:183], v142 offset:17408
	v_lshl_add_u64 v[212:213], s[66:67], 0, v[134:135]
	s_mov_b32 m0, s84
	v_lshl_add_u64 v[214:215], s[68:69], 0, v[136:137]
	global_load_lds_dwordx4 v[212:213], off
	ds_read_b128 v[184:187], v142 offset:18432
	ds_read_b128 v[188:191], v142 offset:19456
	s_mov_b32 m0, s86
	v_lshl_add_u64 v[216:217], s[64:65], 0, v[132:133]
	global_load_lds_dwordx4 v[214:215], off
	ds_read_b128 v[192:195], v142 offset:20480
	ds_read_b128 v[196:199], v142 offset:21504
	s_mov_b32 m0, s85
	v_lshl_add_u64 v[214:215], s[68:69], 0, v[134:135]
	global_load_lds_dwordx4 v[214:215], off
	ds_read_b128 v[200:203], v142 offset:22528
	ds_read_b128 v[206:209], v142 offset:23552
	s_mov_b32 m0, s16
	v_lshl_add_u64 v[214:215], s[64:65], 0, v[130:131]
	global_load_lds_dwordx4 v[214:215], off
	s_mov_b32 m0, s17
	s_nop 0
	global_load_lds_dwordx4 v[216:217], off
	s_waitcnt vmcnt(8) lgkmcnt(0)
	s_setprio 1
	s_barrier
	v_mfma_f32_16x16x32_bf16 v[62:65], v[144:147], v[176:179], v[62:65]
	v_mfma_f32_16x16x32_bf16 v[58:61], v[152:155], v[176:179], v[58:61]
	v_mfma_f32_16x16x32_bf16 v[54:57], v[144:147], v[184:187], v[54:57]
	v_mfma_f32_16x16x32_bf16 v[50:53], v[152:155], v[184:187], v[50:53]
	v_mfma_f32_16x16x32_bf16 v[38:41], v[144:147], v[192:195], v[38:41]
	v_mfma_f32_16x16x32_bf16 v[34:37], v[152:155], v[192:195], v[34:37]
	v_mfma_f32_16x16x32_bf16 v[22:25], v[144:147], v[200:203], v[22:25]
	v_mfma_f32_16x16x32_bf16 v[18:21], v[152:155], v[200:203], v[18:21]
	v_mfma_f32_16x16x32_bf16 v[62:65], v[148:151], v[180:183], v[62:65]
	v_mfma_f32_16x16x32_bf16 v[58:61], v[156:159], v[180:183], v[58:61]
	v_mfma_f32_16x16x32_bf16 v[54:57], v[148:151], v[188:191], v[54:57]
	v_mfma_f32_16x16x32_bf16 v[50:53], v[156:159], v[188:191], v[50:53]
	v_mfma_f32_16x16x32_bf16 v[38:41], v[148:151], v[196:199], v[38:41]
	v_mfma_f32_16x16x32_bf16 v[34:37], v[156:159], v[196:199], v[34:37]
	v_mfma_f32_16x16x32_bf16 v[22:25], v[148:151], v[206:209], v[22:25]
	v_mfma_f32_16x16x32_bf16 v[18:21], v[156:159], v[206:209], v[18:21]
	v_mfma_f32_16x16x32_bf16 v[46:49], v[160:163], v[176:179], v[46:49]
	v_mfma_f32_16x16x32_bf16 v[42:45], v[168:171], v[176:179], v[42:45]
	v_mfma_f32_16x16x32_bf16 v[30:33], v[160:163], v[184:187], v[30:33]
	v_mfma_f32_16x16x32_bf16 v[26:29], v[168:171], v[184:187], v[26:29]
	v_mfma_f32_16x16x32_bf16 v[14:17], v[160:163], v[192:195], v[14:17]
	v_mfma_f32_16x16x32_bf16 v[10:13], v[168:171], v[192:195], v[10:13]
	v_mfma_f32_16x16x32_bf16 v[6:9], v[160:163], v[200:203], v[6:9]
	v_mfma_f32_16x16x32_bf16 v[2:5], v[168:171], v[200:203], v[2:5]
	v_mfma_f32_16x16x32_bf16 v[46:49], v[164:167], v[180:183], v[46:49]
	v_mfma_f32_16x16x32_bf16 v[42:45], v[172:175], v[180:183], v[42:45]
	v_mfma_f32_16x16x32_bf16 v[30:33], v[164:167], v[188:191], v[30:33]
	v_mfma_f32_16x16x32_bf16 v[26:29], v[172:175], v[188:191], v[26:29]
	v_mfma_f32_16x16x32_bf16 v[14:17], v[164:167], v[196:199], v[14:17]
	v_mfma_f32_16x16x32_bf16 v[10:13], v[172:175], v[196:199], v[10:13]
	v_mfma_f32_16x16x32_bf16 v[6:9], v[164:167], v[206:209], v[6:9]
	v_mfma_f32_16x16x32_bf16 v[2:5], v[172:175], v[206:209], v[2:5]
	s_setprio 0
	s_barrier
	v_add_u32_e32 v143, s83, v139
	ds_read_b128 v[144:147], v143
	ds_read_b128 v[148:151], v143 offset:1024
	ds_read_b128 v[152:155], v143 offset:2048
	ds_read_b128 v[156:159], v143 offset:3072
	v_add_u32_e32 v143, s82, v139
	ds_read_b128 v[160:163], v143
	ds_read_b128 v[164:167], v143 offset:1024
	ds_read_b128 v[168:171], v143 offset:2048
	ds_read_b128 v[172:175], v143 offset:3072
	s_mov_b32 m0, s18
	v_lshl_add_u64 v[218:219], s[48:49], 0, v[130:131]
	ds_read_b128 v[176:179], v142 offset:32768
	ds_read_b128 v[180:183], v142 offset:33792
	ds_read_b128 v[184:187], v142 offset:34816
	ds_read_b128 v[188:191], v142 offset:35840
	ds_read_b128 v[192:195], v142 offset:36864
	ds_read_b128 v[196:199], v142 offset:37888
	ds_read_b128 v[200:203], v142 offset:38912
	ds_read_b128 v[206:209], v142 offset:39936
	global_load_lds_dwordx4 v[218:219], off
	s_mov_b32 m0, s19
	v_lshl_add_u64 v[218:219], s[48:49], 0, v[132:133]
	global_load_lds_dwordx4 v[218:219], off
	s_waitcnt vmcnt(8) lgkmcnt(0)
	s_setprio 1
	s_barrier
	v_mfma_f32_16x16x32_bf16 v[126:129], v[144:147], v[176:179], v[126:129]
	v_mfma_f32_16x16x32_bf16 v[122:125], v[152:155], v[176:179], v[122:125]
	v_mfma_f32_16x16x32_bf16 v[118:121], v[144:147], v[184:187], v[118:121]
	v_mfma_f32_16x16x32_bf16 v[114:117], v[152:155], v[184:187], v[114:117]
	v_mfma_f32_16x16x32_bf16 v[102:105], v[144:147], v[192:195], v[102:105]
	v_mfma_f32_16x16x32_bf16 v[98:101], v[152:155], v[192:195], v[98:101]
	v_mfma_f32_16x16x32_bf16 v[86:89], v[144:147], v[200:203], v[86:89]
	v_mfma_f32_16x16x32_bf16 v[82:85], v[152:155], v[200:203], v[82:85]
	v_mfma_f32_16x16x32_bf16 v[126:129], v[148:151], v[180:183], v[126:129]
	v_mfma_f32_16x16x32_bf16 v[122:125], v[156:159], v[180:183], v[122:125]
	v_mfma_f32_16x16x32_bf16 v[118:121], v[148:151], v[188:191], v[118:121]
	v_mfma_f32_16x16x32_bf16 v[114:117], v[156:159], v[188:191], v[114:117]
	v_mfma_f32_16x16x32_bf16 v[102:105], v[148:151], v[196:199], v[102:105]
	v_mfma_f32_16x16x32_bf16 v[98:101], v[156:159], v[196:199], v[98:101]
	v_mfma_f32_16x16x32_bf16 v[86:89], v[148:151], v[206:209], v[86:89]
	v_mfma_f32_16x16x32_bf16 v[82:85], v[156:159], v[206:209], v[82:85]
	v_mfma_f32_16x16x32_bf16 v[110:113], v[160:163], v[176:179], v[110:113]
	v_mfma_f32_16x16x32_bf16 v[106:109], v[168:171], v[176:179], v[106:109]
	v_mfma_f32_16x16x32_bf16 v[94:97], v[160:163], v[184:187], v[94:97]
	v_mfma_f32_16x16x32_bf16 v[90:93], v[168:171], v[184:187], v[90:93]
	v_mfma_f32_16x16x32_bf16 v[78:81], v[160:163], v[192:195], v[78:81]
	v_mfma_f32_16x16x32_bf16 v[74:77], v[168:171], v[192:195], v[74:77]
	v_mfma_f32_16x16x32_bf16 v[70:73], v[160:163], v[200:203], v[70:73]
	v_mfma_f32_16x16x32_bf16 v[66:69], v[168:171], v[200:203], v[66:69]
	v_mfma_f32_16x16x32_bf16 v[110:113], v[164:167], v[180:183], v[110:113]
	v_mfma_f32_16x16x32_bf16 v[106:109], v[172:175], v[180:183], v[106:109]
	v_mfma_f32_16x16x32_bf16 v[94:97], v[164:167], v[188:191], v[94:97]
	v_mfma_f32_16x16x32_bf16 v[90:93], v[172:175], v[188:191], v[90:93]
	v_mfma_f32_16x16x32_bf16 v[78:81], v[164:167], v[196:199], v[78:81]
	v_mfma_f32_16x16x32_bf16 v[74:77], v[172:175], v[196:199], v[74:77]
	v_mfma_f32_16x16x32_bf16 v[70:73], v[164:167], v[206:209], v[70:73]
	v_mfma_f32_16x16x32_bf16 v[66:69], v[172:175], v[206:209], v[66:69]
	s_setprio 0
	s_barrier
	s_mov_b32 m0, s81
	v_lshl_add_u64 v[210:211], v[210:211], 0, s[8:9]
	global_load_lds_dwordx4 v[210:211], off
	ds_read_b128 v[176:179], v142 offset:49152
	ds_read_b128 v[180:183], v142 offset:50176
	s_mov_b32 m0, s79
	v_lshl_add_u64 v[210:211], v[212:213], 0, s[8:9]
	global_load_lds_dwordx4 v[210:211], off
	ds_read_b128 v[184:187], v142 offset:51200
	ds_read_b128 v[188:191], v142 offset:52224
	s_mov_b32 m0, s80
	v_lshl_add_u64 v[210:211], s[46:47], 0, v[136:137]
	global_load_lds_dwordx4 v[210:211], off
	ds_read_b128 v[192:195], v142 offset:53248
	ds_read_b128 v[196:199], v142 offset:54272
	s_mov_b32 m0, s78
	v_lshl_add_u64 v[210:211], s[46:47], 0, v[134:135]
	global_load_lds_dwordx4 v[210:211], off
	ds_read_b128 v[200:203], v142 offset:55296
	ds_read_b128 v[206:209], v142 offset:56320
	s_mov_b32 m0, s30
	v_lshl_add_u64 v[210:211], v[214:215], 0, s[8:9]
	global_load_lds_dwordx4 v[210:211], off
	s_mov_b32 m0, s31
	v_lshl_add_u64 v[210:211], v[216:217], 0, s[8:9]
	global_load_lds_dwordx4 v[210:211], off
	s_waitcnt vmcnt(8) lgkmcnt(0)
	s_setprio 1
	s_barrier
	v_mfma_f32_16x16x32_bf16 v[62:65], v[144:147], v[176:179], v[62:65]
	v_mfma_f32_16x16x32_bf16 v[58:61], v[152:155], v[176:179], v[58:61]
	v_mfma_f32_16x16x32_bf16 v[54:57], v[144:147], v[184:187], v[54:57]
	v_mfma_f32_16x16x32_bf16 v[50:53], v[152:155], v[184:187], v[50:53]
	v_mfma_f32_16x16x32_bf16 v[38:41], v[144:147], v[192:195], v[38:41]
	v_mfma_f32_16x16x32_bf16 v[34:37], v[152:155], v[192:195], v[34:37]
	v_mfma_f32_16x16x32_bf16 v[22:25], v[144:147], v[200:203], v[22:25]
	v_mfma_f32_16x16x32_bf16 v[18:21], v[152:155], v[200:203], v[18:21]
	v_mfma_f32_16x16x32_bf16 v[62:65], v[148:151], v[180:183], v[62:65]
	v_mfma_f32_16x16x32_bf16 v[58:61], v[156:159], v[180:183], v[58:61]
	v_mfma_f32_16x16x32_bf16 v[54:57], v[148:151], v[188:191], v[54:57]
	v_mfma_f32_16x16x32_bf16 v[50:53], v[156:159], v[188:191], v[50:53]
	v_mfma_f32_16x16x32_bf16 v[38:41], v[148:151], v[196:199], v[38:41]
	v_mfma_f32_16x16x32_bf16 v[34:37], v[156:159], v[196:199], v[34:37]
	v_mfma_f32_16x16x32_bf16 v[22:25], v[148:151], v[206:209], v[22:25]
	v_mfma_f32_16x16x32_bf16 v[18:21], v[156:159], v[206:209], v[18:21]
	v_mfma_f32_16x16x32_bf16 v[46:49], v[160:163], v[176:179], v[46:49]
	v_mfma_f32_16x16x32_bf16 v[42:45], v[168:171], v[176:179], v[42:45]
	v_mfma_f32_16x16x32_bf16 v[30:33], v[160:163], v[184:187], v[30:33]
	v_mfma_f32_16x16x32_bf16 v[26:29], v[168:171], v[184:187], v[26:29]
	v_mfma_f32_16x16x32_bf16 v[14:17], v[160:163], v[192:195], v[14:17]
	v_mfma_f32_16x16x32_bf16 v[10:13], v[168:171], v[192:195], v[10:13]
	v_mfma_f32_16x16x32_bf16 v[6:9], v[160:163], v[200:203], v[6:9]
	v_mfma_f32_16x16x32_bf16 v[2:5], v[168:171], v[200:203], v[2:5]
	v_mfma_f32_16x16x32_bf16 v[46:49], v[164:167], v[180:183], v[46:49]
	v_mfma_f32_16x16x32_bf16 v[42:45], v[172:175], v[180:183], v[42:45]
	v_mfma_f32_16x16x32_bf16 v[30:33], v[164:167], v[188:191], v[30:33]
	v_mfma_f32_16x16x32_bf16 v[26:29], v[172:175], v[188:191], v[26:29]
	v_mfma_f32_16x16x32_bf16 v[14:17], v[164:167], v[196:199], v[14:17]
	v_mfma_f32_16x16x32_bf16 v[10:13], v[172:175], v[196:199], v[10:13]
	v_mfma_f32_16x16x32_bf16 v[6:9], v[164:167], v[206:209], v[6:9]
	v_mfma_f32_16x16x32_bf16 v[2:5], v[172:175], v[206:209], v[2:5]
	s_setprio 0
	s_barrier
	s_movk_i32 s48, 0x100
	s_andn2_b64 vcc, exec, s[44:45]
	s_mov_b64 s[46:47], -1
	s_mov_b64 s[44:45], 0
	s_cbranch_vccz .LBB0_313
	s_and_b64 vcc, exec, s[10:11]
	s_cbranch_vccz .LBB0_316
	s_barrier

.LBB0_383:
	s_add_u32 s26, s0, s22
	s_addc_u32 s27, s1, s23
	s_and_b64 s[44:45], s[36:37], exec
	s_cselect_b32 s15, s27, s43
	s_cselect_b32 s39, s26, s42
	s_add_u32 s66, s42, 0x100
	s_addc_u32 s67, s43, 0
	s_mov_b32 s68, -2
	s_mov_b64 s[42:43], 0
	ds_read_b128 v[152:155], v146
	ds_read_b128 v[156:159], v146 offset:1024
	ds_read_b128 v[160:163], v146 offset:2048
	ds_read_b128 v[164:167], v146 offset:3072
	ds_read_b128 v[168:171], v147
	ds_read_b128 v[172:175], v147 offset:1024
	ds_read_b128 v[176:179], v147 offset:2048
	ds_read_b128 v[180:183], v147 offset:3072
	s_add_u32 s44, s42, 0x100
	s_addc_u32 s45, s43, 0
	s_add_u32 s46, s66, s42
	s_addc_u32 s47, s67, s43
	s_cmp_eq_u32 s68, 4
	s_cselect_b32 s48, 0, s44
	s_cselect_b32 s49, 0, s45
	s_cselect_b32 s46, s39, s46
	s_cselect_b32 s47, s15, s47
	s_add_u32 s48, s6, s48
	s_addc_u32 s49, s7, s49
	s_mov_b32 m0, s29
	v_lshl_add_u64 v[218:219], v[138:139], 0, s[42:43]
	ds_read_b128 v[184:187], v148
	ds_read_b128 v[188:191], v148 offset:1024
	ds_read_b128 v[192:195], v148 offset:2048
	ds_read_b128 v[196:199], v148 offset:3072
	ds_read_b128 v[200:203], v148 offset:4096
	ds_read_b128 v[206:209], v148 offset:5120
	ds_read_b128 v[210:213], v148 offset:6144
	ds_read_b128 v[214:217], v148 offset:7168
	global_load_lds_dwordx4 v[218:219], off
	s_mov_b32 m0, s30
	v_lshl_add_u64 v[218:219], v[140:141], 0, s[42:43]
	global_load_lds_dwordx4 v[218:219], off
	s_waitcnt vmcnt(8) lgkmcnt(0)
	s_setprio 1
	s_barrier
	v_mfma_f32_16x16x32_bf16 v[126:129], v[152:155], v[184:187], 0
	v_mfma_f32_16x16x32_bf16 v[122:125], v[160:163], v[184:187], 0
	v_mfma_f32_16x16x32_bf16 v[118:121], v[152:155], v[192:195], 0
	v_mfma_f32_16x16x32_bf16 v[114:117], v[160:163], v[192:195], 0
	v_mfma_f32_16x16x32_bf16 v[102:105], v[152:155], v[200:203], 0
	v_mfma_f32_16x16x32_bf16 v[98:101], v[160:163], v[200:203], 0
	v_mfma_f32_16x16x32_bf16 v[86:89], v[152:155], v[210:213], 0
	v_mfma_f32_16x16x32_bf16 v[82:85], v[160:163], v[210:213], 0
	v_mfma_f32_16x16x32_bf16 v[126:129], v[156:159], v[188:191], v[126:129]
	v_mfma_f32_16x16x32_bf16 v[122:125], v[164:167], v[188:191], v[122:125]
	v_mfma_f32_16x16x32_bf16 v[118:121], v[156:159], v[196:199], v[118:121]
	v_mfma_f32_16x16x32_bf16 v[114:117], v[164:167], v[196:199], v[114:117]
	v_mfma_f32_16x16x32_bf16 v[102:105], v[156:159], v[206:209], v[102:105]
	v_mfma_f32_16x16x32_bf16 v[98:101], v[164:167], v[206:209], v[98:101]
	v_mfma_f32_16x16x32_bf16 v[86:89], v[156:159], v[214:217], v[86:89]
	v_mfma_f32_16x16x32_bf16 v[82:85], v[164:167], v[214:217], v[82:85]
	v_mfma_f32_16x16x32_bf16 v[110:113], v[168:171], v[184:187], 0
	v_mfma_f32_16x16x32_bf16 v[106:109], v[176:179], v[184:187], 0
	v_mfma_f32_16x16x32_bf16 v[94:97], v[168:171], v[192:195], 0
	v_mfma_f32_16x16x32_bf16 v[90:93], v[176:179], v[192:195], 0
	v_mfma_f32_16x16x32_bf16 v[78:81], v[168:171], v[200:203], 0
	v_mfma_f32_16x16x32_bf16 v[74:77], v[176:179], v[200:203], 0
	v_mfma_f32_16x16x32_bf16 v[70:73], v[168:171], v[210:213], 0
	v_mfma_f32_16x16x32_bf16 v[66:69], v[176:179], v[210:213], 0
	v_mfma_f32_16x16x32_bf16 v[110:113], v[172:175], v[188:191], v[110:113]
	v_mfma_f32_16x16x32_bf16 v[106:109], v[180:183], v[188:191], v[106:109]
	v_mfma_f32_16x16x32_bf16 v[94:97], v[172:175], v[196:199], v[94:97]
	v_mfma_f32_16x16x32_bf16 v[90:93], v[180:183], v[196:199], v[90:93]
	v_mfma_f32_16x16x32_bf16 v[78:81], v[172:175], v[206:209], v[78:81]
	v_mfma_f32_16x16x32_bf16 v[74:77], v[180:183], v[206:209], v[74:77]
	v_mfma_f32_16x16x32_bf16 v[70:73], v[172:175], v[214:217], v[70:73]
	v_mfma_f32_16x16x32_bf16 v[66:69], v[180:183], v[214:217], v[66:69]
	s_setprio 0
	s_barrier
	s_mov_b32 m0, s31
	v_lshl_add_u64 v[218:219], s[46:47], 0, v[134:135]
	s_add_u32 s42, s46, 0x20000
	global_load_lds_dwordx4 v[218:219], off
	ds_read_b128 v[184:187], v148 offset:16384
	ds_read_b128 v[188:191], v148 offset:17408
	v_lshl_add_u64 v[220:221], s[46:47], 0, v[130:131]
	s_mov_b32 m0, s33
	s_addc_u32 s43, s47, 0
	global_load_lds_dwordx4 v[220:221], off
	ds_read_b128 v[192:195], v148 offset:18432
	ds_read_b128 v[196:199], v148 offset:19456
	v_lshl_add_u64 v[222:223], s[42:43], 0, v[134:135]
	s_mov_b32 m0, s34
	v_lshl_add_u64 v[224:225], s[48:49], 0, v[132:133]
	global_load_lds_dwordx4 v[222:223], off
	ds_read_b128 v[200:203], v148 offset:20480
	ds_read_b128 v[206:209], v148 offset:21504
	s_mov_b32 m0, s35
	v_lshl_add_u64 v[222:223], s[42:43], 0, v[130:131]
	global_load_lds_dwordx4 v[222:223], off
	ds_read_b128 v[210:213], v148 offset:22528
	ds_read_b128 v[214:217], v148 offset:23552
	s_mov_b32 m0, s2
	v_lshl_add_u64 v[222:223], s[48:49], 0, v[136:137]
	global_load_lds_dwordx4 v[222:223], off
	s_mov_b32 m0, s3
	s_nop 0
	global_load_lds_dwordx4 v[224:225], off
	s_waitcnt vmcnt(8) lgkmcnt(0)
	s_setprio 1
	s_barrier
	v_mfma_f32_16x16x32_bf16 v[62:65], v[152:155], v[184:187], 0
	v_mfma_f32_16x16x32_bf16 v[58:61], v[160:163], v[184:187], 0
	v_mfma_f32_16x16x32_bf16 v[54:57], v[152:155], v[192:195], 0
	v_mfma_f32_16x16x32_bf16 v[50:53], v[160:163], v[192:195], 0
	v_mfma_f32_16x16x32_bf16 v[38:41], v[152:155], v[200:203], 0
	v_mfma_f32_16x16x32_bf16 v[34:37], v[160:163], v[200:203], 0
	v_mfma_f32_16x16x32_bf16 v[22:25], v[152:155], v[210:213], 0
	v_mfma_f32_16x16x32_bf16 v[18:21], v[160:163], v[210:213], 0
	v_mfma_f32_16x16x32_bf16 v[62:65], v[156:159], v[188:191], v[62:65]
	v_mfma_f32_16x16x32_bf16 v[58:61], v[164:167], v[188:191], v[58:61]
	v_mfma_f32_16x16x32_bf16 v[54:57], v[156:159], v[196:199], v[54:57]
	v_mfma_f32_16x16x32_bf16 v[50:53], v[164:167], v[196:199], v[50:53]
	v_mfma_f32_16x16x32_bf16 v[38:41], v[156:159], v[206:209], v[38:41]
	v_mfma_f32_16x16x32_bf16 v[34:37], v[164:167], v[206:209], v[34:37]
	v_mfma_f32_16x16x32_bf16 v[22:25], v[156:159], v[214:217], v[22:25]
	v_mfma_f32_16x16x32_bf16 v[18:21], v[164:167], v[214:217], v[18:21]
	v_mfma_f32_16x16x32_bf16 v[46:49], v[168:171], v[184:187], 0
	v_mfma_f32_16x16x32_bf16 v[42:45], v[176:179], v[184:187], 0
	v_mfma_f32_16x16x32_bf16 v[30:33], v[168:171], v[192:195], 0
	v_mfma_f32_16x16x32_bf16 v[26:29], v[176:179], v[192:195], 0
	v_mfma_f32_16x16x32_bf16 v[14:17], v[168:171], v[200:203], 0
	v_mfma_f32_16x16x32_bf16 v[10:13], v[176:179], v[200:203], 0
	v_mfma_f32_16x16x32_bf16 v[6:9], v[168:171], v[210:213], 0
	v_mfma_f32_16x16x32_bf16 v[2:5], v[176:179], v[210:213], 0
	v_mfma_f32_16x16x32_bf16 v[46:49], v[172:175], v[188:191], v[46:49]
	v_mfma_f32_16x16x32_bf16 v[42:45], v[180:183], v[188:191], v[42:45]
	v_mfma_f32_16x16x32_bf16 v[30:33], v[172:175], v[196:199], v[30:33]
	v_mfma_f32_16x16x32_bf16 v[26:29], v[180:183], v[196:199], v[26:29]
	v_mfma_f32_16x16x32_bf16 v[14:17], v[172:175], v[206:209], v[14:17]
	v_mfma_f32_16x16x32_bf16 v[10:13], v[180:183], v[206:209], v[10:13]
	v_mfma_f32_16x16x32_bf16 v[6:9], v[172:175], v[214:217], v[6:9]
	v_mfma_f32_16x16x32_bf16 v[2:5], v[180:183], v[214:217], v[2:5]
	s_setprio 0
	s_barrier
	ds_read_b128 v[152:155], v149
	ds_read_b128 v[156:159], v149 offset:1024
	ds_read_b128 v[160:163], v149 offset:2048
	ds_read_b128 v[164:167], v149 offset:3072
	ds_read_b128 v[168:171], v150
	ds_read_b128 v[172:175], v150 offset:1024
	ds_read_b128 v[176:179], v150 offset:2048
	ds_read_b128 v[180:183], v150 offset:3072
	s_add_u32 s42, s48, 0x20000
	s_addc_u32 s43, s49, 0
	s_mov_b32 m0, s16
	v_lshl_add_u64 v[226:227], s[42:43], 0, v[136:137]
	ds_read_b128 v[184:187], v148 offset:32768
	ds_read_b128 v[188:191], v148 offset:33792
	ds_read_b128 v[192:195], v148 offset:34816
	ds_read_b128 v[196:199], v148 offset:35840
	ds_read_b128 v[200:203], v148 offset:36864
	ds_read_b128 v[206:209], v148 offset:37888
	ds_read_b128 v[210:213], v148 offset:38912
	ds_read_b128 v[214:217], v148 offset:39936
	global_load_lds_dwordx4 v[226:227], off
	s_mov_b32 m0, s17
	v_lshl_add_u64 v[226:227], s[42:43], 0, v[132:133]
	global_load_lds_dwordx4 v[226:227], off
	s_waitcnt vmcnt(8) lgkmcnt(0)
	s_setprio 1
	s_barrier
	v_mfma_f32_16x16x32_bf16 v[126:129], v[152:155], v[184:187], v[126:129]
	v_mfma_f32_16x16x32_bf16 v[122:125], v[160:163], v[184:187], v[122:125]
	v_mfma_f32_16x16x32_bf16 v[118:121], v[152:155], v[192:195], v[118:121]
	v_mfma_f32_16x16x32_bf16 v[114:117], v[160:163], v[192:195], v[114:117]
	v_mfma_f32_16x16x32_bf16 v[102:105], v[152:155], v[200:203], v[102:105]
	v_mfma_f32_16x16x32_bf16 v[98:101], v[160:163], v[200:203], v[98:101]
	v_mfma_f32_16x16x32_bf16 v[86:89], v[152:155], v[210:213], v[86:89]
	v_mfma_f32_16x16x32_bf16 v[82:85], v[160:163], v[210:213], v[82:85]
	v_mfma_f32_16x16x32_bf16 v[126:129], v[156:159], v[188:191], v[126:129]
	v_mfma_f32_16x16x32_bf16 v[122:125], v[164:167], v[188:191], v[122:125]
	v_mfma_f32_16x16x32_bf16 v[118:121], v[156:159], v[196:199], v[118:121]
	v_mfma_f32_16x16x32_bf16 v[114:117], v[164:167], v[196:199], v[114:117]
	v_mfma_f32_16x16x32_bf16 v[102:105], v[156:159], v[206:209], v[102:105]
	v_mfma_f32_16x16x32_bf16 v[98:101], v[164:167], v[206:209], v[98:101]
	v_mfma_f32_16x16x32_bf16 v[86:89], v[156:159], v[214:217], v[86:89]
	v_mfma_f32_16x16x32_bf16 v[82:85], v[164:167], v[214:217], v[82:85]
	v_mfma_f32_16x16x32_bf16 v[110:113], v[168:171], v[184:187], v[110:113]
	v_mfma_f32_16x16x32_bf16 v[106:109], v[176:179], v[184:187], v[106:109]
	v_mfma_f32_16x16x32_bf16 v[94:97], v[168:171], v[192:195], v[94:97]
	v_mfma_f32_16x16x32_bf16 v[90:93], v[176:179], v[192:195], v[90:93]
	v_mfma_f32_16x16x32_bf16 v[78:81], v[168:171], v[200:203], v[78:81]
	v_mfma_f32_16x16x32_bf16 v[74:77], v[176:179], v[200:203], v[74:77]
	v_mfma_f32_16x16x32_bf16 v[70:73], v[168:171], v[210:213], v[70:73]
	v_mfma_f32_16x16x32_bf16 v[66:69], v[176:179], v[210:213], v[66:69]
	v_mfma_f32_16x16x32_bf16 v[110:113], v[172:175], v[188:191], v[110:113]
	v_mfma_f32_16x16x32_bf16 v[106:109], v[180:183], v[188:191], v[106:109]
	v_mfma_f32_16x16x32_bf16 v[94:97], v[172:175], v[196:199], v[94:97]
	v_mfma_f32_16x16x32_bf16 v[90:93], v[180:183], v[196:199], v[90:93]
	v_mfma_f32_16x16x32_bf16 v[78:81], v[172:175], v[206:209], v[78:81]
	v_mfma_f32_16x16x32_bf16 v[74:77], v[180:183], v[206:209], v[74:77]
	v_mfma_f32_16x16x32_bf16 v[70:73], v[172:175], v[214:217], v[70:73]
	v_mfma_f32_16x16x32_bf16 v[66:69], v[180:183], v[214:217], v[66:69]
	s_setprio 0
	s_barrier
	s_mov_b32 m0, s62
	v_lshl_add_u64 v[218:219], v[218:219], 0, s[10:11]
	s_add_u32 s42, s46, 0x20080
	global_load_lds_dwordx4 v[218:219], off
	ds_read_b128 v[184:187], v148 offset:49152
	ds_read_b128 v[188:191], v148 offset:50176
	v_lshl_add_u64 v[218:219], v[220:221], 0, s[10:11]
	s_mov_b32 m0, s63
	s_addc_u32 s43, s47, 0
	global_load_lds_dwordx4 v[218:219], off
	ds_read_b128 v[192:195], v148 offset:51200
	ds_read_b128 v[196:199], v148 offset:52224
	s_mov_b32 m0, s64
	v_lshl_add_u64 v[218:219], s[42:43], 0, v[134:135]
	global_load_lds_dwordx4 v[218:219], off
	ds_read_b128 v[200:203], v148 offset:53248
	ds_read_b128 v[206:209], v148 offset:54272
	s_mov_b32 m0, s65
	v_lshl_add_u64 v[218:219], s[42:43], 0, v[130:131]
	global_load_lds_dwordx4 v[218:219], off
	ds_read_b128 v[210:213], v148 offset:55296
	ds_read_b128 v[214:217], v148 offset:56320
	s_mov_b32 m0, s25
	v_lshl_add_u64 v[218:219], v[222:223], 0, s[10:11]
	global_load_lds_dwordx4 v[218:219], off
	s_mov_b32 m0, s28
	v_lshl_add_u64 v[218:219], v[224:225], 0, s[10:11]
	global_load_lds_dwordx4 v[218:219], off
	s_waitcnt vmcnt(8) lgkmcnt(0)
	s_setprio 1
	s_barrier
	v_mfma_f32_16x16x32_bf16 v[62:65], v[152:155], v[184:187], v[62:65]
	v_mfma_f32_16x16x32_bf16 v[58:61], v[160:163], v[184:187], v[58:61]
	v_mfma_f32_16x16x32_bf16 v[54:57], v[152:155], v[192:195], v[54:57]
	v_mfma_f32_16x16x32_bf16 v[50:53], v[160:163], v[192:195], v[50:53]
	v_mfma_f32_16x16x32_bf16 v[38:41], v[152:155], v[200:203], v[38:41]
	v_mfma_f32_16x16x32_bf16 v[34:37], v[160:163], v[200:203], v[34:37]
	v_mfma_f32_16x16x32_bf16 v[22:25], v[152:155], v[210:213], v[22:25]
	v_mfma_f32_16x16x32_bf16 v[18:21], v[160:163], v[210:213], v[18:21]
	v_mfma_f32_16x16x32_bf16 v[62:65], v[156:159], v[188:191], v[62:65]
	v_mfma_f32_16x16x32_bf16 v[58:61], v[164:167], v[188:191], v[58:61]
	v_mfma_f32_16x16x32_bf16 v[54:57], v[156:159], v[196:199], v[54:57]
	v_mfma_f32_16x16x32_bf16 v[50:53], v[164:167], v[196:199], v[50:53]
	v_mfma_f32_16x16x32_bf16 v[38:41], v[156:159], v[206:209], v[38:41]
	v_mfma_f32_16x16x32_bf16 v[34:37], v[164:167], v[206:209], v[34:37]
	v_mfma_f32_16x16x32_bf16 v[22:25], v[156:159], v[214:217], v[22:25]
	v_mfma_f32_16x16x32_bf16 v[18:21], v[164:167], v[214:217], v[18:21]
	v_mfma_f32_16x16x32_bf16 v[46:49], v[168:171], v[184:187], v[46:49]
	v_mfma_f32_16x16x32_bf16 v[42:45], v[176:179], v[184:187], v[42:45]
	v_mfma_f32_16x16x32_bf16 v[30:33], v[168:171], v[192:195], v[30:33]
	v_mfma_f32_16x16x32_bf16 v[26:29], v[176:179], v[192:195], v[26:29]
	v_mfma_f32_16x16x32_bf16 v[14:17], v[168:171], v[200:203], v[14:17]
	v_mfma_f32_16x16x32_bf16 v[10:13], v[176:179], v[200:203], v[10:13]
	v_mfma_f32_16x16x32_bf16 v[6:9], v[168:171], v[210:213], v[6:9]
	v_mfma_f32_16x16x32_bf16 v[2:5], v[176:179], v[210:213], v[2:5]
	v_mfma_f32_16x16x32_bf16 v[46:49], v[172:175], v[188:191], v[46:49]
	v_mfma_f32_16x16x32_bf16 v[42:45], v[180:183], v[188:191], v[42:45]
	v_mfma_f32_16x16x32_bf16 v[30:33], v[172:175], v[196:199], v[30:33]
	v_mfma_f32_16x16x32_bf16 v[26:29], v[180:183], v[196:199], v[26:29]
	v_mfma_f32_16x16x32_bf16 v[14:17], v[172:175], v[206:209], v[14:17]
	v_mfma_f32_16x16x32_bf16 v[10:13], v[180:183], v[206:209], v[10:13]
	v_mfma_f32_16x16x32_bf16 v[6:9], v[172:175], v[214:217], v[6:9]
	v_mfma_f32_16x16x32_bf16 v[2:5], v[180:183], v[214:217], v[2:5]
	s_setprio 0
	s_barrier
	s_add_i32 s68, s68, 2
	s_cmp_gt_u32 s68, 5
	s_mov_b64 s[42:43], s[44:45]
.LBB0_384:
	ds_read_b128 v[152:155], v146
	ds_read_b128 v[156:159], v146 offset:1024
	ds_read_b128 v[160:163], v146 offset:2048
	ds_read_b128 v[164:167], v146 offset:3072
	ds_read_b128 v[168:171], v147
	ds_read_b128 v[172:175], v147 offset:1024
	ds_read_b128 v[176:179], v147 offset:2048
	ds_read_b128 v[180:183], v147 offset:3072
	s_add_u32 s44, s42, 0x100
	s_addc_u32 s45, s43, 0
	s_add_u32 s46, s66, s42
	s_addc_u32 s47, s67, s43
	s_cmp_eq_u32 s68, 4
	s_cselect_b32 s48, 0, s44
	s_cselect_b32 s49, 0, s45
	s_cselect_b32 s46, s39, s46
	s_cselect_b32 s47, s15, s47
	s_add_u32 s48, s6, s48
	s_addc_u32 s49, s7, s49
	s_mov_b32 m0, s29
	v_lshl_add_u64 v[218:219], v[138:139], 0, s[42:43]
	ds_read_b128 v[184:187], v148
	ds_read_b128 v[188:191], v148 offset:1024
	ds_read_b128 v[192:195], v148 offset:2048
	ds_read_b128 v[196:199], v148 offset:3072
	ds_read_b128 v[200:203], v148 offset:4096
	ds_read_b128 v[206:209], v148 offset:5120
	ds_read_b128 v[210:213], v148 offset:6144
	ds_read_b128 v[214:217], v148 offset:7168
	global_load_lds_dwordx4 v[218:219], off
	s_mov_b32 m0, s30
	v_lshl_add_u64 v[218:219], v[140:141], 0, s[42:43]
	global_load_lds_dwordx4 v[218:219], off
	s_waitcnt vmcnt(8) lgkmcnt(0)
	s_setprio 1
	s_barrier
	v_mfma_f32_16x16x32_bf16 v[126:129], v[152:155], v[184:187], v[126:129]
	v_mfma_f32_16x16x32_bf16 v[122:125], v[160:163], v[184:187], v[122:125]
	v_mfma_f32_16x16x32_bf16 v[118:121], v[152:155], v[192:195], v[118:121]
	v_mfma_f32_16x16x32_bf16 v[114:117], v[160:163], v[192:195], v[114:117]
	v_mfma_f32_16x16x32_bf16 v[102:105], v[152:155], v[200:203], v[102:105]
	v_mfma_f32_16x16x32_bf16 v[98:101], v[160:163], v[200:203], v[98:101]
	v_mfma_f32_16x16x32_bf16 v[86:89], v[152:155], v[210:213], v[86:89]
	v_mfma_f32_16x16x32_bf16 v[82:85], v[160:163], v[210:213], v[82:85]
	v_mfma_f32_16x16x32_bf16 v[126:129], v[156:159], v[188:191], v[126:129]
	v_mfma_f32_16x16x32_bf16 v[122:125], v[164:167], v[188:191], v[122:125]
	v_mfma_f32_16x16x32_bf16 v[118:121], v[156:159], v[196:199], v[118:121]
	v_mfma_f32_16x16x32_bf16 v[114:117], v[164:167], v[196:199], v[114:117]
	v_mfma_f32_16x16x32_bf16 v[102:105], v[156:159], v[206:209], v[102:105]
	v_mfma_f32_16x16x32_bf16 v[98:101], v[164:167], v[206:209], v[98:101]
	v_mfma_f32_16x16x32_bf16 v[86:89], v[156:159], v[214:217], v[86:89]
	v_mfma_f32_16x16x32_bf16 v[82:85], v[164:167], v[214:217], v[82:85]
	v_mfma_f32_16x16x32_bf16 v[110:113], v[168:171], v[184:187], v[110:113]
	v_mfma_f32_16x16x32_bf16 v[106:109], v[176:179], v[184:187], v[106:109]
	v_mfma_f32_16x16x32_bf16 v[94:97], v[168:171], v[192:195], v[94:97]
	v_mfma_f32_16x16x32_bf16 v[90:93], v[176:179], v[192:195], v[90:93]
	v_mfma_f32_16x16x32_bf16 v[78:81], v[168:171], v[200:203], v[78:81]
	v_mfma_f32_16x16x32_bf16 v[74:77], v[176:179], v[200:203], v[74:77]
	v_mfma_f32_16x16x32_bf16 v[70:73], v[168:171], v[210:213], v[70:73]
	v_mfma_f32_16x16x32_bf16 v[66:69], v[176:179], v[210:213], v[66:69]
	v_mfma_f32_16x16x32_bf16 v[110:113], v[172:175], v[188:191], v[110:113]
	v_mfma_f32_16x16x32_bf16 v[106:109], v[180:183], v[188:191], v[106:109]
	v_mfma_f32_16x16x32_bf16 v[94:97], v[172:175], v[196:199], v[94:97]
	v_mfma_f32_16x16x32_bf16 v[90:93], v[180:183], v[196:199], v[90:93]
	v_mfma_f32_16x16x32_bf16 v[78:81], v[172:175], v[206:209], v[78:81]
	v_mfma_f32_16x16x32_bf16 v[74:77], v[180:183], v[206:209], v[74:77]
	v_mfma_f32_16x16x32_bf16 v[70:73], v[172:175], v[214:217], v[70:73]
	v_mfma_f32_16x16x32_bf16 v[66:69], v[180:183], v[214:217], v[66:69]
	s_setprio 0
	s_barrier
	s_mov_b32 m0, s31
	v_lshl_add_u64 v[218:219], s[46:47], 0, v[134:135]
	s_add_u32 s42, s46, 0x20000
	global_load_lds_dwordx4 v[218:219], off
	ds_read_b128 v[184:187], v148 offset:16384
	ds_read_b128 v[188:191], v148 offset:17408
	v_lshl_add_u64 v[220:221], s[46:47], 0, v[130:131]
	s_mov_b32 m0, s33
	s_addc_u32 s43, s47, 0
	global_load_lds_dwordx4 v[220:221], off
	ds_read_b128 v[192:195], v148 offset:18432
	ds_read_b128 v[196:199], v148 offset:19456
	v_lshl_add_u64 v[222:223], s[42:43], 0, v[134:135]
	s_mov_b32 m0, s34
	v_lshl_add_u64 v[224:225], s[48:49], 0, v[132:133]
	global_load_lds_dwordx4 v[222:223], off
	ds_read_b128 v[200:203], v148 offset:20480
	ds_read_b128 v[206:209], v148 offset:21504
	s_mov_b32 m0, s35
	v_lshl_add_u64 v[222:223], s[42:43], 0, v[130:131]
	global_load_lds_dwordx4 v[222:223], off
	ds_read_b128 v[210:213], v148 offset:22528
	ds_read_b128 v[214:217], v148 offset:23552
	s_mov_b32 m0, s2
	v_lshl_add_u64 v[222:223], s[48:49], 0, v[136:137]
	global_load_lds_dwordx4 v[222:223], off
	s_mov_b32 m0, s3
	s_nop 0
	global_load_lds_dwordx4 v[224:225], off
	s_waitcnt vmcnt(8) lgkmcnt(0)
	s_setprio 1
	s_barrier
	v_mfma_f32_16x16x32_bf16 v[62:65], v[152:155], v[184:187], v[62:65]
	v_mfma_f32_16x16x32_bf16 v[58:61], v[160:163], v[184:187], v[58:61]
	v_mfma_f32_16x16x32_bf16 v[54:57], v[152:155], v[192:195], v[54:57]
	v_mfma_f32_16x16x32_bf16 v[50:53], v[160:163], v[192:195], v[50:53]
	v_mfma_f32_16x16x32_bf16 v[38:41], v[152:155], v[200:203], v[38:41]
	v_mfma_f32_16x16x32_bf16 v[34:37], v[160:163], v[200:203], v[34:37]
	v_mfma_f32_16x16x32_bf16 v[22:25], v[152:155], v[210:213], v[22:25]
	v_mfma_f32_16x16x32_bf16 v[18:21], v[160:163], v[210:213], v[18:21]
	v_mfma_f32_16x16x32_bf16 v[62:65], v[156:159], v[188:191], v[62:65]
	v_mfma_f32_16x16x32_bf16 v[58:61], v[164:167], v[188:191], v[58:61]
	v_mfma_f32_16x16x32_bf16 v[54:57], v[156:159], v[196:199], v[54:57]
	v_mfma_f32_16x16x32_bf16 v[50:53], v[164:167], v[196:199], v[50:53]
	v_mfma_f32_16x16x32_bf16 v[38:41], v[156:159], v[206:209], v[38:41]
	v_mfma_f32_16x16x32_bf16 v[34:37], v[164:167], v[206:209], v[34:37]
	v_mfma_f32_16x16x32_bf16 v[22:25], v[156:159], v[214:217], v[22:25]
	v_mfma_f32_16x16x32_bf16 v[18:21], v[164:167], v[214:217], v[18:21]
	v_mfma_f32_16x16x32_bf16 v[46:49], v[168:171], v[184:187], v[46:49]
	v_mfma_f32_16x16x32_bf16 v[42:45], v[176:179], v[184:187], v[42:45]
	v_mfma_f32_16x16x32_bf16 v[30:33], v[168:171], v[192:195], v[30:33]
	v_mfma_f32_16x16x32_bf16 v[26:29], v[176:179], v[192:195], v[26:29]
	v_mfma_f32_16x16x32_bf16 v[14:17], v[168:171], v[200:203], v[14:17]
	v_mfma_f32_16x16x32_bf16 v[10:13], v[176:179], v[200:203], v[10:13]
	v_mfma_f32_16x16x32_bf16 v[6:9], v[168:171], v[210:213], v[6:9]
	v_mfma_f32_16x16x32_bf16 v[2:5], v[176:179], v[210:213], v[2:5]
	v_mfma_f32_16x16x32_bf16 v[46:49], v[172:175], v[188:191], v[46:49]
	v_mfma_f32_16x16x32_bf16 v[42:45], v[180:183], v[188:191], v[42:45]
	v_mfma_f32_16x16x32_bf16 v[30:33], v[172:175], v[196:199], v[30:33]
	v_mfma_f32_16x16x32_bf16 v[26:29], v[180:183], v[196:199], v[26:29]
	v_mfma_f32_16x16x32_bf16 v[14:17], v[172:175], v[206:209], v[14:17]
	v_mfma_f32_16x16x32_bf16 v[10:13], v[180:183], v[206:209], v[10:13]
	v_mfma_f32_16x16x32_bf16 v[6:9], v[172:175], v[214:217], v[6:9]
	v_mfma_f32_16x16x32_bf16 v[2:5], v[180:183], v[214:217], v[2:5]
	s_setprio 0
	s_barrier
	ds_read_b128 v[152:155], v149
	ds_read_b128 v[156:159], v149 offset:1024
	ds_read_b128 v[160:163], v149 offset:2048
	ds_read_b128 v[164:167], v149 offset:3072
	ds_read_b128 v[168:171], v150
	ds_read_b128 v[172:175], v150 offset:1024
	ds_read_b128 v[176:179], v150 offset:2048
	ds_read_b128 v[180:183], v150 offset:3072
	s_add_u32 s42, s48, 0x20000
	s_addc_u32 s43, s49, 0
	s_mov_b32 m0, s16
	v_lshl_add_u64 v[226:227], s[42:43], 0, v[136:137]
	ds_read_b128 v[184:187], v148 offset:32768
	ds_read_b128 v[188:191], v148 offset:33792
	ds_read_b128 v[192:195], v148 offset:34816
	ds_read_b128 v[196:199], v148 offset:35840
	ds_read_b128 v[200:203], v148 offset:36864
	ds_read_b128 v[206:209], v148 offset:37888
	ds_read_b128 v[210:213], v148 offset:38912
	ds_read_b128 v[214:217], v148 offset:39936
	global_load_lds_dwordx4 v[226:227], off
	s_mov_b32 m0, s17
	v_lshl_add_u64 v[226:227], s[42:43], 0, v[132:133]
	global_load_lds_dwordx4 v[226:227], off
	s_waitcnt vmcnt(8) lgkmcnt(0)
	s_setprio 1
	s_barrier
	v_mfma_f32_16x16x32_bf16 v[126:129], v[152:155], v[184:187], v[126:129]
	v_mfma_f32_16x16x32_bf16 v[122:125], v[160:163], v[184:187], v[122:125]
	v_mfma_f32_16x16x32_bf16 v[118:121], v[152:155], v[192:195], v[118:121]
	v_mfma_f32_16x16x32_bf16 v[114:117], v[160:163], v[192:195], v[114:117]
	v_mfma_f32_16x16x32_bf16 v[102:105], v[152:155], v[200:203], v[102:105]
	v_mfma_f32_16x16x32_bf16 v[98:101], v[160:163], v[200:203], v[98:101]
	v_mfma_f32_16x16x32_bf16 v[86:89], v[152:155], v[210:213], v[86:89]
	v_mfma_f32_16x16x32_bf16 v[82:85], v[160:163], v[210:213], v[82:85]
	v_mfma_f32_16x16x32_bf16 v[126:129], v[156:159], v[188:191], v[126:129]
	v_mfma_f32_16x16x32_bf16 v[122:125], v[164:167], v[188:191], v[122:125]
	v_mfma_f32_16x16x32_bf16 v[118:121], v[156:159], v[196:199], v[118:121]
	v_mfma_f32_16x16x32_bf16 v[114:117], v[164:167], v[196:199], v[114:117]
	v_mfma_f32_16x16x32_bf16 v[102:105], v[156:159], v[206:209], v[102:105]
	v_mfma_f32_16x16x32_bf16 v[98:101], v[164:167], v[206:209], v[98:101]
	v_mfma_f32_16x16x32_bf16 v[86:89], v[156:159], v[214:217], v[86:89]
	v_mfma_f32_16x16x32_bf16 v[82:85], v[164:167], v[214:217], v[82:85]
	v_mfma_f32_16x16x32_bf16 v[110:113], v[168:171], v[184:187], v[110:113]
	v_mfma_f32_16x16x32_bf16 v[106:109], v[176:179], v[184:187], v[106:109]
	v_mfma_f32_16x16x32_bf16 v[94:97], v[168:171], v[192:195], v[94:97]
	v_mfma_f32_16x16x32_bf16 v[90:93], v[176:179], v[192:195], v[90:93]
	v_mfma_f32_16x16x32_bf16 v[78:81], v[168:171], v[200:203], v[78:81]
	v_mfma_f32_16x16x32_bf16 v[74:77], v[176:179], v[200:203], v[74:77]
	v_mfma_f32_16x16x32_bf16 v[70:73], v[168:171], v[210:213], v[70:73]
	v_mfma_f32_16x16x32_bf16 v[66:69], v[176:179], v[210:213], v[66:69]
	v_mfma_f32_16x16x32_bf16 v[110:113], v[172:175], v[188:191], v[110:113]
	v_mfma_f32_16x16x32_bf16 v[106:109], v[180:183], v[188:191], v[106:109]
	v_mfma_f32_16x16x32_bf16 v[94:97], v[172:175], v[196:199], v[94:97]
	v_mfma_f32_16x16x32_bf16 v[90:93], v[180:183], v[196:199], v[90:93]
	v_mfma_f32_16x16x32_bf16 v[78:81], v[172:175], v[206:209], v[78:81]
	v_mfma_f32_16x16x32_bf16 v[74:77], v[180:183], v[206:209], v[74:77]
	v_mfma_f32_16x16x32_bf16 v[70:73], v[172:175], v[214:217], v[70:73]
	v_mfma_f32_16x16x32_bf16 v[66:69], v[180:183], v[214:217], v[66:69]
	s_setprio 0
	s_barrier
	s_mov_b32 m0, s62
	v_lshl_add_u64 v[218:219], v[218:219], 0, s[10:11]
	s_add_u32 s42, s46, 0x20080
	global_load_lds_dwordx4 v[218:219], off
	ds_read_b128 v[184:187], v148 offset:49152
	ds_read_b128 v[188:191], v148 offset:50176
	v_lshl_add_u64 v[218:219], v[220:221], 0, s[10:11]
	s_mov_b32 m0, s63
	s_addc_u32 s43, s47, 0
	global_load_lds_dwordx4 v[218:219], off
	ds_read_b128 v[192:195], v148 offset:51200
	ds_read_b128 v[196:199], v148 offset:52224
	s_mov_b32 m0, s64
	v_lshl_add_u64 v[218:219], s[42:43], 0, v[134:135]
	global_load_lds_dwordx4 v[218:219], off
	ds_read_b128 v[200:203], v148 offset:53248
	ds_read_b128 v[206:209], v148 offset:54272
	s_mov_b32 m0, s65
	v_lshl_add_u64 v[218:219], s[42:43], 0, v[130:131]
	global_load_lds_dwordx4 v[218:219], off
	ds_read_b128 v[210:213], v148 offset:55296
	ds_read_b128 v[214:217], v148 offset:56320
	s_mov_b32 m0, s25
	v_lshl_add_u64 v[218:219], v[222:223], 0, s[10:11]
	global_load_lds_dwordx4 v[218:219], off
	s_mov_b32 m0, s28
	v_lshl_add_u64 v[218:219], v[224:225], 0, s[10:11]
	global_load_lds_dwordx4 v[218:219], off
	s_waitcnt vmcnt(8) lgkmcnt(0)
	s_setprio 1
	s_barrier
	v_mfma_f32_16x16x32_bf16 v[62:65], v[152:155], v[184:187], v[62:65]
	v_mfma_f32_16x16x32_bf16 v[58:61], v[160:163], v[184:187], v[58:61]
	v_mfma_f32_16x16x32_bf16 v[54:57], v[152:155], v[192:195], v[54:57]
	v_mfma_f32_16x16x32_bf16 v[50:53], v[160:163], v[192:195], v[50:53]
	v_mfma_f32_16x16x32_bf16 v[38:41], v[152:155], v[200:203], v[38:41]
	v_mfma_f32_16x16x32_bf16 v[34:37], v[160:163], v[200:203], v[34:37]
	v_mfma_f32_16x16x32_bf16 v[22:25], v[152:155], v[210:213], v[22:25]
	v_mfma_f32_16x16x32_bf16 v[18:21], v[160:163], v[210:213], v[18:21]
	v_mfma_f32_16x16x32_bf16 v[62:65], v[156:159], v[188:191], v[62:65]
	v_mfma_f32_16x16x32_bf16 v[58:61], v[164:167], v[188:191], v[58:61]
	v_mfma_f32_16x16x32_bf16 v[54:57], v[156:159], v[196:199], v[54:57]
	v_mfma_f32_16x16x32_bf16 v[50:53], v[164:167], v[196:199], v[50:53]
	v_mfma_f32_16x16x32_bf16 v[38:41], v[156:159], v[206:209], v[38:41]
	v_mfma_f32_16x16x32_bf16 v[34:37], v[164:167], v[206:209], v[34:37]
	v_mfma_f32_16x16x32_bf16 v[22:25], v[156:159], v[214:217], v[22:25]
	v_mfma_f32_16x16x32_bf16 v[18:21], v[164:167], v[214:217], v[18:21]
	v_mfma_f32_16x16x32_bf16 v[46:49], v[168:171], v[184:187], v[46:49]
	v_mfma_f32_16x16x32_bf16 v[42:45], v[176:179], v[184:187], v[42:45]
	v_mfma_f32_16x16x32_bf16 v[30:33], v[168:171], v[192:195], v[30:33]
	v_mfma_f32_16x16x32_bf16 v[26:29], v[176:179], v[192:195], v[26:29]
	v_mfma_f32_16x16x32_bf16 v[14:17], v[168:171], v[200:203], v[14:17]
	v_mfma_f32_16x16x32_bf16 v[10:13], v[176:179], v[200:203], v[10:13]
	v_mfma_f32_16x16x32_bf16 v[6:9], v[168:171], v[210:213], v[6:9]
	v_mfma_f32_16x16x32_bf16 v[2:5], v[176:179], v[210:213], v[2:5]
	v_mfma_f32_16x16x32_bf16 v[46:49], v[172:175], v[188:191], v[46:49]
	v_mfma_f32_16x16x32_bf16 v[42:45], v[180:183], v[188:191], v[42:45]
	v_mfma_f32_16x16x32_bf16 v[30:33], v[172:175], v[196:199], v[30:33]
	v_mfma_f32_16x16x32_bf16 v[26:29], v[180:183], v[196:199], v[26:29]
	v_mfma_f32_16x16x32_bf16 v[14:17], v[172:175], v[206:209], v[14:17]
	v_mfma_f32_16x16x32_bf16 v[10:13], v[180:183], v[206:209], v[10:13]
	v_mfma_f32_16x16x32_bf16 v[6:9], v[172:175], v[214:217], v[6:9]
	v_mfma_f32_16x16x32_bf16 v[2:5], v[180:183], v[214:217], v[2:5]
	s_setprio 0
	s_barrier
	s_add_i32 s68, s68, 2
	s_cmp_gt_u32 s68, 5
	s_mov_b64 s[42:43], s[44:45]
	s_cbranch_scc0 .LBB0_384
	s_and_b64 vcc, exec, s[12:13]
	s_cbranch_vccz .LBB0_387
	s_barrier

.LBB0_406:
	s_lshl_b32 s74, s12, 7
	s_add_i32 s12, s12, 2
	v_cndmask_b32_e64 v138, 0, 1, s[66:67]
	s_lshl_b64 s[66:67], s[12:13], 7
	s_and_b64 s[68:69], s[64:65], exec
	s_cselect_b32 s66, 0, s66
	s_cselect_b32 s67, 0, s67
	s_add_u32 s70, s8, s66
	s_addc_u32 s71, s9, s67
	s_lshl_b64 s[66:67], s[12:13], 12
	s_add_u32 s12, s48, s66
	s_addc_u32 s66, s49, s67
	s_and_b64 s[64:65], s[64:65], exec
	s_cselect_b32 s73, s14, s66
	s_cselect_b32 s72, s15, s12
	s_add_u32 s76, s10, s74
	s_addc_u32 s77, s11, 0
	s_add_i32 s91, s62, s16
	s_add_i32 m0, s17, 0xc000
	s_add_i32 s92, s17, 0xe000
	s_add_i32 s88, s91, 0x2000
	s_add_u32 s74, s72, 0x10000
	ds_read_b128 v[146:149], v141
	ds_read_b128 v[150:153], v141 offset:1024
	ds_read_b128 v[154:157], v141 offset:2048
	ds_read_b128 v[158:161], v141 offset:3072
	ds_read_b128 v[162:165], v143
	ds_read_b128 v[166:169], v143 offset:1024
	ds_read_b128 v[170:173], v143 offset:2048
	ds_read_b128 v[174:177], v143 offset:3072
	s_addc_u32 s75, s73, 0
	s_add_i32 s90, s63, s16
	s_add_i32 s89, s90, 0x2000
	s_add_i32 s87, 0, 0x18000
	s_add_i32 s86, 0, 0x1c000
	s_add_u32 s68, s70, 0x10000
	s_addc_u32 s69, s71, 0
	s_add_u32 s64, s72, 0x1000
	s_addc_u32 s65, s73, 0
	s_add_i32 s85, s87, s16
	s_add_i32 s83, s85, 0x2000
	s_add_u32 s66, s72, 0x11000
	s_addc_u32 s67, s73, 0
	s_add_i32 s84, s86, s16
	s_add_i32 s12, s84, 0x2000
	v_cmp_ne_u32_e32 vcc, 1, v138
	v_lshl_add_u64 v[202:203], s[76:77], 0, v[136:137]
	v_lshl_add_u64 v[202:203], v[202:203], 0, s[36:37]
	ds_read_b128 v[178:181], v144
	ds_read_b128 v[182:185], v144 offset:1024
	ds_read_b128 v[186:189], v144 offset:2048
	ds_read_b128 v[190:193], v144 offset:3072
	ds_read_b128 v[194:197], v144 offset:4096
	ds_read_b128 v[198:201], v144 offset:5120
	ds_read_b128 v[206:209], v144 offset:6144
	ds_read_b128 v[210:213], v144 offset:7168
	global_load_lds_dwordx4 v[202:203], off
	v_lshl_add_u64 v[202:203], s[76:77], 0, v[132:133]
	s_mov_b32 m0, s92
	v_lshl_add_u64 v[202:203], v[202:203], 0, s[36:37]
	global_load_lds_dwordx4 v[202:203], off
	s_waitcnt vmcnt(8) lgkmcnt(0)
	s_setprio 1
	s_barrier
	v_mfma_f32_16x16x32_bf16 v[126:129], v[146:149], v[178:181], v[126:129]
	v_mfma_f32_16x16x32_bf16 v[122:125], v[154:157], v[178:181], v[122:125]
	v_mfma_f32_16x16x32_bf16 v[118:121], v[146:149], v[186:189], v[118:121]
	v_mfma_f32_16x16x32_bf16 v[110:113], v[154:157], v[186:189], v[110:113]
	v_mfma_f32_16x16x32_bf16 v[102:105], v[146:149], v[194:197], v[102:105]
	v_mfma_f32_16x16x32_bf16 v[98:101], v[154:157], v[194:197], v[98:101]
	v_mfma_f32_16x16x32_bf16 v[86:89], v[146:149], v[206:209], v[86:89]
	v_mfma_f32_16x16x32_bf16 v[82:85], v[154:157], v[206:209], v[82:85]
	v_mfma_f32_16x16x32_bf16 v[126:129], v[150:153], v[182:185], v[126:129]
	v_mfma_f32_16x16x32_bf16 v[122:125], v[158:161], v[182:185], v[122:125]
	v_mfma_f32_16x16x32_bf16 v[118:121], v[150:153], v[190:193], v[118:121]
	v_mfma_f32_16x16x32_bf16 v[110:113], v[158:161], v[190:193], v[110:113]
	v_mfma_f32_16x16x32_bf16 v[102:105], v[150:153], v[198:201], v[102:105]
	v_mfma_f32_16x16x32_bf16 v[98:101], v[158:161], v[198:201], v[98:101]
	v_mfma_f32_16x16x32_bf16 v[86:89], v[150:153], v[210:213], v[86:89]
	v_mfma_f32_16x16x32_bf16 v[82:85], v[158:161], v[210:213], v[82:85]
	v_mfma_f32_16x16x32_bf16 v[114:117], v[162:165], v[178:181], v[114:117]
	v_mfma_f32_16x16x32_bf16 v[106:109], v[170:173], v[178:181], v[106:109]
	v_mfma_f32_16x16x32_bf16 v[94:97], v[162:165], v[186:189], v[94:97]
	v_mfma_f32_16x16x32_bf16 v[90:93], v[170:173], v[186:189], v[90:93]
	v_mfma_f32_16x16x32_bf16 v[78:81], v[162:165], v[194:197], v[78:81]
	v_mfma_f32_16x16x32_bf16 v[74:77], v[170:173], v[194:197], v[74:77]
	v_mfma_f32_16x16x32_bf16 v[70:73], v[162:165], v[206:209], v[70:73]
	v_mfma_f32_16x16x32_bf16 v[66:69], v[170:173], v[206:209], v[66:69]
	v_mfma_f32_16x16x32_bf16 v[114:117], v[166:169], v[182:185], v[114:117]
	v_mfma_f32_16x16x32_bf16 v[106:109], v[174:177], v[182:185], v[106:109]
	v_mfma_f32_16x16x32_bf16 v[94:97], v[166:169], v[190:193], v[94:97]
	v_mfma_f32_16x16x32_bf16 v[90:93], v[174:177], v[190:193], v[90:93]
	v_mfma_f32_16x16x32_bf16 v[78:81], v[166:169], v[198:201], v[78:81]
	v_mfma_f32_16x16x32_bf16 v[74:77], v[174:177], v[198:201], v[74:77]
	v_mfma_f32_16x16x32_bf16 v[70:73], v[166:169], v[210:213], v[70:73]
	v_mfma_f32_16x16x32_bf16 v[66:69], v[174:177], v[210:213], v[66:69]
	s_setprio 0
	s_barrier
	s_mov_b32 m0, s91
	v_lshl_add_u64 v[202:203], s[72:73], 0, v[134:135]
	global_load_lds_dwordx4 v[202:203], off
	ds_read_b128 v[178:181], v144 offset:16384
	ds_read_b128 v[182:185], v144 offset:17408
	v_lshl_add_u64 v[202:203], s[72:73], 0, v[130:131]
	s_mov_b32 m0, s88
	v_lshl_add_u64 v[214:215], s[70:71], 0, v[132:133]
	global_load_lds_dwordx4 v[202:203], off
	ds_read_b128 v[186:189], v144 offset:18432
	ds_read_b128 v[190:193], v144 offset:19456
	s_mov_b32 m0, s90
	v_lshl_add_u64 v[202:203], s[74:75], 0, v[134:135]
	global_load_lds_dwordx4 v[202:203], off
	ds_read_b128 v[194:197], v144 offset:20480
	ds_read_b128 v[198:201], v144 offset:21504
	s_mov_b32 m0, s89
	v_lshl_add_u64 v[202:203], s[74:75], 0, v[130:131]
	global_load_lds_dwordx4 v[202:203], off
	ds_read_b128 v[206:209], v144 offset:22528
	ds_read_b128 v[210:213], v144 offset:23552
	s_mov_b32 m0, s17
	v_lshl_add_u64 v[202:203], s[70:71], 0, v[136:137]
	global_load_lds_dwordx4 v[202:203], off
	s_mov_b32 m0, s18
	s_nop 0
	global_load_lds_dwordx4 v[214:215], off
	s_waitcnt vmcnt(8) lgkmcnt(0)
	s_setprio 1
	s_barrier
	v_mfma_f32_16x16x32_bf16 v[62:65], v[146:149], v[178:181], v[62:65]
	v_mfma_f32_16x16x32_bf16 v[58:61], v[154:157], v[178:181], v[58:61]
	v_mfma_f32_16x16x32_bf16 v[54:57], v[146:149], v[186:189], v[54:57]
	v_mfma_f32_16x16x32_bf16 v[50:53], v[154:157], v[186:189], v[50:53]
	v_mfma_f32_16x16x32_bf16 v[38:41], v[146:149], v[194:197], v[38:41]
	v_mfma_f32_16x16x32_bf16 v[34:37], v[154:157], v[194:197], v[34:37]
	v_mfma_f32_16x16x32_bf16 v[22:25], v[146:149], v[206:209], v[22:25]
	v_mfma_f32_16x16x32_bf16 v[18:21], v[154:157], v[206:209], v[18:21]
	v_mfma_f32_16x16x32_bf16 v[62:65], v[150:153], v[182:185], v[62:65]
	v_mfma_f32_16x16x32_bf16 v[58:61], v[158:161], v[182:185], v[58:61]
	v_mfma_f32_16x16x32_bf16 v[54:57], v[150:153], v[190:193], v[54:57]
	v_mfma_f32_16x16x32_bf16 v[50:53], v[158:161], v[190:193], v[50:53]
	v_mfma_f32_16x16x32_bf16 v[38:41], v[150:153], v[198:201], v[38:41]
	v_mfma_f32_16x16x32_bf16 v[34:37], v[158:161], v[198:201], v[34:37]
	v_mfma_f32_16x16x32_bf16 v[22:25], v[150:153], v[210:213], v[22:25]
	v_mfma_f32_16x16x32_bf16 v[18:21], v[158:161], v[210:213], v[18:21]
	v_mfma_f32_16x16x32_bf16 v[46:49], v[162:165], v[178:181], v[46:49]
	v_mfma_f32_16x16x32_bf16 v[42:45], v[170:173], v[178:181], v[42:45]
	v_mfma_f32_16x16x32_bf16 v[30:33], v[162:165], v[186:189], v[30:33]
	v_mfma_f32_16x16x32_bf16 v[26:29], v[170:173], v[186:189], v[26:29]
	v_mfma_f32_16x16x32_bf16 v[14:17], v[162:165], v[194:197], v[14:17]
	v_mfma_f32_16x16x32_bf16 v[10:13], v[170:173], v[194:197], v[10:13]
	v_mfma_f32_16x16x32_bf16 v[6:9], v[162:165], v[206:209], v[6:9]
	v_mfma_f32_16x16x32_bf16 v[2:5], v[170:173], v[206:209], v[2:5]
	v_mfma_f32_16x16x32_bf16 v[46:49], v[166:169], v[182:185], v[46:49]
	v_mfma_f32_16x16x32_bf16 v[42:45], v[174:177], v[182:185], v[42:45]
	v_mfma_f32_16x16x32_bf16 v[30:33], v[166:169], v[190:193], v[30:33]
	v_mfma_f32_16x16x32_bf16 v[26:29], v[174:177], v[190:193], v[26:29]
	v_mfma_f32_16x16x32_bf16 v[14:17], v[166:169], v[198:201], v[14:17]
	v_mfma_f32_16x16x32_bf16 v[10:13], v[174:177], v[198:201], v[10:13]
	v_mfma_f32_16x16x32_bf16 v[6:9], v[166:169], v[210:213], v[6:9]
	v_mfma_f32_16x16x32_bf16 v[2:5], v[174:177], v[210:213], v[2:5]
	s_setprio 0
	s_barrier
	v_add_u32_e32 v138, s87, v140
	ds_read_b128 v[146:149], v138
	ds_read_b128 v[150:153], v138 offset:1024
	ds_read_b128 v[154:157], v138 offset:2048
	ds_read_b128 v[158:161], v138 offset:3072
	v_add_u32_e32 v138, s86, v140
	ds_read_b128 v[162:165], v138
	ds_read_b128 v[166:169], v138 offset:1024
	ds_read_b128 v[170:173], v138 offset:2048
	ds_read_b128 v[174:177], v138 offset:3072
	s_mov_b32 m0, s19
	v_lshl_add_u64 v[216:217], s[68:69], 0, v[136:137]
	ds_read_b128 v[178:181], v144 offset:32768
	ds_read_b128 v[182:185], v144 offset:33792
	ds_read_b128 v[186:189], v144 offset:34816
	ds_read_b128 v[190:193], v144 offset:35840
	ds_read_b128 v[194:197], v144 offset:36864
	ds_read_b128 v[198:201], v144 offset:37888
	ds_read_b128 v[206:209], v144 offset:38912
	ds_read_b128 v[210:213], v144 offset:39936
	global_load_lds_dwordx4 v[216:217], off
	s_mov_b32 m0, s24
	v_lshl_add_u64 v[216:217], s[68:69], 0, v[132:133]
	global_load_lds_dwordx4 v[216:217], off
	s_waitcnt vmcnt(8) lgkmcnt(0)
	s_setprio 1
	s_barrier
	v_mfma_f32_16x16x32_bf16 v[126:129], v[146:149], v[178:181], v[126:129]
	v_mfma_f32_16x16x32_bf16 v[122:125], v[154:157], v[178:181], v[122:125]
	v_mfma_f32_16x16x32_bf16 v[118:121], v[146:149], v[186:189], v[118:121]
	v_mfma_f32_16x16x32_bf16 v[110:113], v[154:157], v[186:189], v[110:113]
	v_mfma_f32_16x16x32_bf16 v[102:105], v[146:149], v[194:197], v[102:105]
	v_mfma_f32_16x16x32_bf16 v[98:101], v[154:157], v[194:197], v[98:101]
	v_mfma_f32_16x16x32_bf16 v[86:89], v[146:149], v[206:209], v[86:89]
	v_mfma_f32_16x16x32_bf16 v[82:85], v[154:157], v[206:209], v[82:85]
	v_mfma_f32_16x16x32_bf16 v[126:129], v[150:153], v[182:185], v[126:129]
	v_mfma_f32_16x16x32_bf16 v[122:125], v[158:161], v[182:185], v[122:125]
	v_mfma_f32_16x16x32_bf16 v[118:121], v[150:153], v[190:193], v[118:121]
	v_mfma_f32_16x16x32_bf16 v[110:113], v[158:161], v[190:193], v[110:113]
	v_mfma_f32_16x16x32_bf16 v[102:105], v[150:153], v[198:201], v[102:105]
	v_mfma_f32_16x16x32_bf16 v[98:101], v[158:161], v[198:201], v[98:101]
	v_mfma_f32_16x16x32_bf16 v[86:89], v[150:153], v[210:213], v[86:89]
	v_mfma_f32_16x16x32_bf16 v[82:85], v[158:161], v[210:213], v[82:85]
	v_mfma_f32_16x16x32_bf16 v[114:117], v[162:165], v[178:181], v[114:117]
	v_mfma_f32_16x16x32_bf16 v[106:109], v[170:173], v[178:181], v[106:109]
	v_mfma_f32_16x16x32_bf16 v[94:97], v[162:165], v[186:189], v[94:97]
	v_mfma_f32_16x16x32_bf16 v[90:93], v[170:173], v[186:189], v[90:93]
	v_mfma_f32_16x16x32_bf16 v[78:81], v[162:165], v[194:197], v[78:81]
	v_mfma_f32_16x16x32_bf16 v[74:77], v[170:173], v[194:197], v[74:77]
	v_mfma_f32_16x16x32_bf16 v[70:73], v[162:165], v[206:209], v[70:73]
	v_mfma_f32_16x16x32_bf16 v[66:69], v[170:173], v[206:209], v[66:69]
	v_mfma_f32_16x16x32_bf16 v[114:117], v[166:169], v[182:185], v[114:117]
	v_mfma_f32_16x16x32_bf16 v[106:109], v[174:177], v[182:185], v[106:109]
	v_mfma_f32_16x16x32_bf16 v[94:97], v[166:169], v[190:193], v[94:97]
	v_mfma_f32_16x16x32_bf16 v[90:93], v[174:177], v[190:193], v[90:93]
	v_mfma_f32_16x16x32_bf16 v[78:81], v[166:169], v[198:201], v[78:81]
	v_mfma_f32_16x16x32_bf16 v[74:77], v[174:177], v[198:201], v[74:77]
	v_mfma_f32_16x16x32_bf16 v[70:73], v[166:169], v[210:213], v[70:73]
	v_mfma_f32_16x16x32_bf16 v[66:69], v[174:177], v[210:213], v[66:69]
	s_setprio 0
	s_barrier
	s_mov_b32 m0, s85
	v_lshl_add_u64 v[216:217], s[64:65], 0, v[134:135]
	global_load_lds_dwordx4 v[216:217], off
	ds_read_b128 v[178:181], v144 offset:49152
	ds_read_b128 v[182:185], v144 offset:50176
	v_lshl_add_u64 v[216:217], s[64:65], 0, v[130:131]
	s_mov_b32 m0, s83
	v_lshl_add_u64 v[202:203], v[202:203], 0, s[36:37]
	global_load_lds_dwordx4 v[216:217], off
	ds_read_b128 v[186:189], v144 offset:51200
	ds_read_b128 v[190:193], v144 offset:52224
	s_mov_b32 m0, s84
	v_lshl_add_u64 v[216:217], s[66:67], 0, v[134:135]
	global_load_lds_dwordx4 v[216:217], off
	ds_read_b128 v[194:197], v144 offset:53248
	ds_read_b128 v[198:201], v144 offset:54272
	s_mov_b32 m0, s12
	v_lshl_add_u64 v[216:217], s[66:67], 0, v[130:131]
	global_load_lds_dwordx4 v[216:217], off
	ds_read_b128 v[206:209], v144 offset:55296
	ds_read_b128 v[210:213], v144 offset:56320
	s_mov_b32 m0, s31
	s_nop 0
	global_load_lds_dwordx4 v[202:203], off
	s_mov_b32 m0, s33
	v_lshl_add_u64 v[202:203], v[214:215], 0, s[36:37]
	global_load_lds_dwordx4 v[202:203], off
	s_waitcnt vmcnt(8) lgkmcnt(0)
	s_setprio 1
	s_barrier
	v_mfma_f32_16x16x32_bf16 v[62:65], v[146:149], v[178:181], v[62:65]
	v_mfma_f32_16x16x32_bf16 v[58:61], v[154:157], v[178:181], v[58:61]
	v_mfma_f32_16x16x32_bf16 v[54:57], v[146:149], v[186:189], v[54:57]
	v_mfma_f32_16x16x32_bf16 v[50:53], v[154:157], v[186:189], v[50:53]
	v_mfma_f32_16x16x32_bf16 v[38:41], v[146:149], v[194:197], v[38:41]
	v_mfma_f32_16x16x32_bf16 v[34:37], v[154:157], v[194:197], v[34:37]
	v_mfma_f32_16x16x32_bf16 v[22:25], v[146:149], v[206:209], v[22:25]
	v_mfma_f32_16x16x32_bf16 v[18:21], v[154:157], v[206:209], v[18:21]
	v_mfma_f32_16x16x32_bf16 v[62:65], v[150:153], v[182:185], v[62:65]
	v_mfma_f32_16x16x32_bf16 v[58:61], v[158:161], v[182:185], v[58:61]
	v_mfma_f32_16x16x32_bf16 v[54:57], v[150:153], v[190:193], v[54:57]
	v_mfma_f32_16x16x32_bf16 v[50:53], v[158:161], v[190:193], v[50:53]
	v_mfma_f32_16x16x32_bf16 v[38:41], v[150:153], v[198:201], v[38:41]
	v_mfma_f32_16x16x32_bf16 v[34:37], v[158:161], v[198:201], v[34:37]
	v_mfma_f32_16x16x32_bf16 v[22:25], v[150:153], v[210:213], v[22:25]
	v_mfma_f32_16x16x32_bf16 v[18:21], v[158:161], v[210:213], v[18:21]
	v_mfma_f32_16x16x32_bf16 v[46:49], v[162:165], v[178:181], v[46:49]
	v_mfma_f32_16x16x32_bf16 v[42:45], v[170:173], v[178:181], v[42:45]
	v_mfma_f32_16x16x32_bf16 v[30:33], v[162:165], v[186:189], v[30:33]
	v_mfma_f32_16x16x32_bf16 v[26:29], v[170:173], v[186:189], v[26:29]
	v_mfma_f32_16x16x32_bf16 v[14:17], v[162:165], v[194:197], v[14:17]
	v_mfma_f32_16x16x32_bf16 v[10:13], v[170:173], v[194:197], v[10:13]
	v_mfma_f32_16x16x32_bf16 v[6:9], v[162:165], v[206:209], v[6:9]
	v_mfma_f32_16x16x32_bf16 v[2:5], v[170:173], v[206:209], v[2:5]
	v_mfma_f32_16x16x32_bf16 v[46:49], v[166:169], v[182:185], v[46:49]
	v_mfma_f32_16x16x32_bf16 v[42:45], v[174:177], v[182:185], v[42:45]
	v_mfma_f32_16x16x32_bf16 v[30:33], v[166:169], v[190:193], v[30:33]
	v_mfma_f32_16x16x32_bf16 v[26:29], v[174:177], v[190:193], v[26:29]
	v_mfma_f32_16x16x32_bf16 v[14:17], v[166:169], v[198:201], v[14:17]
	v_mfma_f32_16x16x32_bf16 v[10:13], v[174:177], v[198:201], v[10:13]
	v_mfma_f32_16x16x32_bf16 v[6:9], v[166:169], v[210:213], v[6:9]
	v_mfma_f32_16x16x32_bf16 v[2:5], v[174:177], v[210:213], v[2:5]
	s_setprio 0
	s_barrier
	s_mov_b64 s[66:67], 0
	s_mov_b64 s[64:65], -1
	s_mov_b32 s12, 2
	s_cbranch_vccz .LBB0_406
	s_and_b64 vcc, exec, s[22:23]
	s_cbranch_vccz .LBB0_409
	s_barrier

.LBB0_476:
	s_add_u32 s22, s2, s49
	s_addc_u32 s23, s3, s29
	s_and_b64 s[26:27], s[20:21], exec
	s_cselect_b32 s63, s23, s37
	s_cselect_b32 s64, s22, s36
	s_add_u32 s26, s16, s12
	s_addc_u32 s27, s17, s13
	s_and_b64 s[42:43], s[20:21], exec
	s_cselect_b32 s65, s27, s39
	s_cselect_b32 s66, s26, s38
	s_add_u32 s36, s36, 0x20080
	s_addc_u32 s37, s37, 0
	s_add_u32 s67, s38, 0x100
	s_addc_u32 s68, s39, 0
	s_mov_b32 s69, -2
	ds_read_b128 v[148:151], v144
	ds_read_b128 v[152:155], v144 offset:1024
	ds_read_b128 v[156:159], v144 offset:2048
	ds_read_b128 v[160:163], v144 offset:3072
	ds_read_b128 v[164:167], v145
	ds_read_b128 v[168:171], v145 offset:1024
	ds_read_b128 v[172:175], v145 offset:2048
	ds_read_b128 v[176:179], v145 offset:3072
	s_add_u32 s38, s36, 0xfffe0080
	s_addc_u32 s39, s37, -1
	s_cmp_eq_u32 s69, 4
	s_cselect_b32 s43, s63, s39
	s_cselect_b32 s42, s64, s38
	s_cselect_b32 s39, s65, s68
	s_cselect_b32 s38, s66, s67
	v_lshl_add_u64 v[214:215], s[36:37], 0, v[138:139]
	s_add_i32 m0, s19, 0xc000
	ds_read_b128 v[180:183], v146
	ds_read_b128 v[184:187], v146 offset:1024
	ds_read_b128 v[188:191], v146 offset:2048
	ds_read_b128 v[192:195], v146 offset:3072
	ds_read_b128 v[196:199], v146 offset:4096
	ds_read_b128 v[200:203], v146 offset:5120
	ds_read_b128 v[206:209], v146 offset:6144
	ds_read_b128 v[210:213], v146 offset:7168
	global_load_lds_dwordx4 v[214:215], off
	s_add_i32 m0, s19, 0xe000
	v_lshl_add_u64 v[214:215], s[36:37], 0, v[140:141]
	global_load_lds_dwordx4 v[214:215], off
	s_waitcnt vmcnt(8) lgkmcnt(0)
	s_setprio 1
	s_barrier
	v_mfma_f32_16x16x32_bf16 v[126:129], v[148:151], v[180:183], 0
	v_mfma_f32_16x16x32_bf16 v[122:125], v[156:159], v[180:183], 0
	v_mfma_f32_16x16x32_bf16 v[118:121], v[148:151], v[188:191], 0
	v_mfma_f32_16x16x32_bf16 v[114:117], v[156:159], v[188:191], 0
	v_mfma_f32_16x16x32_bf16 v[102:105], v[148:151], v[196:199], 0
	v_mfma_f32_16x16x32_bf16 v[98:101], v[156:159], v[196:199], 0
	v_mfma_f32_16x16x32_bf16 v[86:89], v[148:151], v[206:209], 0
	v_mfma_f32_16x16x32_bf16 v[82:85], v[156:159], v[206:209], 0
	v_mfma_f32_16x16x32_bf16 v[126:129], v[152:155], v[184:187], v[126:129]
	v_mfma_f32_16x16x32_bf16 v[122:125], v[160:163], v[184:187], v[122:125]
	v_mfma_f32_16x16x32_bf16 v[118:121], v[152:155], v[192:195], v[118:121]
	v_mfma_f32_16x16x32_bf16 v[114:117], v[160:163], v[192:195], v[114:117]
	v_mfma_f32_16x16x32_bf16 v[102:105], v[152:155], v[200:203], v[102:105]
	v_mfma_f32_16x16x32_bf16 v[98:101], v[160:163], v[200:203], v[98:101]
	v_mfma_f32_16x16x32_bf16 v[86:89], v[152:155], v[210:213], v[86:89]
	v_mfma_f32_16x16x32_bf16 v[82:85], v[160:163], v[210:213], v[82:85]
	v_mfma_f32_16x16x32_bf16 v[110:113], v[164:167], v[180:183], 0
	v_mfma_f32_16x16x32_bf16 v[106:109], v[172:175], v[180:183], 0
	v_mfma_f32_16x16x32_bf16 v[94:97], v[164:167], v[188:191], 0
	v_mfma_f32_16x16x32_bf16 v[90:93], v[172:175], v[188:191], 0
	v_mfma_f32_16x16x32_bf16 v[78:81], v[164:167], v[196:199], 0
	v_mfma_f32_16x16x32_bf16 v[74:77], v[172:175], v[196:199], 0
	v_mfma_f32_16x16x32_bf16 v[70:73], v[164:167], v[206:209], 0
	v_mfma_f32_16x16x32_bf16 v[66:69], v[172:175], v[206:209], 0
	v_mfma_f32_16x16x32_bf16 v[110:113], v[168:171], v[184:187], v[110:113]
	v_mfma_f32_16x16x32_bf16 v[106:109], v[176:179], v[184:187], v[106:109]
	v_mfma_f32_16x16x32_bf16 v[94:97], v[168:171], v[192:195], v[94:97]
	v_mfma_f32_16x16x32_bf16 v[90:93], v[176:179], v[192:195], v[90:93]
	v_mfma_f32_16x16x32_bf16 v[78:81], v[168:171], v[200:203], v[78:81]
	v_mfma_f32_16x16x32_bf16 v[74:77], v[176:179], v[200:203], v[74:77]
	v_mfma_f32_16x16x32_bf16 v[70:73], v[168:171], v[210:213], v[70:73]
	v_mfma_f32_16x16x32_bf16 v[66:69], v[176:179], v[210:213], v[66:69]
	s_setprio 0
	s_barrier
	s_add_i32 s70, s35, s18
	s_mov_b32 m0, s70
	v_lshl_add_u64 v[214:215], s[38:39], 0, v[134:135]
	global_load_lds_dwordx4 v[214:215], off
	ds_read_b128 v[180:183], v146 offset:16384
	ds_read_b128 v[184:187], v146 offset:17408
	s_add_i32 m0, s70, 0x2000
	s_add_u32 s70, s38, 0x200000
	v_lshl_add_u64 v[216:217], s[38:39], 0, v[130:131]
	s_addc_u32 s71, s39, 0
	s_add_i32 s72, s44, s18
	global_load_lds_dwordx4 v[216:217], off
	ds_read_b128 v[188:191], v146 offset:18432
	ds_read_b128 v[192:195], v146 offset:19456
	v_lshl_add_u64 v[218:219], s[70:71], 0, v[134:135]
	s_mov_b32 m0, s72
	v_lshl_add_u64 v[220:221], s[42:43], 0, v[132:133]
	global_load_lds_dwordx4 v[218:219], off
	ds_read_b128 v[196:199], v146 offset:20480
	ds_read_b128 v[200:203], v146 offset:21504
	s_add_i32 m0, s72, 0x2000
	v_lshl_add_u64 v[218:219], s[70:71], 0, v[130:131]
	global_load_lds_dwordx4 v[218:219], off
	ds_read_b128 v[206:209], v146 offset:22528
	ds_read_b128 v[210:213], v146 offset:23552
	s_mov_b32 m0, s19
	v_lshl_add_u64 v[218:219], s[42:43], 0, v[136:137]
	global_load_lds_dwordx4 v[218:219], off
	s_mov_b32 m0, s24
	s_nop 0
	global_load_lds_dwordx4 v[220:221], off
	s_waitcnt vmcnt(8) lgkmcnt(0)
	s_setprio 1
	s_barrier
	v_mfma_f32_16x16x32_bf16 v[62:65], v[148:151], v[180:183], 0
	v_mfma_f32_16x16x32_bf16 v[58:61], v[156:159], v[180:183], 0
	v_mfma_f32_16x16x32_bf16 v[54:57], v[148:151], v[188:191], 0
	v_mfma_f32_16x16x32_bf16 v[50:53], v[156:159], v[188:191], 0
	v_mfma_f32_16x16x32_bf16 v[38:41], v[148:151], v[196:199], 0
	v_mfma_f32_16x16x32_bf16 v[34:37], v[156:159], v[196:199], 0
	v_mfma_f32_16x16x32_bf16 v[22:25], v[148:151], v[206:209], 0
	v_mfma_f32_16x16x32_bf16 v[18:21], v[156:159], v[206:209], 0
	v_mfma_f32_16x16x32_bf16 v[62:65], v[152:155], v[184:187], v[62:65]
	v_mfma_f32_16x16x32_bf16 v[58:61], v[160:163], v[184:187], v[58:61]
	v_mfma_f32_16x16x32_bf16 v[54:57], v[152:155], v[192:195], v[54:57]
	v_mfma_f32_16x16x32_bf16 v[50:53], v[160:163], v[192:195], v[50:53]
	v_mfma_f32_16x16x32_bf16 v[38:41], v[152:155], v[200:203], v[38:41]
	v_mfma_f32_16x16x32_bf16 v[34:37], v[160:163], v[200:203], v[34:37]
	v_mfma_f32_16x16x32_bf16 v[22:25], v[152:155], v[210:213], v[22:25]
	v_mfma_f32_16x16x32_bf16 v[18:21], v[160:163], v[210:213], v[18:21]
	v_mfma_f32_16x16x32_bf16 v[46:49], v[164:167], v[180:183], 0
	v_mfma_f32_16x16x32_bf16 v[42:45], v[172:175], v[180:183], 0
	v_mfma_f32_16x16x32_bf16 v[30:33], v[164:167], v[188:191], 0
	v_mfma_f32_16x16x32_bf16 v[26:29], v[172:175], v[188:191], 0
	v_mfma_f32_16x16x32_bf16 v[14:17], v[164:167], v[196:199], 0
	v_mfma_f32_16x16x32_bf16 v[10:13], v[172:175], v[196:199], 0
	v_mfma_f32_16x16x32_bf16 v[6:9], v[164:167], v[206:209], 0
	v_mfma_f32_16x16x32_bf16 v[2:5], v[172:175], v[206:209], 0
	v_mfma_f32_16x16x32_bf16 v[46:49], v[168:171], v[184:187], v[46:49]
	v_mfma_f32_16x16x32_bf16 v[42:45], v[176:179], v[184:187], v[42:45]
	v_mfma_f32_16x16x32_bf16 v[30:33], v[168:171], v[192:195], v[30:33]
	v_mfma_f32_16x16x32_bf16 v[26:29], v[176:179], v[192:195], v[26:29]
	v_mfma_f32_16x16x32_bf16 v[14:17], v[168:171], v[200:203], v[14:17]
	v_mfma_f32_16x16x32_bf16 v[10:13], v[176:179], v[200:203], v[10:13]
	v_mfma_f32_16x16x32_bf16 v[6:9], v[168:171], v[210:213], v[6:9]
	v_mfma_f32_16x16x32_bf16 v[2:5], v[176:179], v[210:213], v[2:5]
	s_setprio 0
	s_barrier
	s_add_i32 s70, 0, 0x18000
	v_add_u32_e32 v147, s70, v143
	s_add_i32 s71, 0, 0x1c000
	ds_read_b128 v[148:151], v147
	ds_read_b128 v[152:155], v147 offset:1024
	ds_read_b128 v[156:159], v147 offset:2048
	ds_read_b128 v[160:163], v147 offset:3072
	v_add_u32_e32 v147, s71, v143
	ds_read_b128 v[164:167], v147
	ds_read_b128 v[168:171], v147 offset:1024
	ds_read_b128 v[172:175], v147 offset:2048
	ds_read_b128 v[176:179], v147 offset:3072
	s_add_u32 s42, s42, 0x20000
	s_addc_u32 s43, s43, 0
	s_mov_b32 m0, s25
	v_lshl_add_u64 v[222:223], s[42:43], 0, v[136:137]
	ds_read_b128 v[180:183], v146 offset:32768
	ds_read_b128 v[184:187], v146 offset:33792
	ds_read_b128 v[188:191], v146 offset:34816
	ds_read_b128 v[192:195], v146 offset:35840
	ds_read_b128 v[196:199], v146 offset:36864
	ds_read_b128 v[200:203], v146 offset:37888
	ds_read_b128 v[206:209], v146 offset:38912
	ds_read_b128 v[210:213], v146 offset:39936
	global_load_lds_dwordx4 v[222:223], off
	s_mov_b32 m0, s28
	v_lshl_add_u64 v[222:223], s[42:43], 0, v[132:133]
	global_load_lds_dwordx4 v[222:223], off
	s_waitcnt vmcnt(8) lgkmcnt(0)
	s_setprio 1
	s_barrier
	v_mfma_f32_16x16x32_bf16 v[126:129], v[148:151], v[180:183], v[126:129]
	v_mfma_f32_16x16x32_bf16 v[122:125], v[156:159], v[180:183], v[122:125]
	v_mfma_f32_16x16x32_bf16 v[118:121], v[148:151], v[188:191], v[118:121]
	v_mfma_f32_16x16x32_bf16 v[114:117], v[156:159], v[188:191], v[114:117]
	v_mfma_f32_16x16x32_bf16 v[102:105], v[148:151], v[196:199], v[102:105]
	v_mfma_f32_16x16x32_bf16 v[98:101], v[156:159], v[196:199], v[98:101]
	v_mfma_f32_16x16x32_bf16 v[86:89], v[148:151], v[206:209], v[86:89]
	v_mfma_f32_16x16x32_bf16 v[82:85], v[156:159], v[206:209], v[82:85]
	v_mfma_f32_16x16x32_bf16 v[126:129], v[152:155], v[184:187], v[126:129]
	v_mfma_f32_16x16x32_bf16 v[122:125], v[160:163], v[184:187], v[122:125]
	v_mfma_f32_16x16x32_bf16 v[118:121], v[152:155], v[192:195], v[118:121]
	v_mfma_f32_16x16x32_bf16 v[114:117], v[160:163], v[192:195], v[114:117]
	v_mfma_f32_16x16x32_bf16 v[102:105], v[152:155], v[200:203], v[102:105]
	v_mfma_f32_16x16x32_bf16 v[98:101], v[160:163], v[200:203], v[98:101]
	v_mfma_f32_16x16x32_bf16 v[86:89], v[152:155], v[210:213], v[86:89]
	v_mfma_f32_16x16x32_bf16 v[82:85], v[160:163], v[210:213], v[82:85]
	v_mfma_f32_16x16x32_bf16 v[110:113], v[164:167], v[180:183], v[110:113]
	v_mfma_f32_16x16x32_bf16 v[106:109], v[172:175], v[180:183], v[106:109]
	v_mfma_f32_16x16x32_bf16 v[94:97], v[164:167], v[188:191], v[94:97]
	v_mfma_f32_16x16x32_bf16 v[90:93], v[172:175], v[188:191], v[90:93]
	v_mfma_f32_16x16x32_bf16 v[78:81], v[164:167], v[196:199], v[78:81]
	v_mfma_f32_16x16x32_bf16 v[74:77], v[172:175], v[196:199], v[74:77]
	v_mfma_f32_16x16x32_bf16 v[70:73], v[164:167], v[206:209], v[70:73]
	v_mfma_f32_16x16x32_bf16 v[66:69], v[172:175], v[206:209], v[66:69]
	v_mfma_f32_16x16x32_bf16 v[110:113], v[168:171], v[184:187], v[110:113]
	v_mfma_f32_16x16x32_bf16 v[106:109], v[176:179], v[184:187], v[106:109]
	v_mfma_f32_16x16x32_bf16 v[94:97], v[168:171], v[192:195], v[94:97]
	v_mfma_f32_16x16x32_bf16 v[90:93], v[176:179], v[192:195], v[90:93]
	v_mfma_f32_16x16x32_bf16 v[78:81], v[168:171], v[200:203], v[78:81]
	v_mfma_f32_16x16x32_bf16 v[74:77], v[176:179], v[200:203], v[74:77]
	v_mfma_f32_16x16x32_bf16 v[70:73], v[168:171], v[210:213], v[70:73]
	v_mfma_f32_16x16x32_bf16 v[66:69], v[176:179], v[210:213], v[66:69]
	s_setprio 0
	s_barrier
	s_add_i32 s42, s70, s18
	s_mov_b32 m0, s42
	v_lshl_add_u64 v[214:215], v[214:215], 0, s[8:9]
	global_load_lds_dwordx4 v[214:215], off
	ds_read_b128 v[180:183], v146 offset:49152
	ds_read_b128 v[184:187], v146 offset:50176
	s_add_i32 m0, s42, 0x2000
	s_add_u32 s38, s38, 0x200080
	v_lshl_add_u64 v[214:215], v[216:217], 0, s[8:9]
	s_addc_u32 s39, s39, 0
	s_add_i32 s42, s71, s18
	global_load_lds_dwordx4 v[214:215], off
	ds_read_b128 v[188:191], v146 offset:51200
	ds_read_b128 v[192:195], v146 offset:52224
	s_mov_b32 m0, s42
	v_lshl_add_u64 v[214:215], s[38:39], 0, v[134:135]
	global_load_lds_dwordx4 v[214:215], off
	ds_read_b128 v[196:199], v146 offset:53248
	ds_read_b128 v[200:203], v146 offset:54272
	s_add_i32 m0, s42, 0x2000
	v_lshl_add_u64 v[214:215], s[38:39], 0, v[130:131]
	global_load_lds_dwordx4 v[214:215], off
	ds_read_b128 v[206:209], v146 offset:55296
	ds_read_b128 v[210:213], v146 offset:56320
	s_mov_b32 m0, s33
	v_lshl_add_u64 v[214:215], v[218:219], 0, s[8:9]
	global_load_lds_dwordx4 v[214:215], off
	s_mov_b32 m0, s34
	v_lshl_add_u64 v[214:215], v[220:221], 0, s[8:9]
	global_load_lds_dwordx4 v[214:215], off
	s_waitcnt vmcnt(8) lgkmcnt(0)
	s_setprio 1
	s_barrier
	v_mfma_f32_16x16x32_bf16 v[62:65], v[148:151], v[180:183], v[62:65]
	v_mfma_f32_16x16x32_bf16 v[58:61], v[156:159], v[180:183], v[58:61]
	v_mfma_f32_16x16x32_bf16 v[54:57], v[148:151], v[188:191], v[54:57]
	v_mfma_f32_16x16x32_bf16 v[50:53], v[156:159], v[188:191], v[50:53]
	v_mfma_f32_16x16x32_bf16 v[38:41], v[148:151], v[196:199], v[38:41]
	v_mfma_f32_16x16x32_bf16 v[34:37], v[156:159], v[196:199], v[34:37]
	v_mfma_f32_16x16x32_bf16 v[22:25], v[148:151], v[206:209], v[22:25]
	v_mfma_f32_16x16x32_bf16 v[18:21], v[156:159], v[206:209], v[18:21]
	v_mfma_f32_16x16x32_bf16 v[62:65], v[152:155], v[184:187], v[62:65]
	v_mfma_f32_16x16x32_bf16 v[58:61], v[160:163], v[184:187], v[58:61]
	v_mfma_f32_16x16x32_bf16 v[54:57], v[152:155], v[192:195], v[54:57]
	v_mfma_f32_16x16x32_bf16 v[50:53], v[160:163], v[192:195], v[50:53]
	v_mfma_f32_16x16x32_bf16 v[38:41], v[152:155], v[200:203], v[38:41]
	v_mfma_f32_16x16x32_bf16 v[34:37], v[160:163], v[200:203], v[34:37]
	v_mfma_f32_16x16x32_bf16 v[22:25], v[152:155], v[210:213], v[22:25]
	v_mfma_f32_16x16x32_bf16 v[18:21], v[160:163], v[210:213], v[18:21]
	v_mfma_f32_16x16x32_bf16 v[46:49], v[164:167], v[180:183], v[46:49]
	v_mfma_f32_16x16x32_bf16 v[42:45], v[172:175], v[180:183], v[42:45]
	v_mfma_f32_16x16x32_bf16 v[30:33], v[164:167], v[188:191], v[30:33]
	v_mfma_f32_16x16x32_bf16 v[26:29], v[172:175], v[188:191], v[26:29]
	v_mfma_f32_16x16x32_bf16 v[14:17], v[164:167], v[196:199], v[14:17]
	v_mfma_f32_16x16x32_bf16 v[10:13], v[172:175], v[196:199], v[10:13]
	v_mfma_f32_16x16x32_bf16 v[6:9], v[164:167], v[206:209], v[6:9]
	v_mfma_f32_16x16x32_bf16 v[2:5], v[172:175], v[206:209], v[2:5]
	v_mfma_f32_16x16x32_bf16 v[46:49], v[168:171], v[184:187], v[46:49]
	v_mfma_f32_16x16x32_bf16 v[42:45], v[176:179], v[184:187], v[42:45]
	v_mfma_f32_16x16x32_bf16 v[30:33], v[168:171], v[192:195], v[30:33]
	v_mfma_f32_16x16x32_bf16 v[26:29], v[176:179], v[192:195], v[26:29]
	v_mfma_f32_16x16x32_bf16 v[14:17], v[168:171], v[200:203], v[14:17]
	v_mfma_f32_16x16x32_bf16 v[10:13], v[176:179], v[200:203], v[10:13]
	v_mfma_f32_16x16x32_bf16 v[6:9], v[168:171], v[210:213], v[6:9]
	v_mfma_f32_16x16x32_bf16 v[2:5], v[176:179], v[210:213], v[2:5]
	s_setprio 0
	s_barrier
	s_add_i32 s69, s69, 2
	s_add_u32 s36, s36, 0x100
	s_addc_u32 s37, s37, 0
	s_add_u32 s67, s67, 0x100
	s_addc_u32 s68, s68, 0
	s_cmp_gt_u32 s69, 5
.LBB0_477:
	ds_read_b128 v[148:151], v144
	ds_read_b128 v[152:155], v144 offset:1024
	ds_read_b128 v[156:159], v144 offset:2048
	ds_read_b128 v[160:163], v144 offset:3072
	ds_read_b128 v[164:167], v145
	ds_read_b128 v[168:171], v145 offset:1024
	ds_read_b128 v[172:175], v145 offset:2048
	ds_read_b128 v[176:179], v145 offset:3072
	s_add_u32 s38, s36, 0xfffe0080
	s_addc_u32 s39, s37, -1
	s_cmp_eq_u32 s69, 4
	s_cselect_b32 s43, s63, s39
	s_cselect_b32 s42, s64, s38
	s_cselect_b32 s39, s65, s68
	s_cselect_b32 s38, s66, s67
	v_lshl_add_u64 v[214:215], s[36:37], 0, v[138:139]
	s_add_i32 m0, s19, 0xc000
	ds_read_b128 v[180:183], v146
	ds_read_b128 v[184:187], v146 offset:1024
	ds_read_b128 v[188:191], v146 offset:2048
	ds_read_b128 v[192:195], v146 offset:3072
	ds_read_b128 v[196:199], v146 offset:4096
	ds_read_b128 v[200:203], v146 offset:5120
	ds_read_b128 v[206:209], v146 offset:6144
	ds_read_b128 v[210:213], v146 offset:7168
	global_load_lds_dwordx4 v[214:215], off
	s_add_i32 m0, s19, 0xe000
	v_lshl_add_u64 v[214:215], s[36:37], 0, v[140:141]
	global_load_lds_dwordx4 v[214:215], off
	s_waitcnt vmcnt(8) lgkmcnt(0)
	s_setprio 1
	s_barrier
	v_mfma_f32_16x16x32_bf16 v[126:129], v[148:151], v[180:183], v[126:129]
	v_mfma_f32_16x16x32_bf16 v[122:125], v[156:159], v[180:183], v[122:125]
	v_mfma_f32_16x16x32_bf16 v[118:121], v[148:151], v[188:191], v[118:121]
	v_mfma_f32_16x16x32_bf16 v[114:117], v[156:159], v[188:191], v[114:117]
	v_mfma_f32_16x16x32_bf16 v[102:105], v[148:151], v[196:199], v[102:105]
	v_mfma_f32_16x16x32_bf16 v[98:101], v[156:159], v[196:199], v[98:101]
	v_mfma_f32_16x16x32_bf16 v[86:89], v[148:151], v[206:209], v[86:89]
	v_mfma_f32_16x16x32_bf16 v[82:85], v[156:159], v[206:209], v[82:85]
	v_mfma_f32_16x16x32_bf16 v[126:129], v[152:155], v[184:187], v[126:129]
	v_mfma_f32_16x16x32_bf16 v[122:125], v[160:163], v[184:187], v[122:125]
	v_mfma_f32_16x16x32_bf16 v[118:121], v[152:155], v[192:195], v[118:121]
	v_mfma_f32_16x16x32_bf16 v[114:117], v[160:163], v[192:195], v[114:117]
	v_mfma_f32_16x16x32_bf16 v[102:105], v[152:155], v[200:203], v[102:105]
	v_mfma_f32_16x16x32_bf16 v[98:101], v[160:163], v[200:203], v[98:101]
	v_mfma_f32_16x16x32_bf16 v[86:89], v[152:155], v[210:213], v[86:89]
	v_mfma_f32_16x16x32_bf16 v[82:85], v[160:163], v[210:213], v[82:85]
	v_mfma_f32_16x16x32_bf16 v[110:113], v[164:167], v[180:183], v[110:113]
	v_mfma_f32_16x16x32_bf16 v[106:109], v[172:175], v[180:183], v[106:109]
	v_mfma_f32_16x16x32_bf16 v[94:97], v[164:167], v[188:191], v[94:97]
	v_mfma_f32_16x16x32_bf16 v[90:93], v[172:175], v[188:191], v[90:93]
	v_mfma_f32_16x16x32_bf16 v[78:81], v[164:167], v[196:199], v[78:81]
	v_mfma_f32_16x16x32_bf16 v[74:77], v[172:175], v[196:199], v[74:77]
	v_mfma_f32_16x16x32_bf16 v[70:73], v[164:167], v[206:209], v[70:73]
	v_mfma_f32_16x16x32_bf16 v[66:69], v[172:175], v[206:209], v[66:69]
	v_mfma_f32_16x16x32_bf16 v[110:113], v[168:171], v[184:187], v[110:113]
	v_mfma_f32_16x16x32_bf16 v[106:109], v[176:179], v[184:187], v[106:109]
	v_mfma_f32_16x16x32_bf16 v[94:97], v[168:171], v[192:195], v[94:97]
	v_mfma_f32_16x16x32_bf16 v[90:93], v[176:179], v[192:195], v[90:93]
	v_mfma_f32_16x16x32_bf16 v[78:81], v[168:171], v[200:203], v[78:81]
	v_mfma_f32_16x16x32_bf16 v[74:77], v[176:179], v[200:203], v[74:77]
	v_mfma_f32_16x16x32_bf16 v[70:73], v[168:171], v[210:213], v[70:73]
	v_mfma_f32_16x16x32_bf16 v[66:69], v[176:179], v[210:213], v[66:69]
	s_setprio 0
	s_barrier
	s_add_i32 s70, s35, s18
	s_mov_b32 m0, s70
	v_lshl_add_u64 v[214:215], s[38:39], 0, v[134:135]
	global_load_lds_dwordx4 v[214:215], off
	ds_read_b128 v[180:183], v146 offset:16384
	ds_read_b128 v[184:187], v146 offset:17408
	s_add_i32 m0, s70, 0x2000
	s_add_u32 s70, s38, 0x200000
	v_lshl_add_u64 v[216:217], s[38:39], 0, v[130:131]
	s_addc_u32 s71, s39, 0
	s_add_i32 s72, s44, s18
	global_load_lds_dwordx4 v[216:217], off
	ds_read_b128 v[188:191], v146 offset:18432
	ds_read_b128 v[192:195], v146 offset:19456
	v_lshl_add_u64 v[218:219], s[70:71], 0, v[134:135]
	s_mov_b32 m0, s72
	v_lshl_add_u64 v[220:221], s[42:43], 0, v[132:133]
	global_load_lds_dwordx4 v[218:219], off
	ds_read_b128 v[196:199], v146 offset:20480
	ds_read_b128 v[200:203], v146 offset:21504
	s_add_i32 m0, s72, 0x2000
	v_lshl_add_u64 v[218:219], s[70:71], 0, v[130:131]
	global_load_lds_dwordx4 v[218:219], off
	ds_read_b128 v[206:209], v146 offset:22528
	ds_read_b128 v[210:213], v146 offset:23552
	s_mov_b32 m0, s19
	v_lshl_add_u64 v[218:219], s[42:43], 0, v[136:137]
	global_load_lds_dwordx4 v[218:219], off
	s_mov_b32 m0, s24
	s_nop 0
	global_load_lds_dwordx4 v[220:221], off
	s_waitcnt vmcnt(8) lgkmcnt(0)
	s_setprio 1
	s_barrier
	v_mfma_f32_16x16x32_bf16 v[62:65], v[148:151], v[180:183], v[62:65]
	v_mfma_f32_16x16x32_bf16 v[58:61], v[156:159], v[180:183], v[58:61]
	v_mfma_f32_16x16x32_bf16 v[54:57], v[148:151], v[188:191], v[54:57]
	v_mfma_f32_16x16x32_bf16 v[50:53], v[156:159], v[188:191], v[50:53]
	v_mfma_f32_16x16x32_bf16 v[38:41], v[148:151], v[196:199], v[38:41]
	v_mfma_f32_16x16x32_bf16 v[34:37], v[156:159], v[196:199], v[34:37]
	v_mfma_f32_16x16x32_bf16 v[22:25], v[148:151], v[206:209], v[22:25]
	v_mfma_f32_16x16x32_bf16 v[18:21], v[156:159], v[206:209], v[18:21]
	v_mfma_f32_16x16x32_bf16 v[62:65], v[152:155], v[184:187], v[62:65]
	v_mfma_f32_16x16x32_bf16 v[58:61], v[160:163], v[184:187], v[58:61]
	v_mfma_f32_16x16x32_bf16 v[54:57], v[152:155], v[192:195], v[54:57]
	v_mfma_f32_16x16x32_bf16 v[50:53], v[160:163], v[192:195], v[50:53]
	v_mfma_f32_16x16x32_bf16 v[38:41], v[152:155], v[200:203], v[38:41]
	v_mfma_f32_16x16x32_bf16 v[34:37], v[160:163], v[200:203], v[34:37]
	v_mfma_f32_16x16x32_bf16 v[22:25], v[152:155], v[210:213], v[22:25]
	v_mfma_f32_16x16x32_bf16 v[18:21], v[160:163], v[210:213], v[18:21]
	v_mfma_f32_16x16x32_bf16 v[46:49], v[164:167], v[180:183], v[46:49]
	v_mfma_f32_16x16x32_bf16 v[42:45], v[172:175], v[180:183], v[42:45]
	v_mfma_f32_16x16x32_bf16 v[30:33], v[164:167], v[188:191], v[30:33]
	v_mfma_f32_16x16x32_bf16 v[26:29], v[172:175], v[188:191], v[26:29]
	v_mfma_f32_16x16x32_bf16 v[14:17], v[164:167], v[196:199], v[14:17]
	v_mfma_f32_16x16x32_bf16 v[10:13], v[172:175], v[196:199], v[10:13]
	v_mfma_f32_16x16x32_bf16 v[6:9], v[164:167], v[206:209], v[6:9]
	v_mfma_f32_16x16x32_bf16 v[2:5], v[172:175], v[206:209], v[2:5]
	v_mfma_f32_16x16x32_bf16 v[46:49], v[168:171], v[184:187], v[46:49]
	v_mfma_f32_16x16x32_bf16 v[42:45], v[176:179], v[184:187], v[42:45]
	v_mfma_f32_16x16x32_bf16 v[30:33], v[168:171], v[192:195], v[30:33]
	v_mfma_f32_16x16x32_bf16 v[26:29], v[176:179], v[192:195], v[26:29]
	v_mfma_f32_16x16x32_bf16 v[14:17], v[168:171], v[200:203], v[14:17]
	v_mfma_f32_16x16x32_bf16 v[10:13], v[176:179], v[200:203], v[10:13]
	v_mfma_f32_16x16x32_bf16 v[6:9], v[168:171], v[210:213], v[6:9]
	v_mfma_f32_16x16x32_bf16 v[2:5], v[176:179], v[210:213], v[2:5]
	s_setprio 0
	s_barrier
	s_add_i32 s70, 0, 0x18000
	v_add_u32_e32 v147, s70, v143
	s_add_i32 s71, 0, 0x1c000
	ds_read_b128 v[148:151], v147
	ds_read_b128 v[152:155], v147 offset:1024
	ds_read_b128 v[156:159], v147 offset:2048
	ds_read_b128 v[160:163], v147 offset:3072
	v_add_u32_e32 v147, s71, v143
	ds_read_b128 v[164:167], v147
	ds_read_b128 v[168:171], v147 offset:1024
	ds_read_b128 v[172:175], v147 offset:2048
	ds_read_b128 v[176:179], v147 offset:3072
	s_add_u32 s42, s42, 0x20000
	s_addc_u32 s43, s43, 0
	s_mov_b32 m0, s25
	v_lshl_add_u64 v[222:223], s[42:43], 0, v[136:137]
	ds_read_b128 v[180:183], v146 offset:32768
	ds_read_b128 v[184:187], v146 offset:33792
	ds_read_b128 v[188:191], v146 offset:34816
	ds_read_b128 v[192:195], v146 offset:35840
	ds_read_b128 v[196:199], v146 offset:36864
	ds_read_b128 v[200:203], v146 offset:37888
	ds_read_b128 v[206:209], v146 offset:38912
	ds_read_b128 v[210:213], v146 offset:39936
	global_load_lds_dwordx4 v[222:223], off
	s_mov_b32 m0, s28
	v_lshl_add_u64 v[222:223], s[42:43], 0, v[132:133]
	global_load_lds_dwordx4 v[222:223], off
	s_waitcnt vmcnt(8) lgkmcnt(0)
	s_setprio 1
	s_barrier
	v_mfma_f32_16x16x32_bf16 v[126:129], v[148:151], v[180:183], v[126:129]
	v_mfma_f32_16x16x32_bf16 v[122:125], v[156:159], v[180:183], v[122:125]
	v_mfma_f32_16x16x32_bf16 v[118:121], v[148:151], v[188:191], v[118:121]
	v_mfma_f32_16x16x32_bf16 v[114:117], v[156:159], v[188:191], v[114:117]
	v_mfma_f32_16x16x32_bf16 v[102:105], v[148:151], v[196:199], v[102:105]
	v_mfma_f32_16x16x32_bf16 v[98:101], v[156:159], v[196:199], v[98:101]
	v_mfma_f32_16x16x32_bf16 v[86:89], v[148:151], v[206:209], v[86:89]
	v_mfma_f32_16x16x32_bf16 v[82:85], v[156:159], v[206:209], v[82:85]
	v_mfma_f32_16x16x32_bf16 v[126:129], v[152:155], v[184:187], v[126:129]
	v_mfma_f32_16x16x32_bf16 v[122:125], v[160:163], v[184:187], v[122:125]
	v_mfma_f32_16x16x32_bf16 v[118:121], v[152:155], v[192:195], v[118:121]
	v_mfma_f32_16x16x32_bf16 v[114:117], v[160:163], v[192:195], v[114:117]
	v_mfma_f32_16x16x32_bf16 v[102:105], v[152:155], v[200:203], v[102:105]
	v_mfma_f32_16x16x32_bf16 v[98:101], v[160:163], v[200:203], v[98:101]
	v_mfma_f32_16x16x32_bf16 v[86:89], v[152:155], v[210:213], v[86:89]
	v_mfma_f32_16x16x32_bf16 v[82:85], v[160:163], v[210:213], v[82:85]
	v_mfma_f32_16x16x32_bf16 v[110:113], v[164:167], v[180:183], v[110:113]
	v_mfma_f32_16x16x32_bf16 v[106:109], v[172:175], v[180:183], v[106:109]
	v_mfma_f32_16x16x32_bf16 v[94:97], v[164:167], v[188:191], v[94:97]
	v_mfma_f32_16x16x32_bf16 v[90:93], v[172:175], v[188:191], v[90:93]
	v_mfma_f32_16x16x32_bf16 v[78:81], v[164:167], v[196:199], v[78:81]
	v_mfma_f32_16x16x32_bf16 v[74:77], v[172:175], v[196:199], v[74:77]
	v_mfma_f32_16x16x32_bf16 v[70:73], v[164:167], v[206:209], v[70:73]
	v_mfma_f32_16x16x32_bf16 v[66:69], v[172:175], v[206:209], v[66:69]
	v_mfma_f32_16x16x32_bf16 v[110:113], v[168:171], v[184:187], v[110:113]
	v_mfma_f32_16x16x32_bf16 v[106:109], v[176:179], v[184:187], v[106:109]
	v_mfma_f32_16x16x32_bf16 v[94:97], v[168:171], v[192:195], v[94:97]
	v_mfma_f32_16x16x32_bf16 v[90:93], v[176:179], v[192:195], v[90:93]
	v_mfma_f32_16x16x32_bf16 v[78:81], v[168:171], v[200:203], v[78:81]
	v_mfma_f32_16x16x32_bf16 v[74:77], v[176:179], v[200:203], v[74:77]
	v_mfma_f32_16x16x32_bf16 v[70:73], v[168:171], v[210:213], v[70:73]
	v_mfma_f32_16x16x32_bf16 v[66:69], v[176:179], v[210:213], v[66:69]
	s_setprio 0
	s_barrier
	s_add_i32 s42, s70, s18
	s_mov_b32 m0, s42
	v_lshl_add_u64 v[214:215], v[214:215], 0, s[8:9]
	global_load_lds_dwordx4 v[214:215], off
	ds_read_b128 v[180:183], v146 offset:49152
	ds_read_b128 v[184:187], v146 offset:50176
	s_add_i32 m0, s42, 0x2000
	s_add_u32 s38, s38, 0x200080
	v_lshl_add_u64 v[214:215], v[216:217], 0, s[8:9]
	s_addc_u32 s39, s39, 0
	s_add_i32 s42, s71, s18
	global_load_lds_dwordx4 v[214:215], off
	ds_read_b128 v[188:191], v146 offset:51200
	ds_read_b128 v[192:195], v146 offset:52224
	s_mov_b32 m0, s42
	v_lshl_add_u64 v[214:215], s[38:39], 0, v[134:135]
	global_load_lds_dwordx4 v[214:215], off
	ds_read_b128 v[196:199], v146 offset:53248
	ds_read_b128 v[200:203], v146 offset:54272
	s_add_i32 m0, s42, 0x2000
	v_lshl_add_u64 v[214:215], s[38:39], 0, v[130:131]
	global_load_lds_dwordx4 v[214:215], off
	ds_read_b128 v[206:209], v146 offset:55296
	ds_read_b128 v[210:213], v146 offset:56320
	s_mov_b32 m0, s33
	v_lshl_add_u64 v[214:215], v[218:219], 0, s[8:9]
	global_load_lds_dwordx4 v[214:215], off
	s_mov_b32 m0, s34
	v_lshl_add_u64 v[214:215], v[220:221], 0, s[8:9]
	global_load_lds_dwordx4 v[214:215], off
	s_waitcnt vmcnt(8) lgkmcnt(0)
	s_setprio 1
	s_barrier
	v_mfma_f32_16x16x32_bf16 v[62:65], v[148:151], v[180:183], v[62:65]
	v_mfma_f32_16x16x32_bf16 v[58:61], v[156:159], v[180:183], v[58:61]
	v_mfma_f32_16x16x32_bf16 v[54:57], v[148:151], v[188:191], v[54:57]
	v_mfma_f32_16x16x32_bf16 v[50:53], v[156:159], v[188:191], v[50:53]
	v_mfma_f32_16x16x32_bf16 v[38:41], v[148:151], v[196:199], v[38:41]
	v_mfma_f32_16x16x32_bf16 v[34:37], v[156:159], v[196:199], v[34:37]
	v_mfma_f32_16x16x32_bf16 v[22:25], v[148:151], v[206:209], v[22:25]
	v_mfma_f32_16x16x32_bf16 v[18:21], v[156:159], v[206:209], v[18:21]
	v_mfma_f32_16x16x32_bf16 v[62:65], v[152:155], v[184:187], v[62:65]
	v_mfma_f32_16x16x32_bf16 v[58:61], v[160:163], v[184:187], v[58:61]
	v_mfma_f32_16x16x32_bf16 v[54:57], v[152:155], v[192:195], v[54:57]
	v_mfma_f32_16x16x32_bf16 v[50:53], v[160:163], v[192:195], v[50:53]
	v_mfma_f32_16x16x32_bf16 v[38:41], v[152:155], v[200:203], v[38:41]
	v_mfma_f32_16x16x32_bf16 v[34:37], v[160:163], v[200:203], v[34:37]
	v_mfma_f32_16x16x32_bf16 v[22:25], v[152:155], v[210:213], v[22:25]
	v_mfma_f32_16x16x32_bf16 v[18:21], v[160:163], v[210:213], v[18:21]
	v_mfma_f32_16x16x32_bf16 v[46:49], v[164:167], v[180:183], v[46:49]
	v_mfma_f32_16x16x32_bf16 v[42:45], v[172:175], v[180:183], v[42:45]
	v_mfma_f32_16x16x32_bf16 v[30:33], v[164:167], v[188:191], v[30:33]
	v_mfma_f32_16x16x32_bf16 v[26:29], v[172:175], v[188:191], v[26:29]
	v_mfma_f32_16x16x32_bf16 v[14:17], v[164:167], v[196:199], v[14:17]
	v_mfma_f32_16x16x32_bf16 v[10:13], v[172:175], v[196:199], v[10:13]
	v_mfma_f32_16x16x32_bf16 v[6:9], v[164:167], v[206:209], v[6:9]
	v_mfma_f32_16x16x32_bf16 v[2:5], v[172:175], v[206:209], v[2:5]
	v_mfma_f32_16x16x32_bf16 v[46:49], v[168:171], v[184:187], v[46:49]
	v_mfma_f32_16x16x32_bf16 v[42:45], v[176:179], v[184:187], v[42:45]
	v_mfma_f32_16x16x32_bf16 v[30:33], v[168:171], v[192:195], v[30:33]
	v_mfma_f32_16x16x32_bf16 v[26:29], v[176:179], v[192:195], v[26:29]
	v_mfma_f32_16x16x32_bf16 v[14:17], v[168:171], v[200:203], v[14:17]
	v_mfma_f32_16x16x32_bf16 v[10:13], v[176:179], v[200:203], v[10:13]
	v_mfma_f32_16x16x32_bf16 v[6:9], v[168:171], v[210:213], v[6:9]
	v_mfma_f32_16x16x32_bf16 v[2:5], v[176:179], v[210:213], v[2:5]
	s_setprio 0
	s_barrier
	s_add_i32 s69, s69, 2
	s_add_u32 s36, s36, 0x100
	s_addc_u32 s37, s37, 0
	s_add_u32 s67, s67, 0x100
	s_addc_u32 s68, s68, 0
	s_cmp_gt_u32 s69, 5
	s_cbranch_scc0 .LBB0_477
	s_and_b64 vcc, exec, s[10:11]
	s_cbranch_vccz .LBB0_480
	s_barrier

.LBB0_565:
	v_readlane_b32 s62, v249, 27
	v_readlane_b32 s63, v249, 28
	s_add_u32 s72, s62, s68
	s_addc_u32 s73, s63, s69
	s_and_b64 s[62:63], s[70:71], exec
	s_cselect_b32 s31, s73, s77
	s_cselect_b32 s33, s72, s76
	s_add_u32 s74, s35, s66
	s_addc_u32 s75, s85, s67
	s_and_b64 s[62:63], s[70:71], exec
	s_cselect_b32 s34, s75, s79
	s_cselect_b32 s39, s74, s78
	s_add_i32 s45, s7, -2
	s_add_u32 s76, s76, 0x40080
	s_addc_u32 s77, s77, 0
	s_add_u32 s47, s78, 0x100
	s_addc_u32 s62, s79, 0
	s_mov_b32 s63, 0
	s_waitcnt vmcnt(0)
	ds_read_b128 v[114:117], v190
	ds_read_b128 v[118:121], v190 offset:1024
	ds_read_b128 v[122:125], v190 offset:2048
	ds_read_b128 v[126:129], v190 offset:3072
	ds_read_b128 v[146:149], v191
	ds_read_b128 v[150:153], v191 offset:1024
	ds_read_b128 v[154:157], v191 offset:2048
	ds_read_b128 v[158:161], v191 offset:3072
	s_add_i32 s82, s63, 2
	s_add_u32 s78, s76, 0xfffc0080
	s_addc_u32 s79, s77, -1
	s_cmp_eq_u32 s45, s63
	s_cselect_b32 s81, s31, s79
	s_cselect_b32 s80, s33, s78
	s_cselect_b32 s79, s34, s62
	s_cselect_b32 s78, s39, s47
	v_lshl_add_u64 v[186:187], s[76:77], 0, v[180:181]
	s_add_i32 m0, s87, 0xc000
	ds_read_b128 v[162:165], v192
	ds_read_b128 v[166:169], v192 offset:1024
	ds_read_b128 v[194:197], v192 offset:2048
	ds_read_b128 v[198:201], v192 offset:3072
	ds_read_b128 v[206:209], v192 offset:4096
	ds_read_b128 v[210:213], v192 offset:5120
	ds_read_b128 v[214:217], v192 offset:6144
	ds_read_b128 v[218:221], v192 offset:7168
	global_load_lds_dwordx4 v[186:187], off
	s_add_i32 m0, s87, 0xe000
	v_lshl_add_u64 v[186:187], s[76:77], 0, v[182:183]
	global_load_lds_dwordx4 v[186:187], off
	s_waitcnt vmcnt(8)
	s_waitcnt lgkmcnt(0)
	s_setprio 1
	s_barrier
	v_mfma_f32_16x16x32_bf16 v[142:145], v[114:117], v[162:165], 0
	v_mfma_f32_16x16x32_bf16 v[138:141], v[122:125], v[162:165], 0
	v_mfma_f32_16x16x32_bf16 v[110:113], v[114:117], v[194:197], 0
	v_mfma_f32_16x16x32_bf16 v[106:109], v[122:125], v[194:197], 0
	v_mfma_f32_16x16x32_bf16 v[98:101], v[114:117], v[206:209], 0
	v_mfma_f32_16x16x32_bf16 v[90:93], v[122:125], v[206:209], 0
	v_mfma_f32_16x16x32_bf16 v[82:85], v[114:117], v[214:217], 0
	v_mfma_f32_16x16x32_bf16 v[74:77], v[122:125], v[214:217], 0
	v_mfma_f32_16x16x32_bf16 v[142:145], v[118:121], v[166:169], v[142:145]
	v_mfma_f32_16x16x32_bf16 v[138:141], v[126:129], v[166:169], v[138:141]
	v_mfma_f32_16x16x32_bf16 v[110:113], v[118:121], v[198:201], v[110:113]
	v_mfma_f32_16x16x32_bf16 v[106:109], v[126:129], v[198:201], v[106:109]
	v_mfma_f32_16x16x32_bf16 v[98:101], v[118:121], v[210:213], v[98:101]
	v_mfma_f32_16x16x32_bf16 v[90:93], v[126:129], v[210:213], v[90:93]
	v_mfma_f32_16x16x32_bf16 v[82:85], v[118:121], v[218:221], v[82:85]
	v_mfma_f32_16x16x32_bf16 v[74:77], v[126:129], v[218:221], v[74:77]
	v_mfma_f32_16x16x32_bf16 v[134:137], v[146:149], v[162:165], 0
	v_mfma_f32_16x16x32_bf16 v[130:133], v[154:157], v[162:165], 0
	v_mfma_f32_16x16x32_bf16 v[102:105], v[146:149], v[194:197], 0
	v_mfma_f32_16x16x32_bf16 v[94:97], v[154:157], v[194:197], 0
	v_mfma_f32_16x16x32_bf16 v[86:89], v[146:149], v[206:209], 0
	v_mfma_f32_16x16x32_bf16 v[78:81], v[154:157], v[206:209], 0
	v_mfma_f32_16x16x32_bf16 v[70:73], v[146:149], v[214:217], 0
	v_mfma_f32_16x16x32_bf16 v[66:69], v[154:157], v[214:217], 0
	v_mfma_f32_16x16x32_bf16 v[134:137], v[150:153], v[166:169], v[134:137]
	v_mfma_f32_16x16x32_bf16 v[130:133], v[158:161], v[166:169], v[130:133]
	v_mfma_f32_16x16x32_bf16 v[102:105], v[150:153], v[198:201], v[102:105]
	v_mfma_f32_16x16x32_bf16 v[94:97], v[158:161], v[198:201], v[94:97]
	v_mfma_f32_16x16x32_bf16 v[86:89], v[150:153], v[210:213], v[86:89]
	v_mfma_f32_16x16x32_bf16 v[78:81], v[158:161], v[210:213], v[78:81]
	v_mfma_f32_16x16x32_bf16 v[70:73], v[150:153], v[218:221], v[70:73]
	v_mfma_f32_16x16x32_bf16 v[66:69], v[158:161], v[218:221], v[66:69]
	s_setprio 0
	s_barrier
	s_add_i32 s63, s24, s86
	s_mov_b32 m0, s63
	v_lshl_add_u64 v[186:187], s[78:79], 0, v[172:173]
	global_load_lds_dwordx4 v[186:187], off
	ds_read_b128 v[162:165], v192 offset:16384
	ds_read_b128 v[166:169], v192 offset:17408
	s_add_i32 m0, s63, 0x2000
	s_add_u32 vcc_lo, s78, 0x40000
	v_lshl_add_u64 v[202:203], s[78:79], 0, v[176:177]
	s_addc_u32 vcc_hi, s79, 0
	s_add_i32 s63, s25, s86
	global_load_lds_dwordx4 v[202:203], off
	ds_read_b128 v[194:197], v192 offset:18432
	ds_read_b128 v[198:201], v192 offset:19456
	v_lshl_add_u64 v[222:223], vcc, 0, v[172:173]
	s_mov_b32 m0, s63
	v_lshl_add_u64 v[224:225], s[80:81], 0, v[174:175]
	global_load_lds_dwordx4 v[222:223], off
	ds_read_b128 v[206:209], v192 offset:20480
	ds_read_b128 v[210:213], v192 offset:21504
	s_add_i32 m0, s63, 0x2000
	v_lshl_add_u64 v[222:223], vcc, 0, v[176:177]
	global_load_lds_dwordx4 v[222:223], off
	ds_read_b128 v[214:217], v192 offset:22528
	ds_read_b128 v[218:221], v192 offset:23552
	s_mov_b32 m0, s87
	v_lshl_add_u64 v[222:223], s[80:81], 0, v[170:171]
	global_load_lds_dwordx4 v[222:223], off
	s_mov_b32 m0, s88
	s_nop 0
	global_load_lds_dwordx4 v[224:225], off
	s_waitcnt vmcnt(8) lgkmcnt(0)
	s_setprio 1
	s_barrier
	v_mfma_f32_16x16x32_bf16 v[62:65], v[114:117], v[162:165], 0
	v_mfma_f32_16x16x32_bf16 v[58:61], v[122:125], v[162:165], 0
	v_mfma_f32_16x16x32_bf16 v[50:53], v[114:117], v[194:197], 0
	v_mfma_f32_16x16x32_bf16 v[42:45], v[122:125], v[194:197], 0
	v_mfma_f32_16x16x32_bf16 v[34:37], v[114:117], v[206:209], 0
	v_mfma_f32_16x16x32_bf16 v[26:29], v[122:125], v[206:209], 0
	v_mfma_f32_16x16x32_bf16 v[18:21], v[114:117], v[214:217], 0
	v_mfma_f32_16x16x32_bf16 v[10:13], v[122:125], v[214:217], 0
	v_mfma_f32_16x16x32_bf16 v[62:65], v[118:121], v[166:169], v[62:65]
	v_mfma_f32_16x16x32_bf16 v[58:61], v[126:129], v[166:169], v[58:61]
	v_mfma_f32_16x16x32_bf16 v[50:53], v[118:121], v[198:201], v[50:53]
	v_mfma_f32_16x16x32_bf16 v[42:45], v[126:129], v[198:201], v[42:45]
	v_mfma_f32_16x16x32_bf16 v[34:37], v[118:121], v[210:213], v[34:37]
	v_mfma_f32_16x16x32_bf16 v[26:29], v[126:129], v[210:213], v[26:29]
	v_mfma_f32_16x16x32_bf16 v[18:21], v[118:121], v[218:221], v[18:21]
	v_mfma_f32_16x16x32_bf16 v[10:13], v[126:129], v[218:221], v[10:13]
	v_mfma_f32_16x16x32_bf16 v[54:57], v[146:149], v[162:165], 0
	v_mfma_f32_16x16x32_bf16 v[46:49], v[154:157], v[162:165], 0
	v_mfma_f32_16x16x32_bf16 v[38:41], v[146:149], v[194:197], 0
	v_mfma_f32_16x16x32_bf16 v[30:33], v[154:157], v[194:197], 0
	v_mfma_f32_16x16x32_bf16 v[22:25], v[146:149], v[206:209], 0
	v_mfma_f32_16x16x32_bf16 v[14:17], v[154:157], v[206:209], 0
	v_mfma_f32_16x16x32_bf16 v[6:9], v[146:149], v[214:217], 0
	v_mfma_f32_16x16x32_bf16 v[2:5], v[154:157], v[214:217], 0
	v_mfma_f32_16x16x32_bf16 v[54:57], v[150:153], v[166:169], v[54:57]
	v_mfma_f32_16x16x32_bf16 v[46:49], v[158:161], v[166:169], v[46:49]
	v_mfma_f32_16x16x32_bf16 v[38:41], v[150:153], v[198:201], v[38:41]
	v_mfma_f32_16x16x32_bf16 v[30:33], v[158:161], v[198:201], v[30:33]
	v_mfma_f32_16x16x32_bf16 v[22:25], v[150:153], v[210:213], v[22:25]
	v_mfma_f32_16x16x32_bf16 v[14:17], v[158:161], v[210:213], v[14:17]
	v_mfma_f32_16x16x32_bf16 v[6:9], v[150:153], v[218:221], v[6:9]
	v_mfma_f32_16x16x32_bf16 v[2:5], v[158:161], v[218:221], v[2:5]
	s_setprio 0
	s_barrier
	s_add_i32 s63, 0, 0x18000
	s_add_i32 s83, 0, 0x1c000
	v_add_u32_e32 v126, s63, v189
	v_add_u32_e32 v158, s83, v189
	ds_read_b128 v[114:117], v126
	ds_read_b128 v[118:121], v126 offset:1024
	ds_read_b128 v[122:125], v126 offset:2048
	ds_read_b128 v[126:129], v126 offset:3072
	ds_read_b128 v[146:149], v158
	ds_read_b128 v[150:153], v158 offset:1024
	ds_read_b128 v[154:157], v158 offset:2048
	ds_read_b128 v[158:161], v158 offset:3072
	s_add_u32 s80, s80, 0x40000
	s_addc_u32 s81, s81, 0
	s_mov_b32 m0, s89
	v_lshl_add_u64 v[226:227], s[80:81], 0, v[170:171]
	ds_read_b128 v[162:165], v192 offset:32768
	ds_read_b128 v[166:169], v192 offset:33792
	ds_read_b128 v[194:197], v192 offset:34816
	ds_read_b128 v[198:201], v192 offset:35840
	ds_read_b128 v[206:209], v192 offset:36864
	ds_read_b128 v[210:213], v192 offset:37888
	ds_read_b128 v[214:217], v192 offset:38912
	ds_read_b128 v[218:221], v192 offset:39936
	global_load_lds_dwordx4 v[226:227], off
	s_mov_b32 m0, s90
	v_lshl_add_u64 v[226:227], s[80:81], 0, v[174:175]
	global_load_lds_dwordx4 v[226:227], off
	s_waitcnt vmcnt(8) lgkmcnt(0)
	s_setprio 1
	s_barrier
	v_mfma_f32_16x16x32_bf16 v[142:145], v[114:117], v[162:165], v[142:145]
	v_mfma_f32_16x16x32_bf16 v[138:141], v[122:125], v[162:165], v[138:141]
	v_mfma_f32_16x16x32_bf16 v[110:113], v[114:117], v[194:197], v[110:113]
	v_mfma_f32_16x16x32_bf16 v[106:109], v[122:125], v[194:197], v[106:109]
	v_mfma_f32_16x16x32_bf16 v[98:101], v[114:117], v[206:209], v[98:101]
	v_mfma_f32_16x16x32_bf16 v[90:93], v[122:125], v[206:209], v[90:93]
	v_mfma_f32_16x16x32_bf16 v[82:85], v[114:117], v[214:217], v[82:85]
	v_mfma_f32_16x16x32_bf16 v[74:77], v[122:125], v[214:217], v[74:77]
	v_mfma_f32_16x16x32_bf16 v[142:145], v[118:121], v[166:169], v[142:145]
	v_mfma_f32_16x16x32_bf16 v[138:141], v[126:129], v[166:169], v[138:141]
	v_mfma_f32_16x16x32_bf16 v[110:113], v[118:121], v[198:201], v[110:113]
	v_mfma_f32_16x16x32_bf16 v[106:109], v[126:129], v[198:201], v[106:109]
	v_mfma_f32_16x16x32_bf16 v[98:101], v[118:121], v[210:213], v[98:101]
	v_mfma_f32_16x16x32_bf16 v[90:93], v[126:129], v[210:213], v[90:93]
	v_mfma_f32_16x16x32_bf16 v[82:85], v[118:121], v[218:221], v[82:85]
	v_mfma_f32_16x16x32_bf16 v[74:77], v[126:129], v[218:221], v[74:77]
	v_mfma_f32_16x16x32_bf16 v[134:137], v[146:149], v[162:165], v[134:137]
	v_mfma_f32_16x16x32_bf16 v[130:133], v[154:157], v[162:165], v[130:133]
	v_mfma_f32_16x16x32_bf16 v[102:105], v[146:149], v[194:197], v[102:105]
	v_mfma_f32_16x16x32_bf16 v[94:97], v[154:157], v[194:197], v[94:97]
	v_mfma_f32_16x16x32_bf16 v[86:89], v[146:149], v[206:209], v[86:89]
	v_mfma_f32_16x16x32_bf16 v[78:81], v[154:157], v[206:209], v[78:81]
	v_mfma_f32_16x16x32_bf16 v[70:73], v[146:149], v[214:217], v[70:73]
	v_mfma_f32_16x16x32_bf16 v[66:69], v[154:157], v[214:217], v[66:69]
	v_mfma_f32_16x16x32_bf16 v[134:137], v[150:153], v[166:169], v[134:137]
	v_mfma_f32_16x16x32_bf16 v[130:133], v[158:161], v[166:169], v[130:133]
	v_mfma_f32_16x16x32_bf16 v[102:105], v[150:153], v[198:201], v[102:105]
	v_mfma_f32_16x16x32_bf16 v[94:97], v[158:161], v[198:201], v[94:97]
	v_mfma_f32_16x16x32_bf16 v[86:89], v[150:153], v[210:213], v[86:89]
	v_mfma_f32_16x16x32_bf16 v[78:81], v[158:161], v[210:213], v[78:81]
	v_mfma_f32_16x16x32_bf16 v[70:73], v[150:153], v[218:221], v[70:73]
	v_mfma_f32_16x16x32_bf16 v[66:69], v[158:161], v[218:221], v[66:69]
	s_setprio 0
	s_barrier
	s_add_i32 s63, s63, s86
	s_mov_b32 m0, s63
	v_lshl_add_u64 v[186:187], v[186:187], 0, s[22:23]
	global_load_lds_dwordx4 v[186:187], off
	ds_read_b128 v[162:165], v192 offset:49152
	ds_read_b128 v[166:169], v192 offset:50176
	s_add_i32 m0, s63, 0x2000
	s_add_u32 s78, s78, 0x40080
	v_lshl_add_u64 v[186:187], v[202:203], 0, s[22:23]
	s_addc_u32 s79, s79, 0
	s_add_i32 s63, s83, s86
	global_load_lds_dwordx4 v[186:187], off
	ds_read_b128 v[194:197], v192 offset:51200
	ds_read_b128 v[198:201], v192 offset:52224
	s_mov_b32 m0, s63
	v_lshl_add_u64 v[186:187], s[78:79], 0, v[172:173]
	global_load_lds_dwordx4 v[186:187], off
	ds_read_b128 v[206:209], v192 offset:53248
	ds_read_b128 v[210:213], v192 offset:54272
	s_add_i32 m0, s63, 0x2000
	v_lshl_add_u64 v[186:187], s[78:79], 0, v[176:177]
	global_load_lds_dwordx4 v[186:187], off
	ds_read_b128 v[214:217], v192 offset:55296
	ds_read_b128 v[218:221], v192 offset:56320
	s_mov_b32 m0, s95
	v_lshl_add_u64 v[186:187], v[222:223], 0, s[22:23]
	global_load_lds_dwordx4 v[186:187], off
	s_mov_b32 m0, s96
	v_lshl_add_u64 v[186:187], v[224:225], 0, s[22:23]
	global_load_lds_dwordx4 v[186:187], off
	s_waitcnt vmcnt(8) lgkmcnt(0)
	s_setprio 1
	s_barrier
	v_mfma_f32_16x16x32_bf16 v[62:65], v[114:117], v[162:165], v[62:65]
	v_mfma_f32_16x16x32_bf16 v[58:61], v[122:125], v[162:165], v[58:61]
	v_mfma_f32_16x16x32_bf16 v[50:53], v[114:117], v[194:197], v[50:53]
	v_mfma_f32_16x16x32_bf16 v[42:45], v[122:125], v[194:197], v[42:45]
	v_mfma_f32_16x16x32_bf16 v[34:37], v[114:117], v[206:209], v[34:37]
	v_mfma_f32_16x16x32_bf16 v[26:29], v[122:125], v[206:209], v[26:29]
	v_mfma_f32_16x16x32_bf16 v[18:21], v[114:117], v[214:217], v[18:21]
	v_mfma_f32_16x16x32_bf16 v[10:13], v[122:125], v[214:217], v[10:13]
	v_mfma_f32_16x16x32_bf16 v[62:65], v[118:121], v[166:169], v[62:65]
	v_mfma_f32_16x16x32_bf16 v[58:61], v[126:129], v[166:169], v[58:61]
	v_mfma_f32_16x16x32_bf16 v[50:53], v[118:121], v[198:201], v[50:53]
	v_mfma_f32_16x16x32_bf16 v[42:45], v[126:129], v[198:201], v[42:45]
	v_mfma_f32_16x16x32_bf16 v[34:37], v[118:121], v[210:213], v[34:37]
	v_mfma_f32_16x16x32_bf16 v[26:29], v[126:129], v[210:213], v[26:29]
	v_mfma_f32_16x16x32_bf16 v[18:21], v[118:121], v[218:221], v[18:21]
	v_mfma_f32_16x16x32_bf16 v[10:13], v[126:129], v[218:221], v[10:13]
	v_mfma_f32_16x16x32_bf16 v[54:57], v[146:149], v[162:165], v[54:57]
	v_mfma_f32_16x16x32_bf16 v[46:49], v[154:157], v[162:165], v[46:49]
	v_mfma_f32_16x16x32_bf16 v[38:41], v[146:149], v[194:197], v[38:41]
	v_mfma_f32_16x16x32_bf16 v[30:33], v[154:157], v[194:197], v[30:33]
	v_mfma_f32_16x16x32_bf16 v[22:25], v[146:149], v[206:209], v[22:25]
	v_mfma_f32_16x16x32_bf16 v[14:17], v[154:157], v[206:209], v[14:17]
	v_mfma_f32_16x16x32_bf16 v[6:9], v[146:149], v[214:217], v[6:9]
	v_mfma_f32_16x16x32_bf16 v[2:5], v[154:157], v[214:217], v[2:5]
	v_mfma_f32_16x16x32_bf16 v[54:57], v[150:153], v[166:169], v[54:57]
	v_mfma_f32_16x16x32_bf16 v[46:49], v[158:161], v[166:169], v[46:49]
	v_mfma_f32_16x16x32_bf16 v[38:41], v[150:153], v[198:201], v[38:41]
	v_mfma_f32_16x16x32_bf16 v[30:33], v[158:161], v[198:201], v[30:33]
	v_mfma_f32_16x16x32_bf16 v[22:25], v[150:153], v[210:213], v[22:25]
	v_mfma_f32_16x16x32_bf16 v[14:17], v[158:161], v[210:213], v[14:17]
	v_mfma_f32_16x16x32_bf16 v[6:9], v[150:153], v[218:221], v[6:9]
	v_mfma_f32_16x16x32_bf16 v[2:5], v[158:161], v[218:221], v[2:5]
	s_setprio 0
	s_barrier
	s_add_u32 s76, s76, 0x100
	s_addc_u32 s77, s77, 0
	s_add_u32 s47, s47, 0x100
	s_addc_u32 s62, s62, 0
	s_cmp_ge_i32 s82, s7
	s_mov_b32 s63, s82
.LBB0_566:
	s_waitcnt vmcnt(0)
	ds_read_b128 v[114:117], v190
	ds_read_b128 v[118:121], v190 offset:1024
	ds_read_b128 v[122:125], v190 offset:2048
	ds_read_b128 v[126:129], v190 offset:3072
	ds_read_b128 v[146:149], v191
	ds_read_b128 v[150:153], v191 offset:1024
	ds_read_b128 v[154:157], v191 offset:2048
	ds_read_b128 v[158:161], v191 offset:3072
	s_add_i32 s82, s63, 2
	s_add_u32 s78, s76, 0xfffc0080
	s_addc_u32 s79, s77, -1
	s_cmp_eq_u32 s45, s63
	s_cselect_b32 s81, s31, s79
	s_cselect_b32 s80, s33, s78
	s_cselect_b32 s79, s34, s62
	s_cselect_b32 s78, s39, s47
	v_lshl_add_u64 v[186:187], s[76:77], 0, v[180:181]
	s_add_i32 m0, s87, 0xc000
	ds_read_b128 v[162:165], v192
	ds_read_b128 v[166:169], v192 offset:1024
	ds_read_b128 v[194:197], v192 offset:2048
	ds_read_b128 v[198:201], v192 offset:3072
	ds_read_b128 v[206:209], v192 offset:4096
	ds_read_b128 v[210:213], v192 offset:5120
	ds_read_b128 v[214:217], v192 offset:6144
	ds_read_b128 v[218:221], v192 offset:7168
	global_load_lds_dwordx4 v[186:187], off
	s_add_i32 m0, s87, 0xe000
	v_lshl_add_u64 v[186:187], s[76:77], 0, v[182:183]
	global_load_lds_dwordx4 v[186:187], off
	s_waitcnt vmcnt(8)
	s_waitcnt lgkmcnt(0)
	s_setprio 1
	s_barrier
	v_mfma_f32_16x16x32_bf16 v[142:145], v[114:117], v[162:165], v[142:145]
	v_mfma_f32_16x16x32_bf16 v[138:141], v[122:125], v[162:165], v[138:141]
	v_mfma_f32_16x16x32_bf16 v[110:113], v[114:117], v[194:197], v[110:113]
	v_mfma_f32_16x16x32_bf16 v[106:109], v[122:125], v[194:197], v[106:109]
	v_mfma_f32_16x16x32_bf16 v[98:101], v[114:117], v[206:209], v[98:101]
	v_mfma_f32_16x16x32_bf16 v[90:93], v[122:125], v[206:209], v[90:93]
	v_mfma_f32_16x16x32_bf16 v[82:85], v[114:117], v[214:217], v[82:85]
	v_mfma_f32_16x16x32_bf16 v[74:77], v[122:125], v[214:217], v[74:77]
	v_mfma_f32_16x16x32_bf16 v[142:145], v[118:121], v[166:169], v[142:145]
	v_mfma_f32_16x16x32_bf16 v[138:141], v[126:129], v[166:169], v[138:141]
	v_mfma_f32_16x16x32_bf16 v[110:113], v[118:121], v[198:201], v[110:113]
	v_mfma_f32_16x16x32_bf16 v[106:109], v[126:129], v[198:201], v[106:109]
	v_mfma_f32_16x16x32_bf16 v[98:101], v[118:121], v[210:213], v[98:101]
	v_mfma_f32_16x16x32_bf16 v[90:93], v[126:129], v[210:213], v[90:93]
	v_mfma_f32_16x16x32_bf16 v[82:85], v[118:121], v[218:221], v[82:85]
	v_mfma_f32_16x16x32_bf16 v[74:77], v[126:129], v[218:221], v[74:77]
	v_mfma_f32_16x16x32_bf16 v[134:137], v[146:149], v[162:165], v[134:137]
	v_mfma_f32_16x16x32_bf16 v[130:133], v[154:157], v[162:165], v[130:133]
	v_mfma_f32_16x16x32_bf16 v[102:105], v[146:149], v[194:197], v[102:105]
	v_mfma_f32_16x16x32_bf16 v[94:97], v[154:157], v[194:197], v[94:97]
	v_mfma_f32_16x16x32_bf16 v[86:89], v[146:149], v[206:209], v[86:89]
	v_mfma_f32_16x16x32_bf16 v[78:81], v[154:157], v[206:209], v[78:81]
	v_mfma_f32_16x16x32_bf16 v[70:73], v[146:149], v[214:217], v[70:73]
	v_mfma_f32_16x16x32_bf16 v[66:69], v[154:157], v[214:217], v[66:69]
	v_mfma_f32_16x16x32_bf16 v[134:137], v[150:153], v[166:169], v[134:137]
	v_mfma_f32_16x16x32_bf16 v[130:133], v[158:161], v[166:169], v[130:133]
	v_mfma_f32_16x16x32_bf16 v[102:105], v[150:153], v[198:201], v[102:105]
	v_mfma_f32_16x16x32_bf16 v[94:97], v[158:161], v[198:201], v[94:97]
	v_mfma_f32_16x16x32_bf16 v[86:89], v[150:153], v[210:213], v[86:89]
	v_mfma_f32_16x16x32_bf16 v[78:81], v[158:161], v[210:213], v[78:81]
	v_mfma_f32_16x16x32_bf16 v[70:73], v[150:153], v[218:221], v[70:73]
	v_mfma_f32_16x16x32_bf16 v[66:69], v[158:161], v[218:221], v[66:69]
	s_setprio 0
	s_barrier
	s_add_i32 s63, s24, s86
	s_mov_b32 m0, s63
	v_lshl_add_u64 v[186:187], s[78:79], 0, v[172:173]
	global_load_lds_dwordx4 v[186:187], off
	ds_read_b128 v[162:165], v192 offset:16384
	ds_read_b128 v[166:169], v192 offset:17408
	s_add_i32 m0, s63, 0x2000
	s_add_u32 vcc_lo, s78, 0x40000
	v_lshl_add_u64 v[202:203], s[78:79], 0, v[176:177]
	s_addc_u32 vcc_hi, s79, 0
	s_add_i32 s63, s25, s86
	global_load_lds_dwordx4 v[202:203], off
	ds_read_b128 v[194:197], v192 offset:18432
	ds_read_b128 v[198:201], v192 offset:19456
	v_lshl_add_u64 v[222:223], vcc, 0, v[172:173]
	s_mov_b32 m0, s63
	v_lshl_add_u64 v[224:225], s[80:81], 0, v[174:175]
	global_load_lds_dwordx4 v[222:223], off
	ds_read_b128 v[206:209], v192 offset:20480
	ds_read_b128 v[210:213], v192 offset:21504
	s_add_i32 m0, s63, 0x2000
	v_lshl_add_u64 v[222:223], vcc, 0, v[176:177]
	global_load_lds_dwordx4 v[222:223], off
	ds_read_b128 v[214:217], v192 offset:22528
	ds_read_b128 v[218:221], v192 offset:23552
	s_mov_b32 m0, s87
	v_lshl_add_u64 v[222:223], s[80:81], 0, v[170:171]
	global_load_lds_dwordx4 v[222:223], off
	s_mov_b32 m0, s88
	s_nop 0
	global_load_lds_dwordx4 v[224:225], off
	s_waitcnt vmcnt(8) lgkmcnt(0)
	s_setprio 1
	s_barrier
	v_mfma_f32_16x16x32_bf16 v[62:65], v[114:117], v[162:165], v[62:65]
	v_mfma_f32_16x16x32_bf16 v[58:61], v[122:125], v[162:165], v[58:61]
	v_mfma_f32_16x16x32_bf16 v[50:53], v[114:117], v[194:197], v[50:53]
	v_mfma_f32_16x16x32_bf16 v[42:45], v[122:125], v[194:197], v[42:45]
	v_mfma_f32_16x16x32_bf16 v[34:37], v[114:117], v[206:209], v[34:37]
	v_mfma_f32_16x16x32_bf16 v[26:29], v[122:125], v[206:209], v[26:29]
	v_mfma_f32_16x16x32_bf16 v[18:21], v[114:117], v[214:217], v[18:21]
	v_mfma_f32_16x16x32_bf16 v[10:13], v[122:125], v[214:217], v[10:13]
	v_mfma_f32_16x16x32_bf16 v[62:65], v[118:121], v[166:169], v[62:65]
	v_mfma_f32_16x16x32_bf16 v[58:61], v[126:129], v[166:169], v[58:61]
	v_mfma_f32_16x16x32_bf16 v[50:53], v[118:121], v[198:201], v[50:53]
	v_mfma_f32_16x16x32_bf16 v[42:45], v[126:129], v[198:201], v[42:45]
	v_mfma_f32_16x16x32_bf16 v[34:37], v[118:121], v[210:213], v[34:37]
	v_mfma_f32_16x16x32_bf16 v[26:29], v[126:129], v[210:213], v[26:29]
	v_mfma_f32_16x16x32_bf16 v[18:21], v[118:121], v[218:221], v[18:21]
	v_mfma_f32_16x16x32_bf16 v[10:13], v[126:129], v[218:221], v[10:13]
	v_mfma_f32_16x16x32_bf16 v[54:57], v[146:149], v[162:165], v[54:57]
	v_mfma_f32_16x16x32_bf16 v[46:49], v[154:157], v[162:165], v[46:49]
	v_mfma_f32_16x16x32_bf16 v[38:41], v[146:149], v[194:197], v[38:41]
	v_mfma_f32_16x16x32_bf16 v[30:33], v[154:157], v[194:197], v[30:33]
	v_mfma_f32_16x16x32_bf16 v[22:25], v[146:149], v[206:209], v[22:25]
	v_mfma_f32_16x16x32_bf16 v[14:17], v[154:157], v[206:209], v[14:17]
	v_mfma_f32_16x16x32_bf16 v[6:9], v[146:149], v[214:217], v[6:9]
	v_mfma_f32_16x16x32_bf16 v[2:5], v[154:157], v[214:217], v[2:5]
	v_mfma_f32_16x16x32_bf16 v[54:57], v[150:153], v[166:169], v[54:57]
	v_mfma_f32_16x16x32_bf16 v[46:49], v[158:161], v[166:169], v[46:49]
	v_mfma_f32_16x16x32_bf16 v[38:41], v[150:153], v[198:201], v[38:41]
	v_mfma_f32_16x16x32_bf16 v[30:33], v[158:161], v[198:201], v[30:33]
	v_mfma_f32_16x16x32_bf16 v[22:25], v[150:153], v[210:213], v[22:25]
	v_mfma_f32_16x16x32_bf16 v[14:17], v[158:161], v[210:213], v[14:17]
	v_mfma_f32_16x16x32_bf16 v[6:9], v[150:153], v[218:221], v[6:9]
	v_mfma_f32_16x16x32_bf16 v[2:5], v[158:161], v[218:221], v[2:5]
	s_setprio 0
	s_barrier
	s_add_i32 s63, 0, 0x18000
	s_add_i32 s83, 0, 0x1c000
	v_add_u32_e32 v126, s63, v189
	v_add_u32_e32 v158, s83, v189
	ds_read_b128 v[114:117], v126
	ds_read_b128 v[118:121], v126 offset:1024
	ds_read_b128 v[122:125], v126 offset:2048
	ds_read_b128 v[126:129], v126 offset:3072
	ds_read_b128 v[146:149], v158
	ds_read_b128 v[150:153], v158 offset:1024
	ds_read_b128 v[154:157], v158 offset:2048
	ds_read_b128 v[158:161], v158 offset:3072
	s_add_u32 s80, s80, 0x40000
	s_addc_u32 s81, s81, 0
	s_mov_b32 m0, s89
	v_lshl_add_u64 v[226:227], s[80:81], 0, v[170:171]
	ds_read_b128 v[162:165], v192 offset:32768
	ds_read_b128 v[166:169], v192 offset:33792
	ds_read_b128 v[194:197], v192 offset:34816
	ds_read_b128 v[198:201], v192 offset:35840
	ds_read_b128 v[206:209], v192 offset:36864
	ds_read_b128 v[210:213], v192 offset:37888
	ds_read_b128 v[214:217], v192 offset:38912
	ds_read_b128 v[218:221], v192 offset:39936
	global_load_lds_dwordx4 v[226:227], off
	s_mov_b32 m0, s90
	v_lshl_add_u64 v[226:227], s[80:81], 0, v[174:175]
	global_load_lds_dwordx4 v[226:227], off
	s_waitcnt vmcnt(8) lgkmcnt(0)
	s_setprio 1
	s_barrier
	v_mfma_f32_16x16x32_bf16 v[142:145], v[114:117], v[162:165], v[142:145]
	v_mfma_f32_16x16x32_bf16 v[138:141], v[122:125], v[162:165], v[138:141]
	v_mfma_f32_16x16x32_bf16 v[110:113], v[114:117], v[194:197], v[110:113]
	v_mfma_f32_16x16x32_bf16 v[106:109], v[122:125], v[194:197], v[106:109]
	v_mfma_f32_16x16x32_bf16 v[98:101], v[114:117], v[206:209], v[98:101]
	v_mfma_f32_16x16x32_bf16 v[90:93], v[122:125], v[206:209], v[90:93]
	v_mfma_f32_16x16x32_bf16 v[82:85], v[114:117], v[214:217], v[82:85]
	v_mfma_f32_16x16x32_bf16 v[74:77], v[122:125], v[214:217], v[74:77]
	v_mfma_f32_16x16x32_bf16 v[142:145], v[118:121], v[166:169], v[142:145]
	v_mfma_f32_16x16x32_bf16 v[138:141], v[126:129], v[166:169], v[138:141]
	v_mfma_f32_16x16x32_bf16 v[110:113], v[118:121], v[198:201], v[110:113]
	v_mfma_f32_16x16x32_bf16 v[106:109], v[126:129], v[198:201], v[106:109]
	v_mfma_f32_16x16x32_bf16 v[98:101], v[118:121], v[210:213], v[98:101]
	v_mfma_f32_16x16x32_bf16 v[90:93], v[126:129], v[210:213], v[90:93]
	v_mfma_f32_16x16x32_bf16 v[82:85], v[118:121], v[218:221], v[82:85]
	v_mfma_f32_16x16x32_bf16 v[74:77], v[126:129], v[218:221], v[74:77]
	v_mfma_f32_16x16x32_bf16 v[134:137], v[146:149], v[162:165], v[134:137]
	v_mfma_f32_16x16x32_bf16 v[130:133], v[154:157], v[162:165], v[130:133]
	v_mfma_f32_16x16x32_bf16 v[102:105], v[146:149], v[194:197], v[102:105]
	v_mfma_f32_16x16x32_bf16 v[94:97], v[154:157], v[194:197], v[94:97]
	v_mfma_f32_16x16x32_bf16 v[86:89], v[146:149], v[206:209], v[86:89]
	v_mfma_f32_16x16x32_bf16 v[78:81], v[154:157], v[206:209], v[78:81]
	v_mfma_f32_16x16x32_bf16 v[70:73], v[146:149], v[214:217], v[70:73]
	v_mfma_f32_16x16x32_bf16 v[66:69], v[154:157], v[214:217], v[66:69]
	v_mfma_f32_16x16x32_bf16 v[134:137], v[150:153], v[166:169], v[134:137]
	v_mfma_f32_16x16x32_bf16 v[130:133], v[158:161], v[166:169], v[130:133]
	v_mfma_f32_16x16x32_bf16 v[102:105], v[150:153], v[198:201], v[102:105]
	v_mfma_f32_16x16x32_bf16 v[94:97], v[158:161], v[198:201], v[94:97]
	v_mfma_f32_16x16x32_bf16 v[86:89], v[150:153], v[210:213], v[86:89]
	v_mfma_f32_16x16x32_bf16 v[78:81], v[158:161], v[210:213], v[78:81]
	v_mfma_f32_16x16x32_bf16 v[70:73], v[150:153], v[218:221], v[70:73]
	v_mfma_f32_16x16x32_bf16 v[66:69], v[158:161], v[218:221], v[66:69]
	s_setprio 0
	s_barrier
	s_add_i32 s63, s63, s86
	s_mov_b32 m0, s63
	v_lshl_add_u64 v[186:187], v[186:187], 0, s[22:23]
	global_load_lds_dwordx4 v[186:187], off
	ds_read_b128 v[162:165], v192 offset:49152
	ds_read_b128 v[166:169], v192 offset:50176
	s_add_i32 m0, s63, 0x2000
	s_add_u32 s78, s78, 0x40080
	v_lshl_add_u64 v[186:187], v[202:203], 0, s[22:23]
	s_addc_u32 s79, s79, 0
	s_add_i32 s63, s83, s86
	global_load_lds_dwordx4 v[186:187], off
	ds_read_b128 v[194:197], v192 offset:51200
	ds_read_b128 v[198:201], v192 offset:52224
	s_mov_b32 m0, s63
	v_lshl_add_u64 v[186:187], s[78:79], 0, v[172:173]
	global_load_lds_dwordx4 v[186:187], off
	ds_read_b128 v[206:209], v192 offset:53248
	ds_read_b128 v[210:213], v192 offset:54272
	s_add_i32 m0, s63, 0x2000
	v_lshl_add_u64 v[186:187], s[78:79], 0, v[176:177]
	global_load_lds_dwordx4 v[186:187], off
	ds_read_b128 v[214:217], v192 offset:55296
	ds_read_b128 v[218:221], v192 offset:56320
	s_mov_b32 m0, s95
	v_lshl_add_u64 v[186:187], v[222:223], 0, s[22:23]
	global_load_lds_dwordx4 v[186:187], off
	s_mov_b32 m0, s96
	v_lshl_add_u64 v[186:187], v[224:225], 0, s[22:23]
	global_load_lds_dwordx4 v[186:187], off
	s_waitcnt vmcnt(8) lgkmcnt(0)
	s_setprio 1
	s_barrier
	v_mfma_f32_16x16x32_bf16 v[62:65], v[114:117], v[162:165], v[62:65]
	v_mfma_f32_16x16x32_bf16 v[58:61], v[122:125], v[162:165], v[58:61]
	v_mfma_f32_16x16x32_bf16 v[50:53], v[114:117], v[194:197], v[50:53]
	v_mfma_f32_16x16x32_bf16 v[42:45], v[122:125], v[194:197], v[42:45]
	v_mfma_f32_16x16x32_bf16 v[34:37], v[114:117], v[206:209], v[34:37]
	v_mfma_f32_16x16x32_bf16 v[26:29], v[122:125], v[206:209], v[26:29]
	v_mfma_f32_16x16x32_bf16 v[18:21], v[114:117], v[214:217], v[18:21]
	v_mfma_f32_16x16x32_bf16 v[10:13], v[122:125], v[214:217], v[10:13]
	v_mfma_f32_16x16x32_bf16 v[62:65], v[118:121], v[166:169], v[62:65]
	v_mfma_f32_16x16x32_bf16 v[58:61], v[126:129], v[166:169], v[58:61]
	v_mfma_f32_16x16x32_bf16 v[50:53], v[118:121], v[198:201], v[50:53]
	v_mfma_f32_16x16x32_bf16 v[42:45], v[126:129], v[198:201], v[42:45]
	v_mfma_f32_16x16x32_bf16 v[34:37], v[118:121], v[210:213], v[34:37]
	v_mfma_f32_16x16x32_bf16 v[26:29], v[126:129], v[210:213], v[26:29]
	v_mfma_f32_16x16x32_bf16 v[18:21], v[118:121], v[218:221], v[18:21]
	v_mfma_f32_16x16x32_bf16 v[10:13], v[126:129], v[218:221], v[10:13]
	v_mfma_f32_16x16x32_bf16 v[54:57], v[146:149], v[162:165], v[54:57]
	v_mfma_f32_16x16x32_bf16 v[46:49], v[154:157], v[162:165], v[46:49]
	v_mfma_f32_16x16x32_bf16 v[38:41], v[146:149], v[194:197], v[38:41]
	v_mfma_f32_16x16x32_bf16 v[30:33], v[154:157], v[194:197], v[30:33]
	v_mfma_f32_16x16x32_bf16 v[22:25], v[146:149], v[206:209], v[22:25]
	v_mfma_f32_16x16x32_bf16 v[14:17], v[154:157], v[206:209], v[14:17]
	v_mfma_f32_16x16x32_bf16 v[6:9], v[146:149], v[214:217], v[6:9]
	v_mfma_f32_16x16x32_bf16 v[2:5], v[154:157], v[214:217], v[2:5]
	v_mfma_f32_16x16x32_bf16 v[54:57], v[150:153], v[166:169], v[54:57]
	v_mfma_f32_16x16x32_bf16 v[46:49], v[158:161], v[166:169], v[46:49]
	v_mfma_f32_16x16x32_bf16 v[38:41], v[150:153], v[198:201], v[38:41]
	v_mfma_f32_16x16x32_bf16 v[30:33], v[158:161], v[198:201], v[30:33]
	v_mfma_f32_16x16x32_bf16 v[22:25], v[150:153], v[210:213], v[22:25]
	v_mfma_f32_16x16x32_bf16 v[14:17], v[158:161], v[210:213], v[14:17]
	v_mfma_f32_16x16x32_bf16 v[6:9], v[150:153], v[218:221], v[6:9]
	v_mfma_f32_16x16x32_bf16 v[2:5], v[158:161], v[218:221], v[2:5]
	s_setprio 0
	s_barrier
	s_add_u32 s76, s76, 0x100
	s_addc_u32 s77, s77, 0
	s_add_u32 s47, s47, 0x100
	s_addc_u32 s62, s62, 0
	s_cmp_ge_i32 s82, s7
	s_mov_b32 s63, s82
	s_cbranch_scc0 .LBB0_566
	s_and_b64 vcc, exec, s[26:27]
	s_cbranch_vccz .LBB0_569
	s_barrier

.LBB0_744:
	s_add_u32 s36, s96, s22
	s_addc_u32 s37, s97, s23
	s_and_b64 s[14:15], s[4:5], exec
	s_cselect_b32 s14, s37, s43
	s_cselect_b32 s15, s36, s42
	s_add_u32 s38, s2, s26
	s_addc_u32 s39, s3, s27
	s_and_b64 s[46:47], s[4:5], exec
	s_cselect_b32 s21, s39, s45
	s_cselect_b32 s65, s38, s44
	s_add_u32 s42, s42, 0x40080
	s_addc_u32 s43, s43, 0
	s_add_u32 s66, s44, 0x100
	s_addc_u32 s67, s45, 0
	s_mov_b32 s68, -2
	ds_read_b128 v[154:157], v150
	ds_read_b128 v[158:161], v150 offset:1024
	ds_read_b128 v[162:165], v150 offset:2048
	ds_read_b128 v[166:169], v150 offset:3072
	ds_read_b128 v[170:173], v151
	ds_read_b128 v[174:177], v151 offset:1024
	ds_read_b128 v[178:181], v151 offset:2048
	ds_read_b128 v[182:185], v151 offset:3072
	s_add_u32 s44, s42, 0xfffc0080
	s_addc_u32 s45, s43, -1
	s_cmp_eq_u32 s68, 12
	s_cselect_b32 s47, s14, s45
	s_cselect_b32 s46, s15, s44
	s_cselect_b32 s45, s21, s67
	s_cselect_b32 s44, s65, s66
	v_lshl_add_u64 v[146:147], s[42:43], 0, v[138:139]
	s_add_i32 m0, s19, 0xc000
	ds_read_b128 v[186:189], v152
	ds_read_b128 v[190:193], v152 offset:1024
	ds_read_b128 v[194:197], v152 offset:2048
	ds_read_b128 v[198:201], v152 offset:3072
	ds_read_b128 v[206:209], v152 offset:4096
	ds_read_b128 v[210:213], v152 offset:5120
	ds_read_b128 v[214:217], v152 offset:6144
	ds_read_b128 v[218:221], v152 offset:7168
	global_load_lds_dwordx4 v[146:147], off
	s_add_i32 m0, s19, 0xe000
	v_lshl_add_u64 v[146:147], s[42:43], 0, v[140:141]
	global_load_lds_dwordx4 v[146:147], off
	s_waitcnt vmcnt(8) lgkmcnt(0)
	s_setprio 1
	s_barrier
	v_mfma_f32_16x16x32_bf16 v[126:129], v[154:157], v[186:189], 0
	v_mfma_f32_16x16x32_bf16 v[122:125], v[162:165], v[186:189], 0
	v_mfma_f32_16x16x32_bf16 v[110:113], v[154:157], v[194:197], 0
	v_mfma_f32_16x16x32_bf16 v[106:109], v[162:165], v[194:197], 0
	v_mfma_f32_16x16x32_bf16 v[94:97], v[154:157], v[206:209], 0
	v_mfma_f32_16x16x32_bf16 v[90:93], v[162:165], v[206:209], 0
	v_mfma_f32_16x16x32_bf16 v[78:81], v[154:157], v[214:217], 0
	v_mfma_f32_16x16x32_bf16 v[74:77], v[162:165], v[214:217], 0
	v_mfma_f32_16x16x32_bf16 v[126:129], v[158:161], v[190:193], v[126:129]
	v_mfma_f32_16x16x32_bf16 v[122:125], v[166:169], v[190:193], v[122:125]
	v_mfma_f32_16x16x32_bf16 v[110:113], v[158:161], v[198:201], v[110:113]
	v_mfma_f32_16x16x32_bf16 v[106:109], v[166:169], v[198:201], v[106:109]
	v_mfma_f32_16x16x32_bf16 v[94:97], v[158:161], v[210:213], v[94:97]
	v_mfma_f32_16x16x32_bf16 v[90:93], v[166:169], v[210:213], v[90:93]
	v_mfma_f32_16x16x32_bf16 v[78:81], v[158:161], v[218:221], v[78:81]
	v_mfma_f32_16x16x32_bf16 v[74:77], v[166:169], v[218:221], v[74:77]
	v_mfma_f32_16x16x32_bf16 v[118:121], v[170:173], v[186:189], 0
	v_mfma_f32_16x16x32_bf16 v[114:117], v[178:181], v[186:189], 0
	v_mfma_f32_16x16x32_bf16 v[102:105], v[170:173], v[194:197], 0
	v_mfma_f32_16x16x32_bf16 v[98:101], v[178:181], v[194:197], 0
	v_mfma_f32_16x16x32_bf16 v[86:89], v[170:173], v[206:209], 0
	v_mfma_f32_16x16x32_bf16 v[82:85], v[178:181], v[206:209], 0
	v_mfma_f32_16x16x32_bf16 v[70:73], v[170:173], v[214:217], 0
	v_mfma_f32_16x16x32_bf16 v[66:69], v[178:181], v[214:217], 0
	v_mfma_f32_16x16x32_bf16 v[118:121], v[174:177], v[190:193], v[118:121]
	v_mfma_f32_16x16x32_bf16 v[114:117], v[182:185], v[190:193], v[114:117]
	v_mfma_f32_16x16x32_bf16 v[102:105], v[174:177], v[198:201], v[102:105]
	v_mfma_f32_16x16x32_bf16 v[98:101], v[182:185], v[198:201], v[98:101]
	v_mfma_f32_16x16x32_bf16 v[86:89], v[174:177], v[210:213], v[86:89]
	v_mfma_f32_16x16x32_bf16 v[82:85], v[182:185], v[210:213], v[82:85]
	v_mfma_f32_16x16x32_bf16 v[70:73], v[174:177], v[218:221], v[70:73]
	v_mfma_f32_16x16x32_bf16 v[66:69], v[182:185], v[218:221], v[66:69]
	s_setprio 0
	s_barrier
	s_add_i32 s69, s49, s16
	s_mov_b32 m0, s69
	v_lshl_add_u64 v[146:147], s[44:45], 0, v[134:135]
	global_load_lds_dwordx4 v[146:147], off
	ds_read_b128 v[186:189], v152 offset:16384
	ds_read_b128 v[190:193], v152 offset:17408
	s_add_i32 m0, s69, 0x2000
	s_add_u32 s70, s44, 0x40000
	v_lshl_add_u64 v[202:203], s[44:45], 0, v[130:131]
	s_addc_u32 s71, s45, 0
	s_add_i32 s69, s62, s16
	global_load_lds_dwordx4 v[202:203], off
	ds_read_b128 v[194:197], v152 offset:18432
	ds_read_b128 v[198:201], v152 offset:19456
	v_lshl_add_u64 v[222:223], s[70:71], 0, v[134:135]
	s_mov_b32 m0, s69
	v_lshl_add_u64 v[224:225], s[46:47], 0, v[132:133]
	global_load_lds_dwordx4 v[222:223], off
	ds_read_b128 v[206:209], v152 offset:20480
	ds_read_b128 v[210:213], v152 offset:21504
	s_add_i32 m0, s69, 0x2000
	v_lshl_add_u64 v[222:223], s[70:71], 0, v[130:131]
	global_load_lds_dwordx4 v[222:223], off
	ds_read_b128 v[214:217], v152 offset:22528
	ds_read_b128 v[218:221], v152 offset:23552
	s_mov_b32 m0, s19
	v_lshl_add_u64 v[222:223], s[46:47], 0, v[136:137]
	global_load_lds_dwordx4 v[222:223], off
	s_mov_b32 m0, s24
	s_nop 0
	global_load_lds_dwordx4 v[224:225], off
	s_waitcnt vmcnt(8) lgkmcnt(0)
	s_setprio 1
	s_barrier
	v_mfma_f32_16x16x32_bf16 v[62:65], v[154:157], v[186:189], 0
	v_mfma_f32_16x16x32_bf16 v[58:61], v[162:165], v[186:189], 0
	v_mfma_f32_16x16x32_bf16 v[46:49], v[154:157], v[194:197], 0
	v_mfma_f32_16x16x32_bf16 v[42:45], v[162:165], v[194:197], 0
	v_mfma_f32_16x16x32_bf16 v[30:33], v[154:157], v[206:209], 0
	v_mfma_f32_16x16x32_bf16 v[26:29], v[162:165], v[206:209], 0
	v_mfma_f32_16x16x32_bf16 v[14:17], v[154:157], v[214:217], 0
	v_mfma_f32_16x16x32_bf16 v[10:13], v[162:165], v[214:217], 0
	v_mfma_f32_16x16x32_bf16 v[62:65], v[158:161], v[190:193], v[62:65]
	v_mfma_f32_16x16x32_bf16 v[58:61], v[166:169], v[190:193], v[58:61]
	v_mfma_f32_16x16x32_bf16 v[46:49], v[158:161], v[198:201], v[46:49]
	v_mfma_f32_16x16x32_bf16 v[42:45], v[166:169], v[198:201], v[42:45]
	v_mfma_f32_16x16x32_bf16 v[30:33], v[158:161], v[210:213], v[30:33]
	v_mfma_f32_16x16x32_bf16 v[26:29], v[166:169], v[210:213], v[26:29]
	v_mfma_f32_16x16x32_bf16 v[14:17], v[158:161], v[218:221], v[14:17]
	v_mfma_f32_16x16x32_bf16 v[10:13], v[166:169], v[218:221], v[10:13]
	v_mfma_f32_16x16x32_bf16 v[54:57], v[170:173], v[186:189], 0
	v_mfma_f32_16x16x32_bf16 v[50:53], v[178:181], v[186:189], 0
	v_mfma_f32_16x16x32_bf16 v[38:41], v[170:173], v[194:197], 0
	v_mfma_f32_16x16x32_bf16 v[34:37], v[178:181], v[194:197], 0
	v_mfma_f32_16x16x32_bf16 v[22:25], v[170:173], v[206:209], 0
	v_mfma_f32_16x16x32_bf16 v[18:21], v[178:181], v[206:209], 0
	v_mfma_f32_16x16x32_bf16 v[6:9], v[170:173], v[214:217], 0
	v_mfma_f32_16x16x32_bf16 v[2:5], v[178:181], v[214:217], 0
	v_mfma_f32_16x16x32_bf16 v[54:57], v[174:177], v[190:193], v[54:57]
	v_mfma_f32_16x16x32_bf16 v[50:53], v[182:185], v[190:193], v[50:53]
	v_mfma_f32_16x16x32_bf16 v[38:41], v[174:177], v[198:201], v[38:41]
	v_mfma_f32_16x16x32_bf16 v[34:37], v[182:185], v[198:201], v[34:37]
	v_mfma_f32_16x16x32_bf16 v[22:25], v[174:177], v[210:213], v[22:25]
	v_mfma_f32_16x16x32_bf16 v[18:21], v[182:185], v[210:213], v[18:21]
	v_mfma_f32_16x16x32_bf16 v[6:9], v[174:177], v[218:221], v[6:9]
	v_mfma_f32_16x16x32_bf16 v[2:5], v[182:185], v[218:221], v[2:5]
	s_setprio 0
	s_barrier
	s_add_i32 s69, 0, 0x18000
	v_add_u32_e32 v153, s69, v149
	s_add_i32 s70, 0, 0x1c000
	ds_read_b128 v[154:157], v153
	ds_read_b128 v[158:161], v153 offset:1024
	ds_read_b128 v[162:165], v153 offset:2048
	ds_read_b128 v[166:169], v153 offset:3072
	v_add_u32_e32 v153, s70, v149
	ds_read_b128 v[170:173], v153
	ds_read_b128 v[174:177], v153 offset:1024
	ds_read_b128 v[178:181], v153 offset:2048
	ds_read_b128 v[182:185], v153 offset:3072
	s_add_u32 s46, s46, 0x40000
	s_addc_u32 s47, s47, 0
	s_mov_b32 m0, s25
	v_lshl_add_u64 v[226:227], s[46:47], 0, v[136:137]
	ds_read_b128 v[186:189], v152 offset:32768
	ds_read_b128 v[190:193], v152 offset:33792
	ds_read_b128 v[194:197], v152 offset:34816
	ds_read_b128 v[198:201], v152 offset:35840
	ds_read_b128 v[206:209], v152 offset:36864
	ds_read_b128 v[210:213], v152 offset:37888
	ds_read_b128 v[214:217], v152 offset:38912
	ds_read_b128 v[218:221], v152 offset:39936
	global_load_lds_dwordx4 v[226:227], off
	s_mov_b32 m0, s28
	v_lshl_add_u64 v[226:227], s[46:47], 0, v[132:133]
	global_load_lds_dwordx4 v[226:227], off
	s_waitcnt vmcnt(8) lgkmcnt(0)
	s_setprio 1
	s_barrier
	v_mfma_f32_16x16x32_bf16 v[126:129], v[154:157], v[186:189], v[126:129]
	v_mfma_f32_16x16x32_bf16 v[122:125], v[162:165], v[186:189], v[122:125]
	v_mfma_f32_16x16x32_bf16 v[110:113], v[154:157], v[194:197], v[110:113]
	v_mfma_f32_16x16x32_bf16 v[106:109], v[162:165], v[194:197], v[106:109]
	v_mfma_f32_16x16x32_bf16 v[94:97], v[154:157], v[206:209], v[94:97]
	v_mfma_f32_16x16x32_bf16 v[90:93], v[162:165], v[206:209], v[90:93]
	v_mfma_f32_16x16x32_bf16 v[78:81], v[154:157], v[214:217], v[78:81]
	v_mfma_f32_16x16x32_bf16 v[74:77], v[162:165], v[214:217], v[74:77]
	v_mfma_f32_16x16x32_bf16 v[126:129], v[158:161], v[190:193], v[126:129]
	v_mfma_f32_16x16x32_bf16 v[122:125], v[166:169], v[190:193], v[122:125]
	v_mfma_f32_16x16x32_bf16 v[110:113], v[158:161], v[198:201], v[110:113]
	v_mfma_f32_16x16x32_bf16 v[106:109], v[166:169], v[198:201], v[106:109]
	v_mfma_f32_16x16x32_bf16 v[94:97], v[158:161], v[210:213], v[94:97]
	v_mfma_f32_16x16x32_bf16 v[90:93], v[166:169], v[210:213], v[90:93]
	v_mfma_f32_16x16x32_bf16 v[78:81], v[158:161], v[218:221], v[78:81]
	v_mfma_f32_16x16x32_bf16 v[74:77], v[166:169], v[218:221], v[74:77]
	v_mfma_f32_16x16x32_bf16 v[118:121], v[170:173], v[186:189], v[118:121]
	v_mfma_f32_16x16x32_bf16 v[114:117], v[178:181], v[186:189], v[114:117]
	v_mfma_f32_16x16x32_bf16 v[102:105], v[170:173], v[194:197], v[102:105]
	v_mfma_f32_16x16x32_bf16 v[98:101], v[178:181], v[194:197], v[98:101]
	v_mfma_f32_16x16x32_bf16 v[86:89], v[170:173], v[206:209], v[86:89]
	v_mfma_f32_16x16x32_bf16 v[82:85], v[178:181], v[206:209], v[82:85]
	v_mfma_f32_16x16x32_bf16 v[70:73], v[170:173], v[214:217], v[70:73]
	v_mfma_f32_16x16x32_bf16 v[66:69], v[178:181], v[214:217], v[66:69]
	v_mfma_f32_16x16x32_bf16 v[118:121], v[174:177], v[190:193], v[118:121]
	v_mfma_f32_16x16x32_bf16 v[114:117], v[182:185], v[190:193], v[114:117]
	v_mfma_f32_16x16x32_bf16 v[102:105], v[174:177], v[198:201], v[102:105]
	v_mfma_f32_16x16x32_bf16 v[98:101], v[182:185], v[198:201], v[98:101]
	v_mfma_f32_16x16x32_bf16 v[86:89], v[174:177], v[210:213], v[86:89]
	v_mfma_f32_16x16x32_bf16 v[82:85], v[182:185], v[210:213], v[82:85]
	v_mfma_f32_16x16x32_bf16 v[70:73], v[174:177], v[218:221], v[70:73]
	v_mfma_f32_16x16x32_bf16 v[66:69], v[182:185], v[218:221], v[66:69]
	s_setprio 0
	s_barrier
	s_add_i32 s46, s69, s16
	s_mov_b32 m0, s46
	v_lshl_add_u64 v[146:147], v[146:147], 0, s[10:11]
	global_load_lds_dwordx4 v[146:147], off
	ds_read_b128 v[186:189], v152 offset:49152
	ds_read_b128 v[190:193], v152 offset:50176
	s_add_i32 m0, s46, 0x2000
	s_add_u32 s44, s44, 0x40080
	v_lshl_add_u64 v[146:147], v[202:203], 0, s[10:11]
	s_addc_u32 s45, s45, 0
	s_add_i32 s46, s70, s16
	global_load_lds_dwordx4 v[146:147], off
	ds_read_b128 v[194:197], v152 offset:51200
	ds_read_b128 v[198:201], v152 offset:52224
	s_mov_b32 m0, s46
	v_lshl_add_u64 v[146:147], s[44:45], 0, v[134:135]
	global_load_lds_dwordx4 v[146:147], off
	ds_read_b128 v[206:209], v152 offset:53248
	ds_read_b128 v[210:213], v152 offset:54272
	s_add_i32 m0, s46, 0x2000
	v_lshl_add_u64 v[146:147], s[44:45], 0, v[130:131]
	global_load_lds_dwordx4 v[146:147], off
	ds_read_b128 v[214:217], v152 offset:55296
	ds_read_b128 v[218:221], v152 offset:56320
	s_mov_b32 m0, s33
	v_lshl_add_u64 v[146:147], v[222:223], 0, s[10:11]
	global_load_lds_dwordx4 v[146:147], off
	s_mov_b32 m0, s35
	v_lshl_add_u64 v[146:147], v[224:225], 0, s[10:11]
	global_load_lds_dwordx4 v[146:147], off
	s_waitcnt vmcnt(8) lgkmcnt(0)
	s_setprio 1
	s_barrier
	v_mfma_f32_16x16x32_bf16 v[62:65], v[154:157], v[186:189], v[62:65]
	v_mfma_f32_16x16x32_bf16 v[58:61], v[162:165], v[186:189], v[58:61]
	v_mfma_f32_16x16x32_bf16 v[46:49], v[154:157], v[194:197], v[46:49]
	v_mfma_f32_16x16x32_bf16 v[42:45], v[162:165], v[194:197], v[42:45]
	v_mfma_f32_16x16x32_bf16 v[30:33], v[154:157], v[206:209], v[30:33]
	v_mfma_f32_16x16x32_bf16 v[26:29], v[162:165], v[206:209], v[26:29]
	v_mfma_f32_16x16x32_bf16 v[14:17], v[154:157], v[214:217], v[14:17]
	v_mfma_f32_16x16x32_bf16 v[10:13], v[162:165], v[214:217], v[10:13]
	v_mfma_f32_16x16x32_bf16 v[62:65], v[158:161], v[190:193], v[62:65]
	v_mfma_f32_16x16x32_bf16 v[58:61], v[166:169], v[190:193], v[58:61]
	v_mfma_f32_16x16x32_bf16 v[46:49], v[158:161], v[198:201], v[46:49]
	v_mfma_f32_16x16x32_bf16 v[42:45], v[166:169], v[198:201], v[42:45]
	v_mfma_f32_16x16x32_bf16 v[30:33], v[158:161], v[210:213], v[30:33]
	v_mfma_f32_16x16x32_bf16 v[26:29], v[166:169], v[210:213], v[26:29]
	v_mfma_f32_16x16x32_bf16 v[14:17], v[158:161], v[218:221], v[14:17]
	v_mfma_f32_16x16x32_bf16 v[10:13], v[166:169], v[218:221], v[10:13]
	v_mfma_f32_16x16x32_bf16 v[54:57], v[170:173], v[186:189], v[54:57]
	v_mfma_f32_16x16x32_bf16 v[50:53], v[178:181], v[186:189], v[50:53]
	v_mfma_f32_16x16x32_bf16 v[38:41], v[170:173], v[194:197], v[38:41]
	v_mfma_f32_16x16x32_bf16 v[34:37], v[178:181], v[194:197], v[34:37]
	v_mfma_f32_16x16x32_bf16 v[22:25], v[170:173], v[206:209], v[22:25]
	v_mfma_f32_16x16x32_bf16 v[18:21], v[178:181], v[206:209], v[18:21]
	v_mfma_f32_16x16x32_bf16 v[6:9], v[170:173], v[214:217], v[6:9]
	v_mfma_f32_16x16x32_bf16 v[2:5], v[178:181], v[214:217], v[2:5]
	v_mfma_f32_16x16x32_bf16 v[54:57], v[174:177], v[190:193], v[54:57]
	v_mfma_f32_16x16x32_bf16 v[50:53], v[182:185], v[190:193], v[50:53]
	v_mfma_f32_16x16x32_bf16 v[38:41], v[174:177], v[198:201], v[38:41]
	v_mfma_f32_16x16x32_bf16 v[34:37], v[182:185], v[198:201], v[34:37]
	v_mfma_f32_16x16x32_bf16 v[22:25], v[174:177], v[210:213], v[22:25]
	v_mfma_f32_16x16x32_bf16 v[18:21], v[182:185], v[210:213], v[18:21]
	v_mfma_f32_16x16x32_bf16 v[6:9], v[174:177], v[218:221], v[6:9]
	v_mfma_f32_16x16x32_bf16 v[2:5], v[182:185], v[218:221], v[2:5]
	s_setprio 0
	s_barrier
	s_add_i32 s68, s68, 2
	s_add_u32 s42, s42, 0x100
	s_addc_u32 s43, s43, 0
	s_add_u32 s66, s66, 0x100
	s_addc_u32 s67, s67, 0
	s_cmp_gt_u32 s68, 13
.LBB0_745:
	ds_read_b128 v[154:157], v150
	ds_read_b128 v[158:161], v150 offset:1024
	ds_read_b128 v[162:165], v150 offset:2048
	ds_read_b128 v[166:169], v150 offset:3072
	ds_read_b128 v[170:173], v151
	ds_read_b128 v[174:177], v151 offset:1024
	ds_read_b128 v[178:181], v151 offset:2048
	ds_read_b128 v[182:185], v151 offset:3072
	s_add_u32 s44, s42, 0xfffc0080
	s_addc_u32 s45, s43, -1
	s_cmp_eq_u32 s68, 12
	s_cselect_b32 s47, s14, s45
	s_cselect_b32 s46, s15, s44
	s_cselect_b32 s45, s21, s67
	s_cselect_b32 s44, s65, s66
	v_lshl_add_u64 v[146:147], s[42:43], 0, v[138:139]
	s_add_i32 m0, s19, 0xc000
	ds_read_b128 v[186:189], v152
	ds_read_b128 v[190:193], v152 offset:1024
	ds_read_b128 v[194:197], v152 offset:2048
	ds_read_b128 v[198:201], v152 offset:3072
	ds_read_b128 v[206:209], v152 offset:4096
	ds_read_b128 v[210:213], v152 offset:5120
	ds_read_b128 v[214:217], v152 offset:6144
	ds_read_b128 v[218:221], v152 offset:7168
	global_load_lds_dwordx4 v[146:147], off
	s_add_i32 m0, s19, 0xe000
	v_lshl_add_u64 v[146:147], s[42:43], 0, v[140:141]
	global_load_lds_dwordx4 v[146:147], off
	s_waitcnt vmcnt(8) lgkmcnt(0)
	s_setprio 1
	s_barrier
	v_mfma_f32_16x16x32_bf16 v[126:129], v[154:157], v[186:189], v[126:129]
	v_mfma_f32_16x16x32_bf16 v[122:125], v[162:165], v[186:189], v[122:125]
	v_mfma_f32_16x16x32_bf16 v[110:113], v[154:157], v[194:197], v[110:113]
	v_mfma_f32_16x16x32_bf16 v[106:109], v[162:165], v[194:197], v[106:109]
	v_mfma_f32_16x16x32_bf16 v[94:97], v[154:157], v[206:209], v[94:97]
	v_mfma_f32_16x16x32_bf16 v[90:93], v[162:165], v[206:209], v[90:93]
	v_mfma_f32_16x16x32_bf16 v[78:81], v[154:157], v[214:217], v[78:81]
	v_mfma_f32_16x16x32_bf16 v[74:77], v[162:165], v[214:217], v[74:77]
	v_mfma_f32_16x16x32_bf16 v[126:129], v[158:161], v[190:193], v[126:129]
	v_mfma_f32_16x16x32_bf16 v[122:125], v[166:169], v[190:193], v[122:125]
	v_mfma_f32_16x16x32_bf16 v[110:113], v[158:161], v[198:201], v[110:113]
	v_mfma_f32_16x16x32_bf16 v[106:109], v[166:169], v[198:201], v[106:109]
	v_mfma_f32_16x16x32_bf16 v[94:97], v[158:161], v[210:213], v[94:97]
	v_mfma_f32_16x16x32_bf16 v[90:93], v[166:169], v[210:213], v[90:93]
	v_mfma_f32_16x16x32_bf16 v[78:81], v[158:161], v[218:221], v[78:81]
	v_mfma_f32_16x16x32_bf16 v[74:77], v[166:169], v[218:221], v[74:77]
	v_mfma_f32_16x16x32_bf16 v[118:121], v[170:173], v[186:189], v[118:121]
	v_mfma_f32_16x16x32_bf16 v[114:117], v[178:181], v[186:189], v[114:117]
	v_mfma_f32_16x16x32_bf16 v[102:105], v[170:173], v[194:197], v[102:105]
	v_mfma_f32_16x16x32_bf16 v[98:101], v[178:181], v[194:197], v[98:101]
	v_mfma_f32_16x16x32_bf16 v[86:89], v[170:173], v[206:209], v[86:89]
	v_mfma_f32_16x16x32_bf16 v[82:85], v[178:181], v[206:209], v[82:85]
	v_mfma_f32_16x16x32_bf16 v[70:73], v[170:173], v[214:217], v[70:73]
	v_mfma_f32_16x16x32_bf16 v[66:69], v[178:181], v[214:217], v[66:69]
	v_mfma_f32_16x16x32_bf16 v[118:121], v[174:177], v[190:193], v[118:121]
	v_mfma_f32_16x16x32_bf16 v[114:117], v[182:185], v[190:193], v[114:117]
	v_mfma_f32_16x16x32_bf16 v[102:105], v[174:177], v[198:201], v[102:105]
	v_mfma_f32_16x16x32_bf16 v[98:101], v[182:185], v[198:201], v[98:101]
	v_mfma_f32_16x16x32_bf16 v[86:89], v[174:177], v[210:213], v[86:89]
	v_mfma_f32_16x16x32_bf16 v[82:85], v[182:185], v[210:213], v[82:85]
	v_mfma_f32_16x16x32_bf16 v[70:73], v[174:177], v[218:221], v[70:73]
	v_mfma_f32_16x16x32_bf16 v[66:69], v[182:185], v[218:221], v[66:69]
	s_setprio 0
	s_barrier
	s_add_i32 s69, s49, s16
	s_mov_b32 m0, s69
	v_lshl_add_u64 v[146:147], s[44:45], 0, v[134:135]
	global_load_lds_dwordx4 v[146:147], off
	ds_read_b128 v[186:189], v152 offset:16384
	ds_read_b128 v[190:193], v152 offset:17408
	s_add_i32 m0, s69, 0x2000
	s_add_u32 s70, s44, 0x40000
	v_lshl_add_u64 v[202:203], s[44:45], 0, v[130:131]
	s_addc_u32 s71, s45, 0
	s_add_i32 s69, s62, s16
	global_load_lds_dwordx4 v[202:203], off
	ds_read_b128 v[194:197], v152 offset:18432
	ds_read_b128 v[198:201], v152 offset:19456
	v_lshl_add_u64 v[222:223], s[70:71], 0, v[134:135]
	s_mov_b32 m0, s69
	v_lshl_add_u64 v[224:225], s[46:47], 0, v[132:133]
	global_load_lds_dwordx4 v[222:223], off
	ds_read_b128 v[206:209], v152 offset:20480
	ds_read_b128 v[210:213], v152 offset:21504
	s_add_i32 m0, s69, 0x2000
	v_lshl_add_u64 v[222:223], s[70:71], 0, v[130:131]
	global_load_lds_dwordx4 v[222:223], off
	ds_read_b128 v[214:217], v152 offset:22528
	ds_read_b128 v[218:221], v152 offset:23552
	s_mov_b32 m0, s19
	v_lshl_add_u64 v[222:223], s[46:47], 0, v[136:137]
	global_load_lds_dwordx4 v[222:223], off
	s_mov_b32 m0, s24
	s_nop 0
	global_load_lds_dwordx4 v[224:225], off
	s_waitcnt vmcnt(8) lgkmcnt(0)
	s_setprio 1
	s_barrier
	v_mfma_f32_16x16x32_bf16 v[62:65], v[154:157], v[186:189], v[62:65]
	v_mfma_f32_16x16x32_bf16 v[58:61], v[162:165], v[186:189], v[58:61]
	v_mfma_f32_16x16x32_bf16 v[46:49], v[154:157], v[194:197], v[46:49]
	v_mfma_f32_16x16x32_bf16 v[42:45], v[162:165], v[194:197], v[42:45]
	v_mfma_f32_16x16x32_bf16 v[30:33], v[154:157], v[206:209], v[30:33]
	v_mfma_f32_16x16x32_bf16 v[26:29], v[162:165], v[206:209], v[26:29]
	v_mfma_f32_16x16x32_bf16 v[14:17], v[154:157], v[214:217], v[14:17]
	v_mfma_f32_16x16x32_bf16 v[10:13], v[162:165], v[214:217], v[10:13]
	v_mfma_f32_16x16x32_bf16 v[62:65], v[158:161], v[190:193], v[62:65]
	v_mfma_f32_16x16x32_bf16 v[58:61], v[166:169], v[190:193], v[58:61]
	v_mfma_f32_16x16x32_bf16 v[46:49], v[158:161], v[198:201], v[46:49]
	v_mfma_f32_16x16x32_bf16 v[42:45], v[166:169], v[198:201], v[42:45]
	v_mfma_f32_16x16x32_bf16 v[30:33], v[158:161], v[210:213], v[30:33]
	v_mfma_f32_16x16x32_bf16 v[26:29], v[166:169], v[210:213], v[26:29]
	v_mfma_f32_16x16x32_bf16 v[14:17], v[158:161], v[218:221], v[14:17]
	v_mfma_f32_16x16x32_bf16 v[10:13], v[166:169], v[218:221], v[10:13]
	v_mfma_f32_16x16x32_bf16 v[54:57], v[170:173], v[186:189], v[54:57]
	v_mfma_f32_16x16x32_bf16 v[50:53], v[178:181], v[186:189], v[50:53]
	v_mfma_f32_16x16x32_bf16 v[38:41], v[170:173], v[194:197], v[38:41]
	v_mfma_f32_16x16x32_bf16 v[34:37], v[178:181], v[194:197], v[34:37]
	v_mfma_f32_16x16x32_bf16 v[22:25], v[170:173], v[206:209], v[22:25]
	v_mfma_f32_16x16x32_bf16 v[18:21], v[178:181], v[206:209], v[18:21]
	v_mfma_f32_16x16x32_bf16 v[6:9], v[170:173], v[214:217], v[6:9]
	v_mfma_f32_16x16x32_bf16 v[2:5], v[178:181], v[214:217], v[2:5]
	v_mfma_f32_16x16x32_bf16 v[54:57], v[174:177], v[190:193], v[54:57]
	v_mfma_f32_16x16x32_bf16 v[50:53], v[182:185], v[190:193], v[50:53]
	v_mfma_f32_16x16x32_bf16 v[38:41], v[174:177], v[198:201], v[38:41]
	v_mfma_f32_16x16x32_bf16 v[34:37], v[182:185], v[198:201], v[34:37]
	v_mfma_f32_16x16x32_bf16 v[22:25], v[174:177], v[210:213], v[22:25]
	v_mfma_f32_16x16x32_bf16 v[18:21], v[182:185], v[210:213], v[18:21]
	v_mfma_f32_16x16x32_bf16 v[6:9], v[174:177], v[218:221], v[6:9]
	v_mfma_f32_16x16x32_bf16 v[2:5], v[182:185], v[218:221], v[2:5]
	s_setprio 0
	s_barrier
	s_add_i32 s69, 0, 0x18000
	v_add_u32_e32 v153, s69, v149
	s_add_i32 s70, 0, 0x1c000
	ds_read_b128 v[154:157], v153
	ds_read_b128 v[158:161], v153 offset:1024
	ds_read_b128 v[162:165], v153 offset:2048
	ds_read_b128 v[166:169], v153 offset:3072
	v_add_u32_e32 v153, s70, v149
	ds_read_b128 v[170:173], v153
	ds_read_b128 v[174:177], v153 offset:1024
	ds_read_b128 v[178:181], v153 offset:2048
	ds_read_b128 v[182:185], v153 offset:3072
	s_add_u32 s46, s46, 0x40000
	s_addc_u32 s47, s47, 0
	s_mov_b32 m0, s25
	v_lshl_add_u64 v[226:227], s[46:47], 0, v[136:137]
	ds_read_b128 v[186:189], v152 offset:32768
	ds_read_b128 v[190:193], v152 offset:33792
	ds_read_b128 v[194:197], v152 offset:34816
	ds_read_b128 v[198:201], v152 offset:35840
	ds_read_b128 v[206:209], v152 offset:36864
	ds_read_b128 v[210:213], v152 offset:37888
	ds_read_b128 v[214:217], v152 offset:38912
	ds_read_b128 v[218:221], v152 offset:39936
	global_load_lds_dwordx4 v[226:227], off
	s_mov_b32 m0, s28
	v_lshl_add_u64 v[226:227], s[46:47], 0, v[132:133]
	global_load_lds_dwordx4 v[226:227], off
	s_waitcnt vmcnt(8) lgkmcnt(0)
	s_setprio 1
	s_barrier
	v_mfma_f32_16x16x32_bf16 v[126:129], v[154:157], v[186:189], v[126:129]
	v_mfma_f32_16x16x32_bf16 v[122:125], v[162:165], v[186:189], v[122:125]
	v_mfma_f32_16x16x32_bf16 v[110:113], v[154:157], v[194:197], v[110:113]
	v_mfma_f32_16x16x32_bf16 v[106:109], v[162:165], v[194:197], v[106:109]
	v_mfma_f32_16x16x32_bf16 v[94:97], v[154:157], v[206:209], v[94:97]
	v_mfma_f32_16x16x32_bf16 v[90:93], v[162:165], v[206:209], v[90:93]
	v_mfma_f32_16x16x32_bf16 v[78:81], v[154:157], v[214:217], v[78:81]
	v_mfma_f32_16x16x32_bf16 v[74:77], v[162:165], v[214:217], v[74:77]
	v_mfma_f32_16x16x32_bf16 v[126:129], v[158:161], v[190:193], v[126:129]
	v_mfma_f32_16x16x32_bf16 v[122:125], v[166:169], v[190:193], v[122:125]
	v_mfma_f32_16x16x32_bf16 v[110:113], v[158:161], v[198:201], v[110:113]
	v_mfma_f32_16x16x32_bf16 v[106:109], v[166:169], v[198:201], v[106:109]
	v_mfma_f32_16x16x32_bf16 v[94:97], v[158:161], v[210:213], v[94:97]
	v_mfma_f32_16x16x32_bf16 v[90:93], v[166:169], v[210:213], v[90:93]
	v_mfma_f32_16x16x32_bf16 v[78:81], v[158:161], v[218:221], v[78:81]
	v_mfma_f32_16x16x32_bf16 v[74:77], v[166:169], v[218:221], v[74:77]
	v_mfma_f32_16x16x32_bf16 v[118:121], v[170:173], v[186:189], v[118:121]
	v_mfma_f32_16x16x32_bf16 v[114:117], v[178:181], v[186:189], v[114:117]
	v_mfma_f32_16x16x32_bf16 v[102:105], v[170:173], v[194:197], v[102:105]
	v_mfma_f32_16x16x32_bf16 v[98:101], v[178:181], v[194:197], v[98:101]
	v_mfma_f32_16x16x32_bf16 v[86:89], v[170:173], v[206:209], v[86:89]
	v_mfma_f32_16x16x32_bf16 v[82:85], v[178:181], v[206:209], v[82:85]
	v_mfma_f32_16x16x32_bf16 v[70:73], v[170:173], v[214:217], v[70:73]
	v_mfma_f32_16x16x32_bf16 v[66:69], v[178:181], v[214:217], v[66:69]
	v_mfma_f32_16x16x32_bf16 v[118:121], v[174:177], v[190:193], v[118:121]
	v_mfma_f32_16x16x32_bf16 v[114:117], v[182:185], v[190:193], v[114:117]
	v_mfma_f32_16x16x32_bf16 v[102:105], v[174:177], v[198:201], v[102:105]
	v_mfma_f32_16x16x32_bf16 v[98:101], v[182:185], v[198:201], v[98:101]
	v_mfma_f32_16x16x32_bf16 v[86:89], v[174:177], v[210:213], v[86:89]
	v_mfma_f32_16x16x32_bf16 v[82:85], v[182:185], v[210:213], v[82:85]
	v_mfma_f32_16x16x32_bf16 v[70:73], v[174:177], v[218:221], v[70:73]
	v_mfma_f32_16x16x32_bf16 v[66:69], v[182:185], v[218:221], v[66:69]
	s_setprio 0
	s_barrier
	s_add_i32 s46, s69, s16
	s_mov_b32 m0, s46
	v_lshl_add_u64 v[146:147], v[146:147], 0, s[10:11]
	global_load_lds_dwordx4 v[146:147], off
	ds_read_b128 v[186:189], v152 offset:49152
	ds_read_b128 v[190:193], v152 offset:50176
	s_add_i32 m0, s46, 0x2000
	s_add_u32 s44, s44, 0x40080
	v_lshl_add_u64 v[146:147], v[202:203], 0, s[10:11]
	s_addc_u32 s45, s45, 0
	s_add_i32 s46, s70, s16
	global_load_lds_dwordx4 v[146:147], off
	ds_read_b128 v[194:197], v152 offset:51200
	ds_read_b128 v[198:201], v152 offset:52224
	s_mov_b32 m0, s46
	v_lshl_add_u64 v[146:147], s[44:45], 0, v[134:135]
	global_load_lds_dwordx4 v[146:147], off
	ds_read_b128 v[206:209], v152 offset:53248
	ds_read_b128 v[210:213], v152 offset:54272
	s_add_i32 m0, s46, 0x2000
	v_lshl_add_u64 v[146:147], s[44:45], 0, v[130:131]
	global_load_lds_dwordx4 v[146:147], off
	ds_read_b128 v[214:217], v152 offset:55296
	ds_read_b128 v[218:221], v152 offset:56320
	s_mov_b32 m0, s33
	v_lshl_add_u64 v[146:147], v[222:223], 0, s[10:11]
	global_load_lds_dwordx4 v[146:147], off
	s_mov_b32 m0, s35
	v_lshl_add_u64 v[146:147], v[224:225], 0, s[10:11]
	global_load_lds_dwordx4 v[146:147], off
	s_waitcnt vmcnt(8) lgkmcnt(0)
	s_setprio 1
	s_barrier
	v_mfma_f32_16x16x32_bf16 v[62:65], v[154:157], v[186:189], v[62:65]
	v_mfma_f32_16x16x32_bf16 v[58:61], v[162:165], v[186:189], v[58:61]
	v_mfma_f32_16x16x32_bf16 v[46:49], v[154:157], v[194:197], v[46:49]
	v_mfma_f32_16x16x32_bf16 v[42:45], v[162:165], v[194:197], v[42:45]
	v_mfma_f32_16x16x32_bf16 v[30:33], v[154:157], v[206:209], v[30:33]
	v_mfma_f32_16x16x32_bf16 v[26:29], v[162:165], v[206:209], v[26:29]
	v_mfma_f32_16x16x32_bf16 v[14:17], v[154:157], v[214:217], v[14:17]
	v_mfma_f32_16x16x32_bf16 v[10:13], v[162:165], v[214:217], v[10:13]
	v_mfma_f32_16x16x32_bf16 v[62:65], v[158:161], v[190:193], v[62:65]
	v_mfma_f32_16x16x32_bf16 v[58:61], v[166:169], v[190:193], v[58:61]
	v_mfma_f32_16x16x32_bf16 v[46:49], v[158:161], v[198:201], v[46:49]
	v_mfma_f32_16x16x32_bf16 v[42:45], v[166:169], v[198:201], v[42:45]
	v_mfma_f32_16x16x32_bf16 v[30:33], v[158:161], v[210:213], v[30:33]
	v_mfma_f32_16x16x32_bf16 v[26:29], v[166:169], v[210:213], v[26:29]
	v_mfma_f32_16x16x32_bf16 v[14:17], v[158:161], v[218:221], v[14:17]
	v_mfma_f32_16x16x32_bf16 v[10:13], v[166:169], v[218:221], v[10:13]
	v_mfma_f32_16x16x32_bf16 v[54:57], v[170:173], v[186:189], v[54:57]
	v_mfma_f32_16x16x32_bf16 v[50:53], v[178:181], v[186:189], v[50:53]
	v_mfma_f32_16x16x32_bf16 v[38:41], v[170:173], v[194:197], v[38:41]
	v_mfma_f32_16x16x32_bf16 v[34:37], v[178:181], v[194:197], v[34:37]
	v_mfma_f32_16x16x32_bf16 v[22:25], v[170:173], v[206:209], v[22:25]
	v_mfma_f32_16x16x32_bf16 v[18:21], v[178:181], v[206:209], v[18:21]
	v_mfma_f32_16x16x32_bf16 v[6:9], v[170:173], v[214:217], v[6:9]
	v_mfma_f32_16x16x32_bf16 v[2:5], v[178:181], v[214:217], v[2:5]
	v_mfma_f32_16x16x32_bf16 v[54:57], v[174:177], v[190:193], v[54:57]
	v_mfma_f32_16x16x32_bf16 v[50:53], v[182:185], v[190:193], v[50:53]
	v_mfma_f32_16x16x32_bf16 v[38:41], v[174:177], v[198:201], v[38:41]
	v_mfma_f32_16x16x32_bf16 v[34:37], v[182:185], v[198:201], v[34:37]
	v_mfma_f32_16x16x32_bf16 v[22:25], v[174:177], v[210:213], v[22:25]
	v_mfma_f32_16x16x32_bf16 v[18:21], v[182:185], v[210:213], v[18:21]
	v_mfma_f32_16x16x32_bf16 v[6:9], v[174:177], v[218:221], v[6:9]
	v_mfma_f32_16x16x32_bf16 v[2:5], v[182:185], v[218:221], v[2:5]
	s_setprio 0
	s_barrier
	s_add_i32 s68, s68, 2
	s_add_u32 s42, s42, 0x100
	s_addc_u32 s43, s43, 0
	s_add_u32 s66, s66, 0x100
	s_addc_u32 s67, s67, 0
	s_cmp_gt_u32 s68, 13
	s_cbranch_scc0 .LBB0_745
	s_and_b64 vcc, exec, s[12:13]
	s_cbranch_vccz .LBB0_748
	s_barrier

.LBB0_833:
	s_add_u32 s72, s0, s68
	s_addc_u32 s73, s1, s69
	s_and_b64 s[62:63], s[70:71], exec
	s_cselect_b32 s15, s73, s77
	s_cselect_b32 s33, s72, s76
	s_add_u32 s74, s35, s66
	s_addc_u32 s75, s85, s67
	s_and_b64 s[62:63], s[70:71], exec
	s_cselect_b32 s34, s75, s79
	s_cselect_b32 s39, s74, s78
	s_add_i32 s45, s7, -2
	s_add_u32 s76, s76, 0x100080
	s_addc_u32 s77, s77, 0
	s_add_u32 s47, s78, 0x100
	s_addc_u32 s62, s79, 0
	s_mov_b32 s63, 0
	s_waitcnt vmcnt(0)
	ds_read_b128 v[114:117], v190
	ds_read_b128 v[118:121], v190 offset:1024
	ds_read_b128 v[122:125], v190 offset:2048
	ds_read_b128 v[126:129], v190 offset:3072
	ds_read_b128 v[146:149], v191
	ds_read_b128 v[150:153], v191 offset:1024
	ds_read_b128 v[154:157], v191 offset:2048
	ds_read_b128 v[158:161], v191 offset:3072
	s_add_i32 s82, s63, 2
	s_add_u32 s78, s76, 0xfff00080
	s_addc_u32 s79, s77, -1
	s_cmp_eq_u32 s45, s63
	s_cselect_b32 s81, s15, s79
	s_cselect_b32 s80, s33, s78
	s_cselect_b32 s79, s34, s62
	s_cselect_b32 s78, s39, s47
	v_lshl_add_u64 v[186:187], s[76:77], 0, v[180:181]
	s_add_i32 m0, s87, 0xc000
	ds_read_b128 v[162:165], v192
	ds_read_b128 v[166:169], v192 offset:1024
	ds_read_b128 v[194:197], v192 offset:2048
	ds_read_b128 v[198:201], v192 offset:3072
	ds_read_b128 v[206:209], v192 offset:4096
	ds_read_b128 v[210:213], v192 offset:5120
	ds_read_b128 v[214:217], v192 offset:6144
	ds_read_b128 v[218:221], v192 offset:7168
	global_load_lds_dwordx4 v[186:187], off
	s_add_i32 m0, s87, 0xe000
	v_lshl_add_u64 v[186:187], s[76:77], 0, v[182:183]
	global_load_lds_dwordx4 v[186:187], off
	s_waitcnt vmcnt(8) lgkmcnt(0)
	s_setprio 1
	s_barrier
	v_mfma_f32_16x16x32_bf16 v[142:145], v[114:117], v[162:165], 0
	v_mfma_f32_16x16x32_bf16 v[138:141], v[122:125], v[162:165], 0
	v_mfma_f32_16x16x32_bf16 v[110:113], v[114:117], v[194:197], 0
	v_mfma_f32_16x16x32_bf16 v[106:109], v[122:125], v[194:197], 0
	v_mfma_f32_16x16x32_bf16 v[98:101], v[114:117], v[206:209], 0
	v_mfma_f32_16x16x32_bf16 v[90:93], v[122:125], v[206:209], 0
	v_mfma_f32_16x16x32_bf16 v[82:85], v[114:117], v[214:217], 0
	v_mfma_f32_16x16x32_bf16 v[74:77], v[122:125], v[214:217], 0
	v_mfma_f32_16x16x32_bf16 v[142:145], v[118:121], v[166:169], v[142:145]
	v_mfma_f32_16x16x32_bf16 v[138:141], v[126:129], v[166:169], v[138:141]
	v_mfma_f32_16x16x32_bf16 v[110:113], v[118:121], v[198:201], v[110:113]
	v_mfma_f32_16x16x32_bf16 v[106:109], v[126:129], v[198:201], v[106:109]
	v_mfma_f32_16x16x32_bf16 v[98:101], v[118:121], v[210:213], v[98:101]
	v_mfma_f32_16x16x32_bf16 v[90:93], v[126:129], v[210:213], v[90:93]
	v_mfma_f32_16x16x32_bf16 v[82:85], v[118:121], v[218:221], v[82:85]
	v_mfma_f32_16x16x32_bf16 v[74:77], v[126:129], v[218:221], v[74:77]
	v_mfma_f32_16x16x32_bf16 v[134:137], v[146:149], v[162:165], 0
	v_mfma_f32_16x16x32_bf16 v[130:133], v[154:157], v[162:165], 0
	v_mfma_f32_16x16x32_bf16 v[102:105], v[146:149], v[194:197], 0
	v_mfma_f32_16x16x32_bf16 v[94:97], v[154:157], v[194:197], 0
	v_mfma_f32_16x16x32_bf16 v[86:89], v[146:149], v[206:209], 0
	v_mfma_f32_16x16x32_bf16 v[78:81], v[154:157], v[206:209], 0
	v_mfma_f32_16x16x32_bf16 v[70:73], v[146:149], v[214:217], 0
	v_mfma_f32_16x16x32_bf16 v[66:69], v[154:157], v[214:217], 0
	v_mfma_f32_16x16x32_bf16 v[134:137], v[150:153], v[166:169], v[134:137]
	v_mfma_f32_16x16x32_bf16 v[130:133], v[158:161], v[166:169], v[130:133]
	v_mfma_f32_16x16x32_bf16 v[102:105], v[150:153], v[198:201], v[102:105]
	v_mfma_f32_16x16x32_bf16 v[94:97], v[158:161], v[198:201], v[94:97]
	v_mfma_f32_16x16x32_bf16 v[86:89], v[150:153], v[210:213], v[86:89]
	v_mfma_f32_16x16x32_bf16 v[78:81], v[158:161], v[210:213], v[78:81]
	v_mfma_f32_16x16x32_bf16 v[70:73], v[150:153], v[218:221], v[70:73]
	v_mfma_f32_16x16x32_bf16 v[66:69], v[158:161], v[218:221], v[66:69]
	s_setprio 0
	s_barrier
	s_add_i32 s63, s24, s86
	s_mov_b32 m0, s63
	v_lshl_add_u64 v[186:187], s[78:79], 0, v[172:173]
	global_load_lds_dwordx4 v[186:187], off
	ds_read_b128 v[162:165], v192 offset:16384
	ds_read_b128 v[166:169], v192 offset:17408
	s_add_i32 m0, s63, 0x2000
	s_add_u32 vcc_lo, s78, 0x100000
	v_lshl_add_u64 v[202:203], s[78:79], 0, v[176:177]
	s_addc_u32 vcc_hi, s79, 0
	s_add_i32 s63, s25, s86
	global_load_lds_dwordx4 v[202:203], off
	ds_read_b128 v[194:197], v192 offset:18432
	ds_read_b128 v[198:201], v192 offset:19456
	v_lshl_add_u64 v[222:223], vcc, 0, v[172:173]
	s_mov_b32 m0, s63
	v_lshl_add_u64 v[224:225], s[80:81], 0, v[174:175]
	global_load_lds_dwordx4 v[222:223], off
	ds_read_b128 v[206:209], v192 offset:20480
	ds_read_b128 v[210:213], v192 offset:21504
	s_add_i32 m0, s63, 0x2000
	v_lshl_add_u64 v[222:223], vcc, 0, v[176:177]
	global_load_lds_dwordx4 v[222:223], off
	ds_read_b128 v[214:217], v192 offset:22528
	ds_read_b128 v[218:221], v192 offset:23552
	s_mov_b32 m0, s87
	v_lshl_add_u64 v[222:223], s[80:81], 0, v[170:171]
	global_load_lds_dwordx4 v[222:223], off
	s_mov_b32 m0, s88
	s_nop 0
	global_load_lds_dwordx4 v[224:225], off
	s_waitcnt vmcnt(8) lgkmcnt(0)
	s_setprio 1
	s_barrier
	v_mfma_f32_16x16x32_bf16 v[62:65], v[114:117], v[162:165], 0
	v_mfma_f32_16x16x32_bf16 v[58:61], v[122:125], v[162:165], 0
	v_mfma_f32_16x16x32_bf16 v[50:53], v[114:117], v[194:197], 0
	v_mfma_f32_16x16x32_bf16 v[42:45], v[122:125], v[194:197], 0
	v_mfma_f32_16x16x32_bf16 v[34:37], v[114:117], v[206:209], 0
	v_mfma_f32_16x16x32_bf16 v[26:29], v[122:125], v[206:209], 0
	v_mfma_f32_16x16x32_bf16 v[18:21], v[114:117], v[214:217], 0
	v_mfma_f32_16x16x32_bf16 v[10:13], v[122:125], v[214:217], 0
	v_mfma_f32_16x16x32_bf16 v[62:65], v[118:121], v[166:169], v[62:65]
	v_mfma_f32_16x16x32_bf16 v[58:61], v[126:129], v[166:169], v[58:61]
	v_mfma_f32_16x16x32_bf16 v[50:53], v[118:121], v[198:201], v[50:53]
	v_mfma_f32_16x16x32_bf16 v[42:45], v[126:129], v[198:201], v[42:45]
	v_mfma_f32_16x16x32_bf16 v[34:37], v[118:121], v[210:213], v[34:37]
	v_mfma_f32_16x16x32_bf16 v[26:29], v[126:129], v[210:213], v[26:29]
	v_mfma_f32_16x16x32_bf16 v[18:21], v[118:121], v[218:221], v[18:21]
	v_mfma_f32_16x16x32_bf16 v[10:13], v[126:129], v[218:221], v[10:13]
	v_mfma_f32_16x16x32_bf16 v[54:57], v[146:149], v[162:165], 0
	v_mfma_f32_16x16x32_bf16 v[46:49], v[154:157], v[162:165], 0
	v_mfma_f32_16x16x32_bf16 v[38:41], v[146:149], v[194:197], 0
	v_mfma_f32_16x16x32_bf16 v[30:33], v[154:157], v[194:197], 0
	v_mfma_f32_16x16x32_bf16 v[22:25], v[146:149], v[206:209], 0
	v_mfma_f32_16x16x32_bf16 v[14:17], v[154:157], v[206:209], 0
	v_mfma_f32_16x16x32_bf16 v[6:9], v[146:149], v[214:217], 0
	v_mfma_f32_16x16x32_bf16 v[2:5], v[154:157], v[214:217], 0
	v_mfma_f32_16x16x32_bf16 v[54:57], v[150:153], v[166:169], v[54:57]
	v_mfma_f32_16x16x32_bf16 v[46:49], v[158:161], v[166:169], v[46:49]
	v_mfma_f32_16x16x32_bf16 v[38:41], v[150:153], v[198:201], v[38:41]
	v_mfma_f32_16x16x32_bf16 v[30:33], v[158:161], v[198:201], v[30:33]
	v_mfma_f32_16x16x32_bf16 v[22:25], v[150:153], v[210:213], v[22:25]
	v_mfma_f32_16x16x32_bf16 v[14:17], v[158:161], v[210:213], v[14:17]
	v_mfma_f32_16x16x32_bf16 v[6:9], v[150:153], v[218:221], v[6:9]
	v_mfma_f32_16x16x32_bf16 v[2:5], v[158:161], v[218:221], v[2:5]
	s_setprio 0
	s_barrier
	s_add_i32 s63, 0, 0x18000
	s_add_i32 s83, 0, 0x1c000
	v_add_u32_e32 v126, s63, v189
	v_add_u32_e32 v158, s83, v189
	ds_read_b128 v[114:117], v126
	ds_read_b128 v[118:121], v126 offset:1024
	ds_read_b128 v[122:125], v126 offset:2048
	ds_read_b128 v[126:129], v126 offset:3072
	ds_read_b128 v[146:149], v158
	ds_read_b128 v[150:153], v158 offset:1024
	ds_read_b128 v[154:157], v158 offset:2048
	ds_read_b128 v[158:161], v158 offset:3072
	s_add_u32 s80, s80, 0x100000
	s_addc_u32 s81, s81, 0
	s_mov_b32 m0, s89
	v_lshl_add_u64 v[226:227], s[80:81], 0, v[170:171]
	ds_read_b128 v[162:165], v192 offset:32768
	ds_read_b128 v[166:169], v192 offset:33792
	ds_read_b128 v[194:197], v192 offset:34816
	ds_read_b128 v[198:201], v192 offset:35840
	ds_read_b128 v[206:209], v192 offset:36864
	ds_read_b128 v[210:213], v192 offset:37888
	ds_read_b128 v[214:217], v192 offset:38912
	ds_read_b128 v[218:221], v192 offset:39936
	global_load_lds_dwordx4 v[226:227], off
	s_mov_b32 m0, s90
	v_lshl_add_u64 v[226:227], s[80:81], 0, v[174:175]
	global_load_lds_dwordx4 v[226:227], off
	s_waitcnt vmcnt(8) lgkmcnt(0)
	s_setprio 1
	s_barrier
	v_mfma_f32_16x16x32_bf16 v[142:145], v[114:117], v[162:165], v[142:145]
	v_mfma_f32_16x16x32_bf16 v[138:141], v[122:125], v[162:165], v[138:141]
	v_mfma_f32_16x16x32_bf16 v[110:113], v[114:117], v[194:197], v[110:113]
	v_mfma_f32_16x16x32_bf16 v[106:109], v[122:125], v[194:197], v[106:109]
	v_mfma_f32_16x16x32_bf16 v[98:101], v[114:117], v[206:209], v[98:101]
	v_mfma_f32_16x16x32_bf16 v[90:93], v[122:125], v[206:209], v[90:93]
	v_mfma_f32_16x16x32_bf16 v[82:85], v[114:117], v[214:217], v[82:85]
	v_mfma_f32_16x16x32_bf16 v[74:77], v[122:125], v[214:217], v[74:77]
	v_mfma_f32_16x16x32_bf16 v[142:145], v[118:121], v[166:169], v[142:145]
	v_mfma_f32_16x16x32_bf16 v[138:141], v[126:129], v[166:169], v[138:141]
	v_mfma_f32_16x16x32_bf16 v[110:113], v[118:121], v[198:201], v[110:113]
	v_mfma_f32_16x16x32_bf16 v[106:109], v[126:129], v[198:201], v[106:109]
	v_mfma_f32_16x16x32_bf16 v[98:101], v[118:121], v[210:213], v[98:101]
	v_mfma_f32_16x16x32_bf16 v[90:93], v[126:129], v[210:213], v[90:93]
	v_mfma_f32_16x16x32_bf16 v[82:85], v[118:121], v[218:221], v[82:85]
	v_mfma_f32_16x16x32_bf16 v[74:77], v[126:129], v[218:221], v[74:77]
	v_mfma_f32_16x16x32_bf16 v[134:137], v[146:149], v[162:165], v[134:137]
	v_mfma_f32_16x16x32_bf16 v[130:133], v[154:157], v[162:165], v[130:133]
	v_mfma_f32_16x16x32_bf16 v[102:105], v[146:149], v[194:197], v[102:105]
	v_mfma_f32_16x16x32_bf16 v[94:97], v[154:157], v[194:197], v[94:97]
	v_mfma_f32_16x16x32_bf16 v[86:89], v[146:149], v[206:209], v[86:89]
	v_mfma_f32_16x16x32_bf16 v[78:81], v[154:157], v[206:209], v[78:81]
	v_mfma_f32_16x16x32_bf16 v[70:73], v[146:149], v[214:217], v[70:73]
	v_mfma_f32_16x16x32_bf16 v[66:69], v[154:157], v[214:217], v[66:69]
	v_mfma_f32_16x16x32_bf16 v[134:137], v[150:153], v[166:169], v[134:137]
	v_mfma_f32_16x16x32_bf16 v[130:133], v[158:161], v[166:169], v[130:133]
	v_mfma_f32_16x16x32_bf16 v[102:105], v[150:153], v[198:201], v[102:105]
	v_mfma_f32_16x16x32_bf16 v[94:97], v[158:161], v[198:201], v[94:97]
	v_mfma_f32_16x16x32_bf16 v[86:89], v[150:153], v[210:213], v[86:89]
	v_mfma_f32_16x16x32_bf16 v[78:81], v[158:161], v[210:213], v[78:81]
	v_mfma_f32_16x16x32_bf16 v[70:73], v[150:153], v[218:221], v[70:73]
	v_mfma_f32_16x16x32_bf16 v[66:69], v[158:161], v[218:221], v[66:69]
	s_setprio 0
	s_barrier
	s_add_i32 s63, s63, s86
	s_mov_b32 m0, s63
	v_lshl_add_u64 v[186:187], v[186:187], 0, s[22:23]
	global_load_lds_dwordx4 v[186:187], off
	ds_read_b128 v[162:165], v192 offset:49152
	ds_read_b128 v[166:169], v192 offset:50176
	s_add_i32 m0, s63, 0x2000
	s_add_u32 s78, s78, 0x100080
	v_lshl_add_u64 v[186:187], v[202:203], 0, s[22:23]
	s_addc_u32 s79, s79, 0
	s_add_i32 s63, s83, s86
	global_load_lds_dwordx4 v[186:187], off
	ds_read_b128 v[194:197], v192 offset:51200
	ds_read_b128 v[198:201], v192 offset:52224
	s_mov_b32 m0, s63
	v_lshl_add_u64 v[186:187], s[78:79], 0, v[172:173]
	global_load_lds_dwordx4 v[186:187], off
	ds_read_b128 v[206:209], v192 offset:53248
	ds_read_b128 v[210:213], v192 offset:54272
	s_add_i32 m0, s63, 0x2000
	v_lshl_add_u64 v[186:187], s[78:79], 0, v[176:177]
	global_load_lds_dwordx4 v[186:187], off
	ds_read_b128 v[214:217], v192 offset:55296
	ds_read_b128 v[218:221], v192 offset:56320
	s_mov_b32 m0, s95
	v_lshl_add_u64 v[186:187], v[222:223], 0, s[22:23]
	global_load_lds_dwordx4 v[186:187], off
	s_mov_b32 m0, s96
	v_lshl_add_u64 v[186:187], v[224:225], 0, s[22:23]
	global_load_lds_dwordx4 v[186:187], off
	s_waitcnt vmcnt(8) lgkmcnt(0)
	s_setprio 1
	s_barrier
	v_mfma_f32_16x16x32_bf16 v[62:65], v[114:117], v[162:165], v[62:65]
	v_mfma_f32_16x16x32_bf16 v[58:61], v[122:125], v[162:165], v[58:61]
	v_mfma_f32_16x16x32_bf16 v[50:53], v[114:117], v[194:197], v[50:53]
	v_mfma_f32_16x16x32_bf16 v[42:45], v[122:125], v[194:197], v[42:45]
	v_mfma_f32_16x16x32_bf16 v[34:37], v[114:117], v[206:209], v[34:37]
	v_mfma_f32_16x16x32_bf16 v[26:29], v[122:125], v[206:209], v[26:29]
	v_mfma_f32_16x16x32_bf16 v[18:21], v[114:117], v[214:217], v[18:21]
	v_mfma_f32_16x16x32_bf16 v[10:13], v[122:125], v[214:217], v[10:13]
	v_mfma_f32_16x16x32_bf16 v[62:65], v[118:121], v[166:169], v[62:65]
	v_mfma_f32_16x16x32_bf16 v[58:61], v[126:129], v[166:169], v[58:61]
	v_mfma_f32_16x16x32_bf16 v[50:53], v[118:121], v[198:201], v[50:53]
	v_mfma_f32_16x16x32_bf16 v[42:45], v[126:129], v[198:201], v[42:45]
	v_mfma_f32_16x16x32_bf16 v[34:37], v[118:121], v[210:213], v[34:37]
	v_mfma_f32_16x16x32_bf16 v[26:29], v[126:129], v[210:213], v[26:29]
	v_mfma_f32_16x16x32_bf16 v[18:21], v[118:121], v[218:221], v[18:21]
	v_mfma_f32_16x16x32_bf16 v[10:13], v[126:129], v[218:221], v[10:13]
	v_mfma_f32_16x16x32_bf16 v[54:57], v[146:149], v[162:165], v[54:57]
	v_mfma_f32_16x16x32_bf16 v[46:49], v[154:157], v[162:165], v[46:49]
	v_mfma_f32_16x16x32_bf16 v[38:41], v[146:149], v[194:197], v[38:41]
	v_mfma_f32_16x16x32_bf16 v[30:33], v[154:157], v[194:197], v[30:33]
	v_mfma_f32_16x16x32_bf16 v[22:25], v[146:149], v[206:209], v[22:25]
	v_mfma_f32_16x16x32_bf16 v[14:17], v[154:157], v[206:209], v[14:17]
	v_mfma_f32_16x16x32_bf16 v[6:9], v[146:149], v[214:217], v[6:9]
	v_mfma_f32_16x16x32_bf16 v[2:5], v[154:157], v[214:217], v[2:5]
	v_mfma_f32_16x16x32_bf16 v[54:57], v[150:153], v[166:169], v[54:57]
	v_mfma_f32_16x16x32_bf16 v[46:49], v[158:161], v[166:169], v[46:49]
	v_mfma_f32_16x16x32_bf16 v[38:41], v[150:153], v[198:201], v[38:41]
	v_mfma_f32_16x16x32_bf16 v[30:33], v[158:161], v[198:201], v[30:33]
	v_mfma_f32_16x16x32_bf16 v[22:25], v[150:153], v[210:213], v[22:25]
	v_mfma_f32_16x16x32_bf16 v[14:17], v[158:161], v[210:213], v[14:17]
	v_mfma_f32_16x16x32_bf16 v[6:9], v[150:153], v[218:221], v[6:9]
	v_mfma_f32_16x16x32_bf16 v[2:5], v[158:161], v[218:221], v[2:5]
	s_setprio 0
	s_barrier
	s_add_u32 s76, s76, 0x100
	s_addc_u32 s77, s77, 0
	s_add_u32 s47, s47, 0x100
	s_addc_u32 s62, s62, 0
	s_cmp_ge_i32 s82, s7
	s_mov_b32 s63, s82
.LBB0_834:
	ds_read_b128 v[114:117], v190
	ds_read_b128 v[118:121], v190 offset:1024
	ds_read_b128 v[122:125], v190 offset:2048
	ds_read_b128 v[126:129], v190 offset:3072
	ds_read_b128 v[146:149], v191
	ds_read_b128 v[150:153], v191 offset:1024
	ds_read_b128 v[154:157], v191 offset:2048
	ds_read_b128 v[158:161], v191 offset:3072
	s_add_i32 s82, s63, 2
	s_add_u32 s78, s76, 0xfff00080
	s_addc_u32 s79, s77, -1
	s_cmp_eq_u32 s45, s63
	s_cselect_b32 s81, s15, s79
	s_cselect_b32 s80, s33, s78
	s_cselect_b32 s79, s34, s62
	s_cselect_b32 s78, s39, s47
	v_lshl_add_u64 v[186:187], s[76:77], 0, v[180:181]
	s_add_i32 m0, s87, 0xc000
	ds_read_b128 v[162:165], v192
	ds_read_b128 v[166:169], v192 offset:1024
	ds_read_b128 v[194:197], v192 offset:2048
	ds_read_b128 v[198:201], v192 offset:3072
	ds_read_b128 v[206:209], v192 offset:4096
	ds_read_b128 v[210:213], v192 offset:5120
	ds_read_b128 v[214:217], v192 offset:6144
	ds_read_b128 v[218:221], v192 offset:7168
	global_load_lds_dwordx4 v[186:187], off
	s_add_i32 m0, s87, 0xe000
	v_lshl_add_u64 v[186:187], s[76:77], 0, v[182:183]
	global_load_lds_dwordx4 v[186:187], off
	s_waitcnt vmcnt(8) lgkmcnt(0)
	s_setprio 1
	s_barrier
	v_mfma_f32_16x16x32_bf16 v[142:145], v[114:117], v[162:165], v[142:145]
	v_mfma_f32_16x16x32_bf16 v[138:141], v[122:125], v[162:165], v[138:141]
	v_mfma_f32_16x16x32_bf16 v[110:113], v[114:117], v[194:197], v[110:113]
	v_mfma_f32_16x16x32_bf16 v[106:109], v[122:125], v[194:197], v[106:109]
	v_mfma_f32_16x16x32_bf16 v[98:101], v[114:117], v[206:209], v[98:101]
	v_mfma_f32_16x16x32_bf16 v[90:93], v[122:125], v[206:209], v[90:93]
	v_mfma_f32_16x16x32_bf16 v[82:85], v[114:117], v[214:217], v[82:85]
	v_mfma_f32_16x16x32_bf16 v[74:77], v[122:125], v[214:217], v[74:77]
	v_mfma_f32_16x16x32_bf16 v[142:145], v[118:121], v[166:169], v[142:145]
	v_mfma_f32_16x16x32_bf16 v[138:141], v[126:129], v[166:169], v[138:141]
	v_mfma_f32_16x16x32_bf16 v[110:113], v[118:121], v[198:201], v[110:113]
	v_mfma_f32_16x16x32_bf16 v[106:109], v[126:129], v[198:201], v[106:109]
	v_mfma_f32_16x16x32_bf16 v[98:101], v[118:121], v[210:213], v[98:101]
	v_mfma_f32_16x16x32_bf16 v[90:93], v[126:129], v[210:213], v[90:93]
	v_mfma_f32_16x16x32_bf16 v[82:85], v[118:121], v[218:221], v[82:85]
	v_mfma_f32_16x16x32_bf16 v[74:77], v[126:129], v[218:221], v[74:77]
	v_mfma_f32_16x16x32_bf16 v[134:137], v[146:149], v[162:165], v[134:137]
	v_mfma_f32_16x16x32_bf16 v[130:133], v[154:157], v[162:165], v[130:133]
	v_mfma_f32_16x16x32_bf16 v[102:105], v[146:149], v[194:197], v[102:105]
	v_mfma_f32_16x16x32_bf16 v[94:97], v[154:157], v[194:197], v[94:97]
	v_mfma_f32_16x16x32_bf16 v[86:89], v[146:149], v[206:209], v[86:89]
	v_mfma_f32_16x16x32_bf16 v[78:81], v[154:157], v[206:209], v[78:81]
	v_mfma_f32_16x16x32_bf16 v[70:73], v[146:149], v[214:217], v[70:73]
	v_mfma_f32_16x16x32_bf16 v[66:69], v[154:157], v[214:217], v[66:69]
	v_mfma_f32_16x16x32_bf16 v[134:137], v[150:153], v[166:169], v[134:137]
	v_mfma_f32_16x16x32_bf16 v[130:133], v[158:161], v[166:169], v[130:133]
	v_mfma_f32_16x16x32_bf16 v[102:105], v[150:153], v[198:201], v[102:105]
	v_mfma_f32_16x16x32_bf16 v[94:97], v[158:161], v[198:201], v[94:97]
	v_mfma_f32_16x16x32_bf16 v[86:89], v[150:153], v[210:213], v[86:89]
	v_mfma_f32_16x16x32_bf16 v[78:81], v[158:161], v[210:213], v[78:81]
	v_mfma_f32_16x16x32_bf16 v[70:73], v[150:153], v[218:221], v[70:73]
	v_mfma_f32_16x16x32_bf16 v[66:69], v[158:161], v[218:221], v[66:69]
	s_setprio 0
	s_barrier
	s_add_i32 s63, s24, s86
	s_mov_b32 m0, s63
	v_lshl_add_u64 v[186:187], s[78:79], 0, v[172:173]
	global_load_lds_dwordx4 v[186:187], off
	ds_read_b128 v[162:165], v192 offset:16384
	ds_read_b128 v[166:169], v192 offset:17408
	s_add_i32 m0, s63, 0x2000
	s_add_u32 vcc_lo, s78, 0x100000
	v_lshl_add_u64 v[202:203], s[78:79], 0, v[176:177]
	s_addc_u32 vcc_hi, s79, 0
	s_add_i32 s63, s25, s86
	global_load_lds_dwordx4 v[202:203], off
	ds_read_b128 v[194:197], v192 offset:18432
	ds_read_b128 v[198:201], v192 offset:19456
	v_lshl_add_u64 v[222:223], vcc, 0, v[172:173]
	s_mov_b32 m0, s63
	v_lshl_add_u64 v[224:225], s[80:81], 0, v[174:175]
	global_load_lds_dwordx4 v[222:223], off
	ds_read_b128 v[206:209], v192 offset:20480
	ds_read_b128 v[210:213], v192 offset:21504
	s_add_i32 m0, s63, 0x2000
	v_lshl_add_u64 v[222:223], vcc, 0, v[176:177]
	global_load_lds_dwordx4 v[222:223], off
	ds_read_b128 v[214:217], v192 offset:22528
	ds_read_b128 v[218:221], v192 offset:23552
	s_mov_b32 m0, s87
	v_lshl_add_u64 v[222:223], s[80:81], 0, v[170:171]
	global_load_lds_dwordx4 v[222:223], off
	s_mov_b32 m0, s88
	s_nop 0
	global_load_lds_dwordx4 v[224:225], off
	s_waitcnt vmcnt(8) lgkmcnt(0)
	s_setprio 1
	s_barrier
	v_mfma_f32_16x16x32_bf16 v[62:65], v[114:117], v[162:165], v[62:65]
	v_mfma_f32_16x16x32_bf16 v[58:61], v[122:125], v[162:165], v[58:61]
	v_mfma_f32_16x16x32_bf16 v[50:53], v[114:117], v[194:197], v[50:53]
	v_mfma_f32_16x16x32_bf16 v[42:45], v[122:125], v[194:197], v[42:45]
	v_mfma_f32_16x16x32_bf16 v[34:37], v[114:117], v[206:209], v[34:37]
	v_mfma_f32_16x16x32_bf16 v[26:29], v[122:125], v[206:209], v[26:29]
	v_mfma_f32_16x16x32_bf16 v[18:21], v[114:117], v[214:217], v[18:21]
	v_mfma_f32_16x16x32_bf16 v[10:13], v[122:125], v[214:217], v[10:13]
	v_mfma_f32_16x16x32_bf16 v[62:65], v[118:121], v[166:169], v[62:65]
	v_mfma_f32_16x16x32_bf16 v[58:61], v[126:129], v[166:169], v[58:61]
	v_mfma_f32_16x16x32_bf16 v[50:53], v[118:121], v[198:201], v[50:53]
	v_mfma_f32_16x16x32_bf16 v[42:45], v[126:129], v[198:201], v[42:45]
	v_mfma_f32_16x16x32_bf16 v[34:37], v[118:121], v[210:213], v[34:37]
	v_mfma_f32_16x16x32_bf16 v[26:29], v[126:129], v[210:213], v[26:29]
	v_mfma_f32_16x16x32_bf16 v[18:21], v[118:121], v[218:221], v[18:21]
	v_mfma_f32_16x16x32_bf16 v[10:13], v[126:129], v[218:221], v[10:13]
	v_mfma_f32_16x16x32_bf16 v[54:57], v[146:149], v[162:165], v[54:57]
	v_mfma_f32_16x16x32_bf16 v[46:49], v[154:157], v[162:165], v[46:49]
	v_mfma_f32_16x16x32_bf16 v[38:41], v[146:149], v[194:197], v[38:41]
	v_mfma_f32_16x16x32_bf16 v[30:33], v[154:157], v[194:197], v[30:33]
	v_mfma_f32_16x16x32_bf16 v[22:25], v[146:149], v[206:209], v[22:25]
	v_mfma_f32_16x16x32_bf16 v[14:17], v[154:157], v[206:209], v[14:17]
	v_mfma_f32_16x16x32_bf16 v[6:9], v[146:149], v[214:217], v[6:9]
	v_mfma_f32_16x16x32_bf16 v[2:5], v[154:157], v[214:217], v[2:5]
	v_mfma_f32_16x16x32_bf16 v[54:57], v[150:153], v[166:169], v[54:57]
	v_mfma_f32_16x16x32_bf16 v[46:49], v[158:161], v[166:169], v[46:49]
	v_mfma_f32_16x16x32_bf16 v[38:41], v[150:153], v[198:201], v[38:41]
	v_mfma_f32_16x16x32_bf16 v[30:33], v[158:161], v[198:201], v[30:33]
	v_mfma_f32_16x16x32_bf16 v[22:25], v[150:153], v[210:213], v[22:25]
	v_mfma_f32_16x16x32_bf16 v[14:17], v[158:161], v[210:213], v[14:17]
	v_mfma_f32_16x16x32_bf16 v[6:9], v[150:153], v[218:221], v[6:9]
	v_mfma_f32_16x16x32_bf16 v[2:5], v[158:161], v[218:221], v[2:5]
	s_setprio 0
	s_barrier
	s_add_i32 s63, 0, 0x18000
	s_add_i32 s83, 0, 0x1c000
	v_add_u32_e32 v126, s63, v189
	v_add_u32_e32 v158, s83, v189
	ds_read_b128 v[114:117], v126
	ds_read_b128 v[118:121], v126 offset:1024
	ds_read_b128 v[122:125], v126 offset:2048
	ds_read_b128 v[126:129], v126 offset:3072
	ds_read_b128 v[146:149], v158
	ds_read_b128 v[150:153], v158 offset:1024
	ds_read_b128 v[154:157], v158 offset:2048
	ds_read_b128 v[158:161], v158 offset:3072
	s_add_u32 s80, s80, 0x100000
	s_addc_u32 s81, s81, 0
	s_mov_b32 m0, s89
	v_lshl_add_u64 v[226:227], s[80:81], 0, v[170:171]
	ds_read_b128 v[162:165], v192 offset:32768
	ds_read_b128 v[166:169], v192 offset:33792
	ds_read_b128 v[194:197], v192 offset:34816
	ds_read_b128 v[198:201], v192 offset:35840
	ds_read_b128 v[206:209], v192 offset:36864
	ds_read_b128 v[210:213], v192 offset:37888
	ds_read_b128 v[214:217], v192 offset:38912
	ds_read_b128 v[218:221], v192 offset:39936
	global_load_lds_dwordx4 v[226:227], off
	s_mov_b32 m0, s90
	v_lshl_add_u64 v[226:227], s[80:81], 0, v[174:175]
	global_load_lds_dwordx4 v[226:227], off
	s_waitcnt vmcnt(8) lgkmcnt(0)
	s_setprio 1
	s_barrier
	v_mfma_f32_16x16x32_bf16 v[142:145], v[114:117], v[162:165], v[142:145]
	v_mfma_f32_16x16x32_bf16 v[138:141], v[122:125], v[162:165], v[138:141]
	v_mfma_f32_16x16x32_bf16 v[110:113], v[114:117], v[194:197], v[110:113]
	v_mfma_f32_16x16x32_bf16 v[106:109], v[122:125], v[194:197], v[106:109]
	v_mfma_f32_16x16x32_bf16 v[98:101], v[114:117], v[206:209], v[98:101]
	v_mfma_f32_16x16x32_bf16 v[90:93], v[122:125], v[206:209], v[90:93]
	v_mfma_f32_16x16x32_bf16 v[82:85], v[114:117], v[214:217], v[82:85]
	v_mfma_f32_16x16x32_bf16 v[74:77], v[122:125], v[214:217], v[74:77]
	v_mfma_f32_16x16x32_bf16 v[142:145], v[118:121], v[166:169], v[142:145]
	v_mfma_f32_16x16x32_bf16 v[138:141], v[126:129], v[166:169], v[138:141]
	v_mfma_f32_16x16x32_bf16 v[110:113], v[118:121], v[198:201], v[110:113]
	v_mfma_f32_16x16x32_bf16 v[106:109], v[126:129], v[198:201], v[106:109]
	v_mfma_f32_16x16x32_bf16 v[98:101], v[118:121], v[210:213], v[98:101]
	v_mfma_f32_16x16x32_bf16 v[90:93], v[126:129], v[210:213], v[90:93]
	v_mfma_f32_16x16x32_bf16 v[82:85], v[118:121], v[218:221], v[82:85]
	v_mfma_f32_16x16x32_bf16 v[74:77], v[126:129], v[218:221], v[74:77]
	v_mfma_f32_16x16x32_bf16 v[134:137], v[146:149], v[162:165], v[134:137]
	v_mfma_f32_16x16x32_bf16 v[130:133], v[154:157], v[162:165], v[130:133]
	v_mfma_f32_16x16x32_bf16 v[102:105], v[146:149], v[194:197], v[102:105]
	v_mfma_f32_16x16x32_bf16 v[94:97], v[154:157], v[194:197], v[94:97]
	v_mfma_f32_16x16x32_bf16 v[86:89], v[146:149], v[206:209], v[86:89]
	v_mfma_f32_16x16x32_bf16 v[78:81], v[154:157], v[206:209], v[78:81]
	v_mfma_f32_16x16x32_bf16 v[70:73], v[146:149], v[214:217], v[70:73]
	v_mfma_f32_16x16x32_bf16 v[66:69], v[154:157], v[214:217], v[66:69]
	v_mfma_f32_16x16x32_bf16 v[134:137], v[150:153], v[166:169], v[134:137]
	v_mfma_f32_16x16x32_bf16 v[130:133], v[158:161], v[166:169], v[130:133]
	v_mfma_f32_16x16x32_bf16 v[102:105], v[150:153], v[198:201], v[102:105]
	v_mfma_f32_16x16x32_bf16 v[94:97], v[158:161], v[198:201], v[94:97]
	v_mfma_f32_16x16x32_bf16 v[86:89], v[150:153], v[210:213], v[86:89]
	v_mfma_f32_16x16x32_bf16 v[78:81], v[158:161], v[210:213], v[78:81]
	v_mfma_f32_16x16x32_bf16 v[70:73], v[150:153], v[218:221], v[70:73]
	v_mfma_f32_16x16x32_bf16 v[66:69], v[158:161], v[218:221], v[66:69]
	s_setprio 0
	s_barrier
	s_add_i32 s63, s63, s86
	s_mov_b32 m0, s63
	v_lshl_add_u64 v[186:187], v[186:187], 0, s[22:23]
	global_load_lds_dwordx4 v[186:187], off
	ds_read_b128 v[162:165], v192 offset:49152
	ds_read_b128 v[166:169], v192 offset:50176
	s_add_i32 m0, s63, 0x2000
	s_add_u32 s78, s78, 0x100080
	v_lshl_add_u64 v[186:187], v[202:203], 0, s[22:23]
	s_addc_u32 s79, s79, 0
	s_add_i32 s63, s83, s86
	global_load_lds_dwordx4 v[186:187], off
	ds_read_b128 v[194:197], v192 offset:51200
	ds_read_b128 v[198:201], v192 offset:52224
	s_mov_b32 m0, s63
	v_lshl_add_u64 v[186:187], s[78:79], 0, v[172:173]
	global_load_lds_dwordx4 v[186:187], off
	ds_read_b128 v[206:209], v192 offset:53248
	ds_read_b128 v[210:213], v192 offset:54272
	s_add_i32 m0, s63, 0x2000
	v_lshl_add_u64 v[186:187], s[78:79], 0, v[176:177]
	global_load_lds_dwordx4 v[186:187], off
	ds_read_b128 v[214:217], v192 offset:55296
	ds_read_b128 v[218:221], v192 offset:56320
	s_mov_b32 m0, s95
	v_lshl_add_u64 v[186:187], v[222:223], 0, s[22:23]
	global_load_lds_dwordx4 v[186:187], off
	s_mov_b32 m0, s96
	v_lshl_add_u64 v[186:187], v[224:225], 0, s[22:23]
	global_load_lds_dwordx4 v[186:187], off
	s_waitcnt vmcnt(8) lgkmcnt(0)
	s_setprio 1
	s_barrier
	v_mfma_f32_16x16x32_bf16 v[62:65], v[114:117], v[162:165], v[62:65]
	v_mfma_f32_16x16x32_bf16 v[58:61], v[122:125], v[162:165], v[58:61]
	v_mfma_f32_16x16x32_bf16 v[50:53], v[114:117], v[194:197], v[50:53]
	v_mfma_f32_16x16x32_bf16 v[42:45], v[122:125], v[194:197], v[42:45]
	v_mfma_f32_16x16x32_bf16 v[34:37], v[114:117], v[206:209], v[34:37]
	v_mfma_f32_16x16x32_bf16 v[26:29], v[122:125], v[206:209], v[26:29]
	v_mfma_f32_16x16x32_bf16 v[18:21], v[114:117], v[214:217], v[18:21]
	v_mfma_f32_16x16x32_bf16 v[10:13], v[122:125], v[214:217], v[10:13]
	v_mfma_f32_16x16x32_bf16 v[62:65], v[118:121], v[166:169], v[62:65]
	v_mfma_f32_16x16x32_bf16 v[58:61], v[126:129], v[166:169], v[58:61]
	v_mfma_f32_16x16x32_bf16 v[50:53], v[118:121], v[198:201], v[50:53]
	v_mfma_f32_16x16x32_bf16 v[42:45], v[126:129], v[198:201], v[42:45]
	v_mfma_f32_16x16x32_bf16 v[34:37], v[118:121], v[210:213], v[34:37]
	v_mfma_f32_16x16x32_bf16 v[26:29], v[126:129], v[210:213], v[26:29]
	v_mfma_f32_16x16x32_bf16 v[18:21], v[118:121], v[218:221], v[18:21]
	v_mfma_f32_16x16x32_bf16 v[10:13], v[126:129], v[218:221], v[10:13]
	v_mfma_f32_16x16x32_bf16 v[54:57], v[146:149], v[162:165], v[54:57]
	v_mfma_f32_16x16x32_bf16 v[46:49], v[154:157], v[162:165], v[46:49]
	v_mfma_f32_16x16x32_bf16 v[38:41], v[146:149], v[194:197], v[38:41]
	v_mfma_f32_16x16x32_bf16 v[30:33], v[154:157], v[194:197], v[30:33]
	v_mfma_f32_16x16x32_bf16 v[22:25], v[146:149], v[206:209], v[22:25]
	v_mfma_f32_16x16x32_bf16 v[14:17], v[154:157], v[206:209], v[14:17]
	v_mfma_f32_16x16x32_bf16 v[6:9], v[146:149], v[214:217], v[6:9]
	v_mfma_f32_16x16x32_bf16 v[2:5], v[154:157], v[214:217], v[2:5]
	v_mfma_f32_16x16x32_bf16 v[54:57], v[150:153], v[166:169], v[54:57]
	v_mfma_f32_16x16x32_bf16 v[46:49], v[158:161], v[166:169], v[46:49]
	v_mfma_f32_16x16x32_bf16 v[38:41], v[150:153], v[198:201], v[38:41]
	v_mfma_f32_16x16x32_bf16 v[30:33], v[158:161], v[198:201], v[30:33]
	v_mfma_f32_16x16x32_bf16 v[22:25], v[150:153], v[210:213], v[22:25]
	v_mfma_f32_16x16x32_bf16 v[14:17], v[158:161], v[210:213], v[14:17]
	v_mfma_f32_16x16x32_bf16 v[6:9], v[150:153], v[218:221], v[6:9]
	v_mfma_f32_16x16x32_bf16 v[2:5], v[158:161], v[218:221], v[2:5]
	s_setprio 0
	s_barrier
	s_add_u32 s76, s76, 0x100
	s_addc_u32 s77, s77, 0
	s_add_u32 s47, s47, 0x100
	s_addc_u32 s62, s62, 0
	s_cmp_ge_i32 s82, s7
	s_mov_b32 s63, s82
	s_cbranch_scc0 .LBB0_834
	s_and_b64 vcc, exec, s[26:27]
	s_cbranch_vccz .LBB0_837
	s_barrier

.LBB0_1012:
	s_add_u32 s48, s96, s44
	s_addc_u32 s49, s97, s45
	s_and_b64 s[14:15], s[4:5], exec
	s_cselect_b32 s6, s49, s65
	s_cselect_b32 s14, s48, s64
	s_add_u32 s50, s3, s46
	s_addc_u32 s51, s35, s47
	s_and_b64 s[18:19], s[4:5], exec
	s_cselect_b32 s15, s51, s67
	s_cselect_b32 s17, s50, s66
	s_add_u32 s64, s64, 0x40080
	s_addc_u32 s65, s65, 0
	s_add_u32 s18, s66, 0x100
	s_addc_u32 s19, s67, 0
	s_mov_b32 s24, -2
	s_waitcnt vmcnt(0)
	ds_read_b128 v[130:133], v172
	ds_read_b128 v[134:137], v172 offset:1024
	ds_read_b128 v[138:141], v172 offset:2048
	ds_read_b128 v[142:145], v172 offset:3072
	ds_read_b128 v[164:167], v173
	ds_read_b128 v[176:179], v173 offset:1024
	ds_read_b128 v[180:183], v173 offset:2048
	ds_read_b128 v[184:187], v173 offset:3072
	s_add_u32 s25, s64, 0xfffc0080
	s_addc_u32 s28, s65, -1
	s_cmp_eq_u32 s24, 12
	s_cselect_b32 s69, s6, s28
	s_cselect_b32 s68, s14, s25
	s_cselect_b32 s67, s15, s19
	s_cselect_b32 s66, s17, s18
	v_lshl_add_u64 v[168:169], s[64:65], 0, v[156:157]
	s_add_i32 m0, s73, 0xc000
	ds_read_b128 v[188:191], v174
	ds_read_b128 v[192:195], v174 offset:1024
	ds_read_b128 v[196:199], v174 offset:2048
	ds_read_b128 v[200:203], v174 offset:3072
	ds_read_b128 v[206:209], v174 offset:4096
	ds_read_b128 v[210:213], v174 offset:5120
	ds_read_b128 v[214:217], v174 offset:6144
	ds_read_b128 v[218:221], v174 offset:7168
	global_load_lds_dwordx4 v[168:169], off
	s_add_i32 m0, s73, 0xe000
	v_lshl_add_u64 v[168:169], s[64:65], 0, v[158:159]
	global_load_lds_dwordx4 v[168:169], off
	s_waitcnt vmcnt(8) lgkmcnt(0)
	s_setprio 1
	s_barrier
	v_mfma_f32_16x16x32_bf16 v[126:129], v[130:133], v[188:191], 0
	v_mfma_f32_16x16x32_bf16 v[122:125], v[138:141], v[188:191], 0
	v_mfma_f32_16x16x32_bf16 v[110:113], v[130:133], v[196:199], 0
	v_mfma_f32_16x16x32_bf16 v[106:109], v[138:141], v[196:199], 0
	v_mfma_f32_16x16x32_bf16 v[94:97], v[130:133], v[206:209], 0
	v_mfma_f32_16x16x32_bf16 v[90:93], v[138:141], v[206:209], 0
	v_mfma_f32_16x16x32_bf16 v[78:81], v[130:133], v[214:217], 0
	v_mfma_f32_16x16x32_bf16 v[74:77], v[138:141], v[214:217], 0
	v_mfma_f32_16x16x32_bf16 v[126:129], v[134:137], v[192:195], v[126:129]
	v_mfma_f32_16x16x32_bf16 v[122:125], v[142:145], v[192:195], v[122:125]
	v_mfma_f32_16x16x32_bf16 v[110:113], v[134:137], v[200:203], v[110:113]
	v_mfma_f32_16x16x32_bf16 v[106:109], v[142:145], v[200:203], v[106:109]
	v_mfma_f32_16x16x32_bf16 v[94:97], v[134:137], v[210:213], v[94:97]
	v_mfma_f32_16x16x32_bf16 v[90:93], v[142:145], v[210:213], v[90:93]
	v_mfma_f32_16x16x32_bf16 v[78:81], v[134:137], v[218:221], v[78:81]
	v_mfma_f32_16x16x32_bf16 v[74:77], v[142:145], v[218:221], v[74:77]
	v_mfma_f32_16x16x32_bf16 v[118:121], v[164:167], v[188:191], 0
	v_mfma_f32_16x16x32_bf16 v[114:117], v[180:183], v[188:191], 0
	v_mfma_f32_16x16x32_bf16 v[102:105], v[164:167], v[196:199], 0
	v_mfma_f32_16x16x32_bf16 v[98:101], v[180:183], v[196:199], 0
	v_mfma_f32_16x16x32_bf16 v[86:89], v[164:167], v[206:209], 0
	v_mfma_f32_16x16x32_bf16 v[82:85], v[180:183], v[206:209], 0
	v_mfma_f32_16x16x32_bf16 v[70:73], v[164:167], v[214:217], 0
	v_mfma_f32_16x16x32_bf16 v[66:69], v[180:183], v[214:217], 0
	v_mfma_f32_16x16x32_bf16 v[118:121], v[176:179], v[192:195], v[118:121]
	v_mfma_f32_16x16x32_bf16 v[114:117], v[184:187], v[192:195], v[114:117]
	v_mfma_f32_16x16x32_bf16 v[102:105], v[176:179], v[200:203], v[102:105]
	v_mfma_f32_16x16x32_bf16 v[98:101], v[184:187], v[200:203], v[98:101]
	v_mfma_f32_16x16x32_bf16 v[86:89], v[176:179], v[210:213], v[86:89]
	v_mfma_f32_16x16x32_bf16 v[82:85], v[184:187], v[210:213], v[82:85]
	v_mfma_f32_16x16x32_bf16 v[70:73], v[176:179], v[218:221], v[70:73]
	v_mfma_f32_16x16x32_bf16 v[66:69], v[184:187], v[218:221], v[66:69]
	s_setprio 0
	s_barrier
	s_add_i32 s25, s82, s70
	s_mov_b32 m0, s25
	v_lshl_add_u64 v[168:169], s[66:67], 0, v[150:151]
	global_load_lds_dwordx4 v[168:169], off
	ds_read_b128 v[188:191], v174 offset:16384
	ds_read_b128 v[192:195], v174 offset:17408
	s_add_i32 m0, s25, 0x2000
	s_add_u32 s28, s66, 0x40000
	v_lshl_add_u64 v[222:223], s[66:67], 0, v[146:147]
	s_addc_u32 s29, s67, 0
	s_add_i32 s25, s83, s70
	global_load_lds_dwordx4 v[222:223], off
	ds_read_b128 v[196:199], v174 offset:18432
	ds_read_b128 v[200:203], v174 offset:19456
	v_lshl_add_u64 v[224:225], s[28:29], 0, v[150:151]
	s_mov_b32 m0, s25
	v_lshl_add_u64 v[226:227], s[68:69], 0, v[148:149]
	global_load_lds_dwordx4 v[224:225], off
	ds_read_b128 v[206:209], v174 offset:20480
	ds_read_b128 v[210:213], v174 offset:21504
	s_add_i32 m0, s25, 0x2000
	v_lshl_add_u64 v[224:225], s[28:29], 0, v[146:147]
	global_load_lds_dwordx4 v[224:225], off
	ds_read_b128 v[214:217], v174 offset:22528
	ds_read_b128 v[218:221], v174 offset:23552
	s_mov_b32 m0, s73
	v_lshl_add_u64 v[224:225], s[68:69], 0, v[152:153]
	global_load_lds_dwordx4 v[224:225], off
	s_mov_b32 m0, s74
	s_nop 0
	global_load_lds_dwordx4 v[226:227], off
	s_waitcnt vmcnt(8) lgkmcnt(0)
	s_setprio 1
	s_barrier
	v_mfma_f32_16x16x32_bf16 v[62:65], v[130:133], v[188:191], 0
	v_mfma_f32_16x16x32_bf16 v[58:61], v[138:141], v[188:191], 0
	v_mfma_f32_16x16x32_bf16 v[46:49], v[130:133], v[196:199], 0
	v_mfma_f32_16x16x32_bf16 v[42:45], v[138:141], v[196:199], 0
	v_mfma_f32_16x16x32_bf16 v[30:33], v[130:133], v[206:209], 0
	v_mfma_f32_16x16x32_bf16 v[26:29], v[138:141], v[206:209], 0
	v_mfma_f32_16x16x32_bf16 v[14:17], v[130:133], v[214:217], 0
	v_mfma_f32_16x16x32_bf16 v[10:13], v[138:141], v[214:217], 0
	v_mfma_f32_16x16x32_bf16 v[62:65], v[134:137], v[192:195], v[62:65]
	v_mfma_f32_16x16x32_bf16 v[58:61], v[142:145], v[192:195], v[58:61]
	v_mfma_f32_16x16x32_bf16 v[46:49], v[134:137], v[200:203], v[46:49]
	v_mfma_f32_16x16x32_bf16 v[42:45], v[142:145], v[200:203], v[42:45]
	v_mfma_f32_16x16x32_bf16 v[30:33], v[134:137], v[210:213], v[30:33]
	v_mfma_f32_16x16x32_bf16 v[26:29], v[142:145], v[210:213], v[26:29]
	v_mfma_f32_16x16x32_bf16 v[14:17], v[134:137], v[218:221], v[14:17]
	v_mfma_f32_16x16x32_bf16 v[10:13], v[142:145], v[218:221], v[10:13]
	v_mfma_f32_16x16x32_bf16 v[54:57], v[164:167], v[188:191], 0
	v_mfma_f32_16x16x32_bf16 v[50:53], v[180:183], v[188:191], 0
	v_mfma_f32_16x16x32_bf16 v[38:41], v[164:167], v[196:199], 0
	v_mfma_f32_16x16x32_bf16 v[34:37], v[180:183], v[196:199], 0
	v_mfma_f32_16x16x32_bf16 v[22:25], v[164:167], v[206:209], 0
	v_mfma_f32_16x16x32_bf16 v[18:21], v[180:183], v[206:209], 0
	v_mfma_f32_16x16x32_bf16 v[6:9], v[164:167], v[214:217], 0
	v_mfma_f32_16x16x32_bf16 v[2:5], v[180:183], v[214:217], 0
	v_mfma_f32_16x16x32_bf16 v[54:57], v[176:179], v[192:195], v[54:57]
	v_mfma_f32_16x16x32_bf16 v[50:53], v[184:187], v[192:195], v[50:53]
	v_mfma_f32_16x16x32_bf16 v[38:41], v[176:179], v[200:203], v[38:41]
	v_mfma_f32_16x16x32_bf16 v[34:37], v[184:187], v[200:203], v[34:37]
	v_mfma_f32_16x16x32_bf16 v[22:25], v[176:179], v[210:213], v[22:25]
	v_mfma_f32_16x16x32_bf16 v[18:21], v[184:187], v[210:213], v[18:21]
	v_mfma_f32_16x16x32_bf16 v[6:9], v[176:179], v[218:221], v[6:9]
	v_mfma_f32_16x16x32_bf16 v[2:5], v[184:187], v[218:221], v[2:5]
	s_setprio 0
	s_barrier
	s_add_i32 s25, 0, 0x18000
	s_add_i32 s30, 0, 0x1c000
	v_add_u32_e32 v142, s25, v171
	v_add_u32_e32 v175, s30, v171
	ds_read_b128 v[130:133], v142
	ds_read_b128 v[134:137], v142 offset:1024
	ds_read_b128 v[138:141], v142 offset:2048
	ds_read_b128 v[142:145], v142 offset:3072
	ds_read_b128 v[164:167], v175
	ds_read_b128 v[176:179], v175 offset:1024
	ds_read_b128 v[180:183], v175 offset:2048
	ds_read_b128 v[184:187], v175 offset:3072
	s_add_u32 s28, s68, 0x40000
	s_addc_u32 s29, s69, 0
	s_mov_b32 m0, s75
	v_lshl_add_u64 v[228:229], s[28:29], 0, v[152:153]
	ds_read_b128 v[188:191], v174 offset:32768
	ds_read_b128 v[192:195], v174 offset:33792
	ds_read_b128 v[196:199], v174 offset:34816
	ds_read_b128 v[200:203], v174 offset:35840
	ds_read_b128 v[206:209], v174 offset:36864
	ds_read_b128 v[210:213], v174 offset:37888
	ds_read_b128 v[214:217], v174 offset:38912
	ds_read_b128 v[218:221], v174 offset:39936
	global_load_lds_dwordx4 v[228:229], off
	s_mov_b32 m0, s76
	v_lshl_add_u64 v[228:229], s[28:29], 0, v[148:149]
	global_load_lds_dwordx4 v[228:229], off
	s_waitcnt vmcnt(8) lgkmcnt(0)
	s_setprio 1
	s_barrier
	v_mfma_f32_16x16x32_bf16 v[126:129], v[130:133], v[188:191], v[126:129]
	v_mfma_f32_16x16x32_bf16 v[122:125], v[138:141], v[188:191], v[122:125]
	v_mfma_f32_16x16x32_bf16 v[110:113], v[130:133], v[196:199], v[110:113]
	v_mfma_f32_16x16x32_bf16 v[106:109], v[138:141], v[196:199], v[106:109]
	v_mfma_f32_16x16x32_bf16 v[94:97], v[130:133], v[206:209], v[94:97]
	v_mfma_f32_16x16x32_bf16 v[90:93], v[138:141], v[206:209], v[90:93]
	v_mfma_f32_16x16x32_bf16 v[78:81], v[130:133], v[214:217], v[78:81]
	v_mfma_f32_16x16x32_bf16 v[74:77], v[138:141], v[214:217], v[74:77]
	v_mfma_f32_16x16x32_bf16 v[126:129], v[134:137], v[192:195], v[126:129]
	v_mfma_f32_16x16x32_bf16 v[122:125], v[142:145], v[192:195], v[122:125]
	v_mfma_f32_16x16x32_bf16 v[110:113], v[134:137], v[200:203], v[110:113]
	v_mfma_f32_16x16x32_bf16 v[106:109], v[142:145], v[200:203], v[106:109]
	v_mfma_f32_16x16x32_bf16 v[94:97], v[134:137], v[210:213], v[94:97]
	v_mfma_f32_16x16x32_bf16 v[90:93], v[142:145], v[210:213], v[90:93]
	v_mfma_f32_16x16x32_bf16 v[78:81], v[134:137], v[218:221], v[78:81]
	v_mfma_f32_16x16x32_bf16 v[74:77], v[142:145], v[218:221], v[74:77]
	v_mfma_f32_16x16x32_bf16 v[118:121], v[164:167], v[188:191], v[118:121]
	v_mfma_f32_16x16x32_bf16 v[114:117], v[180:183], v[188:191], v[114:117]
	v_mfma_f32_16x16x32_bf16 v[102:105], v[164:167], v[196:199], v[102:105]
	v_mfma_f32_16x16x32_bf16 v[98:101], v[180:183], v[196:199], v[98:101]
	v_mfma_f32_16x16x32_bf16 v[86:89], v[164:167], v[206:209], v[86:89]
	v_mfma_f32_16x16x32_bf16 v[82:85], v[180:183], v[206:209], v[82:85]
	v_mfma_f32_16x16x32_bf16 v[70:73], v[164:167], v[214:217], v[70:73]
	v_mfma_f32_16x16x32_bf16 v[66:69], v[180:183], v[214:217], v[66:69]
	v_mfma_f32_16x16x32_bf16 v[118:121], v[176:179], v[192:195], v[118:121]
	v_mfma_f32_16x16x32_bf16 v[114:117], v[184:187], v[192:195], v[114:117]
	v_mfma_f32_16x16x32_bf16 v[102:105], v[176:179], v[200:203], v[102:105]
	v_mfma_f32_16x16x32_bf16 v[98:101], v[184:187], v[200:203], v[98:101]
	v_mfma_f32_16x16x32_bf16 v[86:89], v[176:179], v[210:213], v[86:89]
	v_mfma_f32_16x16x32_bf16 v[82:85], v[184:187], v[210:213], v[82:85]
	v_mfma_f32_16x16x32_bf16 v[70:73], v[176:179], v[218:221], v[70:73]
	v_mfma_f32_16x16x32_bf16 v[66:69], v[184:187], v[218:221], v[66:69]
	s_setprio 0
	s_barrier
	s_add_i32 s25, s25, s70
	s_mov_b32 m0, s25
	v_lshl_add_u64 v[168:169], v[168:169], 0, s[36:37]
	global_load_lds_dwordx4 v[168:169], off
	ds_read_b128 v[188:191], v174 offset:49152
	ds_read_b128 v[192:195], v174 offset:50176
	s_add_i32 m0, s25, 0x2000
	s_add_u32 s28, s66, 0x40080
	v_lshl_add_u64 v[168:169], v[222:223], 0, s[36:37]
	s_addc_u32 s29, s67, 0
	s_add_i32 s25, s30, s70
	global_load_lds_dwordx4 v[168:169], off
	ds_read_b128 v[196:199], v174 offset:51200
	ds_read_b128 v[200:203], v174 offset:52224
	s_mov_b32 m0, s25
	v_lshl_add_u64 v[168:169], s[28:29], 0, v[150:151]
	global_load_lds_dwordx4 v[168:169], off
	ds_read_b128 v[206:209], v174 offset:53248
	ds_read_b128 v[210:213], v174 offset:54272
	s_add_i32 m0, s25, 0x2000
	v_lshl_add_u64 v[168:169], s[28:29], 0, v[146:147]
	global_load_lds_dwordx4 v[168:169], off
	ds_read_b128 v[214:217], v174 offset:55296
	ds_read_b128 v[218:221], v174 offset:56320
	s_mov_b32 m0, s79
	v_lshl_add_u64 v[168:169], v[224:225], 0, s[36:37]
	global_load_lds_dwordx4 v[168:169], off
	s_mov_b32 m0, s80
	v_lshl_add_u64 v[168:169], v[226:227], 0, s[36:37]
	global_load_lds_dwordx4 v[168:169], off
	s_waitcnt vmcnt(8) lgkmcnt(0)
	s_setprio 1
	s_barrier
	v_mfma_f32_16x16x32_bf16 v[62:65], v[130:133], v[188:191], v[62:65]
	v_mfma_f32_16x16x32_bf16 v[58:61], v[138:141], v[188:191], v[58:61]
	v_mfma_f32_16x16x32_bf16 v[46:49], v[130:133], v[196:199], v[46:49]
	v_mfma_f32_16x16x32_bf16 v[42:45], v[138:141], v[196:199], v[42:45]
	v_mfma_f32_16x16x32_bf16 v[30:33], v[130:133], v[206:209], v[30:33]
	v_mfma_f32_16x16x32_bf16 v[26:29], v[138:141], v[206:209], v[26:29]
	v_mfma_f32_16x16x32_bf16 v[14:17], v[130:133], v[214:217], v[14:17]
	v_mfma_f32_16x16x32_bf16 v[10:13], v[138:141], v[214:217], v[10:13]
	v_mfma_f32_16x16x32_bf16 v[62:65], v[134:137], v[192:195], v[62:65]
	v_mfma_f32_16x16x32_bf16 v[58:61], v[142:145], v[192:195], v[58:61]
	v_mfma_f32_16x16x32_bf16 v[46:49], v[134:137], v[200:203], v[46:49]
	v_mfma_f32_16x16x32_bf16 v[42:45], v[142:145], v[200:203], v[42:45]
	v_mfma_f32_16x16x32_bf16 v[30:33], v[134:137], v[210:213], v[30:33]
	v_mfma_f32_16x16x32_bf16 v[26:29], v[142:145], v[210:213], v[26:29]
	v_mfma_f32_16x16x32_bf16 v[14:17], v[134:137], v[218:221], v[14:17]
	v_mfma_f32_16x16x32_bf16 v[10:13], v[142:145], v[218:221], v[10:13]
	v_mfma_f32_16x16x32_bf16 v[54:57], v[164:167], v[188:191], v[54:57]
	v_mfma_f32_16x16x32_bf16 v[50:53], v[180:183], v[188:191], v[50:53]
	v_mfma_f32_16x16x32_bf16 v[38:41], v[164:167], v[196:199], v[38:41]
	v_mfma_f32_16x16x32_bf16 v[34:37], v[180:183], v[196:199], v[34:37]
	v_mfma_f32_16x16x32_bf16 v[22:25], v[164:167], v[206:209], v[22:25]
	v_mfma_f32_16x16x32_bf16 v[18:21], v[180:183], v[206:209], v[18:21]
	v_mfma_f32_16x16x32_bf16 v[6:9], v[164:167], v[214:217], v[6:9]
	v_mfma_f32_16x16x32_bf16 v[2:5], v[180:183], v[214:217], v[2:5]
	v_mfma_f32_16x16x32_bf16 v[54:57], v[176:179], v[192:195], v[54:57]
	v_mfma_f32_16x16x32_bf16 v[50:53], v[184:187], v[192:195], v[50:53]
	v_mfma_f32_16x16x32_bf16 v[38:41], v[176:179], v[200:203], v[38:41]
	v_mfma_f32_16x16x32_bf16 v[34:37], v[184:187], v[200:203], v[34:37]
	v_mfma_f32_16x16x32_bf16 v[22:25], v[176:179], v[210:213], v[22:25]
	v_mfma_f32_16x16x32_bf16 v[18:21], v[184:187], v[210:213], v[18:21]
	v_mfma_f32_16x16x32_bf16 v[6:9], v[176:179], v[218:221], v[6:9]
	v_mfma_f32_16x16x32_bf16 v[2:5], v[184:187], v[218:221], v[2:5]
	s_setprio 0
	s_barrier
	s_add_i32 s24, s24, 2
	s_add_u32 s64, s64, 0x100
	s_addc_u32 s65, s65, 0
	s_add_u32 s18, s18, 0x100
	s_addc_u32 s19, s19, 0
	s_cmp_gt_u32 s24, 13
.LBB0_1013:
	ds_read_b128 v[130:133], v172
	ds_read_b128 v[134:137], v172 offset:1024
	ds_read_b128 v[138:141], v172 offset:2048
	ds_read_b128 v[142:145], v172 offset:3072
	ds_read_b128 v[164:167], v173
	ds_read_b128 v[176:179], v173 offset:1024
	ds_read_b128 v[180:183], v173 offset:2048
	ds_read_b128 v[184:187], v173 offset:3072
	s_add_u32 s25, s64, 0xfffc0080
	s_addc_u32 s28, s65, -1
	s_cmp_eq_u32 s24, 12
	s_cselect_b32 s69, s6, s28
	s_cselect_b32 s68, s14, s25
	s_cselect_b32 s67, s15, s19
	s_cselect_b32 s66, s17, s18
	v_lshl_add_u64 v[168:169], s[64:65], 0, v[156:157]
	s_add_i32 m0, s73, 0xc000
	ds_read_b128 v[188:191], v174
	ds_read_b128 v[192:195], v174 offset:1024
	ds_read_b128 v[196:199], v174 offset:2048
	ds_read_b128 v[200:203], v174 offset:3072
	ds_read_b128 v[206:209], v174 offset:4096
	ds_read_b128 v[210:213], v174 offset:5120
	ds_read_b128 v[214:217], v174 offset:6144
	ds_read_b128 v[218:221], v174 offset:7168
	global_load_lds_dwordx4 v[168:169], off
	s_add_i32 m0, s73, 0xe000
	v_lshl_add_u64 v[168:169], s[64:65], 0, v[158:159]
	global_load_lds_dwordx4 v[168:169], off
	s_waitcnt vmcnt(8) lgkmcnt(0)
	s_setprio 1
	s_barrier
	v_mfma_f32_16x16x32_bf16 v[126:129], v[130:133], v[188:191], v[126:129]
	v_mfma_f32_16x16x32_bf16 v[122:125], v[138:141], v[188:191], v[122:125]
	v_mfma_f32_16x16x32_bf16 v[110:113], v[130:133], v[196:199], v[110:113]
	v_mfma_f32_16x16x32_bf16 v[106:109], v[138:141], v[196:199], v[106:109]
	v_mfma_f32_16x16x32_bf16 v[94:97], v[130:133], v[206:209], v[94:97]
	v_mfma_f32_16x16x32_bf16 v[90:93], v[138:141], v[206:209], v[90:93]
	v_mfma_f32_16x16x32_bf16 v[78:81], v[130:133], v[214:217], v[78:81]
	v_mfma_f32_16x16x32_bf16 v[74:77], v[138:141], v[214:217], v[74:77]
	v_mfma_f32_16x16x32_bf16 v[126:129], v[134:137], v[192:195], v[126:129]
	v_mfma_f32_16x16x32_bf16 v[122:125], v[142:145], v[192:195], v[122:125]
	v_mfma_f32_16x16x32_bf16 v[110:113], v[134:137], v[200:203], v[110:113]
	v_mfma_f32_16x16x32_bf16 v[106:109], v[142:145], v[200:203], v[106:109]
	v_mfma_f32_16x16x32_bf16 v[94:97], v[134:137], v[210:213], v[94:97]
	v_mfma_f32_16x16x32_bf16 v[90:93], v[142:145], v[210:213], v[90:93]
	v_mfma_f32_16x16x32_bf16 v[78:81], v[134:137], v[218:221], v[78:81]
	v_mfma_f32_16x16x32_bf16 v[74:77], v[142:145], v[218:221], v[74:77]
	v_mfma_f32_16x16x32_bf16 v[118:121], v[164:167], v[188:191], v[118:121]
	v_mfma_f32_16x16x32_bf16 v[114:117], v[180:183], v[188:191], v[114:117]
	v_mfma_f32_16x16x32_bf16 v[102:105], v[164:167], v[196:199], v[102:105]
	v_mfma_f32_16x16x32_bf16 v[98:101], v[180:183], v[196:199], v[98:101]
	v_mfma_f32_16x16x32_bf16 v[86:89], v[164:167], v[206:209], v[86:89]
	v_mfma_f32_16x16x32_bf16 v[82:85], v[180:183], v[206:209], v[82:85]
	v_mfma_f32_16x16x32_bf16 v[70:73], v[164:167], v[214:217], v[70:73]
	v_mfma_f32_16x16x32_bf16 v[66:69], v[180:183], v[214:217], v[66:69]
	v_mfma_f32_16x16x32_bf16 v[118:121], v[176:179], v[192:195], v[118:121]
	v_mfma_f32_16x16x32_bf16 v[114:117], v[184:187], v[192:195], v[114:117]
	v_mfma_f32_16x16x32_bf16 v[102:105], v[176:179], v[200:203], v[102:105]
	v_mfma_f32_16x16x32_bf16 v[98:101], v[184:187], v[200:203], v[98:101]
	v_mfma_f32_16x16x32_bf16 v[86:89], v[176:179], v[210:213], v[86:89]
	v_mfma_f32_16x16x32_bf16 v[82:85], v[184:187], v[210:213], v[82:85]
	v_mfma_f32_16x16x32_bf16 v[70:73], v[176:179], v[218:221], v[70:73]
	v_mfma_f32_16x16x32_bf16 v[66:69], v[184:187], v[218:221], v[66:69]
	s_setprio 0
	s_barrier
	s_add_i32 s25, s82, s70
	s_mov_b32 m0, s25
	v_lshl_add_u64 v[168:169], s[66:67], 0, v[150:151]
	global_load_lds_dwordx4 v[168:169], off
	ds_read_b128 v[188:191], v174 offset:16384
	ds_read_b128 v[192:195], v174 offset:17408
	s_add_i32 m0, s25, 0x2000
	s_add_u32 s28, s66, 0x40000
	v_lshl_add_u64 v[222:223], s[66:67], 0, v[146:147]
	s_addc_u32 s29, s67, 0
	s_add_i32 s25, s83, s70
	global_load_lds_dwordx4 v[222:223], off
	ds_read_b128 v[196:199], v174 offset:18432
	ds_read_b128 v[200:203], v174 offset:19456
	v_lshl_add_u64 v[224:225], s[28:29], 0, v[150:151]
	s_mov_b32 m0, s25
	v_lshl_add_u64 v[226:227], s[68:69], 0, v[148:149]
	global_load_lds_dwordx4 v[224:225], off
	ds_read_b128 v[206:209], v174 offset:20480
	ds_read_b128 v[210:213], v174 offset:21504
	s_add_i32 m0, s25, 0x2000
	v_lshl_add_u64 v[224:225], s[28:29], 0, v[146:147]
	global_load_lds_dwordx4 v[224:225], off
	ds_read_b128 v[214:217], v174 offset:22528
	ds_read_b128 v[218:221], v174 offset:23552
	s_mov_b32 m0, s73
	v_lshl_add_u64 v[224:225], s[68:69], 0, v[152:153]
	global_load_lds_dwordx4 v[224:225], off
	s_mov_b32 m0, s74
	s_nop 0
	global_load_lds_dwordx4 v[226:227], off
	s_waitcnt vmcnt(8) lgkmcnt(0)
	s_setprio 1
	s_barrier
	v_mfma_f32_16x16x32_bf16 v[62:65], v[130:133], v[188:191], v[62:65]
	v_mfma_f32_16x16x32_bf16 v[58:61], v[138:141], v[188:191], v[58:61]
	v_mfma_f32_16x16x32_bf16 v[46:49], v[130:133], v[196:199], v[46:49]
	v_mfma_f32_16x16x32_bf16 v[42:45], v[138:141], v[196:199], v[42:45]
	v_mfma_f32_16x16x32_bf16 v[30:33], v[130:133], v[206:209], v[30:33]
	v_mfma_f32_16x16x32_bf16 v[26:29], v[138:141], v[206:209], v[26:29]
	v_mfma_f32_16x16x32_bf16 v[14:17], v[130:133], v[214:217], v[14:17]
	v_mfma_f32_16x16x32_bf16 v[10:13], v[138:141], v[214:217], v[10:13]
	v_mfma_f32_16x16x32_bf16 v[62:65], v[134:137], v[192:195], v[62:65]
	v_mfma_f32_16x16x32_bf16 v[58:61], v[142:145], v[192:195], v[58:61]
	v_mfma_f32_16x16x32_bf16 v[46:49], v[134:137], v[200:203], v[46:49]
	v_mfma_f32_16x16x32_bf16 v[42:45], v[142:145], v[200:203], v[42:45]
	v_mfma_f32_16x16x32_bf16 v[30:33], v[134:137], v[210:213], v[30:33]
	v_mfma_f32_16x16x32_bf16 v[26:29], v[142:145], v[210:213], v[26:29]
	v_mfma_f32_16x16x32_bf16 v[14:17], v[134:137], v[218:221], v[14:17]
	v_mfma_f32_16x16x32_bf16 v[10:13], v[142:145], v[218:221], v[10:13]
	v_mfma_f32_16x16x32_bf16 v[54:57], v[164:167], v[188:191], v[54:57]
	v_mfma_f32_16x16x32_bf16 v[50:53], v[180:183], v[188:191], v[50:53]
	v_mfma_f32_16x16x32_bf16 v[38:41], v[164:167], v[196:199], v[38:41]
	v_mfma_f32_16x16x32_bf16 v[34:37], v[180:183], v[196:199], v[34:37]
	v_mfma_f32_16x16x32_bf16 v[22:25], v[164:167], v[206:209], v[22:25]
	v_mfma_f32_16x16x32_bf16 v[18:21], v[180:183], v[206:209], v[18:21]
	v_mfma_f32_16x16x32_bf16 v[6:9], v[164:167], v[214:217], v[6:9]
	v_mfma_f32_16x16x32_bf16 v[2:5], v[180:183], v[214:217], v[2:5]
	v_mfma_f32_16x16x32_bf16 v[54:57], v[176:179], v[192:195], v[54:57]
	v_mfma_f32_16x16x32_bf16 v[50:53], v[184:187], v[192:195], v[50:53]
	v_mfma_f32_16x16x32_bf16 v[38:41], v[176:179], v[200:203], v[38:41]
	v_mfma_f32_16x16x32_bf16 v[34:37], v[184:187], v[200:203], v[34:37]
	v_mfma_f32_16x16x32_bf16 v[22:25], v[176:179], v[210:213], v[22:25]
	v_mfma_f32_16x16x32_bf16 v[18:21], v[184:187], v[210:213], v[18:21]
	v_mfma_f32_16x16x32_bf16 v[6:9], v[176:179], v[218:221], v[6:9]
	v_mfma_f32_16x16x32_bf16 v[2:5], v[184:187], v[218:221], v[2:5]
	s_setprio 0
	s_barrier
	s_add_i32 s25, 0, 0x18000
	s_add_i32 s30, 0, 0x1c000
	v_add_u32_e32 v142, s25, v171
	v_add_u32_e32 v175, s30, v171
	ds_read_b128 v[130:133], v142
	ds_read_b128 v[134:137], v142 offset:1024
	ds_read_b128 v[138:141], v142 offset:2048
	ds_read_b128 v[142:145], v142 offset:3072
	ds_read_b128 v[164:167], v175
	ds_read_b128 v[176:179], v175 offset:1024
	ds_read_b128 v[180:183], v175 offset:2048
	ds_read_b128 v[184:187], v175 offset:3072
	s_add_u32 s28, s68, 0x40000
	s_addc_u32 s29, s69, 0
	s_mov_b32 m0, s75
	v_lshl_add_u64 v[228:229], s[28:29], 0, v[152:153]
	ds_read_b128 v[188:191], v174 offset:32768
	ds_read_b128 v[192:195], v174 offset:33792
	ds_read_b128 v[196:199], v174 offset:34816
	ds_read_b128 v[200:203], v174 offset:35840
	ds_read_b128 v[206:209], v174 offset:36864
	ds_read_b128 v[210:213], v174 offset:37888
	ds_read_b128 v[214:217], v174 offset:38912
	ds_read_b128 v[218:221], v174 offset:39936
	global_load_lds_dwordx4 v[228:229], off
	s_mov_b32 m0, s76
	v_lshl_add_u64 v[228:229], s[28:29], 0, v[148:149]
	global_load_lds_dwordx4 v[228:229], off
	s_waitcnt vmcnt(8) lgkmcnt(0)
	s_setprio 1
	s_barrier
	v_mfma_f32_16x16x32_bf16 v[126:129], v[130:133], v[188:191], v[126:129]
	v_mfma_f32_16x16x32_bf16 v[122:125], v[138:141], v[188:191], v[122:125]
	v_mfma_f32_16x16x32_bf16 v[110:113], v[130:133], v[196:199], v[110:113]
	v_mfma_f32_16x16x32_bf16 v[106:109], v[138:141], v[196:199], v[106:109]
	v_mfma_f32_16x16x32_bf16 v[94:97], v[130:133], v[206:209], v[94:97]
	v_mfma_f32_16x16x32_bf16 v[90:93], v[138:141], v[206:209], v[90:93]
	v_mfma_f32_16x16x32_bf16 v[78:81], v[130:133], v[214:217], v[78:81]
	v_mfma_f32_16x16x32_bf16 v[74:77], v[138:141], v[214:217], v[74:77]
	v_mfma_f32_16x16x32_bf16 v[126:129], v[134:137], v[192:195], v[126:129]
	v_mfma_f32_16x16x32_bf16 v[122:125], v[142:145], v[192:195], v[122:125]
	v_mfma_f32_16x16x32_bf16 v[110:113], v[134:137], v[200:203], v[110:113]
	v_mfma_f32_16x16x32_bf16 v[106:109], v[142:145], v[200:203], v[106:109]
	v_mfma_f32_16x16x32_bf16 v[94:97], v[134:137], v[210:213], v[94:97]
	v_mfma_f32_16x16x32_bf16 v[90:93], v[142:145], v[210:213], v[90:93]
	v_mfma_f32_16x16x32_bf16 v[78:81], v[134:137], v[218:221], v[78:81]
	v_mfma_f32_16x16x32_bf16 v[74:77], v[142:145], v[218:221], v[74:77]
	v_mfma_f32_16x16x32_bf16 v[118:121], v[164:167], v[188:191], v[118:121]
	v_mfma_f32_16x16x32_bf16 v[114:117], v[180:183], v[188:191], v[114:117]
	v_mfma_f32_16x16x32_bf16 v[102:105], v[164:167], v[196:199], v[102:105]
	v_mfma_f32_16x16x32_bf16 v[98:101], v[180:183], v[196:199], v[98:101]
	v_mfma_f32_16x16x32_bf16 v[86:89], v[164:167], v[206:209], v[86:89]
	v_mfma_f32_16x16x32_bf16 v[82:85], v[180:183], v[206:209], v[82:85]
	v_mfma_f32_16x16x32_bf16 v[70:73], v[164:167], v[214:217], v[70:73]
	v_mfma_f32_16x16x32_bf16 v[66:69], v[180:183], v[214:217], v[66:69]
	v_mfma_f32_16x16x32_bf16 v[118:121], v[176:179], v[192:195], v[118:121]
	v_mfma_f32_16x16x32_bf16 v[114:117], v[184:187], v[192:195], v[114:117]
	v_mfma_f32_16x16x32_bf16 v[102:105], v[176:179], v[200:203], v[102:105]
	v_mfma_f32_16x16x32_bf16 v[98:101], v[184:187], v[200:203], v[98:101]
	v_mfma_f32_16x16x32_bf16 v[86:89], v[176:179], v[210:213], v[86:89]
	v_mfma_f32_16x16x32_bf16 v[82:85], v[184:187], v[210:213], v[82:85]
	v_mfma_f32_16x16x32_bf16 v[70:73], v[176:179], v[218:221], v[70:73]
	v_mfma_f32_16x16x32_bf16 v[66:69], v[184:187], v[218:221], v[66:69]
	s_setprio 0
	s_barrier
	s_add_i32 s25, s25, s70
	s_mov_b32 m0, s25
	v_lshl_add_u64 v[168:169], v[168:169], 0, s[36:37]
	global_load_lds_dwordx4 v[168:169], off
	ds_read_b128 v[188:191], v174 offset:49152
	ds_read_b128 v[192:195], v174 offset:50176
	s_add_i32 m0, s25, 0x2000
	s_add_u32 s28, s66, 0x40080
	v_lshl_add_u64 v[168:169], v[222:223], 0, s[36:37]
	s_addc_u32 s29, s67, 0
	s_add_i32 s25, s30, s70
	global_load_lds_dwordx4 v[168:169], off
	ds_read_b128 v[196:199], v174 offset:51200
	ds_read_b128 v[200:203], v174 offset:52224
	s_mov_b32 m0, s25
	v_lshl_add_u64 v[168:169], s[28:29], 0, v[150:151]
	global_load_lds_dwordx4 v[168:169], off
	ds_read_b128 v[206:209], v174 offset:53248
	ds_read_b128 v[210:213], v174 offset:54272
	s_add_i32 m0, s25, 0x2000
	v_lshl_add_u64 v[168:169], s[28:29], 0, v[146:147]
	global_load_lds_dwordx4 v[168:169], off
	ds_read_b128 v[214:217], v174 offset:55296
	ds_read_b128 v[218:221], v174 offset:56320
	s_mov_b32 m0, s79
	v_lshl_add_u64 v[168:169], v[224:225], 0, s[36:37]
	global_load_lds_dwordx4 v[168:169], off
	s_mov_b32 m0, s80
	v_lshl_add_u64 v[168:169], v[226:227], 0, s[36:37]
	global_load_lds_dwordx4 v[168:169], off
	s_waitcnt vmcnt(8) lgkmcnt(0)
	s_setprio 1
	s_barrier
	v_mfma_f32_16x16x32_bf16 v[62:65], v[130:133], v[188:191], v[62:65]
	v_mfma_f32_16x16x32_bf16 v[58:61], v[138:141], v[188:191], v[58:61]
	v_mfma_f32_16x16x32_bf16 v[46:49], v[130:133], v[196:199], v[46:49]
	v_mfma_f32_16x16x32_bf16 v[42:45], v[138:141], v[196:199], v[42:45]
	v_mfma_f32_16x16x32_bf16 v[30:33], v[130:133], v[206:209], v[30:33]
	v_mfma_f32_16x16x32_bf16 v[26:29], v[138:141], v[206:209], v[26:29]
	v_mfma_f32_16x16x32_bf16 v[14:17], v[130:133], v[214:217], v[14:17]
	v_mfma_f32_16x16x32_bf16 v[10:13], v[138:141], v[214:217], v[10:13]
	v_mfma_f32_16x16x32_bf16 v[62:65], v[134:137], v[192:195], v[62:65]
	v_mfma_f32_16x16x32_bf16 v[58:61], v[142:145], v[192:195], v[58:61]
	v_mfma_f32_16x16x32_bf16 v[46:49], v[134:137], v[200:203], v[46:49]
	v_mfma_f32_16x16x32_bf16 v[42:45], v[142:145], v[200:203], v[42:45]
	v_mfma_f32_16x16x32_bf16 v[30:33], v[134:137], v[210:213], v[30:33]
	v_mfma_f32_16x16x32_bf16 v[26:29], v[142:145], v[210:213], v[26:29]
	v_mfma_f32_16x16x32_bf16 v[14:17], v[134:137], v[218:221], v[14:17]
	v_mfma_f32_16x16x32_bf16 v[10:13], v[142:145], v[218:221], v[10:13]
	v_mfma_f32_16x16x32_bf16 v[54:57], v[164:167], v[188:191], v[54:57]
	v_mfma_f32_16x16x32_bf16 v[50:53], v[180:183], v[188:191], v[50:53]
	v_mfma_f32_16x16x32_bf16 v[38:41], v[164:167], v[196:199], v[38:41]
	v_mfma_f32_16x16x32_bf16 v[34:37], v[180:183], v[196:199], v[34:37]
	v_mfma_f32_16x16x32_bf16 v[22:25], v[164:167], v[206:209], v[22:25]
	v_mfma_f32_16x16x32_bf16 v[18:21], v[180:183], v[206:209], v[18:21]
	v_mfma_f32_16x16x32_bf16 v[6:9], v[164:167], v[214:217], v[6:9]
	v_mfma_f32_16x16x32_bf16 v[2:5], v[180:183], v[214:217], v[2:5]
	v_mfma_f32_16x16x32_bf16 v[54:57], v[176:179], v[192:195], v[54:57]
	v_mfma_f32_16x16x32_bf16 v[50:53], v[184:187], v[192:195], v[50:53]
	v_mfma_f32_16x16x32_bf16 v[38:41], v[176:179], v[200:203], v[38:41]
	v_mfma_f32_16x16x32_bf16 v[34:37], v[184:187], v[200:203], v[34:37]
	v_mfma_f32_16x16x32_bf16 v[22:25], v[176:179], v[210:213], v[22:25]
	v_mfma_f32_16x16x32_bf16 v[18:21], v[184:187], v[210:213], v[18:21]
	v_mfma_f32_16x16x32_bf16 v[6:9], v[176:179], v[218:221], v[6:9]
	v_mfma_f32_16x16x32_bf16 v[2:5], v[184:187], v[218:221], v[2:5]
	s_setprio 0
	s_barrier
	s_add_i32 s24, s24, 2
	s_add_u32 s64, s64, 0x100
	s_addc_u32 s65, s65, 0
	s_add_u32 s18, s18, 0x100
	s_addc_u32 s19, s19, 0
	s_cmp_gt_u32 s24, 13
	s_cbranch_scc0 .LBB0_1013
	s_and_b64 vcc, exec, s[38:39]
	s_cbranch_vccz .LBB0_1016
	s_barrier

.LBB0_1427:
	s_add_u32 s90, s35, s86
	s_addc_u32 s91, s64, s87
	s_and_b64 s[14:15], s[88:89], exec
	s_cselect_b32 s14, s91, s11
	s_cselect_b32 s15, s90, s10
	s_add_u32 s92, s65, s74
	s_addc_u32 s93, s68, s75
	s_and_b64 s[66:67], s[88:89], exec
	s_cselect_b32 s51, s93, s95
	s_cselect_b32 s84, s92, s94
	s_add_i32 s85, s18, -2
	s_add_u32 s10, s10, 0x40080
	s_addc_u32 s11, s11, 0
	s_add_u32 vcc_lo, s94, 0x100
	s_addc_u32 vcc_hi, s95, 0
	s_mov_b32 s94, 0
	s_waitcnt vmcnt(0)
	s_add_i32 s66, s94, 2
	s_add_u32 s67, s10, 0xfffc0080
	s_addc_u32 s72, s11, -1
	s_cmp_eq_u32 s85, s94
	s_cselect_b32 s97, s14, s72
	s_cselect_b32 s96, s15, s67
	s_cselect_b32 s95, s51, vcc_hi
	s_cselect_b32 s94, s84, vcc_lo
	s_add_i32 s67, 0, 0x10000
	s_add_i32 s62, 0, 0x14000
	v_add_u32_e32 v126, s67, v199
	v_add_u32_e32 v158, s62, v199
	ds_read_b128 v[114:117], v126
	ds_read_b128 v[118:121], v126 offset:1024
	ds_read_b128 v[122:125], v126 offset:2048
	ds_read_b128 v[126:129], v126 offset:3072
	ds_read_b128 v[146:149], v158
	ds_read_b128 v[150:153], v158 offset:1024
	ds_read_b128 v[154:157], v158 offset:2048
	ds_read_b128 v[158:161], v158 offset:3072
	v_lshl_add_u64 v[202:203], s[10:11], 0, v[196:197]
	s_add_i32 m0, s28, 0xc000
	ds_read_b128 v[162:165], v214
	ds_read_b128 v[166:169], v214 offset:1024
	ds_read_b128 v[216:219], v214 offset:2048
	ds_read_b128 v[220:223], v214 offset:3072
	ds_read_b128 v[224:227], v214 offset:4096
	ds_read_b128 v[228:231], v214 offset:5120
	ds_read_b128 v[232:235], v214 offset:6144
	ds_read_b128 v[236:239], v214 offset:7168
	global_load_lds_dwordx4 v[202:203], off
	s_add_i32 m0, s28, 0xe000
	v_lshl_add_u64 v[202:203], s[10:11], 0, v[176:177]
	global_load_lds_dwordx4 v[202:203], off
	s_waitcnt vmcnt(8) lgkmcnt(0)
	s_setprio 1
	s_barrier
	v_mfma_f32_16x16x32_bf16 v[142:145], v[114:117], v[162:165], 0
	v_mfma_f32_16x16x32_bf16 v[138:141], v[122:125], v[162:165], 0
	v_mfma_f32_16x16x32_bf16 v[110:113], v[114:117], v[216:219], 0
	v_mfma_f32_16x16x32_bf16 v[106:109], v[122:125], v[216:219], 0
	v_mfma_f32_16x16x32_bf16 v[98:101], v[114:117], v[224:227], 0
	v_mfma_f32_16x16x32_bf16 v[90:93], v[122:125], v[224:227], 0
	v_mfma_f32_16x16x32_bf16 v[82:85], v[114:117], v[232:235], 0
	v_mfma_f32_16x16x32_bf16 v[74:77], v[122:125], v[232:235], 0
	v_mfma_f32_16x16x32_bf16 v[142:145], v[118:121], v[166:169], v[142:145]
	v_mfma_f32_16x16x32_bf16 v[138:141], v[126:129], v[166:169], v[138:141]
	v_mfma_f32_16x16x32_bf16 v[110:113], v[118:121], v[220:223], v[110:113]
	v_mfma_f32_16x16x32_bf16 v[106:109], v[126:129], v[220:223], v[106:109]
	v_mfma_f32_16x16x32_bf16 v[98:101], v[118:121], v[228:231], v[98:101]
	v_mfma_f32_16x16x32_bf16 v[90:93], v[126:129], v[228:231], v[90:93]
	v_mfma_f32_16x16x32_bf16 v[82:85], v[118:121], v[236:239], v[82:85]
	v_mfma_f32_16x16x32_bf16 v[74:77], v[126:129], v[236:239], v[74:77]
	v_mfma_f32_16x16x32_bf16 v[134:137], v[146:149], v[162:165], 0
	v_mfma_f32_16x16x32_bf16 v[130:133], v[154:157], v[162:165], 0
	v_mfma_f32_16x16x32_bf16 v[102:105], v[146:149], v[216:219], 0
	v_mfma_f32_16x16x32_bf16 v[94:97], v[154:157], v[216:219], 0
	v_mfma_f32_16x16x32_bf16 v[86:89], v[146:149], v[224:227], 0
	v_mfma_f32_16x16x32_bf16 v[78:81], v[154:157], v[224:227], 0
	v_mfma_f32_16x16x32_bf16 v[70:73], v[146:149], v[232:235], 0
	v_mfma_f32_16x16x32_bf16 v[66:69], v[154:157], v[232:235], 0
	v_mfma_f32_16x16x32_bf16 v[134:137], v[150:153], v[166:169], v[134:137]
	v_mfma_f32_16x16x32_bf16 v[130:133], v[158:161], v[166:169], v[130:133]
	v_mfma_f32_16x16x32_bf16 v[102:105], v[150:153], v[220:223], v[102:105]
	v_mfma_f32_16x16x32_bf16 v[94:97], v[158:161], v[220:223], v[94:97]
	v_mfma_f32_16x16x32_bf16 v[86:89], v[150:153], v[228:231], v[86:89]
	v_mfma_f32_16x16x32_bf16 v[78:81], v[158:161], v[228:231], v[78:81]
	v_mfma_f32_16x16x32_bf16 v[70:73], v[150:153], v[236:239], v[70:73]
	v_mfma_f32_16x16x32_bf16 v[66:69], v[158:161], v[236:239], v[66:69]
	s_setprio 0
	s_barrier
	s_add_i32 s63, s67, s17
	s_mov_b32 m0, s63
	v_lshl_add_u64 v[202:203], s[94:95], 0, v[174:175]
	global_load_lds_dwordx4 v[202:203], off
	ds_read_b128 v[162:165], v214 offset:16384
	ds_read_b128 v[166:169], v214 offset:17408
	s_add_i32 m0, s63, 0x2000
	s_add_u32 s72, s94, 0x40000
	v_lshl_add_u64 v[240:241], s[94:95], 0, v[178:179]
	s_addc_u32 s73, s95, 0
	s_add_i32 s62, s62, s17
	global_load_lds_dwordx4 v[240:241], off
	ds_read_b128 v[216:219], v214 offset:18432
	ds_read_b128 v[220:223], v214 offset:19456
	v_lshl_add_u64 v[242:243], s[72:73], 0, v[174:175]
	s_mov_b32 m0, s62
	v_lshl_add_u64 v[244:245], s[96:97], 0, v[176:177]
	global_load_lds_dwordx4 v[242:243], off
	ds_read_b128 v[224:227], v214 offset:20480
	ds_read_b128 v[228:231], v214 offset:21504
	s_add_i32 m0, s62, 0x2000
	v_lshl_add_u64 v[242:243], s[72:73], 0, v[178:179]
	global_load_lds_dwordx4 v[242:243], off
	ds_read_b128 v[232:235], v214 offset:22528
	ds_read_b128 v[236:239], v214 offset:23552
	s_mov_b32 m0, s28
	v_lshl_add_u64 v[242:243], s[96:97], 0, v[172:173]
	global_load_lds_dwordx4 v[242:243], off
	s_mov_b32 m0, s29
	s_nop 0
	global_load_lds_dwordx4 v[244:245], off
	s_waitcnt vmcnt(8) lgkmcnt(0)
	s_setprio 1
	s_barrier
	v_mfma_f32_16x16x32_bf16 v[62:65], v[114:117], v[162:165], 0
	v_mfma_f32_16x16x32_bf16 v[58:61], v[122:125], v[162:165], 0
	v_mfma_f32_16x16x32_bf16 v[50:53], v[114:117], v[216:219], 0
	v_mfma_f32_16x16x32_bf16 v[42:45], v[122:125], v[216:219], 0
	v_mfma_f32_16x16x32_bf16 v[34:37], v[114:117], v[224:227], 0
	v_mfma_f32_16x16x32_bf16 v[26:29], v[122:125], v[224:227], 0
	v_mfma_f32_16x16x32_bf16 v[18:21], v[114:117], v[232:235], 0
	v_mfma_f32_16x16x32_bf16 v[10:13], v[122:125], v[232:235], 0
	v_mfma_f32_16x16x32_bf16 v[62:65], v[118:121], v[166:169], v[62:65]
	v_mfma_f32_16x16x32_bf16 v[58:61], v[126:129], v[166:169], v[58:61]
	v_mfma_f32_16x16x32_bf16 v[50:53], v[118:121], v[220:223], v[50:53]
	v_mfma_f32_16x16x32_bf16 v[42:45], v[126:129], v[220:223], v[42:45]
	v_mfma_f32_16x16x32_bf16 v[34:37], v[118:121], v[228:231], v[34:37]
	v_mfma_f32_16x16x32_bf16 v[26:29], v[126:129], v[228:231], v[26:29]
	v_mfma_f32_16x16x32_bf16 v[18:21], v[118:121], v[236:239], v[18:21]
	v_mfma_f32_16x16x32_bf16 v[10:13], v[126:129], v[236:239], v[10:13]
	v_mfma_f32_16x16x32_bf16 v[54:57], v[146:149], v[162:165], 0
	v_mfma_f32_16x16x32_bf16 v[46:49], v[154:157], v[162:165], 0
	v_mfma_f32_16x16x32_bf16 v[38:41], v[146:149], v[216:219], 0
	v_mfma_f32_16x16x32_bf16 v[30:33], v[154:157], v[216:219], 0
	v_mfma_f32_16x16x32_bf16 v[22:25], v[146:149], v[224:227], 0
	v_mfma_f32_16x16x32_bf16 v[14:17], v[154:157], v[224:227], 0
	v_mfma_f32_16x16x32_bf16 v[6:9], v[146:149], v[232:235], 0
	v_mfma_f32_16x16x32_bf16 v[2:5], v[154:157], v[232:235], 0
	v_mfma_f32_16x16x32_bf16 v[54:57], v[150:153], v[166:169], v[54:57]
	v_mfma_f32_16x16x32_bf16 v[46:49], v[158:161], v[166:169], v[46:49]
	v_mfma_f32_16x16x32_bf16 v[38:41], v[150:153], v[220:223], v[38:41]
	v_mfma_f32_16x16x32_bf16 v[30:33], v[158:161], v[220:223], v[30:33]
	v_mfma_f32_16x16x32_bf16 v[22:25], v[150:153], v[228:231], v[22:25]
	v_mfma_f32_16x16x32_bf16 v[14:17], v[158:161], v[228:231], v[14:17]
	v_mfma_f32_16x16x32_bf16 v[6:9], v[150:153], v[236:239], v[6:9]
	v_mfma_f32_16x16x32_bf16 v[2:5], v[158:161], v[236:239], v[2:5]
	s_setprio 0
	s_barrier
	s_add_i32 s62, 0, 0x18000
	s_add_i32 s63, 0, 0x1c000
	v_add_u32_e32 v126, s62, v199
	v_add_u32_e32 v158, s63, v199
	ds_read_b128 v[114:117], v126
	ds_read_b128 v[118:121], v126 offset:1024
	ds_read_b128 v[122:125], v126 offset:2048
	ds_read_b128 v[126:129], v126 offset:3072
	ds_read_b128 v[146:149], v158
	ds_read_b128 v[150:153], v158 offset:1024
	ds_read_b128 v[154:157], v158 offset:2048
	ds_read_b128 v[158:161], v158 offset:3072
	s_add_u32 s72, s96, 0x40000
	s_addc_u32 s73, s97, 0
	s_mov_b32 m0, s30
	v_lshl_add_u64 v[246:247], s[72:73], 0, v[172:173]
	ds_read_b128 v[162:165], v214 offset:32768
	ds_read_b128 v[166:169], v214 offset:33792
	ds_read_b128 v[216:219], v214 offset:34816
	ds_read_b128 v[220:223], v214 offset:35840
	ds_read_b128 v[224:227], v214 offset:36864
	ds_read_b128 v[228:231], v214 offset:37888
	ds_read_b128 v[232:235], v214 offset:38912
	ds_read_b128 v[236:239], v214 offset:39936
	global_load_lds_dwordx4 v[246:247], off
	s_mov_b32 m0, s31
	v_lshl_add_u64 v[246:247], s[72:73], 0, v[176:177]
	global_load_lds_dwordx4 v[246:247], off
	s_waitcnt vmcnt(8) lgkmcnt(0)
	s_setprio 1
	s_barrier
	v_mfma_f32_16x16x32_bf16 v[142:145], v[114:117], v[162:165], v[142:145]
	v_mfma_f32_16x16x32_bf16 v[138:141], v[122:125], v[162:165], v[138:141]
	v_mfma_f32_16x16x32_bf16 v[110:113], v[114:117], v[216:219], v[110:113]
	v_mfma_f32_16x16x32_bf16 v[106:109], v[122:125], v[216:219], v[106:109]
	v_mfma_f32_16x16x32_bf16 v[98:101], v[114:117], v[224:227], v[98:101]
	v_mfma_f32_16x16x32_bf16 v[90:93], v[122:125], v[224:227], v[90:93]
	v_mfma_f32_16x16x32_bf16 v[82:85], v[114:117], v[232:235], v[82:85]
	v_mfma_f32_16x16x32_bf16 v[74:77], v[122:125], v[232:235], v[74:77]
	v_mfma_f32_16x16x32_bf16 v[142:145], v[118:121], v[166:169], v[142:145]
	v_mfma_f32_16x16x32_bf16 v[138:141], v[126:129], v[166:169], v[138:141]
	v_mfma_f32_16x16x32_bf16 v[110:113], v[118:121], v[220:223], v[110:113]
	v_mfma_f32_16x16x32_bf16 v[106:109], v[126:129], v[220:223], v[106:109]
	v_mfma_f32_16x16x32_bf16 v[98:101], v[118:121], v[228:231], v[98:101]
	v_mfma_f32_16x16x32_bf16 v[90:93], v[126:129], v[228:231], v[90:93]
	v_mfma_f32_16x16x32_bf16 v[82:85], v[118:121], v[236:239], v[82:85]
	v_mfma_f32_16x16x32_bf16 v[74:77], v[126:129], v[236:239], v[74:77]
	v_mfma_f32_16x16x32_bf16 v[134:137], v[146:149], v[162:165], v[134:137]
	v_mfma_f32_16x16x32_bf16 v[130:133], v[154:157], v[162:165], v[130:133]
	v_mfma_f32_16x16x32_bf16 v[102:105], v[146:149], v[216:219], v[102:105]
	v_mfma_f32_16x16x32_bf16 v[94:97], v[154:157], v[216:219], v[94:97]
	v_mfma_f32_16x16x32_bf16 v[86:89], v[146:149], v[224:227], v[86:89]
	v_mfma_f32_16x16x32_bf16 v[78:81], v[154:157], v[224:227], v[78:81]
	v_mfma_f32_16x16x32_bf16 v[70:73], v[146:149], v[232:235], v[70:73]
	v_mfma_f32_16x16x32_bf16 v[66:69], v[154:157], v[232:235], v[66:69]
	v_mfma_f32_16x16x32_bf16 v[134:137], v[150:153], v[166:169], v[134:137]
	v_mfma_f32_16x16x32_bf16 v[130:133], v[158:161], v[166:169], v[130:133]
	v_mfma_f32_16x16x32_bf16 v[102:105], v[150:153], v[220:223], v[102:105]
	v_mfma_f32_16x16x32_bf16 v[94:97], v[158:161], v[220:223], v[94:97]
	v_mfma_f32_16x16x32_bf16 v[86:89], v[150:153], v[228:231], v[86:89]
	v_mfma_f32_16x16x32_bf16 v[78:81], v[158:161], v[228:231], v[78:81]
	v_mfma_f32_16x16x32_bf16 v[70:73], v[150:153], v[236:239], v[70:73]
	v_mfma_f32_16x16x32_bf16 v[66:69], v[158:161], v[236:239], v[66:69]
	s_setprio 0
	s_barrier
	s_add_i32 s62, s62, s17
	s_mov_b32 m0, s62
	v_lshl_add_u64 v[202:203], v[202:203], 0, s[76:77]
	global_load_lds_dwordx4 v[202:203], off
	ds_read_b128 v[162:165], v214 offset:49152
	ds_read_b128 v[166:169], v214 offset:50176
	s_add_i32 m0, s62, 0x2000
	s_add_u32 s72, s94, 0x40080
	v_lshl_add_u64 v[202:203], v[240:241], 0, s[76:77]
	s_addc_u32 s73, s95, 0
	s_add_i32 s62, s63, s17
	global_load_lds_dwordx4 v[202:203], off
	ds_read_b128 v[216:219], v214 offset:51200
	ds_read_b128 v[220:223], v214 offset:52224
	s_mov_b32 m0, s62
	v_lshl_add_u64 v[202:203], s[72:73], 0, v[174:175]
	global_load_lds_dwordx4 v[202:203], off
	ds_read_b128 v[224:227], v214 offset:53248
	ds_read_b128 v[228:231], v214 offset:54272
	s_add_i32 m0, s62, 0x2000
	v_lshl_add_u64 v[202:203], s[72:73], 0, v[178:179]
	global_load_lds_dwordx4 v[202:203], off
	ds_read_b128 v[232:235], v214 offset:55296
	ds_read_b128 v[236:239], v214 offset:56320
	s_mov_b32 m0, s44
	v_lshl_add_u64 v[202:203], v[242:243], 0, s[76:77]
	global_load_lds_dwordx4 v[202:203], off
	s_mov_b32 m0, s36
	v_lshl_add_u64 v[202:203], v[244:245], 0, s[76:77]
	global_load_lds_dwordx4 v[202:203], off
	s_waitcnt vmcnt(8) lgkmcnt(0)
	s_setprio 1
	s_barrier
	v_mfma_f32_16x16x32_bf16 v[62:65], v[114:117], v[162:165], v[62:65]
	v_mfma_f32_16x16x32_bf16 v[58:61], v[122:125], v[162:165], v[58:61]
	v_mfma_f32_16x16x32_bf16 v[50:53], v[114:117], v[216:219], v[50:53]
	v_mfma_f32_16x16x32_bf16 v[42:45], v[122:125], v[216:219], v[42:45]
	v_mfma_f32_16x16x32_bf16 v[34:37], v[114:117], v[224:227], v[34:37]
	v_mfma_f32_16x16x32_bf16 v[26:29], v[122:125], v[224:227], v[26:29]
	v_mfma_f32_16x16x32_bf16 v[18:21], v[114:117], v[232:235], v[18:21]
	v_mfma_f32_16x16x32_bf16 v[10:13], v[122:125], v[232:235], v[10:13]
	v_mfma_f32_16x16x32_bf16 v[62:65], v[118:121], v[166:169], v[62:65]
	v_mfma_f32_16x16x32_bf16 v[58:61], v[126:129], v[166:169], v[58:61]
	v_mfma_f32_16x16x32_bf16 v[50:53], v[118:121], v[220:223], v[50:53]
	v_mfma_f32_16x16x32_bf16 v[42:45], v[126:129], v[220:223], v[42:45]
	v_mfma_f32_16x16x32_bf16 v[34:37], v[118:121], v[228:231], v[34:37]
	v_mfma_f32_16x16x32_bf16 v[26:29], v[126:129], v[228:231], v[26:29]
	v_mfma_f32_16x16x32_bf16 v[18:21], v[118:121], v[236:239], v[18:21]
	v_mfma_f32_16x16x32_bf16 v[10:13], v[126:129], v[236:239], v[10:13]
	v_mfma_f32_16x16x32_bf16 v[54:57], v[146:149], v[162:165], v[54:57]
	v_mfma_f32_16x16x32_bf16 v[46:49], v[154:157], v[162:165], v[46:49]
	v_mfma_f32_16x16x32_bf16 v[38:41], v[146:149], v[216:219], v[38:41]
	v_mfma_f32_16x16x32_bf16 v[30:33], v[154:157], v[216:219], v[30:33]
	v_mfma_f32_16x16x32_bf16 v[22:25], v[146:149], v[224:227], v[22:25]
	v_mfma_f32_16x16x32_bf16 v[14:17], v[154:157], v[224:227], v[14:17]
	v_mfma_f32_16x16x32_bf16 v[6:9], v[146:149], v[232:235], v[6:9]
	v_mfma_f32_16x16x32_bf16 v[2:5], v[154:157], v[232:235], v[2:5]
	v_mfma_f32_16x16x32_bf16 v[54:57], v[150:153], v[166:169], v[54:57]
	v_mfma_f32_16x16x32_bf16 v[46:49], v[158:161], v[166:169], v[46:49]
	v_mfma_f32_16x16x32_bf16 v[38:41], v[150:153], v[220:223], v[38:41]
	v_mfma_f32_16x16x32_bf16 v[30:33], v[158:161], v[220:223], v[30:33]
	v_mfma_f32_16x16x32_bf16 v[22:25], v[150:153], v[228:231], v[22:25]
	v_mfma_f32_16x16x32_bf16 v[14:17], v[158:161], v[228:231], v[14:17]
	v_mfma_f32_16x16x32_bf16 v[6:9], v[150:153], v[236:239], v[6:9]
	v_mfma_f32_16x16x32_bf16 v[2:5], v[158:161], v[236:239], v[2:5]
	s_setprio 0
	s_barrier
	s_add_u32 s10, s10, 0x100
	s_addc_u32 s11, s11, 0
	s_add_u32 vcc_lo, vcc_lo, 0x100
	s_addc_u32 vcc_hi, vcc_hi, 0
	s_cmp_ge_i32 s66, s18
	s_mov_b32 s94, s66
.LBB0_1428:
	s_add_i32 s66, s94, 2
	s_add_u32 s67, s10, 0xfffc0080
	s_addc_u32 s72, s11, -1
	s_cmp_eq_u32 s85, s94
	s_cselect_b32 s97, s14, s72
	s_cselect_b32 s96, s15, s67
	s_cselect_b32 s95, s51, vcc_hi
	s_cselect_b32 s94, s84, vcc_lo
	s_add_i32 s67, 0, 0x10000
	s_add_i32 s62, 0, 0x14000
	v_add_u32_e32 v126, s67, v199
	v_add_u32_e32 v158, s62, v199
	ds_read_b128 v[114:117], v126
	ds_read_b128 v[118:121], v126 offset:1024
	ds_read_b128 v[122:125], v126 offset:2048
	ds_read_b128 v[126:129], v126 offset:3072
	ds_read_b128 v[146:149], v158
	ds_read_b128 v[150:153], v158 offset:1024
	ds_read_b128 v[154:157], v158 offset:2048
	ds_read_b128 v[158:161], v158 offset:3072
	v_lshl_add_u64 v[202:203], s[10:11], 0, v[196:197]
	s_add_i32 m0, s28, 0xc000
	ds_read_b128 v[162:165], v214
	ds_read_b128 v[166:169], v214 offset:1024
	ds_read_b128 v[216:219], v214 offset:2048
	ds_read_b128 v[220:223], v214 offset:3072
	ds_read_b128 v[224:227], v214 offset:4096
	ds_read_b128 v[228:231], v214 offset:5120
	ds_read_b128 v[232:235], v214 offset:6144
	ds_read_b128 v[236:239], v214 offset:7168
	global_load_lds_dwordx4 v[202:203], off
	s_add_i32 m0, s28, 0xe000
	v_lshl_add_u64 v[202:203], s[10:11], 0, v[176:177]
	global_load_lds_dwordx4 v[202:203], off
	s_waitcnt vmcnt(8) lgkmcnt(0)
	s_setprio 1
	s_barrier
	v_mfma_f32_16x16x32_bf16 v[142:145], v[114:117], v[162:165], v[142:145]
	v_mfma_f32_16x16x32_bf16 v[138:141], v[122:125], v[162:165], v[138:141]
	v_mfma_f32_16x16x32_bf16 v[110:113], v[114:117], v[216:219], v[110:113]
	v_mfma_f32_16x16x32_bf16 v[106:109], v[122:125], v[216:219], v[106:109]
	v_mfma_f32_16x16x32_bf16 v[98:101], v[114:117], v[224:227], v[98:101]
	v_mfma_f32_16x16x32_bf16 v[90:93], v[122:125], v[224:227], v[90:93]
	v_mfma_f32_16x16x32_bf16 v[82:85], v[114:117], v[232:235], v[82:85]
	v_mfma_f32_16x16x32_bf16 v[74:77], v[122:125], v[232:235], v[74:77]
	v_mfma_f32_16x16x32_bf16 v[142:145], v[118:121], v[166:169], v[142:145]
	v_mfma_f32_16x16x32_bf16 v[138:141], v[126:129], v[166:169], v[138:141]
	v_mfma_f32_16x16x32_bf16 v[110:113], v[118:121], v[220:223], v[110:113]
	v_mfma_f32_16x16x32_bf16 v[106:109], v[126:129], v[220:223], v[106:109]
	v_mfma_f32_16x16x32_bf16 v[98:101], v[118:121], v[228:231], v[98:101]
	v_mfma_f32_16x16x32_bf16 v[90:93], v[126:129], v[228:231], v[90:93]
	v_mfma_f32_16x16x32_bf16 v[82:85], v[118:121], v[236:239], v[82:85]
	v_mfma_f32_16x16x32_bf16 v[74:77], v[126:129], v[236:239], v[74:77]
	v_mfma_f32_16x16x32_bf16 v[134:137], v[146:149], v[162:165], v[134:137]
	v_mfma_f32_16x16x32_bf16 v[130:133], v[154:157], v[162:165], v[130:133]
	v_mfma_f32_16x16x32_bf16 v[102:105], v[146:149], v[216:219], v[102:105]
	v_mfma_f32_16x16x32_bf16 v[94:97], v[154:157], v[216:219], v[94:97]
	v_mfma_f32_16x16x32_bf16 v[86:89], v[146:149], v[224:227], v[86:89]
	v_mfma_f32_16x16x32_bf16 v[78:81], v[154:157], v[224:227], v[78:81]
	v_mfma_f32_16x16x32_bf16 v[70:73], v[146:149], v[232:235], v[70:73]
	v_mfma_f32_16x16x32_bf16 v[66:69], v[154:157], v[232:235], v[66:69]
	v_mfma_f32_16x16x32_bf16 v[134:137], v[150:153], v[166:169], v[134:137]
	v_mfma_f32_16x16x32_bf16 v[130:133], v[158:161], v[166:169], v[130:133]
	v_mfma_f32_16x16x32_bf16 v[102:105], v[150:153], v[220:223], v[102:105]
	v_mfma_f32_16x16x32_bf16 v[94:97], v[158:161], v[220:223], v[94:97]
	v_mfma_f32_16x16x32_bf16 v[86:89], v[150:153], v[228:231], v[86:89]
	v_mfma_f32_16x16x32_bf16 v[78:81], v[158:161], v[228:231], v[78:81]
	v_mfma_f32_16x16x32_bf16 v[70:73], v[150:153], v[236:239], v[70:73]
	v_mfma_f32_16x16x32_bf16 v[66:69], v[158:161], v[236:239], v[66:69]
	s_setprio 0
	s_barrier
	s_add_i32 s63, s67, s17
	s_mov_b32 m0, s63
	v_lshl_add_u64 v[202:203], s[94:95], 0, v[174:175]
	global_load_lds_dwordx4 v[202:203], off
	ds_read_b128 v[162:165], v214 offset:16384
	ds_read_b128 v[166:169], v214 offset:17408
	s_add_i32 m0, s63, 0x2000
	s_add_u32 s72, s94, 0x40000
	v_lshl_add_u64 v[240:241], s[94:95], 0, v[178:179]
	s_addc_u32 s73, s95, 0
	s_add_i32 s62, s62, s17
	global_load_lds_dwordx4 v[240:241], off
	ds_read_b128 v[216:219], v214 offset:18432
	ds_read_b128 v[220:223], v214 offset:19456
	v_lshl_add_u64 v[242:243], s[72:73], 0, v[174:175]
	s_mov_b32 m0, s62
	v_lshl_add_u64 v[244:245], s[96:97], 0, v[176:177]
	global_load_lds_dwordx4 v[242:243], off
	ds_read_b128 v[224:227], v214 offset:20480
	ds_read_b128 v[228:231], v214 offset:21504
	s_add_i32 m0, s62, 0x2000
	v_lshl_add_u64 v[242:243], s[72:73], 0, v[178:179]
	global_load_lds_dwordx4 v[242:243], off
	ds_read_b128 v[232:235], v214 offset:22528
	ds_read_b128 v[236:239], v214 offset:23552
	s_mov_b32 m0, s28
	v_lshl_add_u64 v[242:243], s[96:97], 0, v[172:173]
	global_load_lds_dwordx4 v[242:243], off
	s_mov_b32 m0, s29
	s_nop 0
	global_load_lds_dwordx4 v[244:245], off
	s_waitcnt vmcnt(8) lgkmcnt(0)
	s_setprio 1
	s_barrier
	v_mfma_f32_16x16x32_bf16 v[62:65], v[114:117], v[162:165], v[62:65]
	v_mfma_f32_16x16x32_bf16 v[58:61], v[122:125], v[162:165], v[58:61]
	v_mfma_f32_16x16x32_bf16 v[50:53], v[114:117], v[216:219], v[50:53]
	v_mfma_f32_16x16x32_bf16 v[42:45], v[122:125], v[216:219], v[42:45]
	v_mfma_f32_16x16x32_bf16 v[34:37], v[114:117], v[224:227], v[34:37]
	v_mfma_f32_16x16x32_bf16 v[26:29], v[122:125], v[224:227], v[26:29]
	v_mfma_f32_16x16x32_bf16 v[18:21], v[114:117], v[232:235], v[18:21]
	v_mfma_f32_16x16x32_bf16 v[10:13], v[122:125], v[232:235], v[10:13]
	v_mfma_f32_16x16x32_bf16 v[62:65], v[118:121], v[166:169], v[62:65]
	v_mfma_f32_16x16x32_bf16 v[58:61], v[126:129], v[166:169], v[58:61]
	v_mfma_f32_16x16x32_bf16 v[50:53], v[118:121], v[220:223], v[50:53]
	v_mfma_f32_16x16x32_bf16 v[42:45], v[126:129], v[220:223], v[42:45]
	v_mfma_f32_16x16x32_bf16 v[34:37], v[118:121], v[228:231], v[34:37]
	v_mfma_f32_16x16x32_bf16 v[26:29], v[126:129], v[228:231], v[26:29]
	v_mfma_f32_16x16x32_bf16 v[18:21], v[118:121], v[236:239], v[18:21]
	v_mfma_f32_16x16x32_bf16 v[10:13], v[126:129], v[236:239], v[10:13]
	v_mfma_f32_16x16x32_bf16 v[54:57], v[146:149], v[162:165], v[54:57]
	v_mfma_f32_16x16x32_bf16 v[46:49], v[154:157], v[162:165], v[46:49]
	v_mfma_f32_16x16x32_bf16 v[38:41], v[146:149], v[216:219], v[38:41]
	v_mfma_f32_16x16x32_bf16 v[30:33], v[154:157], v[216:219], v[30:33]
	v_mfma_f32_16x16x32_bf16 v[22:25], v[146:149], v[224:227], v[22:25]
	v_mfma_f32_16x16x32_bf16 v[14:17], v[154:157], v[224:227], v[14:17]
	v_mfma_f32_16x16x32_bf16 v[6:9], v[146:149], v[232:235], v[6:9]
	v_mfma_f32_16x16x32_bf16 v[2:5], v[154:157], v[232:235], v[2:5]
	v_mfma_f32_16x16x32_bf16 v[54:57], v[150:153], v[166:169], v[54:57]
	v_mfma_f32_16x16x32_bf16 v[46:49], v[158:161], v[166:169], v[46:49]
	v_mfma_f32_16x16x32_bf16 v[38:41], v[150:153], v[220:223], v[38:41]
	v_mfma_f32_16x16x32_bf16 v[30:33], v[158:161], v[220:223], v[30:33]
	v_mfma_f32_16x16x32_bf16 v[22:25], v[150:153], v[228:231], v[22:25]
	v_mfma_f32_16x16x32_bf16 v[14:17], v[158:161], v[228:231], v[14:17]
	v_mfma_f32_16x16x32_bf16 v[6:9], v[150:153], v[236:239], v[6:9]
	v_mfma_f32_16x16x32_bf16 v[2:5], v[158:161], v[236:239], v[2:5]
	s_setprio 0
	s_barrier
	s_add_i32 s62, 0, 0x18000
	s_add_i32 s63, 0, 0x1c000
	v_add_u32_e32 v126, s62, v199
	v_add_u32_e32 v158, s63, v199
	ds_read_b128 v[114:117], v126
	ds_read_b128 v[118:121], v126 offset:1024
	ds_read_b128 v[122:125], v126 offset:2048
	ds_read_b128 v[126:129], v126 offset:3072
	ds_read_b128 v[146:149], v158
	ds_read_b128 v[150:153], v158 offset:1024
	ds_read_b128 v[154:157], v158 offset:2048
	ds_read_b128 v[158:161], v158 offset:3072
	s_add_u32 s72, s96, 0x40000
	s_addc_u32 s73, s97, 0
	s_mov_b32 m0, s30
	v_lshl_add_u64 v[246:247], s[72:73], 0, v[172:173]
	ds_read_b128 v[162:165], v214 offset:32768
	ds_read_b128 v[166:169], v214 offset:33792
	ds_read_b128 v[216:219], v214 offset:34816
	ds_read_b128 v[220:223], v214 offset:35840
	ds_read_b128 v[224:227], v214 offset:36864
	ds_read_b128 v[228:231], v214 offset:37888
	ds_read_b128 v[232:235], v214 offset:38912
	ds_read_b128 v[236:239], v214 offset:39936
	global_load_lds_dwordx4 v[246:247], off
	s_mov_b32 m0, s31
	v_lshl_add_u64 v[246:247], s[72:73], 0, v[176:177]
	global_load_lds_dwordx4 v[246:247], off
	s_waitcnt vmcnt(8) lgkmcnt(0)
	s_setprio 1
	s_barrier
	v_mfma_f32_16x16x32_bf16 v[142:145], v[114:117], v[162:165], v[142:145]
	v_mfma_f32_16x16x32_bf16 v[138:141], v[122:125], v[162:165], v[138:141]
	v_mfma_f32_16x16x32_bf16 v[110:113], v[114:117], v[216:219], v[110:113]
	v_mfma_f32_16x16x32_bf16 v[106:109], v[122:125], v[216:219], v[106:109]
	v_mfma_f32_16x16x32_bf16 v[98:101], v[114:117], v[224:227], v[98:101]
	v_mfma_f32_16x16x32_bf16 v[90:93], v[122:125], v[224:227], v[90:93]
	v_mfma_f32_16x16x32_bf16 v[82:85], v[114:117], v[232:235], v[82:85]
	v_mfma_f32_16x16x32_bf16 v[74:77], v[122:125], v[232:235], v[74:77]
	v_mfma_f32_16x16x32_bf16 v[142:145], v[118:121], v[166:169], v[142:145]
	v_mfma_f32_16x16x32_bf16 v[138:141], v[126:129], v[166:169], v[138:141]
	v_mfma_f32_16x16x32_bf16 v[110:113], v[118:121], v[220:223], v[110:113]
	v_mfma_f32_16x16x32_bf16 v[106:109], v[126:129], v[220:223], v[106:109]
	v_mfma_f32_16x16x32_bf16 v[98:101], v[118:121], v[228:231], v[98:101]
	v_mfma_f32_16x16x32_bf16 v[90:93], v[126:129], v[228:231], v[90:93]
	v_mfma_f32_16x16x32_bf16 v[82:85], v[118:121], v[236:239], v[82:85]
	v_mfma_f32_16x16x32_bf16 v[74:77], v[126:129], v[236:239], v[74:77]
	v_mfma_f32_16x16x32_bf16 v[134:137], v[146:149], v[162:165], v[134:137]
	v_mfma_f32_16x16x32_bf16 v[130:133], v[154:157], v[162:165], v[130:133]
	v_mfma_f32_16x16x32_bf16 v[102:105], v[146:149], v[216:219], v[102:105]
	v_mfma_f32_16x16x32_bf16 v[94:97], v[154:157], v[216:219], v[94:97]
	v_mfma_f32_16x16x32_bf16 v[86:89], v[146:149], v[224:227], v[86:89]
	v_mfma_f32_16x16x32_bf16 v[78:81], v[154:157], v[224:227], v[78:81]
	v_mfma_f32_16x16x32_bf16 v[70:73], v[146:149], v[232:235], v[70:73]
	v_mfma_f32_16x16x32_bf16 v[66:69], v[154:157], v[232:235], v[66:69]
	v_mfma_f32_16x16x32_bf16 v[134:137], v[150:153], v[166:169], v[134:137]
	v_mfma_f32_16x16x32_bf16 v[130:133], v[158:161], v[166:169], v[130:133]
	v_mfma_f32_16x16x32_bf16 v[102:105], v[150:153], v[220:223], v[102:105]
	v_mfma_f32_16x16x32_bf16 v[94:97], v[158:161], v[220:223], v[94:97]
	v_mfma_f32_16x16x32_bf16 v[86:89], v[150:153], v[228:231], v[86:89]
	v_mfma_f32_16x16x32_bf16 v[78:81], v[158:161], v[228:231], v[78:81]
	v_mfma_f32_16x16x32_bf16 v[70:73], v[150:153], v[236:239], v[70:73]
	v_mfma_f32_16x16x32_bf16 v[66:69], v[158:161], v[236:239], v[66:69]
	s_setprio 0
	s_barrier
	s_add_i32 s62, s62, s17
	s_mov_b32 m0, s62
	v_lshl_add_u64 v[202:203], v[202:203], 0, s[76:77]
	global_load_lds_dwordx4 v[202:203], off
	ds_read_b128 v[162:165], v214 offset:49152
	ds_read_b128 v[166:169], v214 offset:50176
	s_add_i32 m0, s62, 0x2000
	s_add_u32 s72, s94, 0x40080
	v_lshl_add_u64 v[202:203], v[240:241], 0, s[76:77]
	s_addc_u32 s73, s95, 0
	s_add_i32 s62, s63, s17
	global_load_lds_dwordx4 v[202:203], off
	ds_read_b128 v[216:219], v214 offset:51200
	ds_read_b128 v[220:223], v214 offset:52224
	s_mov_b32 m0, s62
	v_lshl_add_u64 v[202:203], s[72:73], 0, v[174:175]
	global_load_lds_dwordx4 v[202:203], off
	ds_read_b128 v[224:227], v214 offset:53248
	ds_read_b128 v[228:231], v214 offset:54272
	s_add_i32 m0, s62, 0x2000
	v_lshl_add_u64 v[202:203], s[72:73], 0, v[178:179]
	global_load_lds_dwordx4 v[202:203], off
	ds_read_b128 v[232:235], v214 offset:55296
	ds_read_b128 v[236:239], v214 offset:56320
	s_mov_b32 m0, s44
	v_lshl_add_u64 v[202:203], v[242:243], 0, s[76:77]
	global_load_lds_dwordx4 v[202:203], off
	s_mov_b32 m0, s36
	v_lshl_add_u64 v[202:203], v[244:245], 0, s[76:77]
	global_load_lds_dwordx4 v[202:203], off
	s_waitcnt vmcnt(8) lgkmcnt(0)
	s_setprio 1
	s_barrier
	v_mfma_f32_16x16x32_bf16 v[62:65], v[114:117], v[162:165], v[62:65]
	v_mfma_f32_16x16x32_bf16 v[58:61], v[122:125], v[162:165], v[58:61]
	v_mfma_f32_16x16x32_bf16 v[50:53], v[114:117], v[216:219], v[50:53]
	v_mfma_f32_16x16x32_bf16 v[42:45], v[122:125], v[216:219], v[42:45]
	v_mfma_f32_16x16x32_bf16 v[34:37], v[114:117], v[224:227], v[34:37]
	v_mfma_f32_16x16x32_bf16 v[26:29], v[122:125], v[224:227], v[26:29]
	v_mfma_f32_16x16x32_bf16 v[18:21], v[114:117], v[232:235], v[18:21]
	v_mfma_f32_16x16x32_bf16 v[10:13], v[122:125], v[232:235], v[10:13]
	v_mfma_f32_16x16x32_bf16 v[62:65], v[118:121], v[166:169], v[62:65]
	v_mfma_f32_16x16x32_bf16 v[58:61], v[126:129], v[166:169], v[58:61]
	v_mfma_f32_16x16x32_bf16 v[50:53], v[118:121], v[220:223], v[50:53]
	v_mfma_f32_16x16x32_bf16 v[42:45], v[126:129], v[220:223], v[42:45]
	v_mfma_f32_16x16x32_bf16 v[34:37], v[118:121], v[228:231], v[34:37]
	v_mfma_f32_16x16x32_bf16 v[26:29], v[126:129], v[228:231], v[26:29]
	v_mfma_f32_16x16x32_bf16 v[18:21], v[118:121], v[236:239], v[18:21]
	v_mfma_f32_16x16x32_bf16 v[10:13], v[126:129], v[236:239], v[10:13]
	v_mfma_f32_16x16x32_bf16 v[54:57], v[146:149], v[162:165], v[54:57]
	v_mfma_f32_16x16x32_bf16 v[46:49], v[154:157], v[162:165], v[46:49]
	v_mfma_f32_16x16x32_bf16 v[38:41], v[146:149], v[216:219], v[38:41]
	v_mfma_f32_16x16x32_bf16 v[30:33], v[154:157], v[216:219], v[30:33]
	v_mfma_f32_16x16x32_bf16 v[22:25], v[146:149], v[224:227], v[22:25]
	v_mfma_f32_16x16x32_bf16 v[14:17], v[154:157], v[224:227], v[14:17]
	v_mfma_f32_16x16x32_bf16 v[6:9], v[146:149], v[232:235], v[6:9]
	v_mfma_f32_16x16x32_bf16 v[2:5], v[154:157], v[232:235], v[2:5]
	v_mfma_f32_16x16x32_bf16 v[54:57], v[150:153], v[166:169], v[54:57]
	v_mfma_f32_16x16x32_bf16 v[46:49], v[158:161], v[166:169], v[46:49]
	v_mfma_f32_16x16x32_bf16 v[38:41], v[150:153], v[220:223], v[38:41]
	v_mfma_f32_16x16x32_bf16 v[30:33], v[158:161], v[220:223], v[30:33]
	v_mfma_f32_16x16x32_bf16 v[22:25], v[150:153], v[228:231], v[22:25]
	v_mfma_f32_16x16x32_bf16 v[14:17], v[158:161], v[228:231], v[14:17]
	v_mfma_f32_16x16x32_bf16 v[6:9], v[150:153], v[236:239], v[6:9]
	v_mfma_f32_16x16x32_bf16 v[2:5], v[158:161], v[236:239], v[2:5]
	s_setprio 0
	s_barrier
	s_add_u32 s10, s10, 0x100
	s_addc_u32 s11, s11, 0
	s_add_u32 vcc_lo, vcc_lo, 0x100
	s_addc_u32 vcc_hi, vcc_hi, 0
	s_cmp_ge_i32 s66, s18
	s_mov_b32 s94, s66
	s_cbranch_scc0 .LBB0_1428
	s_and_b64 vcc, exec, s[82:83]
	s_cbranch_vccz .LBB0_1431
	s_barrier

.LBB0_1618:
	s_add_u32 s24, s96, s20
	s_addc_u32 s25, s97, s21
	s_and_b64 s[14:15], s[4:5], exec
	s_cselect_b32 s14, s25, s29
	s_cselect_b32 s15, s24, s28
	s_add_u32 s26, s2, s22
	s_addc_u32 s27, s3, s23
	s_and_b64 s[36:37], s[4:5], exec
	s_cselect_b32 s17, s27, s31
	s_cselect_b32 s49, s26, s30
	s_add_u32 s28, s28, 0x40080
	s_addc_u32 s29, s29, 0
	s_add_u32 s50, s30, 0x100
	s_addc_u32 s51, s31, 0
	s_mov_b32 s62, -2
	ds_read_b128 v[154:157], v150
	ds_read_b128 v[158:161], v150 offset:1024
	ds_read_b128 v[162:165], v150 offset:2048
	ds_read_b128 v[166:169], v150 offset:3072
	ds_read_b128 v[170:173], v151
	ds_read_b128 v[174:177], v151 offset:1024
	ds_read_b128 v[178:181], v151 offset:2048
	ds_read_b128 v[182:185], v151 offset:3072
	s_add_u32 s30, s28, 0xfffc0080
	s_addc_u32 s31, s29, -1
	s_cmp_eq_u32 s62, 12
	s_cselect_b32 s37, s14, s31
	s_cselect_b32 s36, s15, s30
	s_cselect_b32 s31, s17, s51
	s_cselect_b32 s30, s49, s50
	v_lshl_add_u64 v[146:147], s[28:29], 0, v[138:139]
	s_add_i32 m0, s19, 0xc000
	ds_read_b128 v[186:189], v152
	ds_read_b128 v[190:193], v152 offset:1024
	ds_read_b128 v[194:197], v152 offset:2048
	ds_read_b128 v[198:201], v152 offset:3072
	ds_read_b128 v[206:209], v152 offset:4096
	ds_read_b128 v[210:213], v152 offset:5120
	ds_read_b128 v[214:217], v152 offset:6144
	ds_read_b128 v[218:221], v152 offset:7168
	global_load_lds_dwordx4 v[146:147], off
	s_add_i32 m0, s19, 0xe000
	v_lshl_add_u64 v[146:147], s[28:29], 0, v[140:141]
	global_load_lds_dwordx4 v[146:147], off
	s_waitcnt vmcnt(8) lgkmcnt(0)
	s_setprio 1
	s_barrier
	v_mfma_f32_16x16x32_bf16 v[126:129], v[154:157], v[186:189], 0
	v_mfma_f32_16x16x32_bf16 v[122:125], v[162:165], v[186:189], 0
	v_mfma_f32_16x16x32_bf16 v[110:113], v[154:157], v[194:197], 0
	v_mfma_f32_16x16x32_bf16 v[106:109], v[162:165], v[194:197], 0
	v_mfma_f32_16x16x32_bf16 v[94:97], v[154:157], v[206:209], 0
	v_mfma_f32_16x16x32_bf16 v[90:93], v[162:165], v[206:209], 0
	v_mfma_f32_16x16x32_bf16 v[78:81], v[154:157], v[214:217], 0
	v_mfma_f32_16x16x32_bf16 v[74:77], v[162:165], v[214:217], 0
	v_mfma_f32_16x16x32_bf16 v[126:129], v[158:161], v[190:193], v[126:129]
	v_mfma_f32_16x16x32_bf16 v[122:125], v[166:169], v[190:193], v[122:125]
	v_mfma_f32_16x16x32_bf16 v[110:113], v[158:161], v[198:201], v[110:113]
	v_mfma_f32_16x16x32_bf16 v[106:109], v[166:169], v[198:201], v[106:109]
	v_mfma_f32_16x16x32_bf16 v[94:97], v[158:161], v[210:213], v[94:97]
	v_mfma_f32_16x16x32_bf16 v[90:93], v[166:169], v[210:213], v[90:93]
	v_mfma_f32_16x16x32_bf16 v[78:81], v[158:161], v[218:221], v[78:81]
	v_mfma_f32_16x16x32_bf16 v[74:77], v[166:169], v[218:221], v[74:77]
	v_mfma_f32_16x16x32_bf16 v[118:121], v[170:173], v[186:189], 0
	v_mfma_f32_16x16x32_bf16 v[114:117], v[178:181], v[186:189], 0
	v_mfma_f32_16x16x32_bf16 v[102:105], v[170:173], v[194:197], 0
	v_mfma_f32_16x16x32_bf16 v[98:101], v[178:181], v[194:197], 0
	v_mfma_f32_16x16x32_bf16 v[86:89], v[170:173], v[206:209], 0
	v_mfma_f32_16x16x32_bf16 v[82:85], v[178:181], v[206:209], 0
	v_mfma_f32_16x16x32_bf16 v[70:73], v[170:173], v[214:217], 0
	v_mfma_f32_16x16x32_bf16 v[66:69], v[178:181], v[214:217], 0
	v_mfma_f32_16x16x32_bf16 v[118:121], v[174:177], v[190:193], v[118:121]
	v_mfma_f32_16x16x32_bf16 v[114:117], v[182:185], v[190:193], v[114:117]
	v_mfma_f32_16x16x32_bf16 v[102:105], v[174:177], v[198:201], v[102:105]
	v_mfma_f32_16x16x32_bf16 v[98:101], v[182:185], v[198:201], v[98:101]
	v_mfma_f32_16x16x32_bf16 v[86:89], v[174:177], v[210:213], v[86:89]
	v_mfma_f32_16x16x32_bf16 v[82:85], v[182:185], v[210:213], v[82:85]
	v_mfma_f32_16x16x32_bf16 v[70:73], v[174:177], v[218:221], v[70:73]
	v_mfma_f32_16x16x32_bf16 v[66:69], v[182:185], v[218:221], v[66:69]
	s_setprio 0
	s_barrier
	s_add_i32 s63, s45, s12
	s_mov_b32 m0, s63
	v_lshl_add_u64 v[146:147], s[30:31], 0, v[134:135]
	global_load_lds_dwordx4 v[146:147], off
	ds_read_b128 v[186:189], v152 offset:16384
	ds_read_b128 v[190:193], v152 offset:17408
	s_add_i32 m0, s63, 0x2000
	s_add_u32 s64, s30, 0x40000
	v_lshl_add_u64 v[202:203], s[30:31], 0, v[130:131]
	s_addc_u32 s65, s31, 0
	s_add_i32 s63, s46, s12
	global_load_lds_dwordx4 v[202:203], off
	ds_read_b128 v[194:197], v152 offset:18432
	ds_read_b128 v[198:201], v152 offset:19456
	v_lshl_add_u64 v[222:223], s[64:65], 0, v[134:135]
	s_mov_b32 m0, s63
	v_lshl_add_u64 v[224:225], s[36:37], 0, v[132:133]
	global_load_lds_dwordx4 v[222:223], off
	ds_read_b128 v[206:209], v152 offset:20480
	ds_read_b128 v[210:213], v152 offset:21504
	s_add_i32 m0, s63, 0x2000
	v_lshl_add_u64 v[222:223], s[64:65], 0, v[130:131]
	global_load_lds_dwordx4 v[222:223], off
	ds_read_b128 v[214:217], v152 offset:22528
	ds_read_b128 v[218:221], v152 offset:23552
	s_mov_b32 m0, s19
	v_lshl_add_u64 v[222:223], s[36:37], 0, v[136:137]
	global_load_lds_dwordx4 v[222:223], off
	s_mov_b32 m0, s33
	s_nop 0
	global_load_lds_dwordx4 v[224:225], off
	s_waitcnt vmcnt(8) lgkmcnt(0)
	s_setprio 1
	s_barrier
	v_mfma_f32_16x16x32_bf16 v[62:65], v[154:157], v[186:189], 0
	v_mfma_f32_16x16x32_bf16 v[58:61], v[162:165], v[186:189], 0
	v_mfma_f32_16x16x32_bf16 v[46:49], v[154:157], v[194:197], 0
	v_mfma_f32_16x16x32_bf16 v[42:45], v[162:165], v[194:197], 0
	v_mfma_f32_16x16x32_bf16 v[30:33], v[154:157], v[206:209], 0
	v_mfma_f32_16x16x32_bf16 v[26:29], v[162:165], v[206:209], 0
	v_mfma_f32_16x16x32_bf16 v[14:17], v[154:157], v[214:217], 0
	v_mfma_f32_16x16x32_bf16 v[10:13], v[162:165], v[214:217], 0
	v_mfma_f32_16x16x32_bf16 v[62:65], v[158:161], v[190:193], v[62:65]
	v_mfma_f32_16x16x32_bf16 v[58:61], v[166:169], v[190:193], v[58:61]
	v_mfma_f32_16x16x32_bf16 v[46:49], v[158:161], v[198:201], v[46:49]
	v_mfma_f32_16x16x32_bf16 v[42:45], v[166:169], v[198:201], v[42:45]
	v_mfma_f32_16x16x32_bf16 v[30:33], v[158:161], v[210:213], v[30:33]
	v_mfma_f32_16x16x32_bf16 v[26:29], v[166:169], v[210:213], v[26:29]
	v_mfma_f32_16x16x32_bf16 v[14:17], v[158:161], v[218:221], v[14:17]
	v_mfma_f32_16x16x32_bf16 v[10:13], v[166:169], v[218:221], v[10:13]
	v_mfma_f32_16x16x32_bf16 v[54:57], v[170:173], v[186:189], 0
	v_mfma_f32_16x16x32_bf16 v[50:53], v[178:181], v[186:189], 0
	v_mfma_f32_16x16x32_bf16 v[38:41], v[170:173], v[194:197], 0
	v_mfma_f32_16x16x32_bf16 v[34:37], v[178:181], v[194:197], 0
	v_mfma_f32_16x16x32_bf16 v[22:25], v[170:173], v[206:209], 0
	v_mfma_f32_16x16x32_bf16 v[18:21], v[178:181], v[206:209], 0
	v_mfma_f32_16x16x32_bf16 v[6:9], v[170:173], v[214:217], 0
	v_mfma_f32_16x16x32_bf16 v[2:5], v[178:181], v[214:217], 0
	v_mfma_f32_16x16x32_bf16 v[54:57], v[174:177], v[190:193], v[54:57]
	v_mfma_f32_16x16x32_bf16 v[50:53], v[182:185], v[190:193], v[50:53]
	v_mfma_f32_16x16x32_bf16 v[38:41], v[174:177], v[198:201], v[38:41]
	v_mfma_f32_16x16x32_bf16 v[34:37], v[182:185], v[198:201], v[34:37]
	v_mfma_f32_16x16x32_bf16 v[22:25], v[174:177], v[210:213], v[22:25]
	v_mfma_f32_16x16x32_bf16 v[18:21], v[182:185], v[210:213], v[18:21]
	v_mfma_f32_16x16x32_bf16 v[6:9], v[174:177], v[218:221], v[6:9]
	v_mfma_f32_16x16x32_bf16 v[2:5], v[182:185], v[218:221], v[2:5]
	s_setprio 0
	s_barrier
	s_add_i32 s63, 0, 0x18000
	v_add_u32_e32 v153, s63, v149
	s_add_i32 s64, 0, 0x1c000
	ds_read_b128 v[154:157], v153
	ds_read_b128 v[158:161], v153 offset:1024
	ds_read_b128 v[162:165], v153 offset:2048
	ds_read_b128 v[166:169], v153 offset:3072
	v_add_u32_e32 v153, s64, v149
	ds_read_b128 v[170:173], v153
	ds_read_b128 v[174:177], v153 offset:1024
	ds_read_b128 v[178:181], v153 offset:2048
	ds_read_b128 v[182:185], v153 offset:3072
	s_add_u32 s36, s36, 0x40000
	s_addc_u32 s37, s37, 0
	s_mov_b32 m0, s35
	v_lshl_add_u64 v[226:227], s[36:37], 0, v[136:137]
	ds_read_b128 v[186:189], v152 offset:32768
	ds_read_b128 v[190:193], v152 offset:33792
	ds_read_b128 v[194:197], v152 offset:34816
	ds_read_b128 v[198:201], v152 offset:35840
	ds_read_b128 v[206:209], v152 offset:36864
	ds_read_b128 v[210:213], v152 offset:37888
	ds_read_b128 v[214:217], v152 offset:38912
	ds_read_b128 v[218:221], v152 offset:39936
	global_load_lds_dwordx4 v[226:227], off
	s_mov_b32 m0, s38
	v_lshl_add_u64 v[226:227], s[36:37], 0, v[132:133]
	global_load_lds_dwordx4 v[226:227], off
	s_waitcnt vmcnt(8) lgkmcnt(0)
	s_setprio 1
	s_barrier
	v_mfma_f32_16x16x32_bf16 v[126:129], v[154:157], v[186:189], v[126:129]
	v_mfma_f32_16x16x32_bf16 v[122:125], v[162:165], v[186:189], v[122:125]
	v_mfma_f32_16x16x32_bf16 v[110:113], v[154:157], v[194:197], v[110:113]
	v_mfma_f32_16x16x32_bf16 v[106:109], v[162:165], v[194:197], v[106:109]
	v_mfma_f32_16x16x32_bf16 v[94:97], v[154:157], v[206:209], v[94:97]
	v_mfma_f32_16x16x32_bf16 v[90:93], v[162:165], v[206:209], v[90:93]
	v_mfma_f32_16x16x32_bf16 v[78:81], v[154:157], v[214:217], v[78:81]
	v_mfma_f32_16x16x32_bf16 v[74:77], v[162:165], v[214:217], v[74:77]
	v_mfma_f32_16x16x32_bf16 v[126:129], v[158:161], v[190:193], v[126:129]
	v_mfma_f32_16x16x32_bf16 v[122:125], v[166:169], v[190:193], v[122:125]
	v_mfma_f32_16x16x32_bf16 v[110:113], v[158:161], v[198:201], v[110:113]
	v_mfma_f32_16x16x32_bf16 v[106:109], v[166:169], v[198:201], v[106:109]
	v_mfma_f32_16x16x32_bf16 v[94:97], v[158:161], v[210:213], v[94:97]
	v_mfma_f32_16x16x32_bf16 v[90:93], v[166:169], v[210:213], v[90:93]
	v_mfma_f32_16x16x32_bf16 v[78:81], v[158:161], v[218:221], v[78:81]
	v_mfma_f32_16x16x32_bf16 v[74:77], v[166:169], v[218:221], v[74:77]
	v_mfma_f32_16x16x32_bf16 v[118:121], v[170:173], v[186:189], v[118:121]
	v_mfma_f32_16x16x32_bf16 v[114:117], v[178:181], v[186:189], v[114:117]
	v_mfma_f32_16x16x32_bf16 v[102:105], v[170:173], v[194:197], v[102:105]
	v_mfma_f32_16x16x32_bf16 v[98:101], v[178:181], v[194:197], v[98:101]
	v_mfma_f32_16x16x32_bf16 v[86:89], v[170:173], v[206:209], v[86:89]
	v_mfma_f32_16x16x32_bf16 v[82:85], v[178:181], v[206:209], v[82:85]
	v_mfma_f32_16x16x32_bf16 v[70:73], v[170:173], v[214:217], v[70:73]
	v_mfma_f32_16x16x32_bf16 v[66:69], v[178:181], v[214:217], v[66:69]
	v_mfma_f32_16x16x32_bf16 v[118:121], v[174:177], v[190:193], v[118:121]
	v_mfma_f32_16x16x32_bf16 v[114:117], v[182:185], v[190:193], v[114:117]
	v_mfma_f32_16x16x32_bf16 v[102:105], v[174:177], v[198:201], v[102:105]
	v_mfma_f32_16x16x32_bf16 v[98:101], v[182:185], v[198:201], v[98:101]
	v_mfma_f32_16x16x32_bf16 v[86:89], v[174:177], v[210:213], v[86:89]
	v_mfma_f32_16x16x32_bf16 v[82:85], v[182:185], v[210:213], v[82:85]
	v_mfma_f32_16x16x32_bf16 v[70:73], v[174:177], v[218:221], v[70:73]
	v_mfma_f32_16x16x32_bf16 v[66:69], v[182:185], v[218:221], v[66:69]
	s_setprio 0
	s_barrier
	s_add_i32 s36, s63, s12
	s_mov_b32 m0, s36
	v_lshl_add_u64 v[146:147], v[146:147], 0, s[8:9]
	global_load_lds_dwordx4 v[146:147], off
	ds_read_b128 v[186:189], v152 offset:49152
	ds_read_b128 v[190:193], v152 offset:50176
	s_add_i32 m0, s36, 0x2000
	s_add_u32 s30, s30, 0x40080
	v_lshl_add_u64 v[146:147], v[202:203], 0, s[8:9]
	s_addc_u32 s31, s31, 0
	s_add_i32 s36, s64, s12
	global_load_lds_dwordx4 v[146:147], off
	ds_read_b128 v[194:197], v152 offset:51200
	ds_read_b128 v[198:201], v152 offset:52224
	s_mov_b32 m0, s36
	v_lshl_add_u64 v[146:147], s[30:31], 0, v[134:135]
	global_load_lds_dwordx4 v[146:147], off
	ds_read_b128 v[206:209], v152 offset:53248
	ds_read_b128 v[210:213], v152 offset:54272
	s_add_i32 m0, s36, 0x2000
	v_lshl_add_u64 v[146:147], s[30:31], 0, v[130:131]
	global_load_lds_dwordx4 v[146:147], off
	ds_read_b128 v[214:217], v152 offset:55296
	ds_read_b128 v[218:221], v152 offset:56320
	s_mov_b32 m0, s42
	v_lshl_add_u64 v[146:147], v[222:223], 0, s[8:9]
	global_load_lds_dwordx4 v[146:147], off
	s_mov_b32 m0, s43
	v_lshl_add_u64 v[146:147], v[224:225], 0, s[8:9]
	global_load_lds_dwordx4 v[146:147], off
	s_waitcnt vmcnt(8) lgkmcnt(0)
	s_setprio 1
	s_barrier
	v_mfma_f32_16x16x32_bf16 v[62:65], v[154:157], v[186:189], v[62:65]
	v_mfma_f32_16x16x32_bf16 v[58:61], v[162:165], v[186:189], v[58:61]
	v_mfma_f32_16x16x32_bf16 v[46:49], v[154:157], v[194:197], v[46:49]
	v_mfma_f32_16x16x32_bf16 v[42:45], v[162:165], v[194:197], v[42:45]
	v_mfma_f32_16x16x32_bf16 v[30:33], v[154:157], v[206:209], v[30:33]
	v_mfma_f32_16x16x32_bf16 v[26:29], v[162:165], v[206:209], v[26:29]
	v_mfma_f32_16x16x32_bf16 v[14:17], v[154:157], v[214:217], v[14:17]
	v_mfma_f32_16x16x32_bf16 v[10:13], v[162:165], v[214:217], v[10:13]
	v_mfma_f32_16x16x32_bf16 v[62:65], v[158:161], v[190:193], v[62:65]
	v_mfma_f32_16x16x32_bf16 v[58:61], v[166:169], v[190:193], v[58:61]
	v_mfma_f32_16x16x32_bf16 v[46:49], v[158:161], v[198:201], v[46:49]
	v_mfma_f32_16x16x32_bf16 v[42:45], v[166:169], v[198:201], v[42:45]
	v_mfma_f32_16x16x32_bf16 v[30:33], v[158:161], v[210:213], v[30:33]
	v_mfma_f32_16x16x32_bf16 v[26:29], v[166:169], v[210:213], v[26:29]
	v_mfma_f32_16x16x32_bf16 v[14:17], v[158:161], v[218:221], v[14:17]
	v_mfma_f32_16x16x32_bf16 v[10:13], v[166:169], v[218:221], v[10:13]
	v_mfma_f32_16x16x32_bf16 v[54:57], v[170:173], v[186:189], v[54:57]
	v_mfma_f32_16x16x32_bf16 v[50:53], v[178:181], v[186:189], v[50:53]
	v_mfma_f32_16x16x32_bf16 v[38:41], v[170:173], v[194:197], v[38:41]
	v_mfma_f32_16x16x32_bf16 v[34:37], v[178:181], v[194:197], v[34:37]
	v_mfma_f32_16x16x32_bf16 v[22:25], v[170:173], v[206:209], v[22:25]
	v_mfma_f32_16x16x32_bf16 v[18:21], v[178:181], v[206:209], v[18:21]
	v_mfma_f32_16x16x32_bf16 v[6:9], v[170:173], v[214:217], v[6:9]
	v_mfma_f32_16x16x32_bf16 v[2:5], v[178:181], v[214:217], v[2:5]
	v_mfma_f32_16x16x32_bf16 v[54:57], v[174:177], v[190:193], v[54:57]
	v_mfma_f32_16x16x32_bf16 v[50:53], v[182:185], v[190:193], v[50:53]
	v_mfma_f32_16x16x32_bf16 v[38:41], v[174:177], v[198:201], v[38:41]
	v_mfma_f32_16x16x32_bf16 v[34:37], v[182:185], v[198:201], v[34:37]
	v_mfma_f32_16x16x32_bf16 v[22:25], v[174:177], v[210:213], v[22:25]
	v_mfma_f32_16x16x32_bf16 v[18:21], v[182:185], v[210:213], v[18:21]
	v_mfma_f32_16x16x32_bf16 v[6:9], v[174:177], v[218:221], v[6:9]
	v_mfma_f32_16x16x32_bf16 v[2:5], v[182:185], v[218:221], v[2:5]
	s_setprio 0
	s_barrier
	s_add_i32 s62, s62, 2
	s_add_u32 s28, s28, 0x100
	s_addc_u32 s29, s29, 0
	s_add_u32 s50, s50, 0x100
	s_addc_u32 s51, s51, 0
	s_cmp_gt_u32 s62, 13
.LBB0_1619:
	ds_read_b128 v[154:157], v150
	ds_read_b128 v[158:161], v150 offset:1024
	ds_read_b128 v[162:165], v150 offset:2048
	ds_read_b128 v[166:169], v150 offset:3072
	ds_read_b128 v[170:173], v151
	ds_read_b128 v[174:177], v151 offset:1024
	ds_read_b128 v[178:181], v151 offset:2048
	ds_read_b128 v[182:185], v151 offset:3072
	s_add_u32 s30, s28, 0xfffc0080
	s_addc_u32 s31, s29, -1
	s_cmp_eq_u32 s62, 12
	s_cselect_b32 s37, s14, s31
	s_cselect_b32 s36, s15, s30
	s_cselect_b32 s31, s17, s51
	s_cselect_b32 s30, s49, s50
	v_lshl_add_u64 v[146:147], s[28:29], 0, v[138:139]
	s_add_i32 m0, s19, 0xc000
	ds_read_b128 v[186:189], v152
	ds_read_b128 v[190:193], v152 offset:1024
	ds_read_b128 v[194:197], v152 offset:2048
	ds_read_b128 v[198:201], v152 offset:3072
	ds_read_b128 v[206:209], v152 offset:4096
	ds_read_b128 v[210:213], v152 offset:5120
	ds_read_b128 v[214:217], v152 offset:6144
	ds_read_b128 v[218:221], v152 offset:7168
	global_load_lds_dwordx4 v[146:147], off
	s_add_i32 m0, s19, 0xe000
	v_lshl_add_u64 v[146:147], s[28:29], 0, v[140:141]
	global_load_lds_dwordx4 v[146:147], off
	s_waitcnt vmcnt(8) lgkmcnt(0)
	s_setprio 1
	s_barrier
	v_mfma_f32_16x16x32_bf16 v[126:129], v[154:157], v[186:189], v[126:129]
	v_mfma_f32_16x16x32_bf16 v[122:125], v[162:165], v[186:189], v[122:125]
	v_mfma_f32_16x16x32_bf16 v[110:113], v[154:157], v[194:197], v[110:113]
	v_mfma_f32_16x16x32_bf16 v[106:109], v[162:165], v[194:197], v[106:109]
	v_mfma_f32_16x16x32_bf16 v[94:97], v[154:157], v[206:209], v[94:97]
	v_mfma_f32_16x16x32_bf16 v[90:93], v[162:165], v[206:209], v[90:93]
	v_mfma_f32_16x16x32_bf16 v[78:81], v[154:157], v[214:217], v[78:81]
	v_mfma_f32_16x16x32_bf16 v[74:77], v[162:165], v[214:217], v[74:77]
	v_mfma_f32_16x16x32_bf16 v[126:129], v[158:161], v[190:193], v[126:129]
	v_mfma_f32_16x16x32_bf16 v[122:125], v[166:169], v[190:193], v[122:125]
	v_mfma_f32_16x16x32_bf16 v[110:113], v[158:161], v[198:201], v[110:113]
	v_mfma_f32_16x16x32_bf16 v[106:109], v[166:169], v[198:201], v[106:109]
	v_mfma_f32_16x16x32_bf16 v[94:97], v[158:161], v[210:213], v[94:97]
	v_mfma_f32_16x16x32_bf16 v[90:93], v[166:169], v[210:213], v[90:93]
	v_mfma_f32_16x16x32_bf16 v[78:81], v[158:161], v[218:221], v[78:81]
	v_mfma_f32_16x16x32_bf16 v[74:77], v[166:169], v[218:221], v[74:77]
	v_mfma_f32_16x16x32_bf16 v[118:121], v[170:173], v[186:189], v[118:121]
	v_mfma_f32_16x16x32_bf16 v[114:117], v[178:181], v[186:189], v[114:117]
	v_mfma_f32_16x16x32_bf16 v[102:105], v[170:173], v[194:197], v[102:105]
	v_mfma_f32_16x16x32_bf16 v[98:101], v[178:181], v[194:197], v[98:101]
	v_mfma_f32_16x16x32_bf16 v[86:89], v[170:173], v[206:209], v[86:89]
	v_mfma_f32_16x16x32_bf16 v[82:85], v[178:181], v[206:209], v[82:85]
	v_mfma_f32_16x16x32_bf16 v[70:73], v[170:173], v[214:217], v[70:73]
	v_mfma_f32_16x16x32_bf16 v[66:69], v[178:181], v[214:217], v[66:69]
	v_mfma_f32_16x16x32_bf16 v[118:121], v[174:177], v[190:193], v[118:121]
	v_mfma_f32_16x16x32_bf16 v[114:117], v[182:185], v[190:193], v[114:117]
	v_mfma_f32_16x16x32_bf16 v[102:105], v[174:177], v[198:201], v[102:105]
	v_mfma_f32_16x16x32_bf16 v[98:101], v[182:185], v[198:201], v[98:101]
	v_mfma_f32_16x16x32_bf16 v[86:89], v[174:177], v[210:213], v[86:89]
	v_mfma_f32_16x16x32_bf16 v[82:85], v[182:185], v[210:213], v[82:85]
	v_mfma_f32_16x16x32_bf16 v[70:73], v[174:177], v[218:221], v[70:73]
	v_mfma_f32_16x16x32_bf16 v[66:69], v[182:185], v[218:221], v[66:69]
	s_setprio 0
	s_barrier
	s_add_i32 s63, s45, s12
	s_mov_b32 m0, s63
	v_lshl_add_u64 v[146:147], s[30:31], 0, v[134:135]
	global_load_lds_dwordx4 v[146:147], off
	ds_read_b128 v[186:189], v152 offset:16384
	ds_read_b128 v[190:193], v152 offset:17408
	s_add_i32 m0, s63, 0x2000
	s_add_u32 s64, s30, 0x40000
	v_lshl_add_u64 v[202:203], s[30:31], 0, v[130:131]
	s_addc_u32 s65, s31, 0
	s_add_i32 s63, s46, s12
	global_load_lds_dwordx4 v[202:203], off
	ds_read_b128 v[194:197], v152 offset:18432
	ds_read_b128 v[198:201], v152 offset:19456
	v_lshl_add_u64 v[222:223], s[64:65], 0, v[134:135]
	s_mov_b32 m0, s63
	v_lshl_add_u64 v[224:225], s[36:37], 0, v[132:133]
	global_load_lds_dwordx4 v[222:223], off
	ds_read_b128 v[206:209], v152 offset:20480
	ds_read_b128 v[210:213], v152 offset:21504
	s_add_i32 m0, s63, 0x2000
	v_lshl_add_u64 v[222:223], s[64:65], 0, v[130:131]
	global_load_lds_dwordx4 v[222:223], off
	ds_read_b128 v[214:217], v152 offset:22528
	ds_read_b128 v[218:221], v152 offset:23552
	s_mov_b32 m0, s19
	v_lshl_add_u64 v[222:223], s[36:37], 0, v[136:137]
	global_load_lds_dwordx4 v[222:223], off
	s_mov_b32 m0, s33
	s_nop 0
	global_load_lds_dwordx4 v[224:225], off
	s_waitcnt vmcnt(8) lgkmcnt(0)
	s_setprio 1
	s_barrier
	v_mfma_f32_16x16x32_bf16 v[62:65], v[154:157], v[186:189], v[62:65]
	v_mfma_f32_16x16x32_bf16 v[58:61], v[162:165], v[186:189], v[58:61]
	v_mfma_f32_16x16x32_bf16 v[46:49], v[154:157], v[194:197], v[46:49]
	v_mfma_f32_16x16x32_bf16 v[42:45], v[162:165], v[194:197], v[42:45]
	v_mfma_f32_16x16x32_bf16 v[30:33], v[154:157], v[206:209], v[30:33]
	v_mfma_f32_16x16x32_bf16 v[26:29], v[162:165], v[206:209], v[26:29]
	v_mfma_f32_16x16x32_bf16 v[14:17], v[154:157], v[214:217], v[14:17]
	v_mfma_f32_16x16x32_bf16 v[10:13], v[162:165], v[214:217], v[10:13]
	v_mfma_f32_16x16x32_bf16 v[62:65], v[158:161], v[190:193], v[62:65]
	v_mfma_f32_16x16x32_bf16 v[58:61], v[166:169], v[190:193], v[58:61]
	v_mfma_f32_16x16x32_bf16 v[46:49], v[158:161], v[198:201], v[46:49]
	v_mfma_f32_16x16x32_bf16 v[42:45], v[166:169], v[198:201], v[42:45]
	v_mfma_f32_16x16x32_bf16 v[30:33], v[158:161], v[210:213], v[30:33]
	v_mfma_f32_16x16x32_bf16 v[26:29], v[166:169], v[210:213], v[26:29]
	v_mfma_f32_16x16x32_bf16 v[14:17], v[158:161], v[218:221], v[14:17]
	v_mfma_f32_16x16x32_bf16 v[10:13], v[166:169], v[218:221], v[10:13]
	v_mfma_f32_16x16x32_bf16 v[54:57], v[170:173], v[186:189], v[54:57]
	v_mfma_f32_16x16x32_bf16 v[50:53], v[178:181], v[186:189], v[50:53]
	v_mfma_f32_16x16x32_bf16 v[38:41], v[170:173], v[194:197], v[38:41]
	v_mfma_f32_16x16x32_bf16 v[34:37], v[178:181], v[194:197], v[34:37]
	v_mfma_f32_16x16x32_bf16 v[22:25], v[170:173], v[206:209], v[22:25]
	v_mfma_f32_16x16x32_bf16 v[18:21], v[178:181], v[206:209], v[18:21]
	v_mfma_f32_16x16x32_bf16 v[6:9], v[170:173], v[214:217], v[6:9]
	v_mfma_f32_16x16x32_bf16 v[2:5], v[178:181], v[214:217], v[2:5]
	v_mfma_f32_16x16x32_bf16 v[54:57], v[174:177], v[190:193], v[54:57]
	v_mfma_f32_16x16x32_bf16 v[50:53], v[182:185], v[190:193], v[50:53]
	v_mfma_f32_16x16x32_bf16 v[38:41], v[174:177], v[198:201], v[38:41]
	v_mfma_f32_16x16x32_bf16 v[34:37], v[182:185], v[198:201], v[34:37]
	v_mfma_f32_16x16x32_bf16 v[22:25], v[174:177], v[210:213], v[22:25]
	v_mfma_f32_16x16x32_bf16 v[18:21], v[182:185], v[210:213], v[18:21]
	v_mfma_f32_16x16x32_bf16 v[6:9], v[174:177], v[218:221], v[6:9]
	v_mfma_f32_16x16x32_bf16 v[2:5], v[182:185], v[218:221], v[2:5]
	s_setprio 0
	s_barrier
	s_add_i32 s63, 0, 0x18000
	v_add_u32_e32 v153, s63, v149
	s_add_i32 s64, 0, 0x1c000
	ds_read_b128 v[154:157], v153
	ds_read_b128 v[158:161], v153 offset:1024
	ds_read_b128 v[162:165], v153 offset:2048
	ds_read_b128 v[166:169], v153 offset:3072
	v_add_u32_e32 v153, s64, v149
	ds_read_b128 v[170:173], v153
	ds_read_b128 v[174:177], v153 offset:1024
	ds_read_b128 v[178:181], v153 offset:2048
	ds_read_b128 v[182:185], v153 offset:3072
	s_add_u32 s36, s36, 0x40000
	s_addc_u32 s37, s37, 0
	s_mov_b32 m0, s35
	v_lshl_add_u64 v[226:227], s[36:37], 0, v[136:137]
	ds_read_b128 v[186:189], v152 offset:32768
	ds_read_b128 v[190:193], v152 offset:33792
	ds_read_b128 v[194:197], v152 offset:34816
	ds_read_b128 v[198:201], v152 offset:35840
	ds_read_b128 v[206:209], v152 offset:36864
	ds_read_b128 v[210:213], v152 offset:37888
	ds_read_b128 v[214:217], v152 offset:38912
	ds_read_b128 v[218:221], v152 offset:39936
	global_load_lds_dwordx4 v[226:227], off
	s_mov_b32 m0, s38
	v_lshl_add_u64 v[226:227], s[36:37], 0, v[132:133]
	global_load_lds_dwordx4 v[226:227], off
	s_waitcnt vmcnt(8) lgkmcnt(0)
	s_setprio 1
	s_barrier
	v_mfma_f32_16x16x32_bf16 v[126:129], v[154:157], v[186:189], v[126:129]
	v_mfma_f32_16x16x32_bf16 v[122:125], v[162:165], v[186:189], v[122:125]
	v_mfma_f32_16x16x32_bf16 v[110:113], v[154:157], v[194:197], v[110:113]
	v_mfma_f32_16x16x32_bf16 v[106:109], v[162:165], v[194:197], v[106:109]
	v_mfma_f32_16x16x32_bf16 v[94:97], v[154:157], v[206:209], v[94:97]
	v_mfma_f32_16x16x32_bf16 v[90:93], v[162:165], v[206:209], v[90:93]
	v_mfma_f32_16x16x32_bf16 v[78:81], v[154:157], v[214:217], v[78:81]
	v_mfma_f32_16x16x32_bf16 v[74:77], v[162:165], v[214:217], v[74:77]
	v_mfma_f32_16x16x32_bf16 v[126:129], v[158:161], v[190:193], v[126:129]
	v_mfma_f32_16x16x32_bf16 v[122:125], v[166:169], v[190:193], v[122:125]
	v_mfma_f32_16x16x32_bf16 v[110:113], v[158:161], v[198:201], v[110:113]
	v_mfma_f32_16x16x32_bf16 v[106:109], v[166:169], v[198:201], v[106:109]
	v_mfma_f32_16x16x32_bf16 v[94:97], v[158:161], v[210:213], v[94:97]
	v_mfma_f32_16x16x32_bf16 v[90:93], v[166:169], v[210:213], v[90:93]
	v_mfma_f32_16x16x32_bf16 v[78:81], v[158:161], v[218:221], v[78:81]
	v_mfma_f32_16x16x32_bf16 v[74:77], v[166:169], v[218:221], v[74:77]
	v_mfma_f32_16x16x32_bf16 v[118:121], v[170:173], v[186:189], v[118:121]
	v_mfma_f32_16x16x32_bf16 v[114:117], v[178:181], v[186:189], v[114:117]
	v_mfma_f32_16x16x32_bf16 v[102:105], v[170:173], v[194:197], v[102:105]
	v_mfma_f32_16x16x32_bf16 v[98:101], v[178:181], v[194:197], v[98:101]
	v_mfma_f32_16x16x32_bf16 v[86:89], v[170:173], v[206:209], v[86:89]
	v_mfma_f32_16x16x32_bf16 v[82:85], v[178:181], v[206:209], v[82:85]
	v_mfma_f32_16x16x32_bf16 v[70:73], v[170:173], v[214:217], v[70:73]
	v_mfma_f32_16x16x32_bf16 v[66:69], v[178:181], v[214:217], v[66:69]
	v_mfma_f32_16x16x32_bf16 v[118:121], v[174:177], v[190:193], v[118:121]
	v_mfma_f32_16x16x32_bf16 v[114:117], v[182:185], v[190:193], v[114:117]
	v_mfma_f32_16x16x32_bf16 v[102:105], v[174:177], v[198:201], v[102:105]
	v_mfma_f32_16x16x32_bf16 v[98:101], v[182:185], v[198:201], v[98:101]
	v_mfma_f32_16x16x32_bf16 v[86:89], v[174:177], v[210:213], v[86:89]
	v_mfma_f32_16x16x32_bf16 v[82:85], v[182:185], v[210:213], v[82:85]
	v_mfma_f32_16x16x32_bf16 v[70:73], v[174:177], v[218:221], v[70:73]
	v_mfma_f32_16x16x32_bf16 v[66:69], v[182:185], v[218:221], v[66:69]
	s_setprio 0
	s_barrier
	s_add_i32 s36, s63, s12
	s_mov_b32 m0, s36
	v_lshl_add_u64 v[146:147], v[146:147], 0, s[8:9]
	global_load_lds_dwordx4 v[146:147], off
	ds_read_b128 v[186:189], v152 offset:49152
	ds_read_b128 v[190:193], v152 offset:50176
	s_add_i32 m0, s36, 0x2000
	s_add_u32 s30, s30, 0x40080
	v_lshl_add_u64 v[146:147], v[202:203], 0, s[8:9]
	s_addc_u32 s31, s31, 0
	s_add_i32 s36, s64, s12
	global_load_lds_dwordx4 v[146:147], off
	ds_read_b128 v[194:197], v152 offset:51200
	ds_read_b128 v[198:201], v152 offset:52224
	s_mov_b32 m0, s36
	v_lshl_add_u64 v[146:147], s[30:31], 0, v[134:135]
	global_load_lds_dwordx4 v[146:147], off
	ds_read_b128 v[206:209], v152 offset:53248
	ds_read_b128 v[210:213], v152 offset:54272
	s_add_i32 m0, s36, 0x2000
	v_lshl_add_u64 v[146:147], s[30:31], 0, v[130:131]
	global_load_lds_dwordx4 v[146:147], off
	ds_read_b128 v[214:217], v152 offset:55296
	ds_read_b128 v[218:221], v152 offset:56320
	s_mov_b32 m0, s42
	v_lshl_add_u64 v[146:147], v[222:223], 0, s[8:9]
	global_load_lds_dwordx4 v[146:147], off
	s_mov_b32 m0, s43
	v_lshl_add_u64 v[146:147], v[224:225], 0, s[8:9]
	global_load_lds_dwordx4 v[146:147], off
	s_waitcnt vmcnt(8) lgkmcnt(0)
	s_setprio 1
	s_barrier
	v_mfma_f32_16x16x32_bf16 v[62:65], v[154:157], v[186:189], v[62:65]
	v_mfma_f32_16x16x32_bf16 v[58:61], v[162:165], v[186:189], v[58:61]
	v_mfma_f32_16x16x32_bf16 v[46:49], v[154:157], v[194:197], v[46:49]
	v_mfma_f32_16x16x32_bf16 v[42:45], v[162:165], v[194:197], v[42:45]
	v_mfma_f32_16x16x32_bf16 v[30:33], v[154:157], v[206:209], v[30:33]
	v_mfma_f32_16x16x32_bf16 v[26:29], v[162:165], v[206:209], v[26:29]
	v_mfma_f32_16x16x32_bf16 v[14:17], v[154:157], v[214:217], v[14:17]
	v_mfma_f32_16x16x32_bf16 v[10:13], v[162:165], v[214:217], v[10:13]
	v_mfma_f32_16x16x32_bf16 v[62:65], v[158:161], v[190:193], v[62:65]
	v_mfma_f32_16x16x32_bf16 v[58:61], v[166:169], v[190:193], v[58:61]
	v_mfma_f32_16x16x32_bf16 v[46:49], v[158:161], v[198:201], v[46:49]
	v_mfma_f32_16x16x32_bf16 v[42:45], v[166:169], v[198:201], v[42:45]
	v_mfma_f32_16x16x32_bf16 v[30:33], v[158:161], v[210:213], v[30:33]
	v_mfma_f32_16x16x32_bf16 v[26:29], v[166:169], v[210:213], v[26:29]
	v_mfma_f32_16x16x32_bf16 v[14:17], v[158:161], v[218:221], v[14:17]
	v_mfma_f32_16x16x32_bf16 v[10:13], v[166:169], v[218:221], v[10:13]
	v_mfma_f32_16x16x32_bf16 v[54:57], v[170:173], v[186:189], v[54:57]
	v_mfma_f32_16x16x32_bf16 v[50:53], v[178:181], v[186:189], v[50:53]
	v_mfma_f32_16x16x32_bf16 v[38:41], v[170:173], v[194:197], v[38:41]
	v_mfma_f32_16x16x32_bf16 v[34:37], v[178:181], v[194:197], v[34:37]
	v_mfma_f32_16x16x32_bf16 v[22:25], v[170:173], v[206:209], v[22:25]
	v_mfma_f32_16x16x32_bf16 v[18:21], v[178:181], v[206:209], v[18:21]
	v_mfma_f32_16x16x32_bf16 v[6:9], v[170:173], v[214:217], v[6:9]
	v_mfma_f32_16x16x32_bf16 v[2:5], v[178:181], v[214:217], v[2:5]
	v_mfma_f32_16x16x32_bf16 v[54:57], v[174:177], v[190:193], v[54:57]
	v_mfma_f32_16x16x32_bf16 v[50:53], v[182:185], v[190:193], v[50:53]
	v_mfma_f32_16x16x32_bf16 v[38:41], v[174:177], v[198:201], v[38:41]
	v_mfma_f32_16x16x32_bf16 v[34:37], v[182:185], v[198:201], v[34:37]
	v_mfma_f32_16x16x32_bf16 v[22:25], v[174:177], v[210:213], v[22:25]
	v_mfma_f32_16x16x32_bf16 v[18:21], v[182:185], v[210:213], v[18:21]
	v_mfma_f32_16x16x32_bf16 v[6:9], v[174:177], v[218:221], v[6:9]
	v_mfma_f32_16x16x32_bf16 v[2:5], v[182:185], v[218:221], v[2:5]
	s_setprio 0
	s_barrier
	s_add_i32 s62, s62, 2
	s_add_u32 s28, s28, 0x100
	s_addc_u32 s29, s29, 0
	s_add_u32 s50, s50, 0x100
	s_addc_u32 s51, s51, 0
	s_cmp_gt_u32 s62, 13
	s_cbranch_scc0 .LBB0_1619
	s_and_b64 vcc, exec, s[10:11]
	s_cbranch_vccz .LBB0_1622
	s_barrier

.LBB0_1707:
	v_readlane_b32 s46, v249, 32
	v_readlane_b32 s47, v249, 33
	s_add_u32 s46, s46, s42
	s_addc_u32 s47, s47, s43
	s_and_b64 s[48:49], s[44:45], exec
	s_cselect_b32 s34, s47, s51
	s_cselect_b32 s66, s46, s50
	s_add_u32 s48, s35, s40
	s_addc_u32 s49, s70, s41
	s_and_b64 s[64:65], s[44:45], exec
	s_cselect_b32 s67, s49, s63
	s_cselect_b32 s68, s48, s62
	s_add_i32 s69, s7, -2
	s_add_u32 s50, s50, 0x100080
	s_addc_u32 s51, s51, 0
	s_add_u32 s91, s62, 0x100
	s_addc_u32 s92, s63, 0
	s_mov_b32 s62, 0
	s_waitcnt vmcnt(0)
	ds_read_b128 v[130:133], v168
	ds_read_b128 v[134:137], v168 offset:1024
	ds_read_b128 v[138:141], v168 offset:2048
	ds_read_b128 v[142:145], v168 offset:3072
	ds_read_b128 v[162:165], v169
	ds_read_b128 v[172:175], v169 offset:1024
	ds_read_b128 v[176:179], v169 offset:2048
	ds_read_b128 v[180:183], v169 offset:3072
	s_add_i32 s93, s62, 2
	s_add_u32 s63, s50, 0xfff00080
	s_addc_u32 s64, s51, -1
	s_cmp_eq_u32 s69, s62
	s_cselect_b32 s62, s68, s91
	s_cselect_b32 s65, s34, s64
	s_cselect_b32 s64, s66, s63
	s_cselect_b32 s63, s67, s92
	v_lshl_add_u64 v[218:219], s[50:51], 0, v[156:157]
	s_add_i32 m0, s12, 0xc000
	ds_read_b128 v[184:187], v170
	ds_read_b128 v[188:191], v170 offset:1024
	ds_read_b128 v[192:195], v170 offset:2048
	ds_read_b128 v[196:199], v170 offset:3072
	ds_read_b128 v[200:203], v170 offset:4096
	ds_read_b128 v[206:209], v170 offset:5120
	ds_read_b128 v[210:213], v170 offset:6144
	ds_read_b128 v[214:217], v170 offset:7168
	global_load_lds_dwordx4 v[218:219], off
	s_add_i32 m0, s12, 0xe000
	v_lshl_add_u64 v[218:219], s[50:51], 0, v[158:159]
	global_load_lds_dwordx4 v[218:219], off
	s_waitcnt vmcnt(8) lgkmcnt(0)
	s_setprio 1
	s_barrier
	v_mfma_f32_16x16x32_bf16 v[126:129], v[130:133], v[184:187], 0
	v_mfma_f32_16x16x32_bf16 v[122:125], v[138:141], v[184:187], 0
	v_mfma_f32_16x16x32_bf16 v[110:113], v[130:133], v[192:195], 0
	v_mfma_f32_16x16x32_bf16 v[106:109], v[138:141], v[192:195], 0
	v_mfma_f32_16x16x32_bf16 v[98:101], v[130:133], v[200:203], 0
	v_mfma_f32_16x16x32_bf16 v[90:93], v[138:141], v[200:203], 0
	v_mfma_f32_16x16x32_bf16 v[82:85], v[130:133], v[210:213], 0
	v_mfma_f32_16x16x32_bf16 v[74:77], v[138:141], v[210:213], 0
	v_mfma_f32_16x16x32_bf16 v[126:129], v[134:137], v[188:191], v[126:129]
	v_mfma_f32_16x16x32_bf16 v[122:125], v[142:145], v[188:191], v[122:125]
	v_mfma_f32_16x16x32_bf16 v[110:113], v[134:137], v[196:199], v[110:113]
	v_mfma_f32_16x16x32_bf16 v[106:109], v[142:145], v[196:199], v[106:109]
	v_mfma_f32_16x16x32_bf16 v[98:101], v[134:137], v[206:209], v[98:101]
	v_mfma_f32_16x16x32_bf16 v[90:93], v[142:145], v[206:209], v[90:93]
	v_mfma_f32_16x16x32_bf16 v[82:85], v[134:137], v[214:217], v[82:85]
	v_mfma_f32_16x16x32_bf16 v[74:77], v[142:145], v[214:217], v[74:77]
	v_mfma_f32_16x16x32_bf16 v[118:121], v[162:165], v[184:187], 0
	v_mfma_f32_16x16x32_bf16 v[114:117], v[176:179], v[184:187], 0
	v_mfma_f32_16x16x32_bf16 v[102:105], v[162:165], v[192:195], 0
	v_mfma_f32_16x16x32_bf16 v[94:97], v[176:179], v[192:195], 0
	v_mfma_f32_16x16x32_bf16 v[86:89], v[162:165], v[200:203], 0
	v_mfma_f32_16x16x32_bf16 v[78:81], v[176:179], v[200:203], 0
	v_mfma_f32_16x16x32_bf16 v[70:73], v[162:165], v[210:213], 0
	v_mfma_f32_16x16x32_bf16 v[66:69], v[176:179], v[210:213], 0
	v_mfma_f32_16x16x32_bf16 v[118:121], v[172:175], v[188:191], v[118:121]
	v_mfma_f32_16x16x32_bf16 v[114:117], v[180:183], v[188:191], v[114:117]
	v_mfma_f32_16x16x32_bf16 v[102:105], v[172:175], v[196:199], v[102:105]
	v_mfma_f32_16x16x32_bf16 v[94:97], v[180:183], v[196:199], v[94:97]
	v_mfma_f32_16x16x32_bf16 v[86:89], v[172:175], v[206:209], v[86:89]
	v_mfma_f32_16x16x32_bf16 v[78:81], v[180:183], v[206:209], v[78:81]
	v_mfma_f32_16x16x32_bf16 v[70:73], v[172:175], v[214:217], v[70:73]
	v_mfma_f32_16x16x32_bf16 v[66:69], v[180:183], v[214:217], v[66:69]
	s_setprio 0
	s_barrier
	s_add_i32 s94, s31, s2
	s_mov_b32 m0, s94
	v_lshl_add_u64 v[218:219], s[62:63], 0, v[148:149]
	global_load_lds_dwordx4 v[218:219], off
	ds_read_b128 v[184:187], v170 offset:16384
	ds_read_b128 v[188:191], v170 offset:17408
	s_add_i32 m0, s94, 0x2000
	s_add_u32 s94, s62, 0x100000
	v_lshl_add_u64 v[220:221], s[62:63], 0, v[152:153]
	s_addc_u32 s95, s63, 0
	s_add_i32 s96, s82, s2
	global_load_lds_dwordx4 v[220:221], off
	ds_read_b128 v[192:195], v170 offset:18432
	ds_read_b128 v[196:199], v170 offset:19456
	v_lshl_add_u64 v[222:223], s[94:95], 0, v[148:149]
	s_mov_b32 m0, s96
	v_lshl_add_u64 v[224:225], s[64:65], 0, v[150:151]
	global_load_lds_dwordx4 v[222:223], off
	ds_read_b128 v[200:203], v170 offset:20480
	ds_read_b128 v[206:209], v170 offset:21504
	s_add_i32 m0, s96, 0x2000
	v_lshl_add_u64 v[222:223], s[94:95], 0, v[152:153]
	global_load_lds_dwordx4 v[222:223], off
	ds_read_b128 v[210:213], v170 offset:22528
	ds_read_b128 v[214:217], v170 offset:23552
	s_mov_b32 m0, s12
	v_lshl_add_u64 v[222:223], s[64:65], 0, v[146:147]
	global_load_lds_dwordx4 v[222:223], off
	s_mov_b32 m0, s13
	s_nop 0
	global_load_lds_dwordx4 v[224:225], off
	s_waitcnt vmcnt(8) lgkmcnt(0)
	s_setprio 1
	s_barrier
	v_mfma_f32_16x16x32_bf16 v[62:65], v[130:133], v[184:187], 0
	v_mfma_f32_16x16x32_bf16 v[58:61], v[138:141], v[184:187], 0
	v_mfma_f32_16x16x32_bf16 v[50:53], v[130:133], v[192:195], 0
	v_mfma_f32_16x16x32_bf16 v[42:45], v[138:141], v[192:195], 0
	v_mfma_f32_16x16x32_bf16 v[34:37], v[130:133], v[200:203], 0
	v_mfma_f32_16x16x32_bf16 v[26:29], v[138:141], v[200:203], 0
	v_mfma_f32_16x16x32_bf16 v[18:21], v[130:133], v[210:213], 0
	v_mfma_f32_16x16x32_bf16 v[10:13], v[138:141], v[210:213], 0
	v_mfma_f32_16x16x32_bf16 v[62:65], v[134:137], v[188:191], v[62:65]
	v_mfma_f32_16x16x32_bf16 v[58:61], v[142:145], v[188:191], v[58:61]
	v_mfma_f32_16x16x32_bf16 v[50:53], v[134:137], v[196:199], v[50:53]
	v_mfma_f32_16x16x32_bf16 v[42:45], v[142:145], v[196:199], v[42:45]
	v_mfma_f32_16x16x32_bf16 v[34:37], v[134:137], v[206:209], v[34:37]
	v_mfma_f32_16x16x32_bf16 v[26:29], v[142:145], v[206:209], v[26:29]
	v_mfma_f32_16x16x32_bf16 v[18:21], v[134:137], v[214:217], v[18:21]
	v_mfma_f32_16x16x32_bf16 v[10:13], v[142:145], v[214:217], v[10:13]
	v_mfma_f32_16x16x32_bf16 v[54:57], v[162:165], v[184:187], 0
	v_mfma_f32_16x16x32_bf16 v[46:49], v[176:179], v[184:187], 0
	v_mfma_f32_16x16x32_bf16 v[38:41], v[162:165], v[192:195], 0
	v_mfma_f32_16x16x32_bf16 v[30:33], v[176:179], v[192:195], 0
	v_mfma_f32_16x16x32_bf16 v[22:25], v[162:165], v[200:203], 0
	v_mfma_f32_16x16x32_bf16 v[14:17], v[176:179], v[200:203], 0
	v_mfma_f32_16x16x32_bf16 v[6:9], v[162:165], v[210:213], 0
	v_mfma_f32_16x16x32_bf16 v[2:5], v[176:179], v[210:213], 0
	v_mfma_f32_16x16x32_bf16 v[54:57], v[172:175], v[188:191], v[54:57]
	v_mfma_f32_16x16x32_bf16 v[46:49], v[180:183], v[188:191], v[46:49]
	v_mfma_f32_16x16x32_bf16 v[38:41], v[172:175], v[196:199], v[38:41]
	v_mfma_f32_16x16x32_bf16 v[30:33], v[180:183], v[196:199], v[30:33]
	v_mfma_f32_16x16x32_bf16 v[22:25], v[172:175], v[206:209], v[22:25]
	v_mfma_f32_16x16x32_bf16 v[14:17], v[180:183], v[206:209], v[14:17]
	v_mfma_f32_16x16x32_bf16 v[6:9], v[172:175], v[214:217], v[6:9]
	v_mfma_f32_16x16x32_bf16 v[2:5], v[180:183], v[214:217], v[2:5]
	s_setprio 0
	s_barrier
	s_add_i32 s94, 0, 0x18000
	s_add_i32 s95, 0, 0x1c000
	v_add_u32_e32 v142, s94, v167
	v_add_u32_e32 v154, s95, v167
	ds_read_b128 v[130:133], v142
	ds_read_b128 v[134:137], v142 offset:1024
	ds_read_b128 v[138:141], v142 offset:2048
	ds_read_b128 v[142:145], v142 offset:3072
	ds_read_b128 v[162:165], v154
	ds_read_b128 v[172:175], v154 offset:1024
	ds_read_b128 v[176:179], v154 offset:2048
	ds_read_b128 v[180:183], v154 offset:3072
	s_add_u32 s64, s64, 0x100000
	s_addc_u32 s65, s65, 0
	s_mov_b32 m0, s18
	v_lshl_add_u64 v[226:227], s[64:65], 0, v[146:147]
	ds_read_b128 v[184:187], v170 offset:32768
	ds_read_b128 v[188:191], v170 offset:33792
	ds_read_b128 v[192:195], v170 offset:34816
	ds_read_b128 v[196:199], v170 offset:35840
	ds_read_b128 v[200:203], v170 offset:36864
	ds_read_b128 v[206:209], v170 offset:37888
	ds_read_b128 v[210:213], v170 offset:38912
	ds_read_b128 v[214:217], v170 offset:39936
	global_load_lds_dwordx4 v[226:227], off
	s_mov_b32 m0, s19
	v_lshl_add_u64 v[226:227], s[64:65], 0, v[150:151]
	global_load_lds_dwordx4 v[226:227], off
	s_waitcnt vmcnt(8) lgkmcnt(0)
	s_setprio 1
	s_barrier
	v_mfma_f32_16x16x32_bf16 v[126:129], v[130:133], v[184:187], v[126:129]
	v_mfma_f32_16x16x32_bf16 v[122:125], v[138:141], v[184:187], v[122:125]
	v_mfma_f32_16x16x32_bf16 v[110:113], v[130:133], v[192:195], v[110:113]
	v_mfma_f32_16x16x32_bf16 v[106:109], v[138:141], v[192:195], v[106:109]
	v_mfma_f32_16x16x32_bf16 v[98:101], v[130:133], v[200:203], v[98:101]
	v_mfma_f32_16x16x32_bf16 v[90:93], v[138:141], v[200:203], v[90:93]
	v_mfma_f32_16x16x32_bf16 v[82:85], v[130:133], v[210:213], v[82:85]
	v_mfma_f32_16x16x32_bf16 v[74:77], v[138:141], v[210:213], v[74:77]
	v_mfma_f32_16x16x32_bf16 v[126:129], v[134:137], v[188:191], v[126:129]
	v_mfma_f32_16x16x32_bf16 v[122:125], v[142:145], v[188:191], v[122:125]
	v_mfma_f32_16x16x32_bf16 v[110:113], v[134:137], v[196:199], v[110:113]
	v_mfma_f32_16x16x32_bf16 v[106:109], v[142:145], v[196:199], v[106:109]
	v_mfma_f32_16x16x32_bf16 v[98:101], v[134:137], v[206:209], v[98:101]
	v_mfma_f32_16x16x32_bf16 v[90:93], v[142:145], v[206:209], v[90:93]
	v_mfma_f32_16x16x32_bf16 v[82:85], v[134:137], v[214:217], v[82:85]
	v_mfma_f32_16x16x32_bf16 v[74:77], v[142:145], v[214:217], v[74:77]
	v_mfma_f32_16x16x32_bf16 v[118:121], v[162:165], v[184:187], v[118:121]
	v_mfma_f32_16x16x32_bf16 v[114:117], v[176:179], v[184:187], v[114:117]
	v_mfma_f32_16x16x32_bf16 v[102:105], v[162:165], v[192:195], v[102:105]
	v_mfma_f32_16x16x32_bf16 v[94:97], v[176:179], v[192:195], v[94:97]
	v_mfma_f32_16x16x32_bf16 v[86:89], v[162:165], v[200:203], v[86:89]
	v_mfma_f32_16x16x32_bf16 v[78:81], v[176:179], v[200:203], v[78:81]
	v_mfma_f32_16x16x32_bf16 v[70:73], v[162:165], v[210:213], v[70:73]
	v_mfma_f32_16x16x32_bf16 v[66:69], v[176:179], v[210:213], v[66:69]
	v_mfma_f32_16x16x32_bf16 v[118:121], v[172:175], v[188:191], v[118:121]
	v_mfma_f32_16x16x32_bf16 v[114:117], v[180:183], v[188:191], v[114:117]
	v_mfma_f32_16x16x32_bf16 v[102:105], v[172:175], v[196:199], v[102:105]
	v_mfma_f32_16x16x32_bf16 v[94:97], v[180:183], v[196:199], v[94:97]
	v_mfma_f32_16x16x32_bf16 v[86:89], v[172:175], v[206:209], v[86:89]
	v_mfma_f32_16x16x32_bf16 v[78:81], v[180:183], v[206:209], v[78:81]
	v_mfma_f32_16x16x32_bf16 v[70:73], v[172:175], v[214:217], v[70:73]
	v_mfma_f32_16x16x32_bf16 v[66:69], v[180:183], v[214:217], v[66:69]
	s_setprio 0
	s_barrier
	s_add_i32 s64, s94, s2
	s_mov_b32 m0, s64
	v_lshl_add_u64 v[218:219], v[218:219], 0, s[16:17]
	global_load_lds_dwordx4 v[218:219], off
	ds_read_b128 v[184:187], v170 offset:49152
	ds_read_b128 v[188:191], v170 offset:50176
	s_add_i32 m0, s64, 0x2000
	s_add_u32 s62, s62, 0x100080
	v_lshl_add_u64 v[218:219], v[220:221], 0, s[16:17]
	s_addc_u32 s63, s63, 0
	s_add_i32 s64, s95, s2
	global_load_lds_dwordx4 v[218:219], off
	ds_read_b128 v[192:195], v170 offset:51200
	ds_read_b128 v[196:199], v170 offset:52224
	s_mov_b32 m0, s64
	v_lshl_add_u64 v[218:219], s[62:63], 0, v[148:149]
	global_load_lds_dwordx4 v[218:219], off
	ds_read_b128 v[200:203], v170 offset:53248
	ds_read_b128 v[206:209], v170 offset:54272
	s_add_i32 m0, s64, 0x2000
	v_lshl_add_u64 v[218:219], s[62:63], 0, v[152:153]
	global_load_lds_dwordx4 v[218:219], off
	ds_read_b128 v[210:213], v170 offset:55296
	ds_read_b128 v[214:217], v170 offset:56320
	s_mov_b32 m0, s74
	v_lshl_add_u64 v[218:219], v[222:223], 0, s[16:17]
	global_load_lds_dwordx4 v[218:219], off
	s_mov_b32 m0, s75
	v_lshl_add_u64 v[218:219], v[224:225], 0, s[16:17]
	global_load_lds_dwordx4 v[218:219], off
	s_waitcnt vmcnt(8) lgkmcnt(0)
	s_setprio 1
	s_barrier
	v_mfma_f32_16x16x32_bf16 v[62:65], v[130:133], v[184:187], v[62:65]
	v_mfma_f32_16x16x32_bf16 v[58:61], v[138:141], v[184:187], v[58:61]
	v_mfma_f32_16x16x32_bf16 v[50:53], v[130:133], v[192:195], v[50:53]
	v_mfma_f32_16x16x32_bf16 v[42:45], v[138:141], v[192:195], v[42:45]
	v_mfma_f32_16x16x32_bf16 v[34:37], v[130:133], v[200:203], v[34:37]
	v_mfma_f32_16x16x32_bf16 v[26:29], v[138:141], v[200:203], v[26:29]
	v_mfma_f32_16x16x32_bf16 v[18:21], v[130:133], v[210:213], v[18:21]
	v_mfma_f32_16x16x32_bf16 v[10:13], v[138:141], v[210:213], v[10:13]
	v_mfma_f32_16x16x32_bf16 v[62:65], v[134:137], v[188:191], v[62:65]
	v_mfma_f32_16x16x32_bf16 v[58:61], v[142:145], v[188:191], v[58:61]
	v_mfma_f32_16x16x32_bf16 v[50:53], v[134:137], v[196:199], v[50:53]
	v_mfma_f32_16x16x32_bf16 v[42:45], v[142:145], v[196:199], v[42:45]
	v_mfma_f32_16x16x32_bf16 v[34:37], v[134:137], v[206:209], v[34:37]
	v_mfma_f32_16x16x32_bf16 v[26:29], v[142:145], v[206:209], v[26:29]
	v_mfma_f32_16x16x32_bf16 v[18:21], v[134:137], v[214:217], v[18:21]
	v_mfma_f32_16x16x32_bf16 v[10:13], v[142:145], v[214:217], v[10:13]
	v_mfma_f32_16x16x32_bf16 v[54:57], v[162:165], v[184:187], v[54:57]
	v_mfma_f32_16x16x32_bf16 v[46:49], v[176:179], v[184:187], v[46:49]
	v_mfma_f32_16x16x32_bf16 v[38:41], v[162:165], v[192:195], v[38:41]
	v_mfma_f32_16x16x32_bf16 v[30:33], v[176:179], v[192:195], v[30:33]
	v_mfma_f32_16x16x32_bf16 v[22:25], v[162:165], v[200:203], v[22:25]
	v_mfma_f32_16x16x32_bf16 v[14:17], v[176:179], v[200:203], v[14:17]
	v_mfma_f32_16x16x32_bf16 v[6:9], v[162:165], v[210:213], v[6:9]
	v_mfma_f32_16x16x32_bf16 v[2:5], v[176:179], v[210:213], v[2:5]
	v_mfma_f32_16x16x32_bf16 v[54:57], v[172:175], v[188:191], v[54:57]
	v_mfma_f32_16x16x32_bf16 v[46:49], v[180:183], v[188:191], v[46:49]
	v_mfma_f32_16x16x32_bf16 v[38:41], v[172:175], v[196:199], v[38:41]
	v_mfma_f32_16x16x32_bf16 v[30:33], v[180:183], v[196:199], v[30:33]
	v_mfma_f32_16x16x32_bf16 v[22:25], v[172:175], v[206:209], v[22:25]
	v_mfma_f32_16x16x32_bf16 v[14:17], v[180:183], v[206:209], v[14:17]
	v_mfma_f32_16x16x32_bf16 v[6:9], v[172:175], v[214:217], v[6:9]
	v_mfma_f32_16x16x32_bf16 v[2:5], v[180:183], v[214:217], v[2:5]
	s_setprio 0
	s_barrier
	s_add_u32 s50, s50, 0x100
	s_addc_u32 s51, s51, 0
	s_add_u32 s91, s91, 0x100
	s_addc_u32 s92, s92, 0
	s_cmp_ge_i32 s93, s7
	s_mov_b32 s62, s93
.LBB0_1708:
	ds_read_b128 v[130:133], v168
	ds_read_b128 v[134:137], v168 offset:1024
	ds_read_b128 v[138:141], v168 offset:2048
	ds_read_b128 v[142:145], v168 offset:3072
	ds_read_b128 v[162:165], v169
	ds_read_b128 v[172:175], v169 offset:1024
	ds_read_b128 v[176:179], v169 offset:2048
	ds_read_b128 v[180:183], v169 offset:3072
	s_add_i32 s93, s62, 2
	s_add_u32 s63, s50, 0xfff00080
	s_addc_u32 s64, s51, -1
	s_cmp_eq_u32 s69, s62
	s_cselect_b32 s62, s68, s91
	s_cselect_b32 s65, s34, s64
	s_cselect_b32 s64, s66, s63
	s_cselect_b32 s63, s67, s92
	v_lshl_add_u64 v[218:219], s[50:51], 0, v[156:157]
	s_add_i32 m0, s12, 0xc000
	ds_read_b128 v[184:187], v170
	ds_read_b128 v[188:191], v170 offset:1024
	ds_read_b128 v[192:195], v170 offset:2048
	ds_read_b128 v[196:199], v170 offset:3072
	ds_read_b128 v[200:203], v170 offset:4096
	ds_read_b128 v[206:209], v170 offset:5120
	ds_read_b128 v[210:213], v170 offset:6144
	ds_read_b128 v[214:217], v170 offset:7168
	global_load_lds_dwordx4 v[218:219], off
	s_add_i32 m0, s12, 0xe000
	v_lshl_add_u64 v[218:219], s[50:51], 0, v[158:159]
	global_load_lds_dwordx4 v[218:219], off
	s_waitcnt vmcnt(8) lgkmcnt(0)
	s_setprio 1
	s_barrier
	v_mfma_f32_16x16x32_bf16 v[126:129], v[130:133], v[184:187], v[126:129]
	v_mfma_f32_16x16x32_bf16 v[122:125], v[138:141], v[184:187], v[122:125]
	v_mfma_f32_16x16x32_bf16 v[110:113], v[130:133], v[192:195], v[110:113]
	v_mfma_f32_16x16x32_bf16 v[106:109], v[138:141], v[192:195], v[106:109]
	v_mfma_f32_16x16x32_bf16 v[98:101], v[130:133], v[200:203], v[98:101]
	v_mfma_f32_16x16x32_bf16 v[90:93], v[138:141], v[200:203], v[90:93]
	v_mfma_f32_16x16x32_bf16 v[82:85], v[130:133], v[210:213], v[82:85]
	v_mfma_f32_16x16x32_bf16 v[74:77], v[138:141], v[210:213], v[74:77]
	v_mfma_f32_16x16x32_bf16 v[126:129], v[134:137], v[188:191], v[126:129]
	v_mfma_f32_16x16x32_bf16 v[122:125], v[142:145], v[188:191], v[122:125]
	v_mfma_f32_16x16x32_bf16 v[110:113], v[134:137], v[196:199], v[110:113]
	v_mfma_f32_16x16x32_bf16 v[106:109], v[142:145], v[196:199], v[106:109]
	v_mfma_f32_16x16x32_bf16 v[98:101], v[134:137], v[206:209], v[98:101]
	v_mfma_f32_16x16x32_bf16 v[90:93], v[142:145], v[206:209], v[90:93]
	v_mfma_f32_16x16x32_bf16 v[82:85], v[134:137], v[214:217], v[82:85]
	v_mfma_f32_16x16x32_bf16 v[74:77], v[142:145], v[214:217], v[74:77]
	v_mfma_f32_16x16x32_bf16 v[118:121], v[162:165], v[184:187], v[118:121]
	v_mfma_f32_16x16x32_bf16 v[114:117], v[176:179], v[184:187], v[114:117]
	v_mfma_f32_16x16x32_bf16 v[102:105], v[162:165], v[192:195], v[102:105]
	v_mfma_f32_16x16x32_bf16 v[94:97], v[176:179], v[192:195], v[94:97]
	v_mfma_f32_16x16x32_bf16 v[86:89], v[162:165], v[200:203], v[86:89]
	v_mfma_f32_16x16x32_bf16 v[78:81], v[176:179], v[200:203], v[78:81]
	v_mfma_f32_16x16x32_bf16 v[70:73], v[162:165], v[210:213], v[70:73]
	v_mfma_f32_16x16x32_bf16 v[66:69], v[176:179], v[210:213], v[66:69]
	v_mfma_f32_16x16x32_bf16 v[118:121], v[172:175], v[188:191], v[118:121]
	v_mfma_f32_16x16x32_bf16 v[114:117], v[180:183], v[188:191], v[114:117]
	v_mfma_f32_16x16x32_bf16 v[102:105], v[172:175], v[196:199], v[102:105]
	v_mfma_f32_16x16x32_bf16 v[94:97], v[180:183], v[196:199], v[94:97]
	v_mfma_f32_16x16x32_bf16 v[86:89], v[172:175], v[206:209], v[86:89]
	v_mfma_f32_16x16x32_bf16 v[78:81], v[180:183], v[206:209], v[78:81]
	v_mfma_f32_16x16x32_bf16 v[70:73], v[172:175], v[214:217], v[70:73]
	v_mfma_f32_16x16x32_bf16 v[66:69], v[180:183], v[214:217], v[66:69]
	s_setprio 0
	s_barrier
	s_add_i32 s94, s31, s2
	s_mov_b32 m0, s94
	v_lshl_add_u64 v[218:219], s[62:63], 0, v[148:149]
	global_load_lds_dwordx4 v[218:219], off
	ds_read_b128 v[184:187], v170 offset:16384
	ds_read_b128 v[188:191], v170 offset:17408
	s_add_i32 m0, s94, 0x2000
	s_add_u32 s94, s62, 0x100000
	v_lshl_add_u64 v[220:221], s[62:63], 0, v[152:153]
	s_addc_u32 s95, s63, 0
	s_add_i32 s96, s82, s2
	global_load_lds_dwordx4 v[220:221], off
	ds_read_b128 v[192:195], v170 offset:18432
	ds_read_b128 v[196:199], v170 offset:19456
	v_lshl_add_u64 v[222:223], s[94:95], 0, v[148:149]
	s_mov_b32 m0, s96
	v_lshl_add_u64 v[224:225], s[64:65], 0, v[150:151]
	global_load_lds_dwordx4 v[222:223], off
	ds_read_b128 v[200:203], v170 offset:20480
	ds_read_b128 v[206:209], v170 offset:21504
	s_add_i32 m0, s96, 0x2000
	v_lshl_add_u64 v[222:223], s[94:95], 0, v[152:153]
	global_load_lds_dwordx4 v[222:223], off
	ds_read_b128 v[210:213], v170 offset:22528
	ds_read_b128 v[214:217], v170 offset:23552
	s_mov_b32 m0, s12
	v_lshl_add_u64 v[222:223], s[64:65], 0, v[146:147]
	global_load_lds_dwordx4 v[222:223], off
	s_mov_b32 m0, s13
	s_nop 0
	global_load_lds_dwordx4 v[224:225], off
	s_waitcnt vmcnt(8) lgkmcnt(0)
	s_setprio 1
	s_barrier
	v_mfma_f32_16x16x32_bf16 v[62:65], v[130:133], v[184:187], v[62:65]
	v_mfma_f32_16x16x32_bf16 v[58:61], v[138:141], v[184:187], v[58:61]
	v_mfma_f32_16x16x32_bf16 v[50:53], v[130:133], v[192:195], v[50:53]
	v_mfma_f32_16x16x32_bf16 v[42:45], v[138:141], v[192:195], v[42:45]
	v_mfma_f32_16x16x32_bf16 v[34:37], v[130:133], v[200:203], v[34:37]
	v_mfma_f32_16x16x32_bf16 v[26:29], v[138:141], v[200:203], v[26:29]
	v_mfma_f32_16x16x32_bf16 v[18:21], v[130:133], v[210:213], v[18:21]
	v_mfma_f32_16x16x32_bf16 v[10:13], v[138:141], v[210:213], v[10:13]
	v_mfma_f32_16x16x32_bf16 v[62:65], v[134:137], v[188:191], v[62:65]
	v_mfma_f32_16x16x32_bf16 v[58:61], v[142:145], v[188:191], v[58:61]
	v_mfma_f32_16x16x32_bf16 v[50:53], v[134:137], v[196:199], v[50:53]
	v_mfma_f32_16x16x32_bf16 v[42:45], v[142:145], v[196:199], v[42:45]
	v_mfma_f32_16x16x32_bf16 v[34:37], v[134:137], v[206:209], v[34:37]
	v_mfma_f32_16x16x32_bf16 v[26:29], v[142:145], v[206:209], v[26:29]
	v_mfma_f32_16x16x32_bf16 v[18:21], v[134:137], v[214:217], v[18:21]
	v_mfma_f32_16x16x32_bf16 v[10:13], v[142:145], v[214:217], v[10:13]
	v_mfma_f32_16x16x32_bf16 v[54:57], v[162:165], v[184:187], v[54:57]
	v_mfma_f32_16x16x32_bf16 v[46:49], v[176:179], v[184:187], v[46:49]
	v_mfma_f32_16x16x32_bf16 v[38:41], v[162:165], v[192:195], v[38:41]
	v_mfma_f32_16x16x32_bf16 v[30:33], v[176:179], v[192:195], v[30:33]
	v_mfma_f32_16x16x32_bf16 v[22:25], v[162:165], v[200:203], v[22:25]
	v_mfma_f32_16x16x32_bf16 v[14:17], v[176:179], v[200:203], v[14:17]
	v_mfma_f32_16x16x32_bf16 v[6:9], v[162:165], v[210:213], v[6:9]
	v_mfma_f32_16x16x32_bf16 v[2:5], v[176:179], v[210:213], v[2:5]
	v_mfma_f32_16x16x32_bf16 v[54:57], v[172:175], v[188:191], v[54:57]
	v_mfma_f32_16x16x32_bf16 v[46:49], v[180:183], v[188:191], v[46:49]
	v_mfma_f32_16x16x32_bf16 v[38:41], v[172:175], v[196:199], v[38:41]
	v_mfma_f32_16x16x32_bf16 v[30:33], v[180:183], v[196:199], v[30:33]
	v_mfma_f32_16x16x32_bf16 v[22:25], v[172:175], v[206:209], v[22:25]
	v_mfma_f32_16x16x32_bf16 v[14:17], v[180:183], v[206:209], v[14:17]
	v_mfma_f32_16x16x32_bf16 v[6:9], v[172:175], v[214:217], v[6:9]
	v_mfma_f32_16x16x32_bf16 v[2:5], v[180:183], v[214:217], v[2:5]
	s_setprio 0
	s_barrier
	s_add_i32 s94, 0, 0x18000
	s_add_i32 s95, 0, 0x1c000
	v_add_u32_e32 v142, s94, v167
	v_add_u32_e32 v154, s95, v167
	ds_read_b128 v[130:133], v142
	ds_read_b128 v[134:137], v142 offset:1024
	ds_read_b128 v[138:141], v142 offset:2048
	ds_read_b128 v[142:145], v142 offset:3072
	ds_read_b128 v[162:165], v154
	ds_read_b128 v[172:175], v154 offset:1024
	ds_read_b128 v[176:179], v154 offset:2048
	ds_read_b128 v[180:183], v154 offset:3072
	s_add_u32 s64, s64, 0x100000
	s_addc_u32 s65, s65, 0
	s_mov_b32 m0, s18
	v_lshl_add_u64 v[226:227], s[64:65], 0, v[146:147]
	ds_read_b128 v[184:187], v170 offset:32768
	ds_read_b128 v[188:191], v170 offset:33792
	ds_read_b128 v[192:195], v170 offset:34816
	ds_read_b128 v[196:199], v170 offset:35840
	ds_read_b128 v[200:203], v170 offset:36864
	ds_read_b128 v[206:209], v170 offset:37888
	ds_read_b128 v[210:213], v170 offset:38912
	ds_read_b128 v[214:217], v170 offset:39936
	global_load_lds_dwordx4 v[226:227], off
	s_mov_b32 m0, s19
	v_lshl_add_u64 v[226:227], s[64:65], 0, v[150:151]
	global_load_lds_dwordx4 v[226:227], off
	s_waitcnt vmcnt(8) lgkmcnt(0)
	s_setprio 1
	s_barrier
	v_mfma_f32_16x16x32_bf16 v[126:129], v[130:133], v[184:187], v[126:129]
	v_mfma_f32_16x16x32_bf16 v[122:125], v[138:141], v[184:187], v[122:125]
	v_mfma_f32_16x16x32_bf16 v[110:113], v[130:133], v[192:195], v[110:113]
	v_mfma_f32_16x16x32_bf16 v[106:109], v[138:141], v[192:195], v[106:109]
	v_mfma_f32_16x16x32_bf16 v[98:101], v[130:133], v[200:203], v[98:101]
	v_mfma_f32_16x16x32_bf16 v[90:93], v[138:141], v[200:203], v[90:93]
	v_mfma_f32_16x16x32_bf16 v[82:85], v[130:133], v[210:213], v[82:85]
	v_mfma_f32_16x16x32_bf16 v[74:77], v[138:141], v[210:213], v[74:77]
	v_mfma_f32_16x16x32_bf16 v[126:129], v[134:137], v[188:191], v[126:129]
	v_mfma_f32_16x16x32_bf16 v[122:125], v[142:145], v[188:191], v[122:125]
	v_mfma_f32_16x16x32_bf16 v[110:113], v[134:137], v[196:199], v[110:113]
	v_mfma_f32_16x16x32_bf16 v[106:109], v[142:145], v[196:199], v[106:109]
	v_mfma_f32_16x16x32_bf16 v[98:101], v[134:137], v[206:209], v[98:101]
	v_mfma_f32_16x16x32_bf16 v[90:93], v[142:145], v[206:209], v[90:93]
	v_mfma_f32_16x16x32_bf16 v[82:85], v[134:137], v[214:217], v[82:85]
	v_mfma_f32_16x16x32_bf16 v[74:77], v[142:145], v[214:217], v[74:77]
	v_mfma_f32_16x16x32_bf16 v[118:121], v[162:165], v[184:187], v[118:121]
	v_mfma_f32_16x16x32_bf16 v[114:117], v[176:179], v[184:187], v[114:117]
	v_mfma_f32_16x16x32_bf16 v[102:105], v[162:165], v[192:195], v[102:105]
	v_mfma_f32_16x16x32_bf16 v[94:97], v[176:179], v[192:195], v[94:97]
	v_mfma_f32_16x16x32_bf16 v[86:89], v[162:165], v[200:203], v[86:89]
	v_mfma_f32_16x16x32_bf16 v[78:81], v[176:179], v[200:203], v[78:81]
	v_mfma_f32_16x16x32_bf16 v[70:73], v[162:165], v[210:213], v[70:73]
	v_mfma_f32_16x16x32_bf16 v[66:69], v[176:179], v[210:213], v[66:69]
	v_mfma_f32_16x16x32_bf16 v[118:121], v[172:175], v[188:191], v[118:121]
	v_mfma_f32_16x16x32_bf16 v[114:117], v[180:183], v[188:191], v[114:117]
	v_mfma_f32_16x16x32_bf16 v[102:105], v[172:175], v[196:199], v[102:105]
	v_mfma_f32_16x16x32_bf16 v[94:97], v[180:183], v[196:199], v[94:97]
	v_mfma_f32_16x16x32_bf16 v[86:89], v[172:175], v[206:209], v[86:89]
	v_mfma_f32_16x16x32_bf16 v[78:81], v[180:183], v[206:209], v[78:81]
	v_mfma_f32_16x16x32_bf16 v[70:73], v[172:175], v[214:217], v[70:73]
	v_mfma_f32_16x16x32_bf16 v[66:69], v[180:183], v[214:217], v[66:69]
	s_setprio 0
	s_barrier
	s_add_i32 s64, s94, s2
	s_mov_b32 m0, s64
	v_lshl_add_u64 v[218:219], v[218:219], 0, s[16:17]
	global_load_lds_dwordx4 v[218:219], off
	ds_read_b128 v[184:187], v170 offset:49152
	ds_read_b128 v[188:191], v170 offset:50176
	s_add_i32 m0, s64, 0x2000
	s_add_u32 s62, s62, 0x100080
	v_lshl_add_u64 v[218:219], v[220:221], 0, s[16:17]
	s_addc_u32 s63, s63, 0
	s_add_i32 s64, s95, s2
	global_load_lds_dwordx4 v[218:219], off
	ds_read_b128 v[192:195], v170 offset:51200
	ds_read_b128 v[196:199], v170 offset:52224
	s_mov_b32 m0, s64
	v_lshl_add_u64 v[218:219], s[62:63], 0, v[148:149]
	global_load_lds_dwordx4 v[218:219], off
	ds_read_b128 v[200:203], v170 offset:53248
	ds_read_b128 v[206:209], v170 offset:54272
	s_add_i32 m0, s64, 0x2000
	v_lshl_add_u64 v[218:219], s[62:63], 0, v[152:153]
	global_load_lds_dwordx4 v[218:219], off
	ds_read_b128 v[210:213], v170 offset:55296
	ds_read_b128 v[214:217], v170 offset:56320
	s_mov_b32 m0, s74
	v_lshl_add_u64 v[218:219], v[222:223], 0, s[16:17]
	global_load_lds_dwordx4 v[218:219], off
	s_mov_b32 m0, s75
	v_lshl_add_u64 v[218:219], v[224:225], 0, s[16:17]
	global_load_lds_dwordx4 v[218:219], off
	s_waitcnt vmcnt(8) lgkmcnt(0)
	s_setprio 1
	s_barrier
	v_mfma_f32_16x16x32_bf16 v[62:65], v[130:133], v[184:187], v[62:65]
	v_mfma_f32_16x16x32_bf16 v[58:61], v[138:141], v[184:187], v[58:61]
	v_mfma_f32_16x16x32_bf16 v[50:53], v[130:133], v[192:195], v[50:53]
	v_mfma_f32_16x16x32_bf16 v[42:45], v[138:141], v[192:195], v[42:45]
	v_mfma_f32_16x16x32_bf16 v[34:37], v[130:133], v[200:203], v[34:37]
	v_mfma_f32_16x16x32_bf16 v[26:29], v[138:141], v[200:203], v[26:29]
	v_mfma_f32_16x16x32_bf16 v[18:21], v[130:133], v[210:213], v[18:21]
	v_mfma_f32_16x16x32_bf16 v[10:13], v[138:141], v[210:213], v[10:13]
	v_mfma_f32_16x16x32_bf16 v[62:65], v[134:137], v[188:191], v[62:65]
	v_mfma_f32_16x16x32_bf16 v[58:61], v[142:145], v[188:191], v[58:61]
	v_mfma_f32_16x16x32_bf16 v[50:53], v[134:137], v[196:199], v[50:53]
	v_mfma_f32_16x16x32_bf16 v[42:45], v[142:145], v[196:199], v[42:45]
	v_mfma_f32_16x16x32_bf16 v[34:37], v[134:137], v[206:209], v[34:37]
	v_mfma_f32_16x16x32_bf16 v[26:29], v[142:145], v[206:209], v[26:29]
	v_mfma_f32_16x16x32_bf16 v[18:21], v[134:137], v[214:217], v[18:21]
	v_mfma_f32_16x16x32_bf16 v[10:13], v[142:145], v[214:217], v[10:13]
	v_mfma_f32_16x16x32_bf16 v[54:57], v[162:165], v[184:187], v[54:57]
	v_mfma_f32_16x16x32_bf16 v[46:49], v[176:179], v[184:187], v[46:49]
	v_mfma_f32_16x16x32_bf16 v[38:41], v[162:165], v[192:195], v[38:41]
	v_mfma_f32_16x16x32_bf16 v[30:33], v[176:179], v[192:195], v[30:33]
	v_mfma_f32_16x16x32_bf16 v[22:25], v[162:165], v[200:203], v[22:25]
	v_mfma_f32_16x16x32_bf16 v[14:17], v[176:179], v[200:203], v[14:17]
	v_mfma_f32_16x16x32_bf16 v[6:9], v[162:165], v[210:213], v[6:9]
	v_mfma_f32_16x16x32_bf16 v[2:5], v[176:179], v[210:213], v[2:5]
	v_mfma_f32_16x16x32_bf16 v[54:57], v[172:175], v[188:191], v[54:57]
	v_mfma_f32_16x16x32_bf16 v[46:49], v[180:183], v[188:191], v[46:49]
	v_mfma_f32_16x16x32_bf16 v[38:41], v[172:175], v[196:199], v[38:41]
	v_mfma_f32_16x16x32_bf16 v[30:33], v[180:183], v[196:199], v[30:33]
	v_mfma_f32_16x16x32_bf16 v[22:25], v[172:175], v[206:209], v[22:25]
	v_mfma_f32_16x16x32_bf16 v[14:17], v[180:183], v[206:209], v[14:17]
	v_mfma_f32_16x16x32_bf16 v[6:9], v[172:175], v[214:217], v[6:9]
	v_mfma_f32_16x16x32_bf16 v[2:5], v[180:183], v[214:217], v[2:5]
	s_setprio 0
	s_barrier
	s_add_u32 s50, s50, 0x100
	s_addc_u32 s51, s51, 0
	s_add_u32 s91, s91, 0x100
	s_addc_u32 s92, s92, 0
	s_cmp_ge_i32 s93, s7
	s_mov_b32 s62, s93
	s_cbranch_scc0 .LBB0_1708
	s_and_b64 vcc, exec, s[20:21]
	s_cbranch_vccz .LBB0_1711
	s_barrier
